# outproj tiles: residual/gate addressing hoisted before the main loop, all residual loads issued inside the last k-stage, epilogue is fmac+store only; non-temporal stores for the final output
# speedup vs baseline: 1.1633x; 1.0150x over previous
.LBB0_89:
	s_ashr_i32 s0, s2, 31
	s_lshr_b32 s0, s0, 26
	s_add_i32 s0, s2, s0
	s_andn2_b32 s0, s0, 63
	s_sub_i32 s1, s2, s0
	s_bfe_i32 s22, s1, 0x80000
	s_bfe_u32 s22, s22, 0x3000c
	s_add_i32 s23, s1, s22
	s_bfe_i32 s22, s23, 0x80000
	s_sext_i32_i16 s22, s22
	s_and_b32 s22, s22, -8
	s_add_i32 s22, s22, s0
	v_readlane_b32 s0, v246, 0
	s_or_b32 s22, s22, s0
	s_and_b32 s0, s23, 0xf8
	s_sub_i32 s0, s1, s0
	s_sext_i32_i8 s0, s0
	s_lshl_b32 s24, s22, 7
	s_lshl_b32 s23, s0, 7
	s_mov_b64 s[0:1], s[8:9]
	v_ashrrev_i32_e32 v1, 1, v184
	v_and_b32_e32 v1, 0xffffffc0, v1
	v_lshrrev_b32_e32 v67, 3, v184
	v_and_b32_e32 v67, 4, v67
	v_add_u32_e32 v1, s24, v1
	v_or_b32_e32 v1, v1, v67
	v_and_b32_e32 v68, 0x5f, v184
	v_or_b32_e32 v68, s23, v68
	v_lshlrev_b32_e32 v69, 2, v68
	v_lshl_add_u32 v70, v1, 12, v69
	s_add_i32 s28, s24, 0xffffe000
	s_ashr_i32 s28, s28, 12
	s_mulk_i32 s28, 0xc00
	s_addk_i32 s28, 0x800
	s_cmp_gt_i32 s22, 63
	s_cselect_b32 s28, s28, 0x6800
	v_add_lshl_u32 v71, v68, s28, 2
	v_mov_b32_e32 v218, v70
	v_add_u32_e32 v219, 0x1000, v70
	v_add_u32_e32 v220, 0x2000, v70
	v_add_u32_e32 v221, 0x3000, v70
	v_add_u32_e32 v222, 0x8000, v70
	v_add_u32_e32 v223, 0x9000, v70
	v_add_u32_e32 v224, 0xa000, v70
	v_add_u32_e32 v225, 0xb000, v70
	v_add_u32_e32 v226, 0x10000, v70
	v_add_u32_e32 v227, 0x11000, v70
	v_add_u32_e32 v228, 0x12000, v70
	v_add_u32_e32 v229, 0x13000, v70
	v_add_u32_e32 v230, 0x18000, v70
	v_add_u32_e32 v231, 0x19000, v70
	v_add_u32_e32 v232, 0x1a000, v70
	v_add_u32_e32 v233, 0x1b000, v70
	global_load_dword v234, v71, s[0:1]
	global_load_dword v235, v71, s[0:1] offset:128
	s_barrier
	v_lshrrev_b32_e32 v122, 6, v184
	v_and_b32_e32 v123, 63, v184
	v_readfirstlane_b32 s39, v122
	v_lshrrev_b32_e32 v124, 4, v123
	v_and_b32_e32 v125, 15, v123
	v_lshlrev_b32_e32 v126, 2, v124
	v_xor_b32_e32 v125, v125, v126
	v_mul_u32_u24_e32 v124, 0x14000, v124
	v_readlane_b32 s0, v247, 58
	v_readlane_b32 s1, v247, 59
	s_nop 3
	s_lshl_b32 s101, s39, 12
	s_mul_i32 s100, s39, 0x140000
	s_lshl_b32 s28, s24, 1
	s_add_u32 s100, s100, s28
	s_add_u32 s100, s100, 0x604a000
	s_add_u32 s28, s68, s100
	s_addc_u32 s29, s69, 0
	v_xor_b32_e32 v126, 0, v125
	v_lshl_add_u32 v126, v126, 4, v124
	v_mov_b32_e32 v127, 0
	v_lshl_add_u64 v[98:99], v[126:127], 0, s[28:29]
	s_add_u32 s28, s28, 0x50000
	s_addc_u32 s29, s29, 0
	v_xor_b32_e32 v126, 1, v125
	v_lshl_add_u32 v126, v126, 4, v124
	v_mov_b32_e32 v127, 0
	v_lshl_add_u64 v[100:101], v[126:127], 0, s[28:29]
	s_add_u32 s28, s28, 0x50000
	s_addc_u32 s29, s29, 0
	v_xor_b32_e32 v126, 2, v125
	v_lshl_add_u32 v126, v126, 4, v124
	v_mov_b32_e32 v127, 0
	v_lshl_add_u64 v[102:103], v[126:127], 0, s[28:29]
	s_add_u32 s28, s28, 0x50000
	s_addc_u32 s29, s29, 0
	v_xor_b32_e32 v126, 3, v125
	v_lshl_add_u32 v126, v126, 4, v124
	v_mov_b32_e32 v127, 0
	v_lshl_add_u64 v[104:105], v[126:127], 0, s[28:29]
	v_lshrrev_b32_e32 v124, 3, v123
	v_lshrrev_b32_e32 v125, 4, v123
	v_and_b32_e32 v126, 7, v123
	s_lshl_b32 s100, s39, 5
	s_add_i32 s100, s100, s23
	s_lshl_b32 s100, s100, 11
	s_add_u32 s0, s0, s100
	s_addc_u32 s1, s1, 0
	v_and_b32_e32 v127, 7, v125
	v_xor_b32_e32 v127, v126, v127
	v_lshlrev_b32_e32 v127, 4, v127
	v_lshl_add_u32 v128, v124, 11, v127
	v_mov_b32_e32 v96, v128
	v_mov_b32_e32 v97, 0
	v_lshl_add_u64 v[106:107], v[96:97], 0, s[0:1]
	s_add_u32 s0, s0, 0x4000
	s_addc_u32 s1, s1, 0
	v_add_u32_e32 v127, 4, v125
	v_and_b32_e32 v127, 7, v127
	v_xor_b32_e32 v127, v126, v127
	v_lshlrev_b32_e32 v127, 4, v127
	v_lshl_add_u32 v128, v124, 11, v127
	v_mov_b32_e32 v96, v128
	v_mov_b32_e32 v97, 0
	v_lshl_add_u64 v[108:109], v[96:97], 0, s[0:1]
	s_add_u32 s0, s0, 0x4000
	s_addc_u32 s1, s1, 0
	v_and_b32_e32 v127, 7, v125
	v_xor_b32_e32 v127, v126, v127
	v_lshlrev_b32_e32 v127, 4, v127
	v_lshl_add_u32 v128, v124, 11, v127
	v_mov_b32_e32 v96, v128
	v_mov_b32_e32 v97, 0
	v_lshl_add_u64 v[110:111], v[96:97], 0, s[0:1]
	s_add_u32 s0, s0, 0x4000
	s_addc_u32 s1, s1, 0
	v_add_u32_e32 v127, 4, v125
	v_and_b32_e32 v127, 7, v127
	v_xor_b32_e32 v127, v126, v127
	v_lshlrev_b32_e32 v127, 4, v127
	v_lshl_add_u32 v128, v124, 11, v127
	v_mov_b32_e32 v96, v128
	v_mov_b32_e32 v97, 0
	v_lshl_add_u64 v[112:113], v[96:97], 0, s[0:1]
	s_mov_b32 s28, 0x500000
	s_mov_b32 s29, 0
	s_mov_b32 s36, 128
	s_mov_b32 s37, 0
	s_add_u32 m0, s101, 0x0
	s_nop 0
	global_load_lds_dwordx4 v[98:99], off
	v_lshl_add_u64 v[98:99], v[98:99], 0, s[28:29]
	s_add_u32 m0, s101, 0x400
	s_nop 0
	global_load_lds_dwordx4 v[100:101], off
	v_lshl_add_u64 v[100:101], v[100:101], 0, s[28:29]
	s_add_u32 m0, s101, 0x800
	s_nop 0
	global_load_lds_dwordx4 v[102:103], off
	v_lshl_add_u64 v[102:103], v[102:103], 0, s[28:29]
	s_add_u32 m0, s101, 0xc00
	s_nop 0
	global_load_lds_dwordx4 v[104:105], off
	v_lshl_add_u64 v[104:105], v[104:105], 0, s[28:29]
	s_add_u32 m0, s101, 0x4000
	s_nop 0
	global_load_lds_dwordx4 v[106:107], off
	v_lshl_add_u64 v[106:107], v[106:107], 0, s[36:37]
	s_add_u32 m0, s101, 0x4400
	s_nop 0
	global_load_lds_dwordx4 v[108:109], off
	v_lshl_add_u64 v[108:109], v[108:109], 0, s[36:37]
	s_add_u32 m0, s101, 0x4800
	s_nop 0
	global_load_lds_dwordx4 v[110:111], off
	v_lshl_add_u64 v[110:111], v[110:111], 0, s[36:37]
	s_add_u32 m0, s101, 0x4c00
	s_nop 0
	global_load_lds_dwordx4 v[112:113], off
	v_lshl_add_u64 v[112:113], v[112:113], 0, s[36:37]
	v_and_b32_e32 v122, 31, v123
	v_lshrrev_b32_e32 v124, 5, v123
	v_bfe_u32 v125, v123, 4, 1
	v_bfe_u32 v126, v123, 2, 2
	v_and_b32_e32 v127, 3, v123
	s_lshr_b32 s38, s39, 1
	s_and_b32 s39, s39, 1
	v_lshlrev_b32_e32 v96, 1, v124
	v_add_u32_e32 v96, 0, v96
	v_and_b32_e32 v96, 3, v96
	v_lshl_or_b32 v96, v126, 2, v96
	v_lshrrev_b32_e32 v97, 1, v127
	v_lshl_or_b32 v97, v125, 1, v97
	v_or_b32_e32 v97, 0, v97
	s_lshl_b32 s0, s38, 3
	v_or_b32_e32 v97, s0, v97
	v_xor_b32_e32 v97, v97, v96
	v_lshlrev_b32_e32 v96, 3, v124
	v_add3_u32 v96, v96, v126, 0
	v_lshlrev_b32_e32 v96, 8, v96
	v_lshl_add_u32 v96, v97, 4, v96
	v_and_b32_e32 v97, 1, v127
	v_lshl_add_u32 v114, v97, 3, v96
	v_lshlrev_b32_e32 v96, 1, v124
	v_add_u32_e32 v96, 1, v96
	v_and_b32_e32 v96, 3, v96
	v_lshl_or_b32 v96, v126, 2, v96
	v_lshrrev_b32_e32 v97, 1, v127
	v_lshl_or_b32 v97, v125, 1, v97
	v_or_b32_e32 v97, 0, v97
	s_lshl_b32 s0, s38, 3
	v_or_b32_e32 v97, s0, v97
	v_xor_b32_e32 v97, v97, v96
	v_lshlrev_b32_e32 v96, 3, v124
	v_add3_u32 v96, v96, v126, 4
	v_lshlrev_b32_e32 v96, 8, v96
	v_lshl_add_u32 v96, v97, 4, v96
	v_and_b32_e32 v97, 1, v127
	v_lshl_add_u32 v115, v97, 3, v96
	v_lshlrev_b32_e32 v96, 1, v124
	v_add_u32_e32 v96, 0, v96
	v_and_b32_e32 v96, 3, v96
	v_lshl_or_b32 v96, v126, 2, v96
	v_lshrrev_b32_e32 v97, 1, v127
	v_lshl_or_b32 v97, v125, 1, v97
	v_or_b32_e32 v97, 4, v97
	s_lshl_b32 s0, s38, 3
	v_or_b32_e32 v97, s0, v97
	v_xor_b32_e32 v97, v97, v96
	v_lshlrev_b32_e32 v96, 3, v124
	v_add3_u32 v96, v96, v126, 0
	v_lshlrev_b32_e32 v96, 8, v96
	v_lshl_add_u32 v96, v97, 4, v96
	v_and_b32_e32 v97, 1, v127
	v_lshl_add_u32 v116, v97, 3, v96
	v_lshlrev_b32_e32 v96, 1, v124
	v_add_u32_e32 v96, 1, v96
	v_and_b32_e32 v96, 3, v96
	v_lshl_or_b32 v96, v126, 2, v96
	v_lshrrev_b32_e32 v97, 1, v127
	v_lshl_or_b32 v97, v125, 1, v97
	v_or_b32_e32 v97, 4, v97
	s_lshl_b32 s0, s38, 3
	v_or_b32_e32 v97, s0, v97
	v_xor_b32_e32 v97, v97, v96
	v_lshlrev_b32_e32 v96, 3, v124
	v_add3_u32 v96, v96, v126, 4
	v_lshlrev_b32_e32 v96, 8, v96
	v_lshl_add_u32 v96, v97, 4, v96
	v_and_b32_e32 v97, 1, v127
	v_lshl_add_u32 v117, v97, 3, v96
	v_bfe_u32 v96, v122, 1, 3
	v_xor_b32_e32 v96, v96, v124
	v_lshlrev_b32_e32 v96, 4, v96
	v_lshl_add_u32 v96, v122, 7, v96
	s_lshl_b32 s0, s39, 13
	v_add_u32_e32 v118, s0, v96
	v_xor_b32_e32 v119, 0x20, v118
	v_xor_b32_e32 v120, 0x40, v118
	v_xor_b32_e32 v121, 0x60, v118
	v_mov_b32_e32 v2, 0
	v_mov_b32_e32 v3, v2
	v_mov_b32_e32 v4, v2
	v_mov_b32_e32 v5, v2
	v_mov_b32_e32 v6, v2
	v_mov_b32_e32 v7, v2
	v_mov_b32_e32 v8, v2
	v_mov_b32_e32 v9, v2
	v_mov_b32_e32 v10, v2
	v_mov_b32_e32 v11, v2
	v_mov_b32_e32 v12, v2
	v_mov_b32_e32 v13, v2
	v_mov_b32_e32 v14, v2
	v_mov_b32_e32 v15, v2
	v_mov_b32_e32 v16, v2
	v_mov_b32_e32 v17, v2
	v_mov_b32_e32 v18, v2
	v_mov_b32_e32 v19, v2
	v_mov_b32_e32 v20, v2
	v_mov_b32_e32 v21, v2
	v_mov_b32_e32 v22, v2
	v_mov_b32_e32 v23, v2
	v_mov_b32_e32 v24, v2
	v_mov_b32_e32 v25, v2
	v_mov_b32_e32 v26, v2
	v_mov_b32_e32 v27, v2
	v_mov_b32_e32 v28, v2
	v_mov_b32_e32 v29, v2
	v_mov_b32_e32 v30, v2
	v_mov_b32_e32 v31, v2
	v_mov_b32_e32 v32, v2
	v_mov_b32_e32 v33, v2
	v_mov_b32_e32 v34, v2
	v_mov_b32_e32 v35, v2
	v_mov_b32_e32 v36, v2
	v_mov_b32_e32 v37, v2
	v_mov_b32_e32 v38, v2
	v_mov_b32_e32 v39, v2
	v_mov_b32_e32 v40, v2
	v_mov_b32_e32 v41, v2
	v_mov_b32_e32 v42, v2
	v_mov_b32_e32 v43, v2
	v_mov_b32_e32 v44, v2
	v_mov_b32_e32 v45, v2
	v_mov_b32_e32 v46, v2
	v_mov_b32_e32 v47, v2
	v_mov_b32_e32 v48, v2
	v_mov_b32_e32 v49, v2
	v_mov_b32_e32 v50, v2
	v_mov_b32_e32 v51, v2
	v_mov_b32_e32 v52, v2
	v_mov_b32_e32 v53, v2
	v_mov_b32_e32 v54, v2
	v_mov_b32_e32 v55, v2
	v_mov_b32_e32 v56, v2
	v_mov_b32_e32 v57, v2
	v_mov_b32_e32 v58, v2
	v_mov_b32_e32 v59, v2
	v_mov_b32_e32 v60, v2
	v_mov_b32_e32 v61, v2
	v_mov_b32_e32 v62, v2
	v_mov_b32_e32 v63, v2
	v_mov_b32_e32 v64, v2
	v_mov_b32_e32 v65, v2
	v_readlane_b32 s0, v248, 2
	v_readlane_b32 s1, v248, 3
	s_nop 3
	s_add_u32 s38, s0, 0x20000
	s_addc_u32 s39, s1, 0
	s_mov_b32 s100, 7
.LgemmT_p10_loop:
	s_waitcnt vmcnt(0)
	s_barrier
	ds_read_b64_tr_b16 v[66:67], v114 offset:0
	ds_read_b64_tr_b16 v[68:69], v115 offset:0
	ds_read_b64_tr_b16 v[70:71], v116 offset:0
	ds_read_b64_tr_b16 v[72:73], v117 offset:0
	ds_read_b128 v[74:77], v118 offset:16384
	ds_read_b128 v[78:81], v118 offset:20480
	ds_read_b64_tr_b16 v[82:83], v114 offset:4096
	ds_read_b64_tr_b16 v[84:85], v115 offset:4096
	ds_read_b64_tr_b16 v[86:87], v116 offset:4096
	ds_read_b64_tr_b16 v[88:89], v117 offset:4096
	ds_read_b128 v[90:93], v119 offset:16384
	ds_read_b128 v[94:97], v119 offset:20480
	s_add_u32 m0, s101, 0x8000
	s_nop 0
	global_load_lds_dwordx4 v[98:99], off
	v_lshl_add_u64 v[98:99], v[98:99], 0, s[28:29]
	s_add_u32 m0, s101, 0x8400
	s_nop 0
	global_load_lds_dwordx4 v[100:101], off
	v_lshl_add_u64 v[100:101], v[100:101], 0, s[28:29]
	s_waitcnt lgkmcnt(6)
	v_mfma_f32_32x32x16_bf16 v[50:65], v[66:69], v[74:77], v[50:65]
	v_mfma_f32_32x32x16_bf16 v[34:49], v[66:69], v[78:81], v[34:49]
	v_mfma_f32_32x32x16_bf16 v[18:33], v[70:73], v[74:77], v[18:33]
	v_mfma_f32_32x32x16_bf16 v[2:17], v[70:73], v[78:81], v[2:17]
	ds_read_b64_tr_b16 v[66:67], v114 offset:8192
	ds_read_b64_tr_b16 v[68:69], v115 offset:8192
	ds_read_b64_tr_b16 v[70:71], v116 offset:8192
	ds_read_b64_tr_b16 v[72:73], v117 offset:8192
	ds_read_b128 v[74:77], v120 offset:16384
	ds_read_b128 v[78:81], v120 offset:20480
	s_add_u32 m0, s101, 0x8800
	s_nop 0
	global_load_lds_dwordx4 v[102:103], off
	v_lshl_add_u64 v[102:103], v[102:103], 0, s[28:29]
	s_add_u32 m0, s101, 0x8c00
	s_nop 0
	global_load_lds_dwordx4 v[104:105], off
	v_lshl_add_u64 v[104:105], v[104:105], 0, s[28:29]
	s_waitcnt lgkmcnt(6)
	v_mfma_f32_32x32x16_bf16 v[50:65], v[82:85], v[90:93], v[50:65]
	v_mfma_f32_32x32x16_bf16 v[34:49], v[82:85], v[94:97], v[34:49]
	v_mfma_f32_32x32x16_bf16 v[18:33], v[86:89], v[90:93], v[18:33]
	v_mfma_f32_32x32x16_bf16 v[2:17], v[86:89], v[94:97], v[2:17]
	ds_read_b64_tr_b16 v[82:83], v114 offset:12288
	ds_read_b64_tr_b16 v[84:85], v115 offset:12288
	ds_read_b64_tr_b16 v[86:87], v116 offset:12288
	ds_read_b64_tr_b16 v[88:89], v117 offset:12288
	ds_read_b128 v[90:93], v121 offset:16384
	ds_read_b128 v[94:97], v121 offset:20480
	s_add_u32 m0, s101, 0xc010
	s_nop 0
	global_load_lds_dwordx4 v[106:107], off
	v_lshl_add_u64 v[106:107], v[106:107], 0, s[36:37]
	s_add_u32 m0, s101, 0xc410
	s_nop 0
	global_load_lds_dwordx4 v[108:109], off
	v_lshl_add_u64 v[108:109], v[108:109], 0, s[36:37]
	s_waitcnt lgkmcnt(6)
	v_mfma_f32_32x32x16_bf16 v[50:65], v[66:69], v[74:77], v[50:65]
	v_mfma_f32_32x32x16_bf16 v[34:49], v[66:69], v[78:81], v[34:49]
	v_mfma_f32_32x32x16_bf16 v[18:33], v[70:73], v[74:77], v[18:33]
	v_mfma_f32_32x32x16_bf16 v[2:17], v[70:73], v[78:81], v[2:17]
	s_add_u32 m0, s101, 0xc810
	s_nop 0
	global_load_lds_dwordx4 v[110:111], off
	v_lshl_add_u64 v[110:111], v[110:111], 0, s[36:37]
	s_add_u32 m0, s101, 0xcc10
	s_nop 0
	global_load_lds_dwordx4 v[112:113], off
	v_lshl_add_u64 v[112:113], v[112:113], 0, s[36:37]
	s_waitcnt lgkmcnt(0)
	v_mfma_f32_32x32x16_bf16 v[50:65], v[82:85], v[90:93], v[50:65]
	v_mfma_f32_32x32x16_bf16 v[34:49], v[82:85], v[94:97], v[34:49]
	v_mfma_f32_32x32x16_bf16 v[18:33], v[86:89], v[90:93], v[18:33]
	v_mfma_f32_32x32x16_bf16 v[2:17], v[86:89], v[94:97], v[2:17]
	s_waitcnt vmcnt(0)
	s_barrier
	ds_read_b64_tr_b16 v[66:67], v114 offset:32768
	ds_read_b64_tr_b16 v[68:69], v115 offset:32768
	ds_read_b64_tr_b16 v[70:71], v116 offset:32768
	ds_read_b64_tr_b16 v[72:73], v117 offset:32768
	ds_read_b128 v[74:77], v118 offset:49168
	ds_read_b128 v[78:81], v118 offset:53264
	ds_read_b64_tr_b16 v[82:83], v114 offset:36864
	ds_read_b64_tr_b16 v[84:85], v115 offset:36864
	ds_read_b64_tr_b16 v[86:87], v116 offset:36864
	ds_read_b64_tr_b16 v[88:89], v117 offset:36864
	ds_read_b128 v[90:93], v119 offset:49168
	ds_read_b128 v[94:97], v119 offset:53264
	s_add_u32 m0, s101, 0x0
	s_nop 0
	global_load_lds_dwordx4 v[98:99], off
	v_lshl_add_u64 v[98:99], v[98:99], 0, s[28:29]
	s_add_u32 m0, s101, 0x400
	s_nop 0
	global_load_lds_dwordx4 v[100:101], off
	v_lshl_add_u64 v[100:101], v[100:101], 0, s[28:29]
	s_waitcnt lgkmcnt(6)
	v_mfma_f32_32x32x16_bf16 v[50:65], v[66:69], v[74:77], v[50:65]
	v_mfma_f32_32x32x16_bf16 v[34:49], v[66:69], v[78:81], v[34:49]
	v_mfma_f32_32x32x16_bf16 v[18:33], v[70:73], v[74:77], v[18:33]
	v_mfma_f32_32x32x16_bf16 v[2:17], v[70:73], v[78:81], v[2:17]
	ds_read_b64_tr_b16 v[66:67], v114 offset:40960
	ds_read_b64_tr_b16 v[68:69], v115 offset:40960
	ds_read_b64_tr_b16 v[70:71], v116 offset:40960
	ds_read_b64_tr_b16 v[72:73], v117 offset:40960
	ds_read_b128 v[74:77], v120 offset:49168
	ds_read_b128 v[78:81], v120 offset:53264
	s_add_u32 m0, s101, 0x800
	s_nop 0
	global_load_lds_dwordx4 v[102:103], off
	v_lshl_add_u64 v[102:103], v[102:103], 0, s[28:29]
	s_add_u32 m0, s101, 0xc00
	s_nop 0
	global_load_lds_dwordx4 v[104:105], off
	v_lshl_add_u64 v[104:105], v[104:105], 0, s[28:29]
	s_waitcnt lgkmcnt(6)
	v_mfma_f32_32x32x16_bf16 v[50:65], v[82:85], v[90:93], v[50:65]
	v_mfma_f32_32x32x16_bf16 v[34:49], v[82:85], v[94:97], v[34:49]
	v_mfma_f32_32x32x16_bf16 v[18:33], v[86:89], v[90:93], v[18:33]
	v_mfma_f32_32x32x16_bf16 v[2:17], v[86:89], v[94:97], v[2:17]
	ds_read_b64_tr_b16 v[82:83], v114 offset:45056
	ds_read_b64_tr_b16 v[84:85], v115 offset:45056
	ds_read_b64_tr_b16 v[86:87], v116 offset:45056
	ds_read_b64_tr_b16 v[88:89], v117 offset:45056
	ds_read_b128 v[90:93], v121 offset:49168
	ds_read_b128 v[94:97], v121 offset:53264
	s_add_u32 m0, s101, 0x4000
	s_nop 0
	global_load_lds_dwordx4 v[106:107], off
	v_lshl_add_u64 v[106:107], v[106:107], 0, s[36:37]
	s_add_u32 m0, s101, 0x4400
	s_nop 0
	global_load_lds_dwordx4 v[108:109], off
	v_lshl_add_u64 v[108:109], v[108:109], 0, s[36:37]
	s_waitcnt lgkmcnt(6)
	v_mfma_f32_32x32x16_bf16 v[50:65], v[66:69], v[74:77], v[50:65]
	v_mfma_f32_32x32x16_bf16 v[34:49], v[66:69], v[78:81], v[34:49]
	v_mfma_f32_32x32x16_bf16 v[18:33], v[70:73], v[74:77], v[18:33]
	v_mfma_f32_32x32x16_bf16 v[2:17], v[70:73], v[78:81], v[2:17]
	s_add_u32 m0, s101, 0x4800
	s_nop 0
	global_load_lds_dwordx4 v[110:111], off
	v_lshl_add_u64 v[110:111], v[110:111], 0, s[36:37]
	s_add_u32 m0, s101, 0x4c00
	s_nop 0
	global_load_lds_dwordx4 v[112:113], off
	v_lshl_add_u64 v[112:113], v[112:113], 0, s[36:37]
	s_waitcnt lgkmcnt(0)
	v_mfma_f32_32x32x16_bf16 v[50:65], v[82:85], v[90:93], v[50:65]
	v_mfma_f32_32x32x16_bf16 v[34:49], v[82:85], v[94:97], v[34:49]
	v_mfma_f32_32x32x16_bf16 v[18:33], v[86:89], v[90:93], v[18:33]
	v_mfma_f32_32x32x16_bf16 v[2:17], v[86:89], v[94:97], v[2:17]
	s_sub_u32 s100, s100, 1
	s_cmp_lg_u32 s100, 0
	s_cbranch_scc1 .LgemmT_p10_loop
	s_waitcnt vmcnt(0)
	s_barrier
	ds_read_b64_tr_b16 v[66:67], v114 offset:0
	ds_read_b64_tr_b16 v[68:69], v115 offset:0
	ds_read_b64_tr_b16 v[70:71], v116 offset:0
	ds_read_b64_tr_b16 v[72:73], v117 offset:0
	ds_read_b128 v[74:77], v118 offset:16384
	ds_read_b128 v[78:81], v118 offset:20480
	ds_read_b64_tr_b16 v[82:83], v114 offset:4096
	ds_read_b64_tr_b16 v[84:85], v115 offset:4096
	ds_read_b64_tr_b16 v[86:87], v116 offset:4096
	ds_read_b64_tr_b16 v[88:89], v117 offset:4096
	ds_read_b128 v[90:93], v119 offset:16384
	ds_read_b128 v[94:97], v119 offset:20480
	s_add_u32 m0, s101, 0x8000
	s_nop 0
	global_load_lds_dwordx4 v[98:99], off
	v_lshl_add_u64 v[98:99], v[98:99], 0, s[28:29]
	s_add_u32 m0, s101, 0x8400
	s_nop 0
	global_load_lds_dwordx4 v[100:101], off
	v_lshl_add_u64 v[100:101], v[100:101], 0, s[28:29]
	s_waitcnt lgkmcnt(6)
	v_mfma_f32_32x32x16_bf16 v[50:65], v[66:69], v[74:77], v[50:65]
	v_mfma_f32_32x32x16_bf16 v[34:49], v[66:69], v[78:81], v[34:49]
	v_mfma_f32_32x32x16_bf16 v[18:33], v[70:73], v[74:77], v[18:33]
	v_mfma_f32_32x32x16_bf16 v[2:17], v[70:73], v[78:81], v[2:17]
	ds_read_b64_tr_b16 v[66:67], v114 offset:8192
	ds_read_b64_tr_b16 v[68:69], v115 offset:8192
	ds_read_b64_tr_b16 v[70:71], v116 offset:8192
	ds_read_b64_tr_b16 v[72:73], v117 offset:8192
	ds_read_b128 v[74:77], v120 offset:16384
	ds_read_b128 v[78:81], v120 offset:20480
	s_add_u32 m0, s101, 0x8800
	s_nop 0
	global_load_lds_dwordx4 v[102:103], off
	v_lshl_add_u64 v[102:103], v[102:103], 0, s[28:29]
	s_add_u32 m0, s101, 0x8c00
	s_nop 0
	global_load_lds_dwordx4 v[104:105], off
	v_lshl_add_u64 v[104:105], v[104:105], 0, s[28:29]
	s_waitcnt lgkmcnt(6)
	v_mfma_f32_32x32x16_bf16 v[50:65], v[82:85], v[90:93], v[50:65]
	v_mfma_f32_32x32x16_bf16 v[34:49], v[82:85], v[94:97], v[34:49]
	v_mfma_f32_32x32x16_bf16 v[18:33], v[86:89], v[90:93], v[18:33]
	v_mfma_f32_32x32x16_bf16 v[2:17], v[86:89], v[94:97], v[2:17]
	ds_read_b64_tr_b16 v[82:83], v114 offset:12288
	ds_read_b64_tr_b16 v[84:85], v115 offset:12288
	ds_read_b64_tr_b16 v[86:87], v116 offset:12288
	ds_read_b64_tr_b16 v[88:89], v117 offset:12288
	ds_read_b128 v[90:93], v121 offset:16384
	ds_read_b128 v[94:97], v121 offset:20480
	s_add_u32 m0, s101, 0xc010
	s_nop 0
	global_load_lds_dwordx4 v[106:107], off
	v_lshl_add_u64 v[106:107], v[106:107], 0, s[36:37]
	s_add_u32 m0, s101, 0xc410
	s_nop 0
	global_load_lds_dwordx4 v[108:109], off
	v_lshl_add_u64 v[108:109], v[108:109], 0, s[36:37]
	s_waitcnt lgkmcnt(6)
	v_mfma_f32_32x32x16_bf16 v[50:65], v[66:69], v[74:77], v[50:65]
	v_mfma_f32_32x32x16_bf16 v[34:49], v[66:69], v[78:81], v[34:49]
	v_mfma_f32_32x32x16_bf16 v[18:33], v[70:73], v[74:77], v[18:33]
	v_mfma_f32_32x32x16_bf16 v[2:17], v[70:73], v[78:81], v[2:17]
	s_add_u32 m0, s101, 0xc810
	s_nop 0
	global_load_lds_dwordx4 v[110:111], off
	v_lshl_add_u64 v[110:111], v[110:111], 0, s[36:37]
	s_add_u32 m0, s101, 0xcc10
	s_nop 0
	global_load_lds_dwordx4 v[112:113], off
	v_lshl_add_u64 v[112:113], v[112:113], 0, s[36:37]
	s_waitcnt lgkmcnt(0)
	v_mfma_f32_32x32x16_bf16 v[50:65], v[82:85], v[90:93], v[50:65]
	v_mfma_f32_32x32x16_bf16 v[34:49], v[82:85], v[94:97], v[34:49]
	v_mfma_f32_32x32x16_bf16 v[18:33], v[86:89], v[90:93], v[18:33]
	v_mfma_f32_32x32x16_bf16 v[2:17], v[86:89], v[94:97], v[2:17]
	s_waitcnt vmcnt(0)
	s_barrier
	ds_read_b64_tr_b16 v[66:67], v114 offset:32768
	ds_read_b64_tr_b16 v[68:69], v115 offset:32768
	ds_read_b64_tr_b16 v[70:71], v116 offset:32768
	ds_read_b64_tr_b16 v[72:73], v117 offset:32768
	ds_read_b128 v[74:77], v118 offset:49168
	ds_read_b128 v[78:81], v118 offset:53264
	ds_read_b64_tr_b16 v[82:83], v114 offset:36864
	ds_read_b64_tr_b16 v[84:85], v115 offset:36864
	ds_read_b64_tr_b16 v[86:87], v116 offset:36864
	ds_read_b64_tr_b16 v[88:89], v117 offset:36864
	ds_read_b128 v[90:93], v119 offset:49168
	ds_read_b128 v[94:97], v119 offset:53264
	global_load_dword v129, v218, s[0:1] nt
	global_load_dword v130, v219, s[0:1] nt
	global_load_dword v131, v220, s[0:1] nt
	global_load_dword v132, v221, s[0:1] nt
	global_load_dword v133, v222, s[0:1] nt
	global_load_dword v134, v223, s[0:1] nt
	global_load_dword v135, v224, s[0:1] nt
	global_load_dword v136, v225, s[0:1] nt
	global_load_dword v137, v226, s[0:1] nt
	global_load_dword v138, v227, s[0:1] nt
	global_load_dword v139, v228, s[0:1] nt
	global_load_dword v140, v229, s[0:1] nt
	global_load_dword v141, v230, s[0:1] nt
	global_load_dword v142, v231, s[0:1] nt
	global_load_dword v143, v232, s[0:1] nt
	global_load_dword v144, v233, s[0:1] nt
	s_waitcnt lgkmcnt(6)
	v_mfma_f32_32x32x16_bf16 v[50:65], v[66:69], v[74:77], v[50:65]
	v_mfma_f32_32x32x16_bf16 v[34:49], v[66:69], v[78:81], v[34:49]
	v_mfma_f32_32x32x16_bf16 v[18:33], v[70:73], v[74:77], v[18:33]
	v_mfma_f32_32x32x16_bf16 v[2:17], v[70:73], v[78:81], v[2:17]
	ds_read_b64_tr_b16 v[66:67], v114 offset:40960
	ds_read_b64_tr_b16 v[68:69], v115 offset:40960
	ds_read_b64_tr_b16 v[70:71], v116 offset:40960
	ds_read_b64_tr_b16 v[72:73], v117 offset:40960
	ds_read_b128 v[74:77], v120 offset:49168
	ds_read_b128 v[78:81], v120 offset:53264
	global_load_dword v145, v218, s[0:1] offset:128 nt
	global_load_dword v146, v219, s[0:1] offset:128 nt
	global_load_dword v147, v220, s[0:1] offset:128 nt
	global_load_dword v148, v221, s[0:1] offset:128 nt
	global_load_dword v149, v222, s[0:1] offset:128 nt
	global_load_dword v150, v223, s[0:1] offset:128 nt
	global_load_dword v151, v224, s[0:1] offset:128 nt
	global_load_dword v152, v225, s[0:1] offset:128 nt
	global_load_dword v153, v226, s[0:1] offset:128 nt
	global_load_dword v154, v227, s[0:1] offset:128 nt
	global_load_dword v155, v228, s[0:1] offset:128 nt
	global_load_dword v156, v229, s[0:1] offset:128 nt
	global_load_dword v157, v230, s[0:1] offset:128 nt
	global_load_dword v158, v231, s[0:1] offset:128 nt
	global_load_dword v159, v232, s[0:1] offset:128 nt
	global_load_dword v160, v233, s[0:1] offset:128 nt
	s_waitcnt lgkmcnt(6)
	v_mfma_f32_32x32x16_bf16 v[50:65], v[82:85], v[90:93], v[50:65]
	v_mfma_f32_32x32x16_bf16 v[34:49], v[82:85], v[94:97], v[34:49]
	v_mfma_f32_32x32x16_bf16 v[18:33], v[86:89], v[90:93], v[18:33]
	v_mfma_f32_32x32x16_bf16 v[2:17], v[86:89], v[94:97], v[2:17]
	ds_read_b64_tr_b16 v[82:83], v114 offset:45056
	ds_read_b64_tr_b16 v[84:85], v115 offset:45056
	ds_read_b64_tr_b16 v[86:87], v116 offset:45056
	ds_read_b64_tr_b16 v[88:89], v117 offset:45056
	ds_read_b128 v[90:93], v121 offset:49168
	ds_read_b128 v[94:97], v121 offset:53264
	global_load_dword v161, v218, s[38:39] nt
	global_load_dword v162, v219, s[38:39] nt
	global_load_dword v163, v220, s[38:39] nt
	global_load_dword v164, v221, s[38:39] nt
	global_load_dword v165, v222, s[38:39] nt
	global_load_dword v166, v223, s[38:39] nt
	global_load_dword v167, v224, s[38:39] nt
	global_load_dword v168, v225, s[38:39] nt
	global_load_dword v169, v226, s[38:39] nt
	global_load_dword v170, v227, s[38:39] nt
	global_load_dword v171, v228, s[38:39] nt
	global_load_dword v172, v229, s[38:39] nt
	global_load_dword v173, v230, s[38:39] nt
	global_load_dword v174, v231, s[38:39] nt
	global_load_dword v175, v232, s[38:39] nt
	global_load_dword v176, v233, s[38:39] nt
	s_waitcnt lgkmcnt(6)
	v_mfma_f32_32x32x16_bf16 v[50:65], v[66:69], v[74:77], v[50:65]
	v_mfma_f32_32x32x16_bf16 v[34:49], v[66:69], v[78:81], v[34:49]
	v_mfma_f32_32x32x16_bf16 v[18:33], v[70:73], v[74:77], v[18:33]
	v_mfma_f32_32x32x16_bf16 v[2:17], v[70:73], v[78:81], v[2:17]
	global_load_dword v177, v218, s[38:39] offset:128 nt
	global_load_dword v202, v219, s[38:39] offset:128 nt
	global_load_dword v203, v220, s[38:39] offset:128 nt
	global_load_dword v204, v221, s[38:39] offset:128 nt
	global_load_dword v205, v222, s[38:39] offset:128 nt
	global_load_dword v206, v223, s[38:39] offset:128 nt
	global_load_dword v207, v224, s[38:39] offset:128 nt
	global_load_dword v208, v225, s[38:39] offset:128 nt
	global_load_dword v209, v226, s[38:39] offset:128 nt
	global_load_dword v210, v227, s[38:39] offset:128 nt
	global_load_dword v211, v228, s[38:39] offset:128 nt
	global_load_dword v212, v229, s[38:39] offset:128 nt
	global_load_dword v213, v230, s[38:39] offset:128 nt
	global_load_dword v214, v231, s[38:39] offset:128 nt
	global_load_dword v215, v232, s[38:39] offset:128 nt
	global_load_dword v216, v233, s[38:39] offset:128 nt
	s_waitcnt lgkmcnt(0)
	v_mfma_f32_32x32x16_bf16 v[50:65], v[82:85], v[90:93], v[50:65]
	v_mfma_f32_32x32x16_bf16 v[34:49], v[82:85], v[94:97], v[34:49]
	v_mfma_f32_32x32x16_bf16 v[18:33], v[86:89], v[90:93], v[18:33]
	v_mfma_f32_32x32x16_bf16 v[2:17], v[86:89], v[94:97], v[2:17]
	v_readlane_b32 s38, v248, 2
	v_readlane_b32 s39, v248, 3
	s_nop 3
	s_add_u32 s36, s38, 0x20000
	s_addc_u32 s37, s39, 0
	s_nop 7
	s_waitcnt vmcnt(63)
	v_fmac_f32_e32 v129, v50, v234
	global_store_dword v218, v129, s[38:39] nt
	s_waitcnt vmcnt(63)
	v_fmac_f32_e32 v130, v51, v234
	global_store_dword v219, v130, s[38:39] nt
	s_waitcnt vmcnt(63)
	v_fmac_f32_e32 v131, v52, v234
	global_store_dword v220, v131, s[38:39] nt
	s_waitcnt vmcnt(63)
	v_fmac_f32_e32 v132, v53, v234
	global_store_dword v221, v132, s[38:39] nt
	s_waitcnt vmcnt(63)
	v_fmac_f32_e32 v133, v54, v234
	global_store_dword v222, v133, s[38:39] nt
	s_waitcnt vmcnt(63)
	v_fmac_f32_e32 v134, v55, v234
	global_store_dword v223, v134, s[38:39] nt
	s_waitcnt vmcnt(63)
	v_fmac_f32_e32 v135, v56, v234
	global_store_dword v224, v135, s[38:39] nt
	s_waitcnt vmcnt(63)
	v_fmac_f32_e32 v136, v57, v234
	global_store_dword v225, v136, s[38:39] nt
	s_waitcnt vmcnt(63)
	v_fmac_f32_e32 v137, v58, v234
	global_store_dword v226, v137, s[38:39] nt
	s_waitcnt vmcnt(63)
	v_fmac_f32_e32 v138, v59, v234
	global_store_dword v227, v138, s[38:39] nt
	s_waitcnt vmcnt(63)
	v_fmac_f32_e32 v139, v60, v234
	global_store_dword v228, v139, s[38:39] nt
	s_waitcnt vmcnt(63)
	v_fmac_f32_e32 v140, v61, v234
	global_store_dword v229, v140, s[38:39] nt
	s_waitcnt vmcnt(63)
	v_fmac_f32_e32 v141, v62, v234
	global_store_dword v230, v141, s[38:39] nt
	s_waitcnt vmcnt(63)
	v_fmac_f32_e32 v142, v63, v234
	global_store_dword v231, v142, s[38:39] nt
	s_waitcnt vmcnt(63)
	v_fmac_f32_e32 v143, v64, v234
	global_store_dword v232, v143, s[38:39] nt
	s_waitcnt vmcnt(63)
	v_fmac_f32_e32 v144, v65, v234
	global_store_dword v233, v144, s[38:39] nt
	s_waitcnt vmcnt(63)
	v_fmac_f32_e32 v145, v34, v235
	global_store_dword v218, v145, s[38:39] offset:128 nt
	s_waitcnt vmcnt(63)
	v_fmac_f32_e32 v146, v35, v235
	global_store_dword v219, v146, s[38:39] offset:128 nt
	s_waitcnt vmcnt(63)
	v_fmac_f32_e32 v147, v36, v235
	global_store_dword v220, v147, s[38:39] offset:128 nt
	s_waitcnt vmcnt(63)
	v_fmac_f32_e32 v148, v37, v235
	global_store_dword v221, v148, s[38:39] offset:128 nt
	s_waitcnt vmcnt(63)
	v_fmac_f32_e32 v149, v38, v235
	global_store_dword v222, v149, s[38:39] offset:128 nt
	s_waitcnt vmcnt(63)
	v_fmac_f32_e32 v150, v39, v235
	global_store_dword v223, v150, s[38:39] offset:128 nt
	s_waitcnt vmcnt(63)
	v_fmac_f32_e32 v151, v40, v235
	global_store_dword v224, v151, s[38:39] offset:128 nt
	s_waitcnt vmcnt(63)
	v_fmac_f32_e32 v152, v41, v235
	global_store_dword v225, v152, s[38:39] offset:128 nt
	s_waitcnt vmcnt(63)
	v_fmac_f32_e32 v153, v42, v235
	global_store_dword v226, v153, s[38:39] offset:128 nt
	s_waitcnt vmcnt(63)
	v_fmac_f32_e32 v154, v43, v235
	global_store_dword v227, v154, s[38:39] offset:128 nt
	s_waitcnt vmcnt(63)
	v_fmac_f32_e32 v155, v44, v235
	global_store_dword v228, v155, s[38:39] offset:128 nt
	s_waitcnt vmcnt(63)
	v_fmac_f32_e32 v156, v45, v235
	global_store_dword v229, v156, s[38:39] offset:128 nt
	s_waitcnt vmcnt(63)
	v_fmac_f32_e32 v157, v46, v235
	global_store_dword v230, v157, s[38:39] offset:128 nt
	s_waitcnt vmcnt(63)
	v_fmac_f32_e32 v158, v47, v235
	global_store_dword v231, v158, s[38:39] offset:128 nt
	s_waitcnt vmcnt(63)
	v_fmac_f32_e32 v159, v48, v235
	global_store_dword v232, v159, s[38:39] offset:128 nt
	s_waitcnt vmcnt(63)
	v_fmac_f32_e32 v160, v49, v235
	global_store_dword v233, v160, s[38:39] offset:128 nt
	s_waitcnt vmcnt(63)
	v_fmac_f32_e32 v161, v18, v234
	global_store_dword v218, v161, s[36:37] nt
	s_waitcnt vmcnt(63)
	v_fmac_f32_e32 v162, v19, v234
	global_store_dword v219, v162, s[36:37] nt
	s_waitcnt vmcnt(63)
	v_fmac_f32_e32 v163, v20, v234
	global_store_dword v220, v163, s[36:37] nt
	s_waitcnt vmcnt(63)
	v_fmac_f32_e32 v164, v21, v234
	global_store_dword v221, v164, s[36:37] nt
	s_waitcnt vmcnt(63)
	v_fmac_f32_e32 v165, v22, v234
	global_store_dword v222, v165, s[36:37] nt
	s_waitcnt vmcnt(63)
	v_fmac_f32_e32 v166, v23, v234
	global_store_dword v223, v166, s[36:37] nt
	s_waitcnt vmcnt(63)
	v_fmac_f32_e32 v167, v24, v234
	global_store_dword v224, v167, s[36:37] nt
	s_waitcnt vmcnt(63)
	v_fmac_f32_e32 v168, v25, v234
	global_store_dword v225, v168, s[36:37] nt
	s_waitcnt vmcnt(63)
	v_fmac_f32_e32 v169, v26, v234
	global_store_dword v226, v169, s[36:37] nt
	s_waitcnt vmcnt(63)
	v_fmac_f32_e32 v170, v27, v234
	global_store_dword v227, v170, s[36:37] nt
	s_waitcnt vmcnt(63)
	v_fmac_f32_e32 v171, v28, v234
	global_store_dword v228, v171, s[36:37] nt
	s_waitcnt vmcnt(63)
	v_fmac_f32_e32 v172, v29, v234
	global_store_dword v229, v172, s[36:37] nt
	s_waitcnt vmcnt(63)
	v_fmac_f32_e32 v173, v30, v234
	global_store_dword v230, v173, s[36:37] nt
	s_waitcnt vmcnt(63)
	v_fmac_f32_e32 v174, v31, v234
	global_store_dword v231, v174, s[36:37] nt
	s_waitcnt vmcnt(63)
	v_fmac_f32_e32 v175, v32, v234
	global_store_dword v232, v175, s[36:37] nt
	s_waitcnt vmcnt(63)
	v_fmac_f32_e32 v176, v33, v234
	global_store_dword v233, v176, s[36:37] nt
	s_waitcnt vmcnt(63)
	v_fmac_f32_e32 v177, v2, v235
	global_store_dword v218, v177, s[36:37] offset:128 nt
	s_waitcnt vmcnt(63)
	v_fmac_f32_e32 v202, v3, v235
	global_store_dword v219, v202, s[36:37] offset:128 nt
	s_waitcnt vmcnt(63)
	v_fmac_f32_e32 v203, v4, v235
	global_store_dword v220, v203, s[36:37] offset:128 nt
	s_waitcnt vmcnt(63)
	v_fmac_f32_e32 v204, v5, v235
	global_store_dword v221, v204, s[36:37] offset:128 nt
	s_waitcnt vmcnt(63)
	v_fmac_f32_e32 v205, v6, v235
	global_store_dword v222, v205, s[36:37] offset:128 nt
	s_waitcnt vmcnt(63)
	v_fmac_f32_e32 v206, v7, v235
	global_store_dword v223, v206, s[36:37] offset:128 nt
	s_waitcnt vmcnt(63)
	v_fmac_f32_e32 v207, v8, v235
	global_store_dword v224, v207, s[36:37] offset:128 nt
	s_waitcnt vmcnt(63)
	v_fmac_f32_e32 v208, v9, v235
	global_store_dword v225, v208, s[36:37] offset:128 nt
	s_waitcnt vmcnt(63)
	v_fmac_f32_e32 v209, v10, v235
	global_store_dword v226, v209, s[36:37] offset:128 nt
	s_waitcnt vmcnt(63)
	v_fmac_f32_e32 v210, v11, v235
	global_store_dword v227, v210, s[36:37] offset:128 nt
	s_waitcnt vmcnt(63)
	v_fmac_f32_e32 v211, v12, v235
	global_store_dword v228, v211, s[36:37] offset:128 nt
	s_waitcnt vmcnt(63)
	v_fmac_f32_e32 v212, v13, v235
	global_store_dword v229, v212, s[36:37] offset:128 nt
	s_waitcnt vmcnt(63)
	v_fmac_f32_e32 v213, v14, v235
	global_store_dword v230, v213, s[36:37] offset:128 nt
	s_waitcnt vmcnt(63)
	v_fmac_f32_e32 v214, v15, v235
	global_store_dword v231, v214, s[36:37] offset:128 nt
	s_waitcnt vmcnt(63)
	v_fmac_f32_e32 v215, v16, v235
	global_store_dword v232, v215, s[36:37] offset:128 nt
	s_waitcnt vmcnt(63)
	v_fmac_f32_e32 v216, v17, v235
	global_store_dword v233, v216, s[36:37] offset:128 nt
	v_readlane_b32 s0, v246, 1
	s_nop 1
	s_add_i32 s2, s2, s0
	s_cmpk_gt_i32 s2, 0x13f
	s_cbranch_scc0 .LBB0_89

.LBB0_116:
	s_or_b64 exec, exec, s[50:51]
	v_mov_b32_e32 v1, v6
	s_barrier
	s_waitcnt vmcnt(0)
	v_mul_f32_e32 v4, v15, v14
	v_ashrrev_i32_e32 v2, 31, v1
	v_lshrrev_b32_e32 v2, 24, v2
	v_and_b32_e32 v17, 0xff, v1
	v_add_lshl_u32 v1, v1, v2, 4
	v_and_or_b32 v1, v1, s87, v17
	v_ashrrev_i32_e32 v2, 4, v1
	v_lshlrev_b32_e32 v1, 3, v1
	v_lshl_add_u32 v82, v2, 3, v1
	v_pk_add_f32 v[2:3], v[4:5], 0 op_sel_hi:[1,0]
	v_cvt_f32_i32_e32 v1, v17
	v_sub_f32_e32 v16, 0, v5
	v_add_f32_e32 v22, v2, v3
	v_mov_b32_e32 v23, v0
	v_add_f32_e32 v1, v1, v1
	v_mul_f32_e32 v1, 0x39800000, v1
	v_mul_f32_e32 v1, 0.5, v1
	v_readlane_b32 s4, v245, 24
	v_sin_f32_e32 v28, v1
	ds_write_b64 v82, v[22:23]
	v_sub_f32_e64 v23, 0, -v5
	v_mul_f32_e64 v22, -v16, s21
	v_readlane_b32 s5, v245, 25
	v_cos_f32_e32 v34, v1
	s_nop 2
	v_add_f32_e32 v36, s4, v22
	v_mul_f32_e32 v23, s71, v23
	v_sub_f32_e32 v38, 0, v23
	v_add_f32_e32 v22, v36, v2
	v_add_f32_e32 v23, v23, v0
	v_xor_b32_e32 v35, 0x80000000, v28
	v_pk_mul_f32 v[44:45], v[22:23], v[28:29] op_sel_hi:[1,0]
	v_sub_f32_e32 v42, 0, v23
	v_fma_f32 v46, v22, v34, v45
	v_fma_f32 v47, v23, v34, -v44
	v_mov_b32_e32 v29, v34
	v_mul_f32_e32 v22, v28, v28
	v_mul_f32_e32 v23, v29, v35
	v_sub_f32_e32 v18, 0, v3
	v_pk_fma_f32 v[44:45], v[34:35], v[34:35], v[22:23] op_sel_hi:[0,1,1] neg_lo:[0,0,1] neg_hi:[0,0,1]
	v_pk_fma_f32 v[22:23], v[34:35], v[34:35], v[22:23] op_sel_hi:[0,1,1]
	v_fma_f32 v20, v18, s3, 0
	v_pk_mov_b32 v[48:49], v[22:23], v[44:45] op_sel:[1,0]
	v_add_f32_e32 v26, v2, v20
	ds_write_b64 v82, v[46:47] offset:2176
	v_mov_b32_e32 v46, v44
	v_mov_b32_e32 v47, v23
	v_mul_f32_e32 v27, v34, v44
	v_pk_mul_f32 v[50:51], v[20:21], v[48:49] op_sel_hi:[0,1]
	v_fma_f32 v52, v26, v44, -v50
	v_fma_f32 v53, v26, v47, v51
	v_pk_mul_f32 v[48:49], v[48:49], v[22:23] op_sel:[0,1]
	ds_write_b64 v82, v[52:53] offset:4352
	v_mov_b32_e32 v179, v44
	v_pk_fma_f32 v[52:53], v[44:45], v[46:47], v[48:49] op_sel_hi:[0,1,1] neg_lo:[0,0,1] neg_hi:[0,0,1]
	v_pk_fma_f32 v[44:45], v[44:45], v[46:47], v[48:49] op_sel_hi:[0,1,1]
	v_mov_b32_e32 v48, v52
	v_mov_b32_e32 v49, v45
	v_pk_mul_f32 v[66:67], v[48:49], v[44:45] op_sel:[0,1]
	v_mul_f32_e32 v22, v34, v45
	v_pk_fma_f32 v[68:69], v[52:53], v[48:49], v[66:67] op_sel:[0,0,1] op_sel_hi:[0,1,0] neg_lo:[0,0,1] neg_hi:[0,0,1]
	v_pk_fma_f32 v[66:67], v[52:53], v[48:49], v[66:67] op_sel:[0,0,1] op_sel_hi:[0,1,0]
	v_pk_mov_b32 v[72:73], v[66:67], v[68:69] op_sel:[1,0]
	v_mov_b32_e32 v70, v68
	v_mov_b32_e32 v71, v67
	v_pk_add_f32 v[76:77], v[2:3], v[2:3] op_sel:[0,1] op_sel_hi:[0,1] neg_lo:[0,1] neg_hi:[0,1]
	v_pk_mul_f32 v[78:79], v[72:73], 0 op_sel_hi:[1,0]
	v_fma_f32 v17, v18, s20, 0
	v_pk_fma_f32 v[54:55], v[28:29], v[48:49], v[22:23] op_sel_hi:[1,1,0] neg_lo:[1,0,0] neg_hi:[1,0,0]
	v_mul_f32_e32 v22, v23, v68
	v_fma_f32 v68, v76, v68, -v78
	v_fma_f32 v69, v77, v71, v79
	v_add_f32_e32 v30, v2, v17
	v_sub_f32_e32 v32, v2, v17
	v_mul_f32_e32 v19, v28, v23
	v_mov_b32_e32 v17, v28
	v_mul_f32_e32 v39, v28, v45
	v_pk_mul_f32 v[28:29], v[28:29], v[70:71] op_sel_hi:[0,1]
	ds_write_b64 v82, v[68:69] offset:17408
	v_fma_f32 v68, v34, v70, v29
	v_fma_f32 v29, v34, v71, -v28
	v_sub_f32_e64 v24, 0, -v3
	v_mul_f32_e32 v25, v34, v52
	v_pk_mov_b32 v[56:57], v[44:45], v[52:53] op_sel:[1,0]
	v_mov_b32_e32 v35, v29
	v_sub_f32_e32 v40, v2, v36
	v_mul_f32_e32 v1, v34, v23
	v_pk_mul_f32 v[58:59], v[24:25], v[56:57] op_sel_hi:[0,1]
	v_mul_f32_e32 v28, v42, v29
	v_mul_f32_e32 v29, v42, v68
	v_fma_f32 v60, v2, v52, -v58
	v_fma_f32 v61, v2, v49, v59
	v_pk_mul_f32 v[74:75], v[46:47], v[70:71]
	v_fma_f32 v42, v40, v68, -v28
	v_fma_f32 v43, v40, v35, v29
	v_pk_mul_f32 v[58:59], v[46:47], v[44:45] op_sel:[0,1]
	v_mov_b32_e32 v35, v20
	ds_write_b64 v82, v[60:61] offset:8704
	v_fma_f32 v60, v46, v52, -v59
	v_pk_fma_f32 v[58:59], v[46:47], v[52:53], v[58:59] op_sel:[0,0,1] op_sel_hi:[1,0,0]
	v_sub_f32_e32 v20, v74, v75
	v_sub_f32_e32 v21, v0, v35
	v_sub_f32_e32 v28, 0, v21
	v_mul_f32_e32 v29, v28, v60
	v_mul_f32_e32 v28, v28, v59
	v_fma_f32 v40, v30, v60, -v28
	v_fma_f32 v41, v30, v59, v29
	v_fma_f32 v22, v46, v72, v22
	v_sub_f32_e32 v28, v2, v35
	v_sub_f32_e32 v29, v74, v75
	v_mul_f32_e32 v23, v28, v22
	v_mul_f32_e32 v22, v22, v21
	v_add_f32_e32 v24, v2, v38
	v_add_f32_e32 v25, v25, v39
	v_fma_f32 v30, v20, v28, -v22
	v_fma_f32 v31, v21, v29, v23
	v_pk_mul_f32 v[28:29], v[44:45], v[70:71] op_sel:[1,0]
	ds_write_b64 v82, v[30:31] offset:21760
	v_fma_f32 v30, v52, v70, -v29
	v_fma_f32 v29, v52, v71, v28
	v_mov_b32_e32 v35, v29
	v_mul_f32_e32 v46, v67, v54
	v_mul_f32_e32 v78, v70, v25
	v_mul_f32_e32 v28, v18, v29
	v_mul_f32_e32 v29, v18, v30
	v_fma_f32 v30, v2, v30, -v28
	v_fma_f32 v31, v2, v35, v29
	v_sub_f32_e32 v28, v78, v46
	v_sub_f32_e32 v29, v0, v36
	ds_write_b64 v82, v[30:31] offset:26112
	v_sub_f32_e32 v30, 0, v29
	v_mov_b32_e32 v31, v24
	v_pk_mul_f32 v[34:35], v[30:31], v[54:55] op_sel_hi:[1,0]
	v_pk_mov_b32 v[30:31], v[24:25], v[30:31] op_sel:[1,0]
	v_mul_f32_e32 v66, v67, v25
	v_fma_f32 v36, v24, v30, -v34
	v_fma_f32 v37, v25, v31, v35
	v_fma_f32 v80, v70, v54, v66
	v_sub_f32_e32 v24, v2, v38
	v_sub_f32_e32 v25, v78, v46
	v_readlane_b32 s4, v245, 26
	v_mul_f32_e32 v30, v80, v29
	v_mul_f32_e32 v31, v24, v80
	v_pk_fma_f32 v[50:51], v[16:17], v[178:179], v[0:1] neg_lo:[1,0,0] neg_hi:[1,0,0]
	v_fma_f32 v34, v28, v24, -v30
	v_fma_f32 v35, v29, v25, v31
	v_pk_mul_f32 v[24:25], v[72:73], v[58:59] op_sel:[0,1]
	v_fma_f32 v18, v16, s4, 0
	v_fma_f32 v28, v70, v60, -v24
	v_fma_f32 v25, v71, v60, v25
	v_pk_mul_f32 v[56:57], v[56:57], v[50:51] op_sel:[0,1]
	v_mul_f32_e32 v20, v21, v25
	v_mul_f32_e32 v21, v21, v28
	v_mul_f32_e32 v77, v51, v71
	v_fma_f32 v24, v32, v28, -v20
	v_fma_f32 v25, v32, v25, v21
	v_add_f32_e32 v20, v2, v18
	v_add_f32_e32 v21, v27, v19
	ds_write_b64 v82, v[24:25] offset:30464
	v_fma_f32 v24, v48, v21, -v56
	v_fma_f32 v27, v49, v21, v57
	v_mov_b32_e32 v28, v24
	v_mov_b32_e32 v29, v27
	v_pk_mul_f32 v[32:33], v[70:71], v[28:29]
	ds_write_b64 v82, v[34:35] offset:28288
	v_mul_f32_e64 v17, -v5, s4
	v_mul_f32_e32 v30, v21, v70
	ds_write_b64 v82, v[36:37] offset:10880
	v_sub_f32_e32 v34, v32, v33
	v_sub_f32_e32 v35, v0, v17
	v_sub_f32_e32 v22, v30, v77
	v_sub_f32_e32 v23, v0, v50
	v_sub_f32_e32 v16, 0, v35
	v_mul_f32_e32 v36, v50, v51
	v_mul_f32_e32 v37, v51, v20
	v_pk_mov_b32 v[38:39], v[20:21], v[50:51] op_sel:[1,0]
	ds_write_b64 v82, v[40:41] offset:13056
	v_mov_b32_e32 v1, v4
	v_mov_b32_e32 v4, v17
	v_fma_f32 v40, v20, v38, -v36
	v_fma_f32 v41, v21, v39, v37
	v_mul_f32_e32 v17, v16, v24
	v_mul_f32_e32 v16, v16, v27
	v_mul_f32_e32 v26, v21, v67
	v_fma_f32 v14, v15, v14, v23
	v_fma_f32 v20, v51, v70, v26
	v_fma_f32 v24, v14, v24, -v16
	v_fma_f32 v25, v14, v29, v17
	v_sub_f32_e32 v2, v2, v18
	v_sub_f32_e32 v3, v30, v77
	v_mul_f32_e32 v14, v20, v23
	v_mul_f32_e32 v15, v2, v20
	v_pk_mul_f32 v[26:27], v[72:73], v[28:29]
	v_fma_f32 v16, v22, v2, -v14
	v_fma_f32 v17, v23, v3, v15
	v_sub_f32_e32 v4, v0, v4
	v_sub_f32_e32 v5, v1, v23
	v_pk_mov_b32 v[36:37], v[0:1], v[32:33] op_sel:[1,0]
	v_pk_add_f32 v[2:3], v[26:27], v[26:27] op_sel:[0,1] op_sel_hi:[0,1]
	v_sub_f32_e32 v32, v36, v23
	v_sub_f32_e32 v33, v37, v33
	v_pk_mul_f32 v[2:3], v[4:5], v[2:3]
	v_mov_b32_e32 v1, v12
	v_fma_f32 v4, v34, v32, -v2
	v_fma_f32 v5, v35, v33, v3
	ds_write_b64 v82, v[42:43] offset:19584
	ds_write_b64 v82, v[40:41] offset:6528
	ds_write_b64 v82, v[24:25] offset:15232
	ds_write_b64 v82, v[16:17] offset:23936
	ds_write_b64 v82, v[4:5] offset:32640
	s_waitcnt lgkmcnt(0)
	s_barrier
	s_mov_b32 s54, s71
	v_ashrrev_i32_e32 v2, 31, v1
	v_lshrrev_b32_e32 v2, 28, v2
	v_and_b32_e32 v70, 15, v1
	v_add_u32_e32 v1, v1, v2
	v_ashrrev_i32_e32 v1, 4, v1
	v_lshlrev_b32_e32 v2, 11, v1
	v_lshl_add_u32 v1, v1, 7, v2
	v_lshl_or_b32 v1, v70, 3, v1
	ds_read2_b64 v[20:23], v1 offset1:17
	ds_read2_b64 v[24:27], v1 offset0:68 offset1:85
	ds_read2_b64 v[28:31], v1 offset0:136 offset1:153
	ds_read2_b64 v[32:35], v1 offset0:170 offset1:187
	ds_read2_b64 v[36:39], v1 offset0:204 offset1:221
	ds_read2_b64 v[40:43], v1 offset0:238 offset1:255
	ds_read2_b64 v[44:47], v1 offset0:34 offset1:51
	ds_read2_b64 v[48:51], v1 offset0:102 offset1:119
	s_waitcnt lgkmcnt(5)
	v_pk_add_f32 v[18:19], v[28:29], v[20:21]
	s_waitcnt lgkmcnt(2)
	v_pk_mov_b32 v[68:69], v[34:35], v[42:43] op_sel:[1,0]
	s_waitcnt lgkmcnt(1)
	v_pk_add_f32 v[64:65], v[46:47], v[34:35]
	s_waitcnt lgkmcnt(0)
	v_pk_add_f32 v[66:67], v[50:51], v[42:43]
	v_mov_b32_e32 v35, v43
	v_pk_add_f32 v[42:43], v[64:65], v[66:67] neg_lo:[0,1] neg_hi:[0,1]
	v_sub_f32_e32 v68, v47, v68
	v_sub_f32_e32 v69, v50, v69
	v_pk_add_f32 v[16:17], v[64:65], v[66:67]
	v_mul_f32_e32 v64, 0x3f3504f3, v43
	v_mul_f32_e32 v67, 0xbf3504f3, v43
	v_cvt_f32_i32_e32 v43, v70
	v_sub_f32_e32 v34, v46, v34
	v_sub_f32_e32 v35, v51, v35
	v_pk_add_f32 v[28:29], v[20:21], v[28:29] neg_lo:[0,1] neg_hi:[0,1]
	v_add_f32_e32 v43, v43, v43
	v_pk_add_f32 v[20:21], v[24:25], v[36:37] neg_lo:[0,1] neg_hi:[0,1]
	v_pk_add_f32 v[52:53], v[36:37], v[24:25]
	v_pk_add_f32 v[54:55], v[22:23], v[30:31]
	v_pk_add_f32 v[56:57], v[26:27], v[38:39]
	v_sub_f32_e32 v46, v34, v35
	v_mul_f32_e32 v43, 0x3b800000, v43
	v_pk_mov_b32 v[24:25], v[20:21], v[20:21] op_sel:[1,0]
	v_add_f32_e32 v36, v28, v21
	v_sub_f32_e32 v37, v29, v20
	v_pk_add_f32 v[34:35], v[34:35], v[34:35] op_sel:[0,1] op_sel_hi:[0,1]
	s_mov_b32 s55, s21
	v_pk_add_f32 v[4:5], v[54:55], v[56:57]
	v_pk_add_f32 v[58:59], v[44:45], v[32:33]
	v_pk_add_f32 v[60:61], v[48:49], v[40:41]
	v_pk_add_f32 v[54:55], v[54:55], v[56:57] neg_lo:[0,1] neg_hi:[0,1]
	v_mul_f32_e32 v43, 0.5, v43
	v_pk_add_f32 v[20:21], v[68:69], v[68:69] op_sel:[0,1] op_sel_hi:[0,1] neg_lo:[0,1] neg_hi:[0,1]
	s_mov_b32 s70, s21
	v_pk_mul_f32 v[34:35], v[34:35], s[54:55]
	v_pk_add_f32 v[14:15], v[58:59], v[60:61]
	v_pk_add_f32 v[62:63], v[58:59], v[60:61] neg_lo:[0,1] neg_hi:[0,1]
	v_add_f32_e32 v50, v68, v69
	v_pk_mul_f32 v[56:57], v[54:55], s[20:21] op_sel_hi:[1,0]
	v_mul_f32_e32 v42, 0x3f3504f3, v42
	v_sin_f32_e32 v58, v43
	s_nop 1
	v_cos_f32_e32 v76, v43
	s_nop 1
	v_fma_f32 v68, v20, s70, v34
	v_fma_f32 v69, v21, s71, -v35
	v_pk_add_f32 v[2:3], v[18:19], v[52:53]
	v_mov_b32_e32 v20, v18
	v_sub_f32_e32 v18, v64, v42
	v_sub_f32_e32 v19, v19, v53
	v_sub_f32_e32 v20, v20, v52
	v_sub_f32_e32 v21, v57, v56
	v_mov_b32_e32 v35, v42
	v_pk_add_f32 v[42:43], v[18:19], v[62:63] op_sel:[1,0] op_sel_hi:[0,1]
	v_mov_b32_e32 v53, v62
	v_sub_f32_e32 v34, v59, v61
	v_sub_f32_e32 v35, v67, v35
	v_sub_f32_e32 v62, v44, v32
	v_sub_f32_e32 v63, v22, v30
	v_sub_f32_e32 v64, v49, v41
	v_sub_f32_e32 v65, v27, v39
	v_mul_f32_e32 v78, 0x3f6c835e, v50
	v_mul_f32_e32 v79, 0x3ec3ef15, v46
	v_sub_f32_e32 v22, v45, v33
	v_sub_f32_e32 v23, v23, v31
	v_sub_f32_e32 v27, v26, v38
	v_sub_f32_e32 v26, v48, v40
	v_pk_add_f32 v[32:33], v[62:63], v[64:65] neg_lo:[0,1] neg_hi:[0,1]
	v_readlane_b32 s5, v245, 27
	v_pk_fma_f32 v[54:55], v[54:55], s[20:21], v[56:57] op_sel:[0,0,1] op_sel_hi:[1,0,0]
	v_pk_add_f32 v[66:67], v[62:63], v[64:65]
	v_pk_add_f32 v[30:31], v[22:23], v[26:27] neg_lo:[0,1] neg_hi:[0,1]
	v_pk_add_f32 v[22:23], v[22:23], v[26:27]
	s_mov_b32 s56, s3
	s_mov_b32 s57, s76
	v_mov_b32_e32 v39, v29
	v_mov_b32_e32 v27, v25
	v_mov_b32_e32 v52, v54
	v_pk_add_f32 v[54:55], v[54:55], v[18:19] neg_lo:[0,1] neg_hi:[0,1]
	v_mul_f32_e32 v26, 0x3ec3ef15, v33
	v_pk_mul_f32 v[40:41], v[32:33], s[56:57]
	s_mov_b32 s56, s20
	s_mov_b32 s57, s71
	v_mul_f32_e32 v33, s5, v32
	v_mul_f32_e32 v32, s4, v50
	v_sub_f32_e32 v24, v28, v24
	v_sub_f32_e32 v25, v79, v78
	v_pk_mul_f32 v[28:29], v[66:67], s[70:71] op_sel:[1,0]
	v_add_f32_e32 v56, v18, v52
	v_sub_f32_e32 v53, v19, v53
	v_pk_add_f32 v[18:19], v[42:43], v[54:55]
	v_mul_f32_e32 v38, 0x3f6c835e, v23
	v_mul_f32_e32 v43, 0x3f3504f3, v66
	v_mul_f32_e32 v44, 0x3f3504f3, v30
	v_pk_fma_f32 v[40:41], v[22:23], s[56:57], v[40:41]
	v_fma_f32 v23, v22, s31, v33
	v_fma_f32 v22, v46, s30, v32
	v_fma_f32 v32, v31, s54, v28
	v_fma_f32 v33, v31, s55, -v29
	v_pk_add_f32 v[26:27], v[38:39], v[26:27]
	v_add_f32_e32 v28, v44, v43
	v_fma_f32 v29, v30, s20, -v43
	v_pk_add_f32 v[30:31], v[36:37], v[28:29]
	v_pk_add_f32 v[38:39], v[32:33], v[68:69]
	v_xor_b32_e32 v77, 0x80000000, v58
	v_pk_add_f32 v[44:45], v[38:39], v[30:31]
	v_pk_add_f32 v[70:71], v[2:3], v[14:15]
	v_pk_mul_f32 v[50:51], v[58:59], v[44:45] op_sel_hi:[0,1]
	v_fma_f32 v62, v76, v44, v51
	v_fma_f32 v63, v76, v45, -v50
	v_mov_b32_e32 v59, v76
	v_pk_add_f32 v[72:73], v[4:5], v[16:17]
	v_mul_f32_e32 v44, v58, v58
	v_mul_f32_e32 v45, v59, v77
	v_pk_add_f32 v[74:75], v[72:73], v[70:71]
	v_pk_fma_f32 v[50:51], v[76:77], v[76:77], v[44:45] op_sel_hi:[0,1,1] neg_lo:[0,0,1] neg_hi:[0,0,1]
	v_pk_fma_f32 v[44:45], v[76:77], v[76:77], v[44:45] op_sel_hi:[0,1,1]
	v_pk_add_f32 v[60:61], v[20:21], v[34:35]
	ds_write2_b64 v1, v[74:75], v[62:63] offset1:17
	v_pk_add_f32 v[20:21], v[20:21], v[34:35] neg_lo:[0,1] neg_hi:[0,1]
	v_add_f32_e32 v34, v60, v56
	v_add_f32_e32 v35, v61, v53
	v_mov_b32_e32 v62, v50
	v_mov_b32_e32 v63, v45
	v_mul_f32_e32 v74, v45, v45
	v_mul_f32_e32 v75, v45, v50
	v_pk_mul_f32 v[44:45], v[34:35], v[44:45] op_sel:[1,1] op_sel_hi:[0,1]
	v_pk_fma_f32 v[78:79], v[50:51], v[62:63], v[74:75] op_sel_hi:[0,1,1] neg_lo:[0,0,1] neg_hi:[0,0,1]
	v_pk_fma_f32 v[74:75], v[50:51], v[62:63], v[74:75] op_sel_hi:[0,1,1]
	v_fma_f32 v88, v34, v50, -v44
	v_fma_f32 v89, v35, v50, v45
	v_pk_mul_f32 v[44:45], v[62:63], v[74:75] op_sel:[0,1]
	v_pk_add_f32 v[32:33], v[32:33], v[68:69] neg_lo:[0,1] neg_hi:[0,1]
	v_fma_f32 v50, v62, v78, -v45
	v_fma_f32 v45, v63, v78, v44
	v_sub_f32_e32 v42, v42, v54
	v_mov_b32_e32 v69, v45
	v_mov_b32_e32 v77, v58
	v_mov_b32_e32 v80, v78
	v_mov_b32_e32 v81, v75
	v_pk_add_f32 v[90:91], v[20:21], v[20:21] op_sel:[0,1] op_sel_hi:[0,1]
	v_mul_f32_e32 v43, v42, v50
	v_mul_f32_e32 v42, v42, v45
	v_pk_mul_f32 v[64:65], v[76:77], v[62:63]
	v_pk_mul_f32 v[66:67], v[58:59], v[62:63]
	v_mov_b32_e32 v68, v50
	v_fma_f32 v44, v90, v50, -v42
	v_pk_mul_f32 v[50:51], v[80:81], v[74:75] op_sel:[0,1]
	v_pk_add_f32 v[30:31], v[30:31], v[38:39] neg_lo:[0,1] neg_hi:[0,1]
	v_pk_add_f32 v[38:39], v[40:41], v[24:25]
	v_pk_add_f32 v[46:47], v[26:27], v[22:23]
	v_fma_f32 v45, v91, v69, v43
	v_pk_fma_f32 v[54:55], v[78:79], v[80:81], v[50:51] op_sel:[0,0,1] op_sel_hi:[0,1,0] neg_lo:[0,0,1] neg_hi:[0,0,1]
	v_pk_fma_f32 v[50:51], v[78:79], v[80:81], v[50:51] op_sel:[0,0,1] op_sel_hi:[0,1,0]
	v_mov_b32_e32 v92, v64
	v_pk_mov_b32 v[64:65], v[64:65], v[66:67] op_sel:[1,0]
	v_pk_add_f32 v[48:49], v[38:39], v[46:47]
	v_pk_add_f32 v[42:43], v[70:71], v[72:73] neg_lo:[0,1] neg_hi:[0,1]
	v_pk_mov_b32 v[72:73], v[50:51], v[54:55] op_sel:[1,0]
	v_add_f32_e32 v66, v92, v64
	v_sub_f32_e32 v64, v92, v64
	v_sub_f32_e32 v65, v67, v65
	v_pk_mul_f32 v[82:83], v[76:77], v[80:81]
	v_pk_mul_f32 v[84:85], v[58:59], v[80:81]
	v_pk_add_f32 v[28:29], v[36:37], v[28:29] neg_lo:[0,1] neg_hi:[0,1]
	v_mov_b32_e32 v70, v54
	v_mov_b32_e32 v71, v51
	v_pk_mul_f32 v[58:59], v[58:59], v[72:73] op_sel_hi:[0,1]
	v_pk_mul_f32 v[94:95], v[48:49], v[64:65] op_sel:[0,1]
	v_pk_mov_b32 v[86:87], v[74:75], v[78:79] op_sel:[1,0]
	v_pk_add_f32 v[34:35], v[28:29], v[32:33] op_sel:[0,1] op_sel_hi:[1,0]
	v_pk_add_f32 v[28:29], v[28:29], v[32:33] op_sel:[0,1] op_sel_hi:[1,0] neg_lo:[0,1] neg_hi:[0,1]
	v_fma_f32 v74, v76, v70, v58
	v_fma_f32 v59, v76, v71, -v59
	v_fma_f32 v96, v48, v66, -v95
	v_fma_f32 v97, v49, v66, v94
	v_mov_b32_e32 v98, v82
	v_mov_b32_e32 v99, v85
	v_pk_mov_b32 v[82:83], v[82:83], v[84:85] op_sel:[1,0]
	v_mov_b32_e32 v77, v59
	v_pk_mul_f32 v[48:49], v[80:81], v[64:65] op_sel:[0,1]
	v_pk_add_f32 v[84:85], v[98:99], v[82:83]
	v_sub_f32_e32 v83, v99, v83
	v_mov_b32_e32 v93, v65
	v_fma_f32 v64, v80, v66, -v49
	v_fma_f32 v49, v81, v66, v48
	v_mul_f32_e32 v36, v29, v83
	v_mul_f32_e32 v37, v34, v83
	v_mul_f32_e32 v58, v31, v59
	v_mul_f32_e32 v59, v31, v74
	v_mov_b32_e32 v92, v66
	v_mov_b32_e32 v66, v64
	v_mov_b32_e32 v67, v49
	v_mov_b32_e32 v98, v84
	v_mov_b32_e32 v99, v83
	v_fma_f32 v82, v34, v84, -v36
	v_fma_f32 v83, v29, v84, v37
	v_fma_f32 v74, v30, v74, -v58
	v_fma_f32 v75, v30, v77, v59
	v_pk_mul_f32 v[50:51], v[42:43], v[50:51] op_sel:[1,1] op_sel_hi:[0,1]
	v_pk_mul_f32 v[90:91], v[62:63], v[70:71]
	v_pk_mul_f32 v[62:63], v[62:63], v[72:73]
	ds_write2_b64 v1, v[88:89], v[96:97] offset0:34 offset1:51
	v_pk_mul_f32 v[88:89], v[92:93], v[70:71]
	v_pk_mul_f32 v[92:93], v[92:93], v[72:73]
	v_pk_mul_f32 v[94:95], v[80:81], v[70:71]
	v_pk_mul_f32 v[96:97], v[80:81], v[72:73]
	v_pk_mul_f32 v[32:33], v[70:71], v[98:99]
	v_pk_mul_f32 v[36:37], v[72:73], v[98:99]
	v_pk_mul_f32 v[30:31], v[70:71], v[68:69]
	v_pk_mul_f32 v[58:59], v[72:73], v[68:69]
	v_pk_mul_f32 v[68:69], v[70:71], v[66:67]
	v_pk_mul_f32 v[70:71], v[72:73], v[66:67]
	v_fma_f32 v72, v42, v54, -v50
	v_fma_f32 v73, v43, v54, v51
	v_sub_f32_e32 v42, v60, v56
	v_sub_f32_e32 v43, v53, v61
	v_pk_add_f32 v[50:51], v[62:63], v[62:63] op_sel:[0,1] op_sel_hi:[0,1]
	v_pk_mul_f32 v[50:51], v[42:43], v[50:51] op_sel:[1,0] op_sel_hi:[0,1]
	v_pk_add_f32 v[52:53], v[90:91], v[90:91] op_sel:[0,1] op_sel_hi:[0,1] neg_lo:[0,1] neg_hi:[0,1]
	v_fma_f32 v54, v42, v52, -v50
	v_fma_f32 v55, v43, v53, v51
	v_pk_add_f32 v[2:3], v[2:3], v[14:15] neg_lo:[0,1] neg_hi:[0,1]
	v_sub_f32_e32 v38, v38, v46
	v_sub_f32_e32 v39, v47, v39
	v_pk_add_f32 v[42:43], v[92:93], v[92:93] op_sel:[0,1] op_sel_hi:[0,1]
	v_pk_add_f32 v[4:5], v[4:5], v[16:17] neg_lo:[0,1] neg_hi:[0,1]
	v_pk_mul_f32 v[42:43], v[38:39], v[42:43] op_sel:[1,0] op_sel_hi:[0,1]
	v_pk_add_f32 v[46:47], v[88:89], v[88:89] op_sel:[0,1] op_sel_hi:[0,1] neg_lo:[0,1] neg_hi:[0,1]
	v_pk_add_f32 v[14:15], v[2:3], v[4:5] op_sel:[0,1] op_sel_hi:[1,0]
	v_pk_add_f32 v[2:3], v[2:3], v[4:5] op_sel:[0,1] op_sel_hi:[1,0] neg_lo:[0,1] neg_hi:[0,1]
	v_fma_f32 v50, v38, v46, -v42
	v_fma_f32 v51, v39, v47, v43
	v_pk_mul_f32 v[16:17], v[2:3], v[86:87] op_sel:[1,0]
	v_fma_f32 v38, v14, v78, -v16
	v_fma_f32 v39, v14, v81, v17
	v_mov_b32_e32 v5, v15
	v_pk_add_f32 v[16:17], v[96:97], v[96:97] op_sel:[0,1] op_sel_hi:[0,1]
	v_mul_f32_e32 v14, v15, v16
	v_mul_f32_e32 v15, v2, v17
	v_pk_add_f32 v[16:17], v[94:95], v[94:95] op_sel:[0,1] op_sel_hi:[0,1] neg_lo:[0,1] neg_hi:[0,1]
	v_fma_f32 v2, v2, v16, -v14
	v_fma_f32 v3, v5, v17, v15
	v_pk_add_f32 v[16:17], v[36:37], v[36:37] op_sel:[0,1] op_sel_hi:[0,1]
	v_mul_f32_e32 v14, v35, v16
	v_mul_f32_e32 v15, v28, v17
	v_pk_add_f32 v[16:17], v[32:33], v[32:33] op_sel:[0,1] op_sel_hi:[0,1] neg_lo:[0,1] neg_hi:[0,1]
	v_fma_f32 v28, v28, v16, -v14
	v_fma_f32 v29, v35, v17, v15
	v_pk_add_f32 v[14:15], v[58:59], v[58:59] op_sel:[0,1] op_sel_hi:[0,1]
	ds_write2_b64 v1, v[2:3], v[28:29] offset0:204 offset1:221
	v_sub_f32_e32 v2, v20, v21
	v_sub_f32_e32 v3, v30, v31
	v_mul_f32_e32 v4, v18, v14
	v_mul_f32_e32 v5, v2, v15
	v_pk_mov_b32 v[14:15], v[2:3], v[18:19] op_sel:[1,0]
	v_fma_f32 v16, v2, v14, -v4
	v_fma_f32 v17, v3, v15, v5
	v_sub_f32_e32 v2, v24, v40
	v_sub_f32_e32 v3, v26, v22
	v_sub_f32_e32 v4, v41, v25
	v_sub_f32_e32 v5, v27, v23
	ds_write2_b64 v1, v[72:73], v[74:75] offset0:136 offset1:153
	v_pk_add_f32 v[14:15], v[4:5], v[2:3]
	v_sub_f32_e32 v18, v2, v4
	v_sub_f32_e32 v2, v5, v3
	v_mul_f32_e32 v3, v2, v64
	v_mul_f32_e32 v2, v2, v49
	v_fma_f32 v4, v14, v64, -v2
	v_fma_f32 v5, v14, v67, v3
	ds_write2_b64 v1, v[44:45], v[4:5] offset0:102 offset1:119
	v_pk_add_f32 v[4:5], v[70:71], v[70:71] op_sel:[0,1] op_sel_hi:[0,1]
	v_mul_f32_e32 v2, v15, v4
	v_mul_f32_e32 v3, v18, v5
	v_pk_add_f32 v[4:5], v[68:69], v[68:69] op_sel:[0,1] op_sel_hi:[0,1] neg_lo:[0,1] neg_hi:[0,1]
	v_fma_f32 v14, v18, v4, -v2
	v_fma_f32 v15, v15, v5, v3
	ds_write2_b64 v1, v[54:55], v[50:51] offset0:170 offset1:187
	ds_write2_b64 v1, v[38:39], v[82:83] offset0:68 offset1:85
	ds_write2_b64 v1, v[16:17], v[14:15] offset0:238 offset1:255
	v_mov_b32_e32 v1, v6
	s_waitcnt lgkmcnt(0)
	s_barrier
	v_readlane_b32 s56, v245, 46
	v_mul_lo_u32 v1, v1, s33
	ds_read2_b64 v[2:5], v1 offset1:1
	ds_read2_b64 v[14:17], v1 offset0:8 offset1:9
	ds_read2_b64 v[18:21], v1 offset0:10 offset1:11
	ds_read2_b64 v[22:25], v1 offset0:12 offset1:13
	ds_read2_b64 v[26:29], v1 offset0:14 offset1:15
	ds_read2_b64 v[30:33], v1 offset0:2 offset1:3
	ds_read2_b64 v[34:37], v1 offset0:4 offset1:5
	ds_read2_b64 v[38:41], v1 offset0:6 offset1:7
	s_waitcnt lgkmcnt(7)
	v_mov_b32_e32 v1, v4
	v_mov_b32_e32 v42, v2
	v_mov_b32_e32 v43, v4
	v_mov_b32_e32 v4, v5
	v_mov_b32_e32 v5, v3
	s_waitcnt lgkmcnt(6)
	v_mov_b32_e32 v44, v14
	v_mov_b32_e32 v45, v16
	v_mov_b32_e32 v16, v17
	v_mov_b32_e32 v17, v15
	v_pk_add_f32 v[46:47], v[2:3], v[14:15] neg_lo:[0,1] neg_hi:[0,1]
	v_pk_add_f32 v[2:3], v[2:3], v[14:15]
	s_waitcnt lgkmcnt(1)
	v_mov_b32_e32 v15, v36
	v_mov_b32_e32 v49, v36
	v_mov_b32_e32 v36, v37
	v_mov_b32_e32 v37, v35
	v_mov_b32_e32 v50, v22
	v_mov_b32_e32 v51, v24
	v_mov_b32_e32 v24, v25
	v_mov_b32_e32 v25, v23
	v_mov_b32_e32 v48, v34
	v_pk_add_f32 v[52:53], v[34:35], v[22:23] neg_lo:[0,1] neg_hi:[0,1]
	v_pk_add_f32 v[22:23], v[34:35], v[22:23]
	v_pk_mov_b32 v[34:35], v[0:1], v[4:5] op_sel:[1,0]
	v_pk_mov_b32 v[54:55], v[44:45], v[16:17] op_sel:[1,0]
	v_pk_add_f32 v[4:5], v[4:5], v[16:17]
	v_pk_mov_b32 v[14:15], v[14:15], v[36:37] op_sel:[1,0]
	v_pk_mov_b32 v[16:17], v[50:51], v[24:25] op_sel:[1,0]
	v_pk_add_f32 v[42:43], v[42:43], v[44:45]
	v_pk_add_f32 v[44:45], v[48:49], v[50:51]
	v_pk_add_f32 v[24:25], v[36:37], v[24:25]
	v_pk_add_f32 v[48:49], v[2:3], v[22:23] neg_lo:[0,1] neg_hi:[0,1]
	v_pk_add_f32 v[2:3], v[2:3], v[22:23]
	v_pk_add_f32 v[22:23], v[34:35], v[54:55]
	v_pk_add_f32 v[34:35], v[34:35], v[54:55] neg_lo:[0,1] neg_hi:[0,1]
	v_pk_add_f32 v[36:37], v[14:15], v[16:17]
	v_pk_add_f32 v[14:15], v[14:15], v[16:17] neg_lo:[0,1] neg_hi:[0,1]
	v_add_f32_e32 v1, v46, v53
	v_sub_f32_e32 v50, v47, v52
	v_sub_f32_e32 v51, v46, v53
	v_add_f32_e32 v53, v47, v52
	v_pk_add_f32 v[16:17], v[42:43], v[44:45]
	v_pk_add_f32 v[4:5], v[4:5], v[24:25]
	v_add_f32_e32 v52, v34, v15
	v_sub_f32_e32 v54, v35, v14
	v_sub_f32_e32 v55, v34, v15
	v_add_f32_e32 v56, v35, v14
	v_pk_add_f32 v[14:15], v[30:31], v[18:19] neg_lo:[0,1] neg_hi:[0,1]
	v_pk_add_f32 v[24:25], v[30:31], v[18:19]
	s_xor_b64 s[50:51], s[40:41], -1
	v_pk_add_f32 v[42:43], v[22:23], v[36:37]
	v_pk_add_f32 v[22:23], v[22:23], v[36:37] neg_lo:[0,1] neg_hi:[0,1]
	s_waitcnt lgkmcnt(0)
	v_pk_add_f32 v[34:35], v[38:39], v[26:27] neg_lo:[0,1] neg_hi:[0,1]
	v_pk_add_f32 v[36:37], v[38:39], v[26:27]
	v_add_f32_e32 v44, v30, v18
	v_add_f32_e32 v45, v32, v20
	v_add_f32_e32 v18, v33, v21
	v_add_f32_e32 v19, v31, v19
	v_readlane_b32 s62, v245, 52
	v_add_f32_e32 v30, v38, v26
	v_add_f32_e32 v31, v40, v28
	v_add_f32_e32 v26, v41, v29
	v_add_f32_e32 v27, v39, v27
	v_pk_add_f32 v[46:47], v[24:25], v[36:37] neg_lo:[0,1] neg_hi:[0,1]
	v_pk_add_f32 v[24:25], v[24:25], v[36:37]
	v_add_f32_e32 v36, v14, v35
	v_sub_f32_e32 v37, v15, v34
	v_sub_f32_e32 v38, v14, v35
	v_add_f32_e32 v39, v15, v34
	v_pk_add_f32 v[14:15], v[32:33], v[20:21]
	v_pk_add_f32 v[20:21], v[32:33], v[20:21] neg_lo:[0,1] neg_hi:[0,1]
	v_pk_add_f32 v[32:33], v[40:41], v[28:29]
	v_pk_add_f32 v[28:29], v[40:41], v[28:29] neg_lo:[0,1] neg_hi:[0,1]
	v_readlane_b32 s63, v245, 53
	s_add_u32 s52, s62, s52
	v_pk_add_f32 v[30:31], v[44:45], v[30:31]
	v_pk_add_f32 v[18:19], v[18:19], v[26:27]
	v_sub_f32_e32 v27, v21, v28
	v_add_f32_e32 v21, v21, v28
	v_mul_f32_e32 v22, 0x3f3504f3, v22
	v_mul_f32_e32 v41, 0x3ec3ef15, v55
	v_mul_f32_e32 v45, 0xbf6c835e, v55
	s_addc_u32 s53, s63, s53
	s_mov_b32 s96, s10
	s_add_i32 s24, s1, s10
	v_readlane_b32 s4, v245, 56
	v_pk_add_f32 v[34:35], v[14:15], v[32:33]
	v_pk_add_f32 v[14:15], v[14:15], v[32:33] neg_lo:[0,1] neg_hi:[0,1]
	v_add_f32_e32 v26, v20, v29
	v_sub_f32_e32 v20, v20, v29
	v_fmamk_f32 v33, v23, 0x3f3504f3, v22
	v_fma_f32 v40, v23, s20, -v22
	v_fmac_f32_e32 v41, 0x3f6c835e, v56
	v_fmac_f32_e32 v45, 0x3ec3ef15, v56
	v_mul_f32_e32 v22, 0x3f3504f3, v36
	v_mul_f32_e32 v56, 0xbec3ef15, v21
	v_mul_f32_e32 v57, 0xbf6c835e, v21
	s_lshl_b64 s[54:55], s[24:25], 2
	v_readlane_b32 s8, v245, 60
	v_fmamk_f32 v32, v37, 0x3f3504f3, v22
	v_fma_f32 v36, v37, s20, -v22
	v_mul_f32_e32 v44, 0xbf3504f3, v14
	v_fmac_f32_e32 v56, 0xbf6c835e, v20
	v_fmac_f32_e32 v57, 0x3ec3ef15, v20
	v_pk_add_f32 v[20:21], v[2:3], v[24:25]
	v_pk_add_f32 v[22:23], v[42:43], v[34:35]
	v_readlane_b32 s57, v245, 47
	v_readlane_b32 s9, v245, 61
	s_add_u32 s56, s8, s54
	v_mul_f32_e32 v28, 0x3f6c835e, v52
	v_mul_f32_e32 v29, 0xbec3ef15, v52
	v_fmamk_f32 v52, v15, 0x3f3504f3, v44
	v_fmac_f32_e32 v44, 0xbf3504f3, v15
	v_pk_add_f32 v[2:3], v[2:3], v[24:25] neg_lo:[0,1] neg_hi:[0,1]
	v_pk_add_f32 v[24:25], v[16:17], v[30:31] neg_lo:[0,1] neg_hi:[0,1]
	v_pk_add_f32 v[14:15], v[22:23], v[20:21]
	v_pk_add_f32 v[16:17], v[20:21], v[22:23] neg_lo:[0,1] neg_hi:[0,1]
	s_addc_u32 s57, s9, s55
	global_load_dword v148, v0, s[52:53]
	global_load_dword v22, v0, s[42:43]
	global_load_dword v149, v0, s[44:45]
	global_load_dword v23, v0, s[46:47]
	global_load_dword v150, v0, s[56:57]
	global_load_dword v151, v0, s[48:49]
	global_load_dword v152, v186, s[56:57]
	global_load_dword v153, v187, s[56:57]
	v_readlane_b32 s10, v245, 62
	v_readlane_b32 s11, v245, 63
	s_add_u32 s52, s10, s54
	s_addc_u32 s53, s11, s55
	global_load_dword v154, v0, s[52:53]
	v_mul_f32_e32 v37, 0xbf3504f3, v38
	v_fmamk_f32 v55, v39, 0x3f3504f3, v37
	v_fmac_f32_e32 v37, 0xbf3504f3, v39
	v_mul_f32_e32 v38, 0x3ec3ef15, v26
	v_mul_f32_e32 v39, 0xbf6c835e, v26
	v_fmac_f32_e32 v28, 0x3ec3ef15, v54
	v_fmac_f32_e32 v29, 0x3f6c835e, v54
	v_fmac_f32_e32 v38, 0x3f6c835e, v27
	v_fmac_f32_e32 v39, 0x3ec3ef15, v27
	v_pk_add_f32 v[26:27], v[42:43], v[34:35] neg_lo:[0,1] neg_hi:[0,1]
	v_pk_add_f32 v[4:5], v[4:5], v[18:19] neg_lo:[0,1] neg_hi:[0,1]
	v_pk_add_f32 v[72:73], v[2:3], v[26:27] op_sel:[0,1] op_sel_hi:[1,0]
	v_pk_add_f32 v[2:3], v[2:3], v[26:27] op_sel:[0,1] op_sel_hi:[1,0] neg_lo:[0,1] neg_hi:[0,1]
	v_pk_add_f32 v[74:75], v[24:25], v[4:5] neg_lo:[0,1] neg_hi:[0,1]
	v_pk_add_f32 v[4:5], v[24:25], v[4:5]
	v_add_f32_e32 v25, v1, v32
	v_add_f32_e32 v27, v50, v36
	v_sub_f32_e32 v1, v1, v32
	v_sub_f32_e32 v31, v50, v36
	v_add_f32_e32 v30, v28, v38
	v_add_f32_e32 v32, v29, v39
	v_sub_f32_e32 v35, v28, v38
	v_sub_f32_e32 v29, v29, v39
	v_add_f32_e32 v24, v30, v25
	v_add_f32_e32 v26, v32, v27
	v_sub_f32_e32 v28, v25, v30
	v_sub_f32_e32 v30, v27, v32
	v_add_f32_e32 v32, v29, v1
	v_sub_f32_e32 v34, v31, v35
	v_sub_f32_e32 v36, v1, v29
	v_add_f32_e32 v38, v35, v31
	v_add_f32_e32 v1, v48, v47
	v_sub_f32_e32 v25, v49, v46
	v_sub_f32_e32 v27, v48, v47
	v_add_f32_e32 v29, v49, v46
	v_add_f32_e32 v31, v33, v52
	v_add_f32_e32 v35, v40, v44
	v_sub_f32_e32 v33, v33, v52
	v_sub_f32_e32 v39, v40, v44
	s_and_b64 s[40:41], s[40:41], exec
	s_mov_b32 s1, 0x5000000
	v_add_f32_e32 v40, v1, v31
	v_add_f32_e32 v42, v25, v35
	v_sub_f32_e32 v44, v1, v31
	v_sub_f32_e32 v46, v25, v35
	v_add_f32_e32 v48, v27, v39
	v_sub_f32_e32 v50, v29, v33
	v_sub_f32_e32 v52, v27, v39
	v_add_f32_e32 v54, v29, v33
	v_add_f32_e32 v1, v51, v55
	v_add_f32_e32 v25, v53, v37
	v_sub_f32_e32 v27, v51, v55
	v_sub_f32_e32 v29, v53, v37
	v_add_f32_e32 v31, v41, v56
	v_add_f32_e32 v33, v45, v57
	v_sub_f32_e32 v35, v41, v56
	v_sub_f32_e32 v37, v45, v57
	s_cselect_b32 s1, s1, 0xa000000
	v_readlane_b32 s4, v244, 11
	s_mov_b32 s2, 0
	v_add_f32_e32 v56, v31, v1
	v_add_f32_e32 v58, v33, v25
	v_sub_f32_e32 v60, v1, v31
	v_sub_f32_e32 v62, v25, v33
	v_add_f32_e32 v64, v37, v27
	v_sub_f32_e32 v66, v29, v35
	v_sub_f32_e32 v68, v27, v37
	v_add_f32_e32 v70, v35, v29
	s_add_u32 s1, s4, s1
	v_mov_b32_e32 v18, v72
	v_mov_b32_e32 v19, v3
	v_mov_b32_e32 v20, v74
	v_mov_b32_e32 v21, v5
	s_addc_u32 s94, s97, 0
	v_pk_mov_b32 v[72:73], v[2:3], v[72:73] op_sel:[1,0]
	v_pk_mov_b32 v[74:75], v[4:5], v[74:75] op_sel:[1,0]
	v_mov_b32_e32 v41, v40
	v_mov_b32_e32 v45, v44
	v_mov_b32_e32 v49, v48
	v_mov_b32_e32 v51, v50
	v_mov_b32_e32 v53, v52
	v_mov_b32_e32 v55, v54
	v_mov_b32_e32 v25, v24
	v_mov_b32_e32 v29, v28
	v_mov_b32_e32 v33, v32
	v_mov_b32_e32 v35, v34
	v_mov_b32_e32 v37, v36
	v_mov_b32_e32 v39, v38
	v_mov_b32_e32 v57, v56
	v_mov_b32_e32 v61, v60
	v_mov_b32_e32 v65, v64
	v_mov_b32_e32 v67, v66
	v_mov_b32_e32 v69, v68
	v_mov_b32_e32 v71, v70
	v_pk_mov_b32 v[76:77], v[14:15], v[14:15] op_sel:[1,0]
	v_mov_b32_e32 v27, v26
	v_mov_b32_e32 v43, v42
	v_mov_b32_e32 v59, v58
	v_pk_mov_b32 v[78:79], v[16:17], v[16:17] op_sel:[1,0]
	v_mov_b32_e32 v31, v30
	v_mov_b32_e32 v47, v46
	v_mov_b32_e32 v63, v62
	s_mov_b64 s[40:41], -1
	s_mov_b32 s24, s2
	v_readlane_b32 s58, v245, 48
	v_readlane_b32 s59, v245, 49
	v_readlane_b32 s60, v245, 50
	v_readlane_b32 s61, v245, 51
	v_readlane_b32 s5, v245, 57
	v_readlane_b32 s6, v245, 58
	v_readlane_b32 s7, v245, 59
	v_readlane_b32 s12, v244, 0
	v_readlane_b32 s13, v244, 1
	v_readlane_b32 s14, v244, 2
	v_readlane_b32 s15, v244, 3
	v_readlane_b32 s16, v244, 4
	v_readlane_b32 s17, v244, 5
	v_readlane_b32 s18, v244, 6
	v_readlane_b32 s19, v244, 7
	s_branch .LBB0_118

.LBB0_214:
	v_mov_b32_e32 v1, v12
	s_barrier
	v_pk_add_f32 v[118:119], v[2:3], v[4:5]
	v_ashrrev_i32_e32 v114, 31, v1
	v_lshrrev_b32_e32 v114, 24, v114
	v_and_b32_e32 v126, 0xff, v1
	v_add_lshl_u32 v1, v1, v114, 4
	v_pk_mov_b32 v[122:123], v[2:3], v[104:105] op_sel:[1,0]
	v_and_or_b32 v1, v1, s87, v126
	v_sub_f32_e32 v2, v2, v4
	v_sub_f32_e32 v3, v105, v89
	v_ashrrev_i32_e32 v114, 4, v1
	v_cvt_f32_i32_e32 v4, v126
	v_lshlrev_b32_e32 v1, 3, v1
	v_lshl_add_u32 v155, v114, 3, v1
	v_pk_add_f32 v[114:115], v[112:113], v[100:101]
	v_pk_add_f32 v[116:117], v[108:109], v[92:93]
	v_pk_add_f32 v[120:121], v[104:105], v[88:89]
	v_add_f32_e32 v1, v2, v3
	v_sub_f32_e32 v2, v2, v3
	v_add_f32_e32 v3, v4, v4
	v_mul_f32_e32 v3, 0x39800000, v3
	v_pk_add_f32 v[128:129], v[114:115], v[116:117]
	v_pk_add_f32 v[130:131], v[118:119], v[120:121]
	v_mul_f32_e32 v3, 0.5, v3
	v_pk_add_f32 v[132:133], v[128:129], v[130:131]
	v_sub_f32_e32 v122, v122, v5
	v_sub_f32_e32 v123, v123, v88
	v_sin_f32_e32 v4, v3
	v_mul_f32_e32 v124, 0x3f3504f3, v2
	v_cos_f32_e32 v126, v3
	v_pk_add_f32 v[2:3], v[132:133], 0 op_sel_hi:[1,0]
	v_sub_f32_e32 v5, v122, v123
	ds_write_b64 v155, v[2:3]
	v_pk_add_f32 v[2:3], v[112:113], v[100:101] neg_lo:[0,1] neg_hi:[0,1]
	v_pk_add_f32 v[136:137], v[108:109], v[92:93] neg_lo:[0,1] neg_hi:[0,1]
	v_mul_f32_e32 v1, 0x3f3504f3, v1
	v_mul_f32_e32 v125, 0x3f3504f3, v5
	v_pk_add_f32 v[138:139], v[2:3], v[136:137] op_sel:[0,1] op_sel_hi:[1,0]
	v_pk_add_f32 v[2:3], v[2:3], v[136:137] op_sel:[0,1] op_sel_hi:[1,0] neg_lo:[0,1] neg_hi:[0,1]
	v_add_f32_e32 v140, v125, v1
	v_fma_f32 v141, v5, s20, -v1
	v_add_f32_e32 v142, v138, v140
	v_add_f32_e32 v143, v3, v141
	v_xor_b32_e32 v127, 0x80000000, v4
	v_pk_add_f32 v[144:145], v[142:143], 0 op_sel_hi:[1,0]
	v_pk_mul_f32 v[146:147], v[144:145], v[4:5] op_sel:[1,0] op_sel_hi:[0,0]
	v_mov_b32_e32 v5, v126
	v_mul_f32_e32 v158, v4, v4
	v_mul_f32_e32 v159, v5, v127
	v_pk_add_f32 v[114:115], v[114:115], v[116:117] neg_lo:[0,1] neg_hi:[0,1]
	v_pk_add_f32 v[116:117], v[118:119], v[120:121] neg_lo:[0,1] neg_hi:[0,1]
	v_pk_fma_f32 v[160:161], v[126:127], v[126:127], v[158:159] op_sel_hi:[0,1,1] neg_lo:[0,0,1] neg_hi:[0,0,1]
	v_pk_fma_f32 v[158:159], v[126:127], v[126:127], v[158:159] op_sel_hi:[0,1,1]
	v_fma_f32 v156, v144, v126, v146
	v_fma_f32 v157, v145, v126, -v147
	v_pk_add_f32 v[118:119], v[114:115], v[116:117] op_sel:[0,1] op_sel_hi:[1,0]
	v_pk_add_f32 v[120:121], v[114:115], v[116:117] op_sel:[0,1] op_sel_hi:[1,0] neg_lo:[0,1] neg_hi:[0,1]
	v_pk_mov_b32 v[168:169], v[158:159], v[160:161] op_sel:[1,0]
	v_mov_b32_e32 v144, v118
	v_mov_b32_e32 v145, v121
	v_pk_add_f32 v[122:123], v[122:123], v[122:123] op_sel:[0,1] op_sel_hi:[0,1]
	s_mov_b32 s2, s20
	v_mov_b32_e32 v162, v160
	v_mov_b32_e32 v163, v159
	v_mov_b32_e32 v127, v4
	v_pk_mul_f32 v[170:171], v[158:159], v[168:169] op_sel:[1,0]
	v_pk_add_f32 v[146:147], v[144:145], 0 op_sel_hi:[1,0]
	v_pk_fma_f32 v[122:123], v[122:123], s[2:3], v[124:125] op_sel_hi:[1,1,0] neg_lo:[0,0,1] neg_hi:[0,0,1]
	v_pk_mul_f32 v[164:165], v[126:127], v[162:163]
	v_pk_mul_f32 v[166:167], v[4:5], v[162:163]
	v_pk_fma_f32 v[172:173], v[160:161], v[162:163], v[170:171] op_sel_hi:[0,1,1] neg_lo:[0,0,1] neg_hi:[0,0,1]
	v_pk_fma_f32 v[170:171], v[160:161], v[162:163], v[170:171] op_sel_hi:[0,1,1]
	v_add_f32_e32 v124, v2, v122
	v_add_f32_e32 v125, v139, v123
	v_mov_b32_e32 v174, v172
	v_mov_b32_e32 v175, v171
	v_mov_b32_e32 v214, v164
	v_pk_mov_b32 v[164:165], v[164:165], v[166:167] op_sel:[1,0]
	v_pk_mul_f32 v[158:159], v[146:147], v[158:159] op_sel:[1,1] op_sel_hi:[0,1]
	ds_write_b64 v155, v[156:157] offset:2176
	v_pk_add_f32 v[156:157], v[124:125], 0 op_sel_hi:[1,0]
	v_pk_mul_f32 v[202:203], v[174:175], v[174:175]
	v_pk_mul_f32 v[204:205], v[174:175], v[170:171] op_sel:[0,1] op_sel_hi:[1,0]
	v_add_f32_e32 v166, v214, v164
	v_sub_f32_e32 v164, v214, v164
	v_sub_f32_e32 v165, v167, v165
	v_fma_f32 v224, v146, v160, -v158
	v_fma_f32 v225, v147, v160, v159
	v_mov_b32_e32 v206, v202
	v_mov_b32_e32 v207, v204
	v_pk_mov_b32 v[202:203], v[202:203], v[204:205] op_sel:[1,0]
	v_pk_mul_f32 v[146:147], v[156:157], v[164:165] op_sel:[0,1]
	v_pk_add_f32 v[204:205], v[206:207], v[202:203] neg_lo:[0,1] neg_hi:[0,1]
	v_pk_add_f32 v[202:203], v[206:207], v[202:203]
	v_fma_f32 v158, v156, v166, -v147
	v_fma_f32 v159, v157, v166, v146
	v_mul_f32_e32 v181, v126, v171
	v_mul_f32_e32 v183, v4, v172
	v_mov_b32_e32 v206, v204
	v_mov_b32_e32 v207, v203
	v_mov_b32_e32 v215, v165
	v_pk_mul_f32 v[156:157], v[168:169], v[170:171] op_sel:[0,1]
	v_pk_mul_f32 v[164:165], v[174:175], v[164:165] op_sel:[0,1]
	v_mul_f32_e32 v1, v4, v171
	v_pk_mul_f32 v[4:5], v[4:5], v[206:207]
	ds_write_b64 v155, v[158:159] offset:6528
	v_sub_f32_e32 v146, v3, v141
	v_sub_f32_e32 v147, v181, v183
	v_fma_f32 v158, v162, v172, -v156
	v_fma_f32 v180, v174, v166, -v165
	v_mul_f32_e32 v177, v126, v172
	v_pk_mov_b32 v[208:209], v[202:203], v[204:205] op_sel:[1,0]
	v_pk_mul_f32 v[126:127], v[126:127], v[206:207]
	v_mul_f32_e32 v219, v171, v204
	v_mul_f32_e32 v221, v172, v203
	v_pk_mov_b32 v[222:223], v[170:171], v[172:173] op_sel:[1,0]
	v_mul_f32_e32 v171, v203, v158
	v_mul_f32_e32 v227, v203, v180
	v_pk_mul_f32 v[202:203], v[132:133], v[202:203] op_sel:[1,1] op_sel_hi:[0,1]
	v_pk_add_f32 v[4:5], v[4:5], v[4:5] op_sel:[1,0] op_sel_hi:[1,0] neg_lo:[0,1] neg_hi:[0,1]
	v_fma_f32 v228, v132, v204, -v202
	v_fma_f32 v229, v133, v204, v203
	v_pk_mul_f32 v[4:5], v[142:143], v[4:5] op_sel:[1,0] op_sel_hi:[0,1]
	v_pk_add_f32 v[126:127], v[126:127], v[126:127] op_sel:[0,1] op_sel_hi:[0,1]
	v_pk_mul_f32 v[212:213], v[162:163], v[208:209]
	v_fma_f32 v132, v142, v126, -v4
	v_fma_f32 v133, v143, v127, v5
	v_pk_mul_f32 v[210:211], v[162:163], v[206:207]
	v_pk_mov_b32 v[4:5], v[120:121], v[118:119] op_sel:[1,0]
	v_pk_add_f32 v[120:121], v[212:213], v[212:213] op_sel:[0,1] op_sel_hi:[0,1]
	v_mov_b32_e32 v214, v166
	v_pk_mul_f32 v[4:5], v[4:5], v[120:121]
	v_pk_add_f32 v[120:121], v[210:211], v[210:211] op_sel:[0,1] op_sel_hi:[0,1] neg_lo:[0,1] neg_hi:[0,1]
	v_pk_mul_f32 v[208:209], v[214:215], v[208:209]
	v_fma_f32 v126, v118, v120, -v4
	v_fma_f32 v127, v145, v121, v5
	v_pk_mul_f32 v[216:217], v[214:215], v[206:207]
	v_pk_add_f32 v[4:5], v[208:209], v[208:209] op_sel:[0,1] op_sel_hi:[0,1]
	v_pk_mul_f32 v[214:215], v[174:175], v[206:207]
	v_pk_mul_f32 v[4:5], v[124:125], v[4:5] op_sel:[1,0] op_sel_hi:[0,1]
	v_pk_add_f32 v[120:121], v[216:217], v[216:217] op_sel:[0,1] op_sel_hi:[0,1] neg_lo:[0,1] neg_hi:[0,1]
	v_pk_add_f32 v[134:135], v[128:129], v[130:131] neg_lo:[0,1] neg_hi:[0,1]
	ds_write_b64 v155, v[126:127] offset:21760
	v_fma_f32 v126, v124, v120, -v4
	v_fma_f32 v127, v125, v121, v5
	v_sub_f32_e32 v4, v128, v130
	v_sub_f32_e32 v5, v214, v215
	v_pk_mul_f32 v[222:223], v[134:135], v[222:223] op_sel:[1,0]
	v_add_f32_e32 v116, 0, v4
	ds_write_b64 v155, v[126:127] offset:23936
	v_add_f32_e32 v120, v135, v0
	v_add_f32_e32 v121, v221, v219
	v_fma_f32 v124, v116, v172, -v222
	v_fma_f32 v125, v116, v175, v223
	ds_write_b64 v155, v[224:225] offset:4352
	v_mul_f32_e32 v126, v120, v121
	v_mul_f32_e32 v127, v121, v4
	v_pk_mov_b32 v[120:121], v[4:5], v[120:121] op_sel:[1,0]
	ds_write_b64 v155, v[228:229] offset:17408
	v_fma_f32 v128, v4, v120, -v126
	v_fma_f32 v129, v5, v121, v127
	ds_write_b64 v155, v[132:133] offset:19584
	v_sub_f32_e32 v4, v138, v140
	ds_write_b64 v155, v[124:125] offset:8704
	ds_write_b64 v155, v[128:129] offset:26112
	v_add_f32_e32 v120, v4, v0
	v_add_f32_e32 v121, v177, v1
	v_mul_f32_e32 v128, v146, v147
	v_mul_f32_e32 v129, v147, v120
	v_pk_mov_b32 v[130:131], v[120:121], v[146:147] op_sel:[1,0]
	v_mul_f32_e32 v116, v204, v121
	v_mul_f32_e32 v126, v206, v147
	v_mul_f32_e32 v127, v207, v121
	v_fma_f32 v132, v120, v130, -v128
	v_fma_f32 v133, v121, v131, v129
	v_add_f32_e32 v134, 0, v146
	v_fma_f32 v157, v163, v172, v157
	v_fma_f32 v124, -v206, v121, v116
	v_fma_f32 v125, -v207, v147, v116
	v_mov_b32_e32 v135, v4
	v_pk_add_f32 v[120:121], v[126:127], v[126:127] op_sel:[1,0] op_sel_hi:[1,0]
	v_mov_b32_e32 v161, v157
	v_pk_mul_f32 v[120:121], v[134:135], v[120:121]
	v_mov_b32_e32 v127, v125
	v_pk_mov_b32 v[124:125], v[124:125], v[134:135] op_sel:[1,0]
	v_mul_f32_e32 v162, v206, v158
	v_mul_f32_e32 v163, v207, v161
	v_fma_f32 v4, v4, v124, -v120
	v_fma_f32 v5, v127, v125, v121
	v_mul_f32_e32 v1, v204, v157
	ds_write_b64 v155, v[132:133] offset:10880
	ds_write_b64 v155, v[4:5] offset:28288
	v_sub_f32_e32 v4, v114, v117
	v_sub_f32_e32 v5, v162, v163
	v_mul_f32_e32 v156, v119, v157
	v_mul_f32_e32 v157, v119, v158
	v_fma_f32 v165, v175, v166, v164
	v_add_f32_e32 v114, 0, v4
	v_mov_b32_e32 v167, v165
	v_add_f32_e32 v116, v119, v0
	v_add_f32_e32 v117, v171, v1
	v_fma_f32 v118, v114, v158, -v156
	v_fma_f32 v119, v114, v161, v157
	v_mul_f32_e32 v182, v206, v180
	v_mul_f32_e32 v183, v207, v167
	v_sub_f32_e32 v139, v139, v123
	v_mul_f32_e32 v114, v116, v117
	v_mul_f32_e32 v115, v117, v4
	v_pk_mov_b32 v[116:117], v[4:5], v[116:117] op_sel:[1,0]
	v_mul_f32_e32 v1, v204, v165
	v_fma_f32 v120, v4, v116, -v114
	v_fma_f32 v121, v5, v117, v115
	v_sub_f32_e32 v2, v2, v122
	v_sub_f32_e32 v3, v182, v183
	v_mul_f32_e32 v164, v139, v165
	v_mul_f32_e32 v165, v139, v180
	v_add_f32_e32 v4, 0, v2
	v_add_f32_e32 v114, v139, v0
	v_add_f32_e32 v115, v227, v1
	v_fma_f32 v116, v4, v180, -v164
	v_fma_f32 v117, v4, v167, v165
	ds_write_b64 v155, v[118:119] offset:13056
	ds_write_b64 v155, v[120:121] offset:30464
	v_mul_f32_e32 v4, v114, v115
	v_mul_f32_e32 v5, v115, v2
	v_pk_mov_b32 v[114:115], v[2:3], v[114:115] op_sel:[1,0]
	v_mov_b32_e32 v1, v6
	v_fma_f32 v118, v2, v114, -v4
	v_fma_f32 v119, v3, v115, v5
	s_mov_b32 s88, s71
	ds_write_b64 v155, v[116:117] offset:15232
	ds_write_b64 v155, v[118:119] offset:32640
	s_waitcnt lgkmcnt(0)
	s_barrier
	s_mov_b32 s89, s21
	v_ashrrev_i32_e32 v2, 31, v1
	v_lshrrev_b32_e32 v2, 28, v2
	v_and_b32_e32 v155, 15, v1
	v_add_u32_e32 v1, v1, v2
	v_ashrrev_i32_e32 v1, 4, v1
	v_lshlrev_b32_e32 v2, 11, v1
	v_lshl_add_u32 v1, v1, 7, v2
	v_lshl_or_b32 v1, v155, 3, v1
	ds_read2_b64 v[120:123], v1 offset1:17
	ds_read2_b64 v[124:127], v1 offset0:68 offset1:85
	ds_read2_b64 v[128:131], v1 offset0:136 offset1:153
	ds_read2_b64 v[132:135], v1 offset0:170 offset1:187
	ds_read2_b64 v[136:139], v1 offset0:204 offset1:221
	ds_read2_b64 v[140:143], v1 offset0:238 offset1:255
	ds_read2_b64 v[144:147], v1 offset0:34 offset1:51
	ds_read2_b64 v[156:159], v1 offset0:102 offset1:119
	s_waitcnt lgkmcnt(5)
	v_pk_add_f32 v[118:119], v[128:129], v[120:121]
	s_waitcnt lgkmcnt(2)
	v_pk_mov_b32 v[176:177], v[134:135], v[142:143] op_sel:[1,0]
	s_waitcnt lgkmcnt(1)
	v_pk_add_f32 v[172:173], v[146:147], v[134:135]
	s_waitcnt lgkmcnt(0)
	v_pk_add_f32 v[174:175], v[158:159], v[142:143]
	v_mov_b32_e32 v135, v143
	v_pk_add_f32 v[142:143], v[172:173], v[174:175] neg_lo:[0,1] neg_hi:[0,1]
	v_sub_f32_e32 v176, v147, v176
	v_sub_f32_e32 v177, v158, v177
	v_pk_add_f32 v[116:117], v[172:173], v[174:175]
	v_mul_f32_e32 v172, 0x3f3504f3, v143
	v_mul_f32_e32 v175, 0xbf3504f3, v143
	v_cvt_f32_i32_e32 v143, v155
	v_sub_f32_e32 v134, v146, v134
	v_sub_f32_e32 v135, v159, v135
	v_pk_add_f32 v[128:129], v[120:121], v[128:129] neg_lo:[0,1] neg_hi:[0,1]
	v_add_f32_e32 v143, v143, v143
	v_pk_add_f32 v[120:121], v[124:125], v[136:137] neg_lo:[0,1] neg_hi:[0,1]
	v_pk_add_f32 v[160:161], v[136:137], v[124:125]
	v_pk_add_f32 v[162:163], v[122:123], v[130:131]
	v_pk_add_f32 v[164:165], v[126:127], v[138:139]
	v_sub_f32_e32 v146, v134, v135
	v_mul_f32_e32 v143, 0x3b800000, v143
	v_pk_mov_b32 v[124:125], v[120:121], v[120:121] op_sel:[1,0]
	v_add_f32_e32 v136, v128, v121
	v_sub_f32_e32 v137, v129, v120
	v_pk_add_f32 v[134:135], v[134:135], v[134:135] op_sel:[0,1] op_sel_hi:[0,1]
	v_pk_add_f32 v[4:5], v[162:163], v[164:165]
	v_pk_add_f32 v[166:167], v[144:145], v[132:133]
	v_pk_add_f32 v[168:169], v[156:157], v[140:141]
	v_pk_add_f32 v[162:163], v[162:163], v[164:165] neg_lo:[0,1] neg_hi:[0,1]
	v_mul_f32_e32 v143, 0.5, v143
	v_pk_add_f32 v[120:121], v[176:177], v[176:177] op_sel:[0,1] op_sel_hi:[0,1] neg_lo:[0,1] neg_hi:[0,1]
	s_mov_b32 s70, s21
	v_pk_mul_f32 v[134:135], v[134:135], s[88:89]
	v_pk_add_f32 v[114:115], v[166:167], v[168:169]
	v_pk_add_f32 v[170:171], v[166:167], v[168:169] neg_lo:[0,1] neg_hi:[0,1]
	v_add_f32_e32 v158, v176, v177
	v_pk_mul_f32 v[164:165], v[162:163], s[20:21] op_sel_hi:[1,0]
	v_mul_f32_e32 v142, 0x3f3504f3, v142
	v_sin_f32_e32 v166, v143
	s_nop 1
	v_cos_f32_e32 v204, v143
	s_nop 1
	v_fma_f32 v176, v120, s70, v134
	v_fma_f32 v177, v121, s71, -v135
	v_pk_add_f32 v[2:3], v[118:119], v[160:161]
	v_mov_b32_e32 v120, v118
	v_sub_f32_e32 v118, v172, v142
	v_sub_f32_e32 v119, v119, v161
	v_sub_f32_e32 v120, v120, v160
	v_sub_f32_e32 v121, v165, v164
	v_mov_b32_e32 v135, v142
	v_pk_add_f32 v[142:143], v[118:119], v[170:171] op_sel:[1,0] op_sel_hi:[0,1]
	v_mov_b32_e32 v161, v170
	v_sub_f32_e32 v134, v167, v169
	v_sub_f32_e32 v135, v175, v135
	v_sub_f32_e32 v170, v144, v132
	v_sub_f32_e32 v171, v122, v130
	v_sub_f32_e32 v172, v157, v141
	v_sub_f32_e32 v173, v127, v139
	v_mul_f32_e32 v155, 0x3f6c835e, v158
	v_mul_f32_e32 v179, 0x3ec3ef15, v146
	v_sub_f32_e32 v122, v145, v133
	v_sub_f32_e32 v123, v123, v131
	v_sub_f32_e32 v127, v126, v138
	v_sub_f32_e32 v126, v156, v140
	v_pk_add_f32 v[132:133], v[170:171], v[172:173] neg_lo:[0,1] neg_hi:[0,1]
	v_pk_fma_f32 v[162:163], v[162:163], s[20:21], v[164:165] op_sel:[0,0,1] op_sel_hi:[1,0,0]
	v_pk_add_f32 v[174:175], v[170:171], v[172:173]
	v_pk_add_f32 v[130:131], v[122:123], v[126:127] neg_lo:[0,1] neg_hi:[0,1]
	v_pk_add_f32 v[122:123], v[122:123], v[126:127]
	v_mov_b32_e32 v139, v129
	v_mov_b32_e32 v127, v125
	v_mov_b32_e32 v160, v162
	v_pk_add_f32 v[162:163], v[162:163], v[118:119] neg_lo:[0,1] neg_hi:[0,1]
	v_mul_f32_e32 v126, 0x3ec3ef15, v133
	v_pk_mul_f32 v[140:141], v[132:133], s[20:21]
	s_mov_b32 s90, s20
	s_mov_b32 s91, s71
	v_mul_f32_e32 v133, s73, v132
	v_mul_f32_e32 v132, s72, v158
	v_sub_f32_e32 v124, v128, v124
	v_sub_f32_e32 v125, v179, v155
	v_pk_mul_f32 v[128:129], v[174:175], s[70:71] op_sel:[1,0]
	v_add_f32_e32 v164, v118, v160
	v_sub_f32_e32 v161, v119, v161
	v_pk_add_f32 v[118:119], v[142:143], v[162:163]
	v_mul_f32_e32 v138, 0x3f6c835e, v123
	v_mul_f32_e32 v143, 0x3f3504f3, v174
	v_mul_f32_e32 v144, 0x3f3504f3, v130
	v_pk_fma_f32 v[140:141], v[122:123], s[90:91], v[140:141] neg_lo:[0,0,1] neg_hi:[0,0,1]
	v_fma_f32 v123, v122, s31, -v133
	v_fma_f32 v122, v146, s30, -v132
	v_fma_f32 v132, v131, s88, v128
	v_fma_f32 v133, v131, s89, -v129
	v_pk_add_f32 v[126:127], v[138:139], v[126:127]
	v_add_f32_e32 v128, v144, v143
	v_fma_f32 v129, v130, s20, -v143
	v_pk_add_f32 v[130:131], v[136:137], v[128:129]
	v_pk_add_f32 v[138:139], v[132:133], v[176:177]
	v_xor_b32_e32 v205, 0x80000000, v166
	v_pk_add_f32 v[144:145], v[138:139], v[130:131]
	v_pk_add_f32 v[180:181], v[2:3], v[114:115]
	v_pk_mul_f32 v[158:159], v[166:167], v[144:145] op_sel_hi:[0,1]
	v_fma_f32 v170, v204, v144, v159
	v_fma_f32 v171, v204, v145, -v158
	v_mov_b32_e32 v167, v204
	v_pk_add_f32 v[182:183], v[4:5], v[116:117]
	v_mul_f32_e32 v144, v166, v166
	v_mul_f32_e32 v145, v167, v205
	v_pk_add_f32 v[202:203], v[182:183], v[180:181]
	v_pk_fma_f32 v[158:159], v[204:205], v[204:205], v[144:145] op_sel_hi:[0,1,1] neg_lo:[0,0,1] neg_hi:[0,0,1]
	v_pk_fma_f32 v[144:145], v[204:205], v[204:205], v[144:145] op_sel_hi:[0,1,1]
	v_pk_add_f32 v[168:169], v[120:121], v[134:135]
	ds_write2_b64 v1, v[202:203], v[170:171] offset1:17
	v_pk_add_f32 v[120:121], v[120:121], v[134:135] neg_lo:[0,1] neg_hi:[0,1]
	v_add_f32_e32 v134, v168, v164
	v_add_f32_e32 v135, v169, v161
	v_mov_b32_e32 v170, v158
	v_mov_b32_e32 v171, v145
	v_mul_f32_e32 v202, v145, v145
	v_mul_f32_e32 v203, v145, v158
	v_pk_mul_f32 v[144:145], v[134:135], v[144:145] op_sel:[1,1] op_sel_hi:[0,1]
	v_pk_fma_f32 v[206:207], v[158:159], v[170:171], v[202:203] op_sel_hi:[0,1,1] neg_lo:[0,0,1] neg_hi:[0,0,1]
	v_pk_fma_f32 v[202:203], v[158:159], v[170:171], v[202:203] op_sel_hi:[0,1,1]
	v_fma_f32 v216, v134, v158, -v144
	v_fma_f32 v217, v135, v158, v145
	v_pk_mul_f32 v[144:145], v[170:171], v[202:203] op_sel:[0,1]
	v_pk_add_f32 v[132:133], v[132:133], v[176:177] neg_lo:[0,1] neg_hi:[0,1]
	v_fma_f32 v158, v170, v206, -v145
	v_fma_f32 v145, v171, v206, v144
	v_sub_f32_e32 v142, v142, v162
	v_mov_b32_e32 v177, v145
	v_mov_b32_e32 v205, v166
	v_mov_b32_e32 v208, v206
	v_mov_b32_e32 v209, v203
	v_pk_add_f32 v[218:219], v[120:121], v[120:121] op_sel:[0,1] op_sel_hi:[0,1]
	v_mul_f32_e32 v143, v142, v158
	v_mul_f32_e32 v142, v142, v145
	v_pk_mul_f32 v[172:173], v[204:205], v[170:171]
	v_pk_mul_f32 v[174:175], v[166:167], v[170:171]
	v_mov_b32_e32 v176, v158
	v_fma_f32 v144, v218, v158, -v142
	v_pk_mul_f32 v[158:159], v[208:209], v[202:203] op_sel:[0,1]
	v_pk_add_f32 v[130:131], v[130:131], v[138:139] neg_lo:[0,1] neg_hi:[0,1]
	v_pk_add_f32 v[138:139], v[140:141], v[124:125]
	v_pk_add_f32 v[146:147], v[126:127], v[122:123]
	v_fma_f32 v145, v219, v177, v143
	v_pk_fma_f32 v[162:163], v[206:207], v[208:209], v[158:159] op_sel:[0,0,1] op_sel_hi:[0,1,0] neg_lo:[0,0,1] neg_hi:[0,0,1]
	v_pk_fma_f32 v[158:159], v[206:207], v[208:209], v[158:159] op_sel:[0,0,1] op_sel_hi:[0,1,0]
	v_mov_b32_e32 v220, v172
	v_pk_mov_b32 v[172:173], v[172:173], v[174:175] op_sel:[1,0]
	v_pk_add_f32 v[156:157], v[138:139], v[146:147]
	v_pk_add_f32 v[142:143], v[180:181], v[182:183] neg_lo:[0,1] neg_hi:[0,1]
	v_pk_mov_b32 v[182:183], v[158:159], v[162:163] op_sel:[1,0]
	v_add_f32_e32 v174, v220, v172
	v_sub_f32_e32 v172, v220, v172
	v_sub_f32_e32 v173, v175, v173
	v_pk_mul_f32 v[210:211], v[204:205], v[208:209]
	v_pk_mul_f32 v[212:213], v[166:167], v[208:209]
	v_pk_add_f32 v[128:129], v[136:137], v[128:129] neg_lo:[0,1] neg_hi:[0,1]
	v_mov_b32_e32 v180, v162
	v_mov_b32_e32 v181, v159
	v_pk_mul_f32 v[166:167], v[166:167], v[182:183] op_sel_hi:[0,1]
	v_pk_mul_f32 v[222:223], v[156:157], v[172:173] op_sel:[0,1]
	v_pk_mov_b32 v[214:215], v[202:203], v[206:207] op_sel:[1,0]
	v_pk_add_f32 v[134:135], v[128:129], v[132:133] op_sel:[0,1] op_sel_hi:[1,0]
	v_pk_add_f32 v[128:129], v[128:129], v[132:133] op_sel:[0,1] op_sel_hi:[1,0] neg_lo:[0,1] neg_hi:[0,1]
	v_fma_f32 v202, v204, v180, v166
	v_fma_f32 v167, v204, v181, -v167
	v_fma_f32 v224, v156, v174, -v223
	v_fma_f32 v225, v157, v174, v222
	v_mov_b32_e32 v226, v210
	v_pk_mov_b32 v[210:211], v[210:211], v[212:213] op_sel:[1,0]
	v_mov_b32_e32 v205, v167
	v_pk_mul_f32 v[156:157], v[208:209], v[172:173] op_sel:[0,1]
	v_add_f32_e32 v212, v226, v210
	v_sub_f32_e32 v211, v213, v211
	v_mov_b32_e32 v221, v173
	v_fma_f32 v172, v208, v174, -v157
	v_fma_f32 v157, v209, v174, v156
	v_mul_f32_e32 v136, v129, v211
	v_mul_f32_e32 v137, v134, v211
	v_mul_f32_e32 v166, v131, v167
	v_mul_f32_e32 v167, v131, v202
	v_mov_b32_e32 v220, v174
	v_mov_b32_e32 v174, v172
	v_mov_b32_e32 v175, v157
	v_mov_b32_e32 v226, v212
	v_mov_b32_e32 v227, v211
	v_fma_f32 v210, v134, v212, -v136
	v_fma_f32 v211, v129, v212, v137
	v_fma_f32 v202, v130, v202, -v166
	v_fma_f32 v203, v130, v205, v167
	v_pk_mul_f32 v[158:159], v[142:143], v[158:159] op_sel:[1,1] op_sel_hi:[0,1]
	v_pk_mul_f32 v[218:219], v[170:171], v[180:181]
	v_pk_mul_f32 v[170:171], v[170:171], v[182:183]
	ds_write2_b64 v1, v[216:217], v[224:225] offset0:34 offset1:51
	v_pk_mul_f32 v[216:217], v[220:221], v[180:181]
	v_pk_mul_f32 v[220:221], v[220:221], v[182:183]
	v_pk_mul_f32 v[222:223], v[208:209], v[180:181]
	v_pk_mul_f32 v[224:225], v[208:209], v[182:183]
	v_pk_mul_f32 v[132:133], v[180:181], v[226:227]
	v_pk_mul_f32 v[136:137], v[182:183], v[226:227]
	v_pk_mul_f32 v[130:131], v[180:181], v[176:177]
	v_pk_mul_f32 v[166:167], v[182:183], v[176:177]
	v_pk_mul_f32 v[176:177], v[180:181], v[174:175]
	v_pk_mul_f32 v[180:181], v[182:183], v[174:175]
	v_fma_f32 v182, v142, v162, -v158
	v_fma_f32 v183, v143, v162, v159
	v_sub_f32_e32 v142, v168, v164
	v_sub_f32_e32 v143, v161, v169
	v_pk_add_f32 v[158:159], v[170:171], v[170:171] op_sel:[0,1] op_sel_hi:[0,1]
	v_pk_mul_f32 v[158:159], v[142:143], v[158:159] op_sel:[1,0] op_sel_hi:[0,1]
	v_pk_add_f32 v[160:161], v[218:219], v[218:219] op_sel:[0,1] op_sel_hi:[0,1] neg_lo:[0,1] neg_hi:[0,1]
	v_fma_f32 v162, v142, v160, -v158
	v_fma_f32 v163, v143, v161, v159
	v_pk_add_f32 v[2:3], v[2:3], v[114:115] neg_lo:[0,1] neg_hi:[0,1]
	v_sub_f32_e32 v138, v138, v146
	v_sub_f32_e32 v139, v147, v139
	v_pk_add_f32 v[142:143], v[220:221], v[220:221] op_sel:[0,1] op_sel_hi:[0,1]
	v_pk_add_f32 v[4:5], v[4:5], v[116:117] neg_lo:[0,1] neg_hi:[0,1]
	v_pk_mul_f32 v[142:143], v[138:139], v[142:143] op_sel:[1,0] op_sel_hi:[0,1]
	v_pk_add_f32 v[146:147], v[216:217], v[216:217] op_sel:[0,1] op_sel_hi:[0,1] neg_lo:[0,1] neg_hi:[0,1]
	v_pk_add_f32 v[114:115], v[2:3], v[4:5] op_sel:[0,1] op_sel_hi:[1,0]
	v_pk_add_f32 v[2:3], v[2:3], v[4:5] op_sel:[0,1] op_sel_hi:[1,0] neg_lo:[0,1] neg_hi:[0,1]
	v_fma_f32 v158, v138, v146, -v142
	v_fma_f32 v159, v139, v147, v143
	v_pk_mul_f32 v[116:117], v[2:3], v[214:215] op_sel:[1,0]
	v_fma_f32 v138, v114, v206, -v116
	v_fma_f32 v139, v114, v209, v117
	v_mov_b32_e32 v5, v115
	v_pk_add_f32 v[116:117], v[224:225], v[224:225] op_sel:[0,1] op_sel_hi:[0,1]
	v_mul_f32_e32 v114, v115, v116
	v_mul_f32_e32 v115, v2, v117
	v_pk_add_f32 v[116:117], v[222:223], v[222:223] op_sel:[0,1] op_sel_hi:[0,1] neg_lo:[0,1] neg_hi:[0,1]
	v_fma_f32 v2, v2, v116, -v114
	v_fma_f32 v3, v5, v117, v115
	v_pk_add_f32 v[116:117], v[136:137], v[136:137] op_sel:[0,1] op_sel_hi:[0,1]
	v_mul_f32_e32 v114, v135, v116
	v_mul_f32_e32 v115, v128, v117
	v_pk_add_f32 v[116:117], v[132:133], v[132:133] op_sel:[0,1] op_sel_hi:[0,1] neg_lo:[0,1] neg_hi:[0,1]
	v_fma_f32 v128, v128, v116, -v114
	v_fma_f32 v129, v135, v117, v115
	v_pk_add_f32 v[114:115], v[166:167], v[166:167] op_sel:[0,1] op_sel_hi:[0,1]
	ds_write2_b64 v1, v[2:3], v[128:129] offset0:204 offset1:221
	v_sub_f32_e32 v2, v120, v121
	v_sub_f32_e32 v3, v130, v131
	v_mul_f32_e32 v4, v118, v114
	v_mul_f32_e32 v5, v2, v115
	v_pk_mov_b32 v[114:115], v[2:3], v[118:119] op_sel:[1,0]
	v_fma_f32 v116, v2, v114, -v4
	v_fma_f32 v117, v3, v115, v5
	v_sub_f32_e32 v2, v124, v140
	v_sub_f32_e32 v3, v126, v122
	v_sub_f32_e32 v4, v141, v125
	v_sub_f32_e32 v5, v127, v123
	ds_write2_b64 v1, v[182:183], v[202:203] offset0:136 offset1:153
	v_pk_add_f32 v[114:115], v[4:5], v[2:3]
	v_sub_f32_e32 v118, v2, v4
	v_sub_f32_e32 v2, v5, v3
	v_mul_f32_e32 v3, v2, v172
	v_mul_f32_e32 v2, v2, v157
	v_fma_f32 v4, v114, v172, -v2
	v_fma_f32 v5, v114, v175, v3
	ds_write2_b64 v1, v[144:145], v[4:5] offset0:102 offset1:119
	v_pk_add_f32 v[4:5], v[180:181], v[180:181] op_sel:[0,1] op_sel_hi:[0,1]
	v_mul_f32_e32 v2, v115, v4
	v_mul_f32_e32 v3, v118, v5
	v_pk_add_f32 v[4:5], v[176:177], v[176:177] op_sel:[0,1] op_sel_hi:[0,1] neg_lo:[0,1] neg_hi:[0,1]
	v_fma_f32 v114, v118, v4, -v2
	v_fma_f32 v115, v115, v5, v3
	ds_write2_b64 v1, v[162:163], v[158:159] offset0:170 offset1:187
	ds_write2_b64 v1, v[138:139], v[210:211] offset0:68 offset1:85
	ds_write2_b64 v1, v[116:117], v[114:115] offset0:238 offset1:255
	v_mov_b32_e32 v1, v12
	s_waitcnt lgkmcnt(0)
	s_barrier
	s_mov_b32 s77, s71
	v_mul_lo_u32 v1, v1, s33
	ds_read2_b64 v[2:5], v1 offset1:1
	ds_read2_b64 v[114:117], v1 offset0:2 offset1:3
	ds_read2_b64 v[118:121], v1 offset0:9 offset1:10
	ds_read2_b64 v[122:125], v1 offset0:4 offset1:5
	ds_read2_b64 v[126:129], v1 offset0:6 offset1:7
	ds_read2_b64 v[130:133], v1 offset0:13 offset1:14
	ds_read2_b64 v[134:137], v1 offset0:8 offset1:15
	ds_read2_b64 v[138:141], v1 offset0:11 offset1:12
	s_waitcnt lgkmcnt(5)
	v_add_f32_e32 v1, v4, v118
	s_waitcnt lgkmcnt(3)
	s_waitcnt lgkmcnt(2)
	v_add_f32_e32 v144, v124, v130
	s_waitcnt lgkmcnt(1)
	v_pk_add_f32 v[168:169], v[2:3], v[134:135]
	v_pk_add_f32 v[2:3], v[2:3], v[134:135] neg_lo:[0,1] neg_hi:[0,1]
	s_waitcnt lgkmcnt(0)
	v_pk_add_f32 v[134:135], v[122:123], v[140:141]
	v_pk_add_f32 v[122:123], v[122:123], v[140:141] neg_lo:[0,1] neg_hi:[0,1]
	v_add_f32_e32 v143, v1, v144
	v_sub_f32_e32 v1, v1, v144
	v_mov_b32_e32 v164, v115
	v_add_f32_e32 v170, v2, v123
	v_sub_f32_e32 v171, v3, v122
	v_add_f32_e32 v144, v116, v138
	v_add_f32_e32 v145, v128, v136
	v_mov_b32_e32 v166, v127
	v_add_f32_e32 v142, v5, v119
	v_add_f32_e32 v146, v117, v139
	v_add_f32_e32 v147, v129, v137
	v_mov_b32_e32 v156, v117
	v_add_f32_e32 v172, v115, v121
	v_add_f32_e32 v173, v114, v120
	v_mov_b32_e32 v115, v4
	v_sub_f32_e32 v4, v164, v121
	v_sub_f32_e32 v5, v5, v119
	v_add_f32_e32 v155, v125, v131
	v_sub_f32_e32 v116, v116, v138
	v_sub_f32_e32 v117, v129, v137
	v_sub_f32_e32 v114, v114, v120
	v_sub_f32_e32 v115, v115, v118
	v_add_f32_e32 v118, v127, v133
	v_add_f32_e32 v119, v126, v132
	v_mov_b32_e32 v127, v124
	v_sub_f32_e32 v124, v166, v133
	v_sub_f32_e32 v125, v125, v131
	v_mov_b32_e32 v159, v136
	v_pk_add_f32 v[136:137], v[116:117], v[116:117] op_sel_hi:[0,1] neg_lo:[0,1] neg_hi:[0,1]
	v_sub_f32_e32 v120, v126, v132
	v_sub_f32_e32 v121, v127, v130
	v_sub_f32_e32 v156, v156, v139
	v_sub_f32_e32 v157, v128, v159
	v_pk_add_f32 v[132:133], v[114:115], v[124:125] neg_lo:[0,1] neg_hi:[0,1]
	v_pk_add_f32 v[164:165], v[4:5], v[120:121]
	v_add_f32_e32 v116, v116, v117
	v_add_f32_e32 v117, v114, v124
	v_mov_b32_e32 v167, v4
	v_sub_f32_e32 v4, v5, v121
	v_add_f32_e32 v114, v115, v125
	v_pk_add_f32 v[138:139], v[156:157], v[156:157] op_sel:[0,1] op_sel_hi:[1,0]
	v_mov_b32_e32 v166, v156
	v_pk_mov_b32 v[156:157], v[156:157], v[120:121] op_sel:[1,0]
	v_pk_mul_f32 v[120:121], v[4:5], s[88:89] op_sel_hi:[0,1]
	v_pk_mul_f32 v[114:115], v[114:115], s[70:71] op_sel_hi:[0,1]
	v_pk_add_f32 v[156:157], v[166:167], v[156:157] neg_lo:[0,1] neg_hi:[0,1]
	v_sub_f32_e32 v160, v142, v155
	v_pk_add_f32 v[128:129], v[144:145], v[144:145] op_sel:[0,1] op_sel_hi:[1,0]
	v_sub_f32_e32 v144, v144, v145
	v_add_f32_e32 v124, v2, v123
	v_add_f32_e32 v125, v120, v114
	v_fma_f32 v166, v4, s88, v114
	v_fma_f32 v167, v4, s89, -v115
	v_mul_f32_e32 v145, 0x3f3504f3, v1
	v_mul_f32_e32 v159, 0x3f3504f3, v160
	v_mul_f32_e32 v162, 0x3f3504f3, v144
	v_mul_f32_e32 v140, 0x3ec3ef15, v133
	v_mul_f32_e32 v120, 0x3f6c835e, v165
	v_sub_f32_e32 v4, v121, v115
	v_sub_f32_e32 v5, v3, v122
	v_sub_f32_e32 v114, v168, v134
	v_sub_f32_e32 v115, v159, v145
	v_add_f32_e32 v120, v120, v140
	v_add_f32_e32 v121, v3, v122
	v_pk_mul_f32 v[140:141], v[116:117], s[72:73]
	v_pk_mul_f32 v[144:145], v[116:117], s[74:75]
	v_pk_mul_f32 v[116:117], v[116:117], s[88:89] op_sel_hi:[0,1]
	v_fma_f32 v206, v156, s70, v116
	v_fma_f32 v207, v156, s71, -v117
	v_pk_add_f32 v[116:117], v[146:147], v[146:147] op_sel:[0,1] op_sel_hi:[0,1] neg_lo:[0,1] neg_hi:[0,1]
	v_pk_fma_f32 v[176:177], v[156:157], s[72:73], v[144:145] neg_lo:[0,0,1] neg_hi:[0,0,1]
	v_fmac_f32_e32 v145, 0x3f3504f3, v157
	v_pk_fma_f32 v[140:141], v[156:157], s[74:75], v[140:141]
	v_pk_mul_f32 v[156:157], v[116:117], s[2:3]
	v_mov_b32_e32 v163, v135
	v_mov_b32_e32 v182, v138
	v_sub_f32_e32 v208, v156, v162
	v_sub_f32_e32 v209, v169, v163
	v_pk_fma_f32 v[116:117], v[116:117], s[2:3], v[162:163] op_sel_hi:[1,1,0] neg_lo:[0,0,1] neg_hi:[0,0,1]
	v_pk_mul_f32 v[138:139], v[138:139], s[88:89] op_sel_hi:[0,1]
	v_mul_f32_e32 v3, s77, v137
	v_pk_add_f32 v[174:175], v[168:169], v[134:135] neg_lo:[0,1] neg_hi:[0,1]
	v_add_f32_e32 v126, v169, v135
	v_add_f32_e32 v127, v172, v118
	v_pk_add_f32 v[130:131], v[172:173], v[118:119] neg_lo:[0,1] neg_hi:[0,1]
	v_mov_b32_e32 v181, v137
	v_pk_mov_b32 v[204:205], v[136:137], v[164:165] op_sel:[1,0]
	v_sub_f32_e32 v2, v2, v123
	v_sub_f32_e32 v3, v3, v139
	v_pk_fma_f32 v[122:123], v[136:137], s[76:77], v[138:139] op_sel:[1,0,0] neg_lo:[0,0,1] neg_hi:[0,0,1]
	v_pk_mov_b32 v[136:137], v[172:173], v[146:147] op_sel:[1,0]
	v_fmamk_f32 v160, v1, 0x3f3504f3, v159
	v_mov_b32_e32 v183, v132
	v_mov_b32_e32 v210, v118
	v_add_f32_e32 v134, v168, v134
	v_add_f32_e32 v135, v142, v155
	v_add_f32_e32 v118, v136, v119
	v_add_f32_e32 v119, v137, v147
	v_sub_f32_e32 v146, v174, v130
	v_add_f32_e32 v147, v175, v131
	v_pk_mul_f32 v[158:159], v[132:133], s[20:21]
	v_pk_mul_f32 v[132:133], v[182:183], s[74:75]
	v_pk_mul_f32 v[182:183], v[182:183], s[72:73]
	v_sub_f32_e32 v156, v172, v210
	v_sub_f32_e32 v157, v157, v162
	v_add_f32_e32 v130, v208, v160
	v_sub_f32_e32 v163, v209, v131
	v_mov_b32_e32 v180, v164
	v_pk_fma_f32 v[202:203], v[164:165], s[90:91], v[158:159] neg_lo:[0,0,1] neg_hi:[0,0,1]
	v_pk_fma_f32 v[164:165], v[164:165], s[2:3], v[158:159] op_sel_hi:[0,1,0] neg_lo:[0,0,1] neg_hi:[0,0,1]
	v_add_f32_e32 v136, v126, v127
	v_add_f32_e32 v137, v135, v119
	v_mov_b32_e32 v142, v134
	v_mov_b32_e32 v138, v118
	v_pk_add_f32 v[118:119], v[134:135], v[118:119] neg_lo:[0,1] neg_hi:[0,1]
	v_pk_add_f32 v[134:135], v[166:167], v[206:207]
	v_pk_add_f32 v[166:167], v[114:115], v[156:157]
	s_mov_b32 s92, s71
	s_mov_b32 s93, s3
	v_fma_f32 v158, v180, s78, -v158
	v_fma_f32 v159, v181, s79, -v182
	v_pk_fma_f32 v[180:181], v[204:205], s[30:31], v[182:183] neg_lo:[0,0,1] neg_hi:[0,0,1]
	v_add_f32_e32 v116, v160, v116
	v_add_f32_e32 v117, v115, v117
	v_add_f32_e32 v130, v166, v130
	v_add_f32_e32 v131, v167, v163
	v_pk_fma_f32 v[132:133], v[204:205], s[92:93], v[132:133] neg_lo:[0,0,1] neg_hi:[0,0,1]
	v_add_f32_e32 v138, v142, v138
	v_add_f32_e32 v139, v143, v128
	v_sub_f32_e32 v116, v166, v116
	v_sub_f32_e32 v117, v163, v117
	v_add_f32_e32 v162, v2, v164
	v_add_f32_e32 v163, v121, v165
	v_pk_add_f32 v[164:165], v[120:121], v[180:181]
	v_pk_add_f32 v[166:167], v[202:203], v[2:3]
	v_mov_b32_e32 v202, v120
	v_mov_b32_e32 v3, v120
	v_pk_add_f32 v[168:169], v[136:137], v[136:137] op_sel:[1,0] op_sel_hi:[1,0]
	v_mov_b32_e32 v142, v126
	v_pk_mov_b32 v[126:127], v[126:127], v[128:129] op_sel:[1,0]
	v_add_f32_e32 v128, v170, v145
	v_add_f32_e32 v129, v171, v177
	v_sub_f32_e32 v120, v203, v132
	v_sub_f32_e32 v121, v121, v133
	v_pk_add_f32 v[132:133], v[166:167], v[164:165]
	v_pk_add_f32 v[166:167], v[138:139], v[138:139] op_sel:[1,0] op_sel_hi:[1,0]
	v_pk_mul_f32 v[168:169], v[76:77], v[168:169]
	v_pk_add_f32 v[124:125], v[124:125], v[140:141] op_sel:[0,1] op_sel_hi:[1,0] neg_lo:[0,1] neg_hi:[0,1]
	v_pk_add_f32 v[140:141], v[134:135], v[128:129]
	v_fma_f32 v170, v14, v166, -v168
	v_fma_f32 v171, v15, v167, v169
	v_pk_add_f32 v[126:127], v[142:143], v[126:127] neg_lo:[0,1] neg_hi:[0,1]
	v_pk_mul_f32 v[166:167], v[26:27], v[140:141] op_sel:[0,1] op_sel_hi:[1,0]
	v_pk_add_f32 v[4:5], v[4:5], v[176:177] neg_lo:[0,1] neg_hi:[0,1]
	v_fma_f32 v168, v24, v140, -v166
	v_fma_f32 v141, v25, v141, v167
	v_pk_mul_f32 v[166:167], v[42:43], v[130:131] op_sel:[0,1] op_sel_hi:[1,0]
	v_pk_add_f32 v[128:129], v[128:129], v[134:135] neg_lo:[0,1] neg_hi:[0,1]
	v_pk_add_f32 v[134:135], v[4:5], v[124:125]
	v_sub_f32_e32 v143, v5, v125
	v_fma_f32 v172, v40, v130, -v166
	v_fma_f32 v131, v41, v131, v167
	v_pk_mul_f32 v[166:167], v[58:59], v[132:133] op_sel:[0,1] op_sel_hi:[1,0]
	v_pk_add_f32 v[176:177], v[126:127], v[126:127] op_sel:[0,1] op_sel_hi:[0,1] neg_lo:[0,1] neg_hi:[0,1]
	v_mov_b32_e32 v145, v143
	v_sub_f32_e32 v114, v115, v157
	v_sub_f32_e32 v115, v160, v208
	v_fma_f32 v174, v56, v132, -v166
	v_fma_f32 v133, v57, v133, v167
	v_pk_add_f32 v[166:167], v[118:119], v[118:119] op_sel:[0,1] op_sel_hi:[0,1]
	v_pk_mul_f32 v[176:177], v[72:73], v[176:177]
	v_pk_add_f32 v[156:157], v[146:147], v[114:115]
	v_pk_add_f32 v[114:115], v[146:147], v[114:115] neg_lo:[0,1] neg_hi:[0,1]
	v_fma_f32 v180, v18, v166, -v176
	v_fma_f32 v181, v19, v167, v177
	v_mul_f32_e32 v142, v34, v143
	v_mul_f32_e32 v143, v35, v134
	v_pk_add_f32 v[122:123], v[202:203], v[122:123]
	v_pk_add_f32 v[2:3], v[2:3], v[158:159] neg_lo:[0,1] neg_hi:[0,1]
	v_fma_f32 v166, v32, v134, -v142
	v_fma_f32 v143, v33, v145, v143
	v_pk_add_f32 v[122:123], v[162:163], v[122:123] neg_lo:[0,1] neg_hi:[0,1]
	v_pk_add_f32 v[158:159], v[120:121], v[2:3]
	v_sub_f32_e32 v163, v121, v3
	v_mul_f32_e32 v144, v50, v115
	v_mul_f32_e32 v145, v51, v156
	v_pk_add_f32 v[136:137], v[136:137], v[136:137] op_sel:[0,1] op_sel_hi:[0,1] neg_lo:[0,1] neg_hi:[0,1]
	v_fma_f32 v176, v48, v156, -v144
	v_fma_f32 v145, v49, v115, v145
	v_mul_f32_e32 v146, v66, v163
	v_mul_f32_e32 v147, v67, v158
	v_pk_add_f32 v[138:139], v[138:139], v[138:139] op_sel:[0,1] op_sel_hi:[0,1] neg_lo:[0,1] neg_hi:[0,1]
	v_pk_mul_f32 v[136:137], v[78:79], v[136:137]
	v_fma_f32 v162, v64, v158, -v146
	v_fma_f32 v147, v65, v163, v147
	v_fma_f32 v164, v16, v138, -v136
	v_fma_f32 v165, v17, v139, v137
	v_sub_f32_e32 v4, v124, v4
	v_pk_mul_f32 v[136:137], v[30:31], v[128:129] op_sel:[0,1] op_sel_hi:[1,0]
	v_sub_f32_e32 v2, v2, v120
	v_fma_f32 v138, v28, v128, -v136
	v_fma_f32 v129, v29, v129, v137
	v_pk_mul_f32 v[136:137], v[46:47], v[116:117] op_sel:[0,1] op_sel_hi:[1,0]
	v_pk_add_f32 v[126:127], v[126:127], v[126:127] op_sel:[1,0] op_sel_hi:[1,0]
	v_mov_b32_e32 v124, v4
	v_mov_b32_e32 v160, v114
	v_mov_b32_e32 v120, v2
	v_fma_f32 v182, v44, v116, -v136
	v_fma_f32 v117, v45, v117, v137
	v_pk_mul_f32 v[136:137], v[62:63], v[122:123] op_sel:[0,1] op_sel_hi:[1,0]
	v_pk_add_f32 v[118:119], v[118:119], v[118:119] op_sel:[0,1] op_sel_hi:[0,1] neg_lo:[0,1] neg_hi:[0,1]
	v_pk_mul_f32 v[126:127], v[74:75], v[126:127]
	v_fma_f32 v202, v60, v122, -v136
	v_fma_f32 v123, v61, v123, v137
	v_fma_f32 v136, v20, v118, -v126
	v_fma_f32 v137, v21, v119, v127
	v_mul_f32_e32 v5, v39, v4
	v_mul_f32_e32 v4, v38, v135
	v_mul_f32_e32 v115, v55, v114
	v_mul_f32_e32 v114, v54, v157
	v_mul_f32_e32 v3, v71, v2
	v_mul_f32_e32 v2, v70, v159
	v_fma_f32 v118, v36, v124, -v4
	v_fma_f32 v5, v37, v135, v5
	v_fma_f32 v124, v52, v160, -v114
	v_fma_f32 v126, v68, v120, -v2
	v_fma_f32 v3, v69, v159, v3
	v_fma_f32 v115, v53, v157, v115
	v_add_f32_e32 v206, v172, v182
	v_add_f32_e32 v207, v131, v117
	v_add_f32_e32 v212, v174, v202
	v_add_f32_e32 v213, v133, v123
	v_add_f32_e32 v214, v162, v126
	v_add_f32_e32 v215, v147, v3
	v_mov_b32_e32 v128, v117
	v_sub_f32_e32 v116, v174, v202
	v_sub_f32_e32 v117, v131, v117
	v_sub_f32_e32 v2, v147, v3
	v_sub_f32_e32 v3, v176, v124
	v_mov_b32_e32 v119, v5
	v_add_f32_e32 v158, v168, v138
	v_add_f32_e32 v159, v141, v129
	v_add_f32_e32 v208, v176, v124
	v_add_f32_e32 v209, v145, v115
	v_sub_f32_e32 v4, v145, v115
	v_sub_f32_e32 v5, v143, v5
	v_mov_b32_e32 v142, v124
	v_sub_f32_e32 v122, v133, v123
	v_sub_f32_e32 v123, v172, v182
	v_sub_f32_e32 v114, v162, v126
	v_sub_f32_e32 v115, v145, v115
	v_pk_add_f32 v[124:125], v[116:117], v[2:3]
	v_pk_add_f32 v[2:3], v[116:117], v[2:3] neg_lo:[0,1] neg_hi:[0,1]
	v_sub_f32_e32 v139, v168, v138
	v_sub_f32_e32 v138, v172, v182
	v_sub_f32_e32 v128, v131, v128
	v_sub_f32_e32 v129, v141, v129
	v_pk_add_f32 v[126:127], v[122:123], v[114:115] neg_lo:[0,1] neg_hi:[0,1]
	v_pk_add_f32 v[114:115], v[122:123], v[114:115]
	v_pk_add_f32 v[120:121], v[170:171], v[164:165]
	v_pk_add_f32 v[134:135], v[180:181], v[136:137]
	v_add_f32_e32 v160, v166, v118
	v_add_f32_e32 v161, v143, v119
	v_sub_f32_e32 v119, v166, v118
	v_sub_f32_e32 v118, v176, v142
	v_pk_add_f32 v[130:131], v[138:139], v[4:5]
	v_mul_f32_e32 v141, 0x3f3504f3, v125
	v_mul_f32_e32 v116, s74, v124
	v_mul_f32_e32 v117, s75, v3
	v_mul_f32_e32 v4, 0x3f6c835e, v126
	v_pk_add_f32 v[156:157], v[120:121], v[134:135]
	v_pk_add_f32 v[210:211], v[206:207], v[208:209]
	v_pk_add_f32 v[216:217], v[212:213], v[214:215]
	v_pk_add_f32 v[120:121], v[120:121], v[134:135] neg_lo:[0,1] neg_hi:[0,1]
	v_pk_add_f32 v[134:135], v[206:207], v[208:209] neg_lo:[0,1] neg_hi:[0,1]
	v_fma_f32 v116, v126, s72, -v116
	v_fma_f32 v117, v115, s73, -v117
	v_fma_f32 v122, v124, s80, -v4
	v_add_f32_e32 v4, v129, v119
	v_pk_add_f32 v[204:205], v[158:159], v[160:161]
	v_pk_add_f32 v[136:137], v[180:181], v[136:137] neg_lo:[0,1] neg_hi:[0,1]
	v_mov_b32_e32 v206, v158
	v_sub_f32_e32 v158, v159, v161
	v_sub_f32_e32 v159, v213, v215
	v_pk_add_f32 v[132:133], v[128:129], v[118:119] neg_lo:[0,1] neg_hi:[0,1]
	v_pk_mul_f32 v[118:119], v[4:5], s[88:89] op_sel_hi:[0,1]
	v_sub_f32_e32 v4, v139, v5
	v_pk_add_f32 v[164:165], v[170:171], v[164:165] neg_lo:[0,1] neg_hi:[0,1]
	v_mov_b32_e32 v171, v136
	v_sub_f32_e32 v206, v206, v160
	v_sub_f32_e32 v207, v212, v214
	v_pk_mul_f32 v[158:159], v[158:159], s[20:21] op_sel_hi:[1,0]
	v_fma_f32 v128, v4, s70, -v118
	v_fma_f32 v129, v4, s71, v119
	v_fma_f32 v161, v207, s3, -v159
	v_fma_f32 v208, v206, s2, v158
	v_pk_fma_f32 v[158:159], v[206:207], s[20:21], v[158:159] op_sel_hi:[1,0,1] neg_lo:[0,0,1] neg_hi:[0,0,1]
	v_pk_add_f32 v[206:207], v[120:121], v[134:135] op_sel:[0,1] op_sel_hi:[1,0] neg_lo:[0,1] neg_hi:[0,1]
	v_pk_add_f32 v[120:121], v[120:121], v[134:135] op_sel:[0,1] op_sel_hi:[1,0]
	v_mul_f32_e32 v170, 0x3f6c835e, v133
	s_mov_b32 s92, s3
	s_mov_b32 s93, s21
	v_pk_mul_f32 v[132:133], v[132:133], s[90:91]
	v_pk_mul_f32 v[4:5], v[114:115], s[70:71] op_sel_hi:[0,1]
	v_sub_f32_e32 v180, v164, v137
	v_pk_add_f32 v[136:137], v[164:165], v[136:137] op_sel:[0,1] op_sel_hi:[1,0]
	v_mov_b32_e32 v135, v121
	v_mul_f32_e32 v164, 0x3ec3ef15, v131
	v_mul_f32_e32 v121, 0x3f3504f3, v127
	v_fma_f32 v142, v130, s92, -v132
	v_fma_f32 v131, v131, s93, v133
	v_fma_f32 v114, v2, s88, -v4
	v_fma_f32 v115, v2, s89, v5
	v_mov_b32_e32 v1, v6
	v_mov_b32_e32 v181, v137
	v_pk_add_f32 v[124:125], v[164:165], v[170:171] neg_lo:[0,1] neg_hi:[0,1]
	v_sub_f32_e32 v140, v121, v141
	v_fmac_f32_e32 v141, 0x3f3504f3, v127
	s_barrier
	v_pk_add_f32 v[218:219], v[156:157], v[210:211]
	v_pk_add_f32 v[220:221], v[204:205], v[216:217]
	v_pk_add_f32 v[2:3], v[180:181], v[140:141]
	v_pk_add_f32 v[4:5], v[128:129], v[114:115]
	v_add_f32_e32 v126, v142, v136
	v_add_f32_e32 v127, v131, v122
	v_pk_add_f32 v[132:133], v[124:125], v[116:117]
	v_mul_lo_u32 v1, v1, s33
	v_pk_add_f32 v[222:223], v[218:219], v[220:221]
	v_mov_b32_e32 v134, v206
	v_add_f32_e32 v212, v158, v161
	v_add_f32_e32 v213, v159, v208
	v_pk_add_f32 v[118:119], v[2:3], v[4:5]
	v_pk_add_f32 v[138:139], v[132:133], v[126:127]
	v_pk_add_f32 v[214:215], v[134:135], v[212:213]
	ds_write2_b64 v1, v[222:223], v[118:119] offset1:1
	ds_write2_b64 v1, v[214:215], v[138:139] offset0:2 offset1:3
	v_pk_add_f32 v[118:119], v[156:157], v[210:211] neg_lo:[0,1] neg_hi:[0,1]
	v_pk_add_f32 v[138:139], v[204:205], v[216:217] neg_lo:[0,1] neg_hi:[0,1]
	v_pk_add_f32 v[114:115], v[128:129], v[114:115] neg_lo:[0,1] neg_hi:[0,1]
	v_pk_add_f32 v[144:145], v[118:119], v[138:139] op_sel:[0,1] op_sel_hi:[1,0] neg_lo:[0,1] neg_hi:[0,1]
	v_pk_add_f32 v[118:119], v[118:119], v[138:139] op_sel:[0,1] op_sel_hi:[1,0]
	v_pk_add_f32 v[138:139], v[180:181], v[140:141] neg_lo:[0,1] neg_hi:[0,1]
	v_pk_add_f32 v[128:129], v[138:139], v[114:115] op_sel:[0,1] op_sel_hi:[1,0] neg_lo:[0,1] neg_hi:[0,1]
	v_pk_add_f32 v[114:115], v[138:139], v[114:115] op_sel:[0,1] op_sel_hi:[1,0]
	v_mov_b32_e32 v138, v144
	v_mov_b32_e32 v139, v119
	v_mov_b32_e32 v140, v128
	v_mov_b32_e32 v141, v115
	ds_write2_b64 v1, v[138:139], v[140:141] offset0:4 offset1:5
	v_mov_b32_e32 v121, v207
	v_sub_f32_e32 v138, v208, v159
	v_sub_f32_e32 v139, v158, v161
	v_sub_f32_e32 v122, v131, v122
	v_sub_f32_e32 v123, v124, v116
	v_sub_f32_e32 v116, v136, v142
	v_sub_f32_e32 v117, v125, v117
	v_pk_add_f32 v[140:141], v[120:121], v[138:139] neg_lo:[0,1] neg_hi:[0,1]
	v_pk_add_f32 v[120:121], v[120:121], v[138:139]
	v_pk_add_f32 v[124:125], v[116:117], v[122:123] neg_lo:[0,1] neg_hi:[0,1]
	v_pk_add_f32 v[116:117], v[116:117], v[122:123]
	v_mov_b32_e32 v122, v140
	v_mov_b32_e32 v123, v121
	v_mov_b32_e32 v130, v124
	v_mov_b32_e32 v131, v117
	ds_write2_b64 v1, v[122:123], v[130:131] offset0:6 offset1:7
	v_pk_add_f32 v[122:123], v[218:219], v[220:221] neg_lo:[0,1] neg_hi:[0,1]
	v_pk_add_f32 v[2:3], v[2:3], v[4:5] neg_lo:[0,1] neg_hi:[0,1]
	ds_write2_b64 v1, v[122:123], v[2:3] offset0:8 offset1:9
	v_pk_add_f32 v[2:3], v[134:135], v[212:213] neg_lo:[0,1] neg_hi:[0,1]
	v_sub_f32_e32 v4, v126, v132
	v_sub_f32_e32 v5, v133, v127
	v_mov_b32_e32 v119, v145
	v_mov_b32_e32 v115, v129
	v_mov_b32_e32 v121, v141
	v_mov_b32_e32 v117, v125
	ds_write2_b64 v1, v[2:3], v[4:5] offset0:10 offset1:11
	ds_write2_b64 v1, v[118:119], v[114:115] offset0:12 offset1:13
	ds_write2_b64 v1, v[120:121], v[116:117] offset0:14 offset1:15
	v_mov_b32_e32 v1, v12
	s_waitcnt lgkmcnt(0)
	s_barrier
	v_mov_b32_e32 v155, 0
	v_ashrrev_i32_e32 v2, 31, v1
	v_lshrrev_b32_e32 v2, 28, v2
	v_and_b32_e32 v142, 15, v1
	v_add_u32_e32 v1, v1, v2
	v_ashrrev_i32_e32 v1, 4, v1
	v_lshlrev_b32_e32 v2, 11, v1
	v_lshl_add_u32 v1, v1, 7, v2
	v_lshl_or_b32 v1, v142, 3, v1
	ds_read2_b64 v[2:5], v1 offset1:17
	ds_read2_b64 v[114:117], v1 offset0:34 offset1:51
	ds_read2_b64 v[118:121], v1 offset0:68 offset1:85
	ds_read2_b64 v[122:125], v1 offset0:102 offset1:119
	ds_read2_b64 v[126:129], v1 offset0:136 offset1:153
	ds_read2_b64 v[130:133], v1 offset0:170 offset1:187
	ds_read2_b64 v[134:137], v1 offset0:204 offset1:221
	ds_read2_b64 v[138:141], v1 offset0:238 offset1:255
	s_waitcnt lgkmcnt(4)
	v_mov_b32_e32 v214, v122
	v_cvt_f32_i32_e32 v142, v142
	v_mov_b32_e32 v215, v121
	v_pk_mov_b32 v[120:121], v[122:123], v[120:121] op_sel:[1,0]
	v_add_f32_e32 v142, v142, v142
	v_mul_f32_e32 v142, 0x3b800000, v142
	v_mul_f32_e32 v142, 0.5, v142
	v_sin_f32_e32 v143, v142
	v_cos_f32_e32 v142, v142
	v_mul_f32_e32 v146, v143, v143
	v_mul_f32_e32 v144, v142, v143
	v_pk_fma_f32 v[146:147], v[142:143], v[142:143], v[146:147] op_sel_hi:[1,1,0] neg_lo:[0,0,1] neg_hi:[0,0,1]
	v_add_f32_e32 v144, v144, v144
	v_mov_b32_e32 v156, v146
	v_mov_b32_e32 v157, v142
	v_mov_b32_e32 v145, v143
	v_pk_mul_f32 v[158:159], v[156:157], v[146:147] op_sel_hi:[1,0]
	v_pk_mul_f32 v[162:163], v[144:145], v[146:147] op_sel_hi:[1,0]
	v_pk_fma_f32 v[170:171], v[144:145], v[144:145], v[158:159] op_sel_hi:[1,0,1] neg_lo:[1,0,0] neg_hi:[1,0,0]
	v_pk_fma_f32 v[164:165], v[156:157], v[144:145], v[162:163] op_sel_hi:[1,0,1]
	v_mov_b32_e32 v172, v170
	v_mov_b32_e32 v173, v142
	v_mov_b32_e32 v180, v144
	v_mov_b32_e32 v181, v164
	v_mul_f32_e32 v161, v157, v144
	v_mov_b32_e32 v166, v164
	v_mov_b32_e32 v167, v143
	v_pk_mul_f32 v[174:175], v[172:173], v[170:171] op_sel_hi:[1,0]
	v_mov_b32_e32 v147, v170
	v_pk_mul_f32 v[202:203], v[180:181], v[170:171] op_sel_hi:[1,0]
	v_pk_mul_f32 v[204:205], v[166:167], v[146:147]
	v_pk_mul_f32 v[182:183], v[164:165], v[180:181] op_sel_hi:[0,1]
	v_add_f32_e32 v160, v203, v203
	v_add_f32_e32 v161, v161, v163
	v_pk_fma_f32 v[162:163], v[172:173], v[180:181], v[204:205]
	v_fma_f32 v158, -v166, v164, v174
	v_fma_f32 v159, -v167, v144, v159
	v_mul_f32_e32 v168, v170, v165
	v_mul_f32_e32 v204, v164, v171
	v_pk_mul_f32 v[206:207], v[166:167], v[170:171] op_sel_hi:[1,0]
	v_pk_fma_f32 v[166:167], v[166:167], v[164:165], v[174:175] op_sel_hi:[1,0,1] neg_lo:[1,0,0] neg_hi:[1,0,0]
	v_pk_fma_f32 v[174:175], v[170:171], v[146:147], v[182:183] op_sel_hi:[0,1,1] neg_lo:[0,0,1] neg_hi:[0,0,1]
	v_pk_fma_f32 v[182:183], v[146:147], v[164:165], v[202:203] op_sel_hi:[1,0,1]
	v_add_f32_e32 v168, v168, v204
	v_add_f32_e32 v169, v203, v203
	v_mov_b32_e32 v205, v142
	v_pk_mul_f32 v[180:181], v[164:165], v[164:165] op_sel_hi:[0,1]
	v_pk_fma_f32 v[172:173], v[172:173], v[164:165], v[206:207] op_sel_hi:[1,0,1]
	v_mov_b32_e32 v204, v166
	v_mul_f32_e32 v142, v183, v146
	v_mul_f32_e32 v143, v143, v166
	v_pk_fma_f32 v[180:181], v[170:171], v[170:171], v[180:181] op_sel_hi:[0,1,1] neg_lo:[0,0,1] neg_hi:[0,0,1]
	v_fma_f32 v142, v204, v144, v142
	v_fma_f32 v143, v205, v183, v143
	v_pk_mov_b32 v[206:207], v[182:183], v[164:165] op_sel:[1,0]
	v_mov_b32_e32 v205, v170
	v_pk_mul_f32 v[208:209], v[206:207], v[168:169]
	v_pk_mul_f32 v[206:207], v[206:207], v[180:181] op_sel:[0,1] op_sel_hi:[1,0]
	v_pk_mul_f32 v[172:173], v[172:173], v[174:175]
	v_pk_fma_f32 v[174:175], v[204:205], v[180:181], v[208:209] op_sel:[0,1,0] op_sel_hi:[1,0,1] neg_lo:[0,0,1] neg_hi:[0,0,1]
	v_pk_fma_f32 v[204:205], v[204:205], v[168:169], v[206:207]
	v_mov_b32_e32 v206, v114
	v_mov_b32_e32 v207, v5
	v_pk_mov_b32 v[4:5], v[114:115], v[4:5] op_sel:[1,0]
	v_pk_mul_f32 v[176:177], v[144:145], v[164:165] op_sel_hi:[1,0]
	v_pk_mul_f32 v[202:203], v[144:145], v[182:183] op_sel:[0,1]
	v_pk_mul_f32 v[114:115], v[4:5], v[144:145]
	v_pk_mul_f32 v[144:145], v[206:207], v[144:145]
	v_mul_f32_e32 v160, v170, v160
	v_mul_f32_e32 v161, v166, v161
	v_pk_fma_f32 v[208:209], v[206:207], v[156:157], v[114:115] neg_lo:[0,0,1] neg_hi:[0,0,1]
	v_fma_f32 v115, v207, v157, v115
	v_fma_f32 v207, v5, v157, -v145
	v_fma_f32 v4, v4, v156, v144
	v_pk_fma_f32 v[176:177], v[156:157], v[170:171], v[176:177] op_sel_hi:[1,0,1] neg_lo:[0,0,1] neg_hi:[0,0,1]
	v_pk_fma_f32 v[202:203], v[156:157], v[166:167], v[202:203] op_sel_hi:[1,0,1] neg_lo:[0,0,1] neg_hi:[0,0,1]
	v_fma_f32 v158, v164, v158, v160
	v_fma_f32 v159, v183, v159, v161
	v_pk_mul_f32 v[160:161], v[182:183], v[162:163] op_sel:[1,0]
	v_mul_f32_e32 v206, v117, v165
	v_pk_mul_f32 v[122:123], v[120:121], v[162:163]
	v_pk_mul_f32 v[162:163], v[214:215], v[162:163]
	v_pk_fma_f32 v[160:161], v[166:167], v[176:177], v[160:161] op_sel_hi:[0,1,1] neg_lo:[0,0,1] neg_hi:[0,0,1]
	v_fma_f32 v156, v116, v171, -v206
	v_mov_b32_e32 v210, v118
	v_mov_b32_e32 v211, v117
	v_pk_mov_b32 v[116:117], v[118:119], v[116:117] op_sel:[1,0]
	v_fma_f32 v216, v214, v176, -v122
	v_fma_f32 v123, v215, v177, v123
	v_pk_fma_f32 v[214:215], v[120:121], v[176:177], v[162:163] neg_lo:[0,0,1] neg_hi:[0,0,1]
	v_fma_f32 v120, v120, v176, v162
	v_mov_b32_e32 v177, v119
	v_mul_f32_e32 v119, v118, v164
	v_mul_f32_e32 v118, v125, v168
	v_mul_f32_e32 v122, v125, v181
	v_pk_mul_f32 v[146:147], v[164:165], v[182:183] op_sel:[0,1]
	v_pk_mul_f32 v[116:117], v[116:117], v[164:165]
	v_mov_b32_e32 v176, v124
	v_fma_f32 v124, v124, v168, v122
	s_waitcnt lgkmcnt(2)
	v_mov_b32_e32 v168, v130
	v_mov_b32_e32 v169, v129
	v_pk_mov_b32 v[128:129], v[130:131], v[128:129] op_sel:[1,0]
	v_pk_fma_f32 v[146:147], v[170:171], v[166:167], v[146:147] op_sel_hi:[1,0,1] neg_lo:[0,0,1] neg_hi:[0,0,1]
	v_fma_f32 v212, v210, v170, -v116
	v_fma_f32 v117, v211, v171, v117
	v_pk_mov_b32 v[170:171], v[180:181], v[170:171] op_sel:[1,0]
	v_pk_mul_f32 v[130:131], v[128:129], v[142:143]
	v_pk_mul_f32 v[142:143], v[168:169], v[142:143]
	v_fma_f32 v164, v176, v170, -v118
	v_fma_f32 v119, v177, v171, v119
	v_pk_fma_f32 v[170:171], v[168:169], v[202:203], v[130:131] neg_lo:[0,0,1] neg_hi:[0,0,1]
	v_fma_f32 v131, v169, v203, v131
	v_fma_f32 v169, v129, v203, -v143
	v_fma_f32 v128, v128, v202, v142
	v_pk_mov_b32 v[180:181], v[146:147], v[166:167] op_sel:[1,0]
	v_mul_f32_e32 v202, v133, v159
	v_mul_f32_e32 v203, v126, v183
	v_pk_fma_f32 v[172:173], v[166:167], v[182:183], v[172:173]
	v_fma_f32 v218, v132, v180, -v202
	v_fma_f32 v177, v127, v181, v203
	v_mov_b32_e32 v181, v133
	s_waitcnt lgkmcnt(1)
	v_mul_f32_e32 v133, v132, v159
	v_mul_f32_e32 v132, v135, v158
	v_fma_f32 v158, v134, v146, -v132
	v_fma_f32 v133, v181, v147, v133
	s_waitcnt lgkmcnt(0)
	v_mov_b32_e32 v180, v138
	v_mov_b32_e32 v181, v137
	v_pk_mov_b32 v[136:137], v[138:139], v[136:137] op_sel:[1,0]
	v_pk_mul_f32 v[138:139], v[136:137], v[172:173]
	v_pk_mul_f32 v[172:173], v[180:181], v[172:173]
	v_pk_fma_f32 v[202:203], v[180:181], v[160:161], v[138:139] neg_lo:[0,0,1] neg_hi:[0,0,1]
	v_fma_f32 v139, v181, v161, v139
	v_fma_f32 v181, v137, v161, -v173
	v_fma_f32 v136, v136, v160, v172
	v_mov_b32_e32 v173, v135
	v_mul_f32_e32 v135, v134, v205
	v_mul_f32_e32 v134, v141, v204
	v_fma_f32 v220, v140, v174, -v134
	v_fma_f32 v135, v173, v175, v135
	v_pk_mov_b32 v[172:173], v[126:127], v[140:141] op_sel:[1,0]
	v_mul_f32_e32 v172, v172, v183
	v_mul_f32_e32 v173, v173, v204
	v_fma_f32 v140, v126, v166, -v172
	v_fma_f32 v127, v141, v174, v173
	v_mov_b32_e32 v141, v127
	v_add_f32_e32 v172, v156, v218
	v_add_f32_e32 v173, v3, v177
	v_mov_b32_e32 v219, v128
	v_mov_b32_e32 v211, v117
	v_mov_b32_e32 v147, v133
	v_mov_b32_e32 v167, v124
	v_add_f32_e32 v174, v164, v220
	v_add_f32_e32 v175, v119, v135
	v_add_f32_e32 v142, v207, v169
	v_add_f32_e32 v143, v4, v128
	v_add_f32_e32 v144, v215, v181
	v_add_f32_e32 v145, v120, v136
	v_add_f32_e32 v160, v208, v170
	v_add_f32_e32 v161, v115, v131
	v_sub_f32_e32 v114, v4, v128
	v_sub_f32_e32 v115, v115, v131
	v_mov_b32_e32 v221, v136
	v_sub_f32_e32 v5, v4, v219
	v_sub_f32_e32 v4, v156, v218
	v_sub_f32_e32 v124, v124, v127
	v_sub_f32_e32 v125, v216, v202
	v_add_f32_e32 v162, v216, v202
	v_add_f32_e32 v163, v123, v139
	v_mov_b32_e32 v206, v208
	v_sub_f32_e32 v122, v120, v136
	v_sub_f32_e32 v123, v123, v139
	v_mov_b32_e32 v217, v215
	v_mov_b32_e32 v180, v202
	v_sub_f32_e32 v116, v117, v133
	v_sub_f32_e32 v117, v208, v170
	v_sub_f32_e32 v121, v120, v221
	v_sub_f32_e32 v120, v164, v220
	v_pk_add_f32 v[126:127], v[4:5], v[124:125]
	v_pk_add_f32 v[4:5], v[4:5], v[124:125] neg_lo:[0,1] neg_hi:[0,1]
	v_add_f32_e32 v166, v2, v140
	v_add_f32_e32 v167, v167, v141
	v_sub_f32_e32 v168, v206, v170
	v_sub_f32_e32 v169, v207, v169
	v_pk_add_f32 v[130:131], v[216:217], v[180:181] neg_lo:[0,1] neg_hi:[0,1]
	v_pk_add_f32 v[132:133], v[116:117], v[120:121] neg_lo:[0,1] neg_hi:[0,1]
	v_pk_add_f32 v[116:117], v[116:117], v[120:121]
	v_sub_f32_e32 v2, v2, v140
	v_sub_f32_e32 v3, v3, v177
	v_sub_f32_e32 v118, v119, v135
	v_sub_f32_e32 v119, v212, v158
	v_pk_add_f32 v[128:129], v[168:169], v[122:123]
	v_pk_add_f32 v[136:137], v[114:115], v[130:131] neg_lo:[0,1] neg_hi:[0,1]
	v_mul_f32_e32 v139, 0x3f3504f3, v127
	v_mul_f32_e32 v120, s74, v126
	v_mul_f32_e32 v121, s75, v5
	v_mul_f32_e32 v114, 0x3f6c835e, v132
	v_add_f32_e32 v146, v212, v158
	v_add_f32_e32 v147, v211, v147
	v_sub_f32_e32 v134, v2, v118
	v_pk_add_f32 v[140:141], v[2:3], v[118:119]
	v_mul_f32_e32 v2, 0x3ec3ef15, v129
	v_mul_f32_e32 v118, 0x3f6c835e, v137
	v_fma_f32 v120, v132, s72, -v120
	v_fma_f32 v121, v117, s73, -v121
	v_fma_f32 v124, v126, s80, -v114
	v_add_f32_e32 v114, v115, v131
	v_pk_add_f32 v[2:3], v[2:3], v[118:119] neg_lo:[0,1] neg_hi:[0,1]
	v_pk_mul_f32 v[114:115], v[114:115], s[88:89] op_sel_hi:[0,1]
	v_sub_f32_e32 v118, v169, v123
	v_pk_add_f32 v[204:205], v[142:143], v[144:145]
	v_pk_add_f32 v[222:223], v[146:147], v[166:167]
	v_sub_f32_e32 v158, v166, v146
	v_sub_f32_e32 v159, v160, v162
	v_mov_b32_e32 v176, v143
	v_mov_b32_e32 v212, v145
	v_fma_f32 v122, v118, s70, -v114
	v_fma_f32 v123, v118, s71, v115
	v_sub_f32_e32 v142, v142, v144
	v_sub_f32_e32 v143, v172, v174
	v_sub_f32_e32 v144, v161, v163
	v_sub_f32_e32 v145, v147, v167
	v_pk_mul_f32 v[136:137], v[136:137], s[90:91]
	v_pk_mul_f32 v[114:115], v[116:117], s[70:71] op_sel_hi:[0,1]
	v_mov_b32_e32 v213, v175
	v_pk_mul_f32 v[144:145], v[144:145], s[20:21] op_sel_hi:[1,0]
	v_mul_f32_e32 v130, 0x3f3504f3, v133
	v_fma_f32 v156, v128, s92, -v136
	v_fma_f32 v129, v129, s93, v137
	v_fma_f32 v116, v4, s88, -v114
	v_fma_f32 v117, v4, s89, v115
	v_pk_add_f32 v[182:183], v[160:161], v[162:163]
	v_pk_add_f32 v[210:211], v[172:173], v[174:175]
	v_mov_b32_e32 v135, v141
	v_sub_f32_e32 v176, v176, v212
	v_sub_f32_e32 v177, v173, v213
	v_fma_f32 v147, v143, s3, -v145
	v_fma_f32 v160, v142, s2, v144
	v_sub_f32_e32 v138, v130, v139
	v_fmac_f32_e32 v139, 0x3f3504f3, v133
	v_pk_add_f32 v[224:225], v[204:205], v[210:211]
	v_pk_add_f32 v[226:227], v[182:183], v[222:223]
	v_pk_fma_f32 v[142:143], v[142:143], s[20:21], v[144:145] op_sel_hi:[1,0,1] neg_lo:[0,0,1] neg_hi:[0,0,1]
	v_sub_f32_e32 v144, v158, v176
	v_pk_add_f32 v[166:167], v[158:159], v[176:177]
	v_pk_add_f32 v[4:5], v[134:135], v[138:139]
	v_pk_add_f32 v[114:115], v[122:123], v[116:117]
	v_add_f32_e32 v126, v156, v140
	v_add_f32_e32 v127, v129, v124
	v_pk_add_f32 v[130:131], v[2:3], v[120:121]
	v_pk_add_f32 v[228:229], v[226:227], v[224:225]
	v_mov_b32_e32 v145, v167
	v_add_f32_e32 v162, v142, v147
	v_add_f32_e32 v163, v143, v160
	v_pk_add_f32 v[118:119], v[4:5], v[114:115]
	v_pk_add_f32 v[132:133], v[130:131], v[126:127]
	v_pk_add_f32 v[172:173], v[144:145], v[162:163]
	ds_write2_b64 v1, v[228:229], v[118:119] offset1:17
	ds_write2_b64 v1, v[172:173], v[132:133] offset0:34 offset1:51
	v_mov_b32_e32 v119, v204
	v_mov_b32_e32 v133, v210
	v_mov_b32_e32 v210, v183
	v_mov_b32_e32 v204, v223
	v_sub_f32_e32 v118, v222, v182
	v_sub_f32_e32 v119, v119, v133
	v_pk_add_f32 v[132:133], v[210:211], v[204:205] neg_lo:[0,1] neg_hi:[0,1]
	v_pk_add_f32 v[134:135], v[134:135], v[138:139] neg_lo:[0,1] neg_hi:[0,1]
	v_pk_add_f32 v[116:117], v[122:123], v[116:117] neg_lo:[0,1] neg_hi:[0,1]
	v_sub_f32_e32 v136, v118, v132
	v_pk_add_f32 v[164:165], v[118:119], v[132:133]
	v_pk_add_f32 v[122:123], v[134:135], v[116:117] op_sel:[0,1] op_sel_hi:[1,0] neg_lo:[0,1] neg_hi:[0,1]
	v_pk_add_f32 v[116:117], v[134:135], v[116:117] op_sel:[0,1] op_sel_hi:[1,0]
	v_mov_b32_e32 v137, v165
	v_mov_b32_e32 v134, v122
	v_mov_b32_e32 v135, v117
	ds_write2_b64 v1, v[136:137], v[134:135] offset0:68 offset1:85
	v_sub_f32_e32 v167, v177, v159
	v_mov_b32_e32 v161, v142
	v_mov_b32_e32 v146, v143
	v_mov_b32_e32 v157, v121
	v_pk_add_f32 v[134:135], v[160:161], v[146:147] neg_lo:[0,1] neg_hi:[0,1]
	v_sub_f32_e32 v124, v129, v124
	v_sub_f32_e32 v125, v2, v120
	v_sub_f32_e32 v2, v140, v156
	v_sub_f32_e32 v3, v3, v157
	v_pk_add_f32 v[136:137], v[166:167], v[134:135] neg_lo:[0,1] neg_hi:[0,1]
	v_pk_add_f32 v[134:135], v[166:167], v[134:135]
	v_pk_add_f32 v[120:121], v[2:3], v[124:125] neg_lo:[0,1] neg_hi:[0,1]
	v_pk_add_f32 v[2:3], v[2:3], v[124:125]
	v_mov_b32_e32 v138, v136
	v_mov_b32_e32 v139, v135
	v_mov_b32_e32 v124, v120
	v_mov_b32_e32 v125, v3
	ds_write2_b64 v1, v[138:139], v[124:125] offset0:102 offset1:119
	v_mov_b32_e32 v125, v225
	v_mov_b32_e32 v225, v227
	v_sub_f32_e32 v124, v226, v224
	v_sub_f32_e32 v125, v125, v225
	v_pk_add_f32 v[4:5], v[4:5], v[114:115] neg_lo:[0,1] neg_hi:[0,1]
	ds_write2_b64 v1, v[124:125], v[4:5] offset0:136 offset1:153
	v_pk_add_f32 v[4:5], v[144:145], v[162:163] neg_lo:[0,1] neg_hi:[0,1]
	v_sub_f32_e32 v114, v126, v130
	v_sub_f32_e32 v115, v131, v127
	ds_write2_b64 v1, v[4:5], v[114:115] offset0:170 offset1:187
	v_sub_f32_e32 v165, v133, v119
	v_mov_b32_e32 v135, v137
	v_mov_b32_e32 v3, v121
	v_mov_b32_e32 v117, v123
	ds_write2_b64 v1, v[134:135], v[2:3] offset0:238 offset1:255
	v_mov_b32_e32 v2, v6
	ds_write2_b64 v1, v[164:165], v[116:117] offset0:204 offset1:221
	s_waitcnt lgkmcnt(0)
	s_barrier
	s_lshl_b64 s[88:89], s[24:25], 1
	v_ashrrev_i32_e32 v3, 31, v2
	v_lshrrev_b32_e32 v3, 24, v3
	v_and_b32_e32 v1, 0xff, v2
	v_add_lshl_u32 v2, v2, v3, 4
	v_and_or_b32 v2, v2, s87, v1
	v_ashrrev_i32_e32 v3, 4, v2
	v_lshlrev_b32_e32 v2, 3, v2
	v_lshl_add_u32 v2, v3, 3, v2
	ds_read_b64 v[114:115], v2
	ds_read_b64 v[144:145], v2 offset:2176
	ds_read_b64 v[142:143], v2 offset:4352
	ds_read_b64 v[140:141], v2 offset:6528
	ds_read_b64 v[138:139], v2 offset:8704
	ds_read_b64 v[136:137], v2 offset:10880
	ds_read_b64 v[134:135], v2 offset:13056
	ds_read_b64 v[132:133], v2 offset:15232
	ds_read_b64 v[130:131], v2 offset:17408
	ds_read_b64 v[128:129], v2 offset:19584
	ds_read_b64 v[126:127], v2 offset:21760
	ds_read_b64 v[124:125], v2 offset:23936
	ds_read_b64 v[122:123], v2 offset:26112
	ds_read_b64 v[120:121], v2 offset:28288
	ds_read_b64 v[118:119], v2 offset:30464
	ds_read_b64 v[116:117], v2 offset:32640
	s_add_u32 s88, s1, s88
	s_addc_u32 s89, s94, s89
	v_lshl_add_u64 v[4:5], v[12:13], 1, s[88:89]
	v_mov_b32_e32 v158, 0
	s_and_saveexec_b64 s[90:91], s[36:37]
	s_cbranch_execz .LBB0_216
	global_load_ushort v2, v[4:5], off offset:-2
	s_waitcnt vmcnt(0)
	v_lshlrev_b32_e32 v158, 16, v2

.LBB0_346:
	s_or_b64 exec, exec, s[92:93]
	v_cndmask_b32_e64 v2, 0, v114, s[60:61]
	s_waitcnt vmcnt(1)
	v_fmac_f32_e32 v2, v1, v36
	v_add_f32_e32 v36, v2, v37
	v_cndmask_b32_e64 v37, 0, v114, s[58:59]
	v_fmac_f32_e32 v37, v1, v35
	v_add_f32_e32 v37, v37, v34
	v_cndmask_b32_e64 v34, 0, v114, s[56:57]
	v_fmac_f32_e32 v34, v1, v31
	v_add_f32_e32 v31, v34, v33
	v_cndmask_b32_e64 v33, 0, v114, s[54:55]
	v_fmac_f32_e32 v33, v1, v30
	v_cndmask_b32_e64 v30, 0, v114, s[52:53]
	v_fmac_f32_e32 v30, v1, v27
	v_cndmask_b32_e64 v27, 0, v114, s[50:51]
	v_fmac_f32_e32 v27, v1, v26
	v_add_f32_e32 v34, v30, v28
	v_add_f32_e32 v28, v27, v25
	v_cndmask_b32_e64 v25, 0, v114, s[0:1]
	v_fmac_f32_e32 v25, v1, v23
	v_cndmask_b32_e64 v23, 0, v114, s[48:49]
	v_fmac_f32_e32 v23, v1, v22
	v_cndmask_b32_e64 v22, 0, v114, s[46:47]
	v_fmac_f32_e32 v22, v1, v19
	v_cndmask_b32_e64 v19, 0, v114, s[44:45]
	v_fmac_f32_e32 v19, v1, v18
	v_add_f32_e32 v21, v23, v21
	v_add_f32_e32 v23, v19, v17
	v_cndmask_b32_e64 v17, 0, v114, s[42:43]
	v_fmac_f32_e32 v17, v1, v15
	v_cndmask_b32_e64 v15, 0, v114, s[40:41]
	v_fmac_f32_e32 v15, v1, v14
	v_add_f32_e32 v15, v15, v13
	v_cndmask_b32_e64 v13, 0, v114, s[38:39]
	v_fmac_f32_e32 v13, v1, v9
	v_cndmask_b32_e64 v9, 0, v114, s[36:37]
	v_fmac_f32_e32 v9, v1, v7
	v_cndmask_b32_e64 v2, 0, v114, s[62:63]
	v_add_f32_e32 v14, v9, v4
	v_cndmask_b32_e32 v4, 0, v114, vcc
	s_waitcnt vmcnt(0)
	v_fmac_f32_e32 v2, v1, v38
	v_fmac_f32_e32 v4, v1, v3
	v_mov_b32_e32 v1, v122
	v_add_f32_e32 v19, v2, v32
	s_barrier
	v_add_f32_e32 v30, v25, v24
	v_ashrrev_i32_e32 v2, 31, v1
	v_lshrrev_b32_e32 v2, 24, v2
	v_and_b32_e32 v7, 0xff, v1
	v_add_lshl_u32 v1, v1, v2, 4
	v_add_f32_e32 v25, v17, v16
	v_add_f32_e32 v16, v13, v11
	v_and_or_b32 v1, v1, s87, v7
	v_ashrrev_i32_e32 v2, 4, v1
	v_lshlrev_b32_e32 v1, 3, v1
	v_sub_f32_e32 v42, v16, v34
	v_sub_f32_e32 v43, v14, v28
	v_lshl_add_u32 v9, v2, 3, v1
	v_add_f32_e32 v1, 0, v42
	v_mul_f32_e32 v11, 0x3f3504f3, v1
	v_add_f32_e32 v22, v22, v20
	v_cvt_f32_i32_e32 v1, v7
	v_add_f32_e32 v24, v4, v5
	v_add_f32_e32 v29, v33, v29
	v_pk_add_f32 v[26:27], v[24:25], v[30:31]
	v_add_f32_e32 v1, v1, v1
	v_add_f32_e32 v2, v26, v27
	v_pk_add_f32 v[40:41], v[14:15], v[28:29]
	v_pk_add_f32 v[44:45], v[22:23], v[36:37] neg_lo:[0,1] neg_hi:[0,1]
	v_add_f32_e32 v34, v16, v34
	v_add_f32_e32 v35, v22, v36
	v_sub_f32_e32 v36, v15, v29
	v_add_f32_e32 v14, v23, v37
	v_add_f32_e32 v15, v21, v19
	v_mul_f32_e32 v1, 0x39800000, v1
	v_add_f32_e32 v4, v34, v35
	v_sub_f32_e32 v3, v21, v19
	v_pk_add_f32 v[18:19], v[40:41], v[14:15] neg_lo:[0,1] neg_hi:[0,1]
	v_pk_add_f32 v[14:15], v[40:41], v[14:15]
	v_mul_f32_e32 v1, 0.5, v1
	s_xor_b64 s[92:93], s[96:97], -1
	v_sub_f32_e32 v20, 0, v3
	v_add_f32_e32 v40, 0, v3
	v_sin_f32_e32 v50, v1
	s_and_b64 s[0:1], s[96:97], exec
	v_sub_f32_e32 v33, v25, v31
	v_add_f32_e32 v28, 0, v43
	v_add_f32_e32 v48, v2, v4
	v_add_f32_e32 v49, v14, v15
	v_cos_f32_e32 v56, v1
	s_mov_b32 s70, s21
	v_sub_f32_e32 v39, 0, v33
	v_sub_f32_e32 v38, 0, v45
	v_add_f32_e32 v52, v48, v49
	v_mov_b32_e32 v53, v0
	s_mov_b32 s0, s71
	s_mov_b32 s1, s21
	v_pk_mul_f32 v[28:29], v[28:29], s[70:71] op_sel_hi:[0,1]
	v_add_f32_e32 v16, 0, v36
	v_mul_f32_e32 v17, 0x3f3504f3, v18
	ds_write_b64 v9, v[52:53]
	v_fma_f32 v52, v38, s0, v28
	v_fma_f32 v53, v38, s1, -v29
	v_xor_b32_e32 v57, 0x80000000, v50
	v_pk_mul_f32 v[28:29], v[16:17], s[0:1] op_sel_hi:[0,1]
	v_fma_f32 v58, v20, s70, v28
	v_fma_f32 v59, v20, s71, -v29
	v_mov_b32_e32 v51, v56
	v_mul_f32_e32 v46, 0x3f3504f3, v19
	v_mul_f32_e32 v68, v50, v50
	v_mul_f32_e32 v69, v51, v57
	v_fma_f32 v22, v18, s20, 0
	v_sub_f32_e32 v16, v26, v27
	v_sub_f32_e32 v17, v0, v17
	v_sub_f32_e32 v20, v0, v46
	v_sub_f32_e32 v21, v34, v35
	v_mov_b32_e32 v1, v46
	v_pk_fma_f32 v[70:71], v[56:57], v[56:57], v[68:69] op_sel_hi:[0,1,1] neg_lo:[0,0,1] neg_hi:[0,0,1]
	v_pk_fma_f32 v[68:69], v[56:57], v[56:57], v[68:69] op_sel_hi:[0,1,1]
	v_add_f32_e32 v26, v22, v20
	v_sub_f32_e32 v34, v22, v20
	v_sub_f32_e32 v35, v0, v21
	v_add_f32_e32 v46, v16, v0
	v_sub_f32_e32 v61, v17, v1
	v_mov_b32_e32 v72, v70
	v_mov_b32_e32 v73, v69
	v_mul_f32_e32 v78, v69, v69
	v_mul_f32_e32 v79, v69, v70
	v_sub_f32_e32 v14, v14, v15
	v_add_f32_e32 v62, v46, v26
	v_add_f32_e32 v63, v61, v35
	v_pk_fma_f32 v[80:81], v[70:71], v[72:73], v[78:79] op_sel_hi:[0,1,1] neg_lo:[0,0,1] neg_hi:[0,0,1]
	v_pk_fma_f32 v[78:79], v[70:71], v[72:73], v[78:79] op_sel_hi:[0,1,1]
	v_mul_f32_e32 v31, 0x3f6c835e, v40
	v_mul_f32_e32 v25, 0x3ec3ef15, v36
	v_sub_f32_e32 v54, 0, v14
	v_pk_mul_f32 v[68:69], v[62:63], v[68:69] op_sel:[1,1] op_sel_hi:[0,1]
	v_mul_f32_e64 v13, -v44, s20
	v_add_f32_e32 v18, 0, v21
	v_sub_f32_e32 v22, v22, v20
	v_pk_add_f32 v[20:21], v[24:25], v[30:31] neg_lo:[0,1] neg_hi:[0,1]
	v_mul_f32_e32 v55, v54, v80
	v_mul_f32_e32 v54, v54, v79
	v_fma_f32 v88, v62, v70, -v68
	v_fma_f32 v89, v63, v70, v69
	v_add_f32_e32 v24, 0, v20
	v_add_f32_e32 v62, v13, v11
	v_fma_f32 v63, -v44, s20, -v11
	v_pk_add_f32 v[28:29], v[52:53], v[58:59]
	v_pk_add_f32 v[30:31], v[44:45], 0 op_sel_hi:[1,0]
	v_pk_add_f32 v[44:45], v[52:53], v[58:59] neg_lo:[0,1] neg_hi:[0,1]
	v_sub_f32_e32 v52, v24, v62
	v_sub_f32_e32 v53, v39, v63
	v_add_f32_e32 v24, v24, v62
	v_add_f32_e32 v25, v63, v39
	v_mov_b32_e32 v57, v50
	v_pk_add_f32 v[38:39], v[24:25], v[28:29]
	v_fmamk_f32 v34, v19, 0x3f3504f3, v17
	v_pk_mul_f32 v[58:59], v[38:39], v[50:51] op_sel_hi:[1,0]
	v_sub_f32_e32 v64, v18, v22
	v_fma_f32 v62, v38, v56, v59
	v_fma_f32 v63, v39, v56, -v58
	v_pk_mul_f32 v[58:59], v[72:73], v[78:79] op_sel:[0,1]
	ds_write_b64 v9, v[62:63] offset:2176
	v_fma_f32 v62, v72, v80, -v59
	v_fma_f32 v59, v73, v80, v58
	v_mov_b32_e32 v82, v80
	v_mov_b32_e32 v83, v79
	v_add_f32_e32 v60, v16, v34
	v_pk_mul_f32 v[84:85], v[56:57], v[82:83]
	v_pk_mul_f32 v[86:87], v[50:51], v[82:83]
	v_mul_f32_e32 v65, v64, v62
	v_mul_f32_e32 v64, v64, v59
	v_pk_add_f32 v[24:25], v[24:25], v[28:29] neg_lo:[0,1] neg_hi:[0,1]
	v_pk_add_f32 v[28:29], v[52:53], v[44:45] op_sel:[0,1] op_sel_hi:[1,0]
	v_pk_add_f32 v[44:45], v[52:53], v[44:45] op_sel:[0,1] op_sel_hi:[1,0] neg_lo:[0,1] neg_hi:[0,1]
	v_fma_f32 v70, v60, v62, -v64
	v_fma_f32 v71, v60, v59, v65
	v_pk_mov_b32 v[102:103], v[86:87], v[84:85] op_sel:[1,0]
	v_mov_b32_e32 v87, v85
	v_pk_mul_f32 v[64:65], v[82:83], v[78:79] op_sel:[0,1]
	v_pk_add_f32 v[84:85], v[102:103], v[86:87]
	v_pk_add_f32 v[86:87], v[102:103], v[86:87] neg_lo:[0,1] neg_hi:[0,1]
	ds_write_b64 v9, v[70:71] offset:13056
	v_pk_fma_f32 v[70:71], v[80:81], v[82:83], v[64:65] op_sel:[0,0,1] op_sel_hi:[0,1,0] neg_lo:[0,0,1] neg_hi:[0,0,1]
	v_pk_fma_f32 v[64:65], v[80:81], v[82:83], v[64:65] op_sel:[0,0,1] op_sel_hi:[0,1,0]
	v_mul_f32_e32 v38, v45, v86
	v_mul_f32_e32 v39, v28, v86
	ds_write_b64 v9, v[88:89] offset:4352
	v_mov_b32_e32 v88, v70
	v_mov_b32_e32 v89, v65
	v_pk_mov_b32 v[90:91], v[64:65], v[70:71] op_sel:[1,0]
	v_mov_b32_e32 v102, v86
	v_pk_mov_b32 v[104:105], v[84:85], v[86:87] op_sel:[1,0]
	v_fma_f32 v86, v28, v85, -v38
	v_fma_f32 v87, v45, v85, v39
	v_mul_f32_e32 v32, 0x3ec3ef15, v43
	v_mul_f32_e32 v66, 0x3f6c835e, v31
	v_pk_mul_f32 v[76:77], v[50:51], v[72:73]
	v_mov_b32_e32 v103, v85
	v_pk_add_f32 v[48:49], v[48:49], v[48:49] op_sel:[0,1] op_sel_hi:[0,1] neg_lo:[0,1] neg_hi:[0,1]
	v_pk_mul_f32 v[84:85], v[90:91], 0 op_sel_hi:[1,0]
	v_pk_mul_f32 v[50:51], v[50:51], v[88:89] op_sel_hi:[0,1]
	v_add_f32_e32 v32, v32, v66
	v_add_f32_e32 v33, v33, v0
	v_pk_mul_f32 v[66:67], v[42:43], s[20:21]
	s_mov_b32 s36, s20
	s_mov_b32 s37, s71
	v_mul_f32_e32 v40, s72, v40
	v_mul_f32_e32 v41, s73, v42
	v_mul_f32_e32 v1, v79, v70
	ds_write_b64 v9, v[86:87] offset:10880
	v_fma_f32 v86, v48, v70, -v84
	v_mul_f32_e32 v23, v70, v59
	v_fma_f32 v70, v56, v88, v51
	v_fma_f32 v51, v56, v89, -v50
	v_pk_fma_f32 v[42:43], v[30:31], s[36:37], v[66:67] neg_lo:[0,0,1] neg_hi:[0,0,1]
	v_fma_f32 v31, v30, s31, -v41
	v_fma_f32 v30, v36, s30, -v40
	v_pk_mul_f32 v[74:75], v[56:57], v[72:73]
	v_mov_b32_e32 v57, v51
	v_pk_add_f32 v[36:37], v[32:33], v[30:31]
	v_pk_add_f32 v[40:41], v[42:43], v[20:21]
	v_mov_b32_e32 v94, v74
	v_pk_mov_b32 v[74:75], v[74:75], v[76:77] op_sel:[1,0]
	v_mul_f32_e32 v50, v25, v51
	v_mul_f32_e32 v51, v25, v70
	v_pk_add_f32 v[66:67], v[36:37], v[40:41]
	v_pk_mul_f32 v[92:93], v[72:73], v[88:89]
	v_pk_mul_f32 v[72:73], v[72:73], v[90:91]
	v_add_f32_e32 v76, v94, v74
	v_sub_f32_e32 v74, v94, v74
	v_sub_f32_e32 v75, v77, v75
	v_fma_f32 v70, v24, v70, -v50
	v_fma_f32 v71, v24, v57, v51
	v_pk_mul_f32 v[96:97], v[66:67], v[74:75] op_sel:[0,1]
	v_sub_f32_e32 v24, v46, v26
	v_sub_f32_e32 v25, v35, v61
	v_pk_add_f32 v[26:27], v[72:73], v[72:73] op_sel:[0,1] op_sel_hi:[0,1]
	v_fma_f32 v98, v66, v76, -v97
	v_fma_f32 v99, v67, v76, v96
	v_pk_mul_f32 v[26:27], v[24:25], v[26:27] op_sel:[1,0] op_sel_hi:[0,1]
	v_pk_add_f32 v[46:47], v[92:93], v[92:93] op_sel:[0,1] op_sel_hi:[0,1] neg_lo:[0,1] neg_hi:[0,1]
	v_fma_f32 v50, v24, v46, -v26
	v_fma_f32 v51, v25, v47, v27
	ds_write_b64 v9, v[98:99] offset:6528
	v_mul_f32_e32 v96, v76, v88
	v_mul_f32_e32 v97, v75, v89
	v_mul_f32_e32 v94, v76, v90
	v_mul_f32_e32 v95, v75, v91
	v_pk_mul_f32 v[98:99], v[82:83], v[88:89]
	v_sub_f32_e32 v24, v40, v36
	v_sub_f32_e32 v25, v37, v41
	v_pk_add_f32 v[26:27], v[94:95], v[94:95] op_sel:[0,1] op_sel_hi:[0,1]
	v_pk_mul_f32 v[26:27], v[24:25], v[26:27] op_sel:[1,0] op_sel_hi:[0,1]
	v_pk_add_f32 v[36:37], v[96:97], v[96:97] op_sel:[0,1] op_sel_hi:[0,1] neg_lo:[0,1] neg_hi:[0,1]
	v_sub_f32_e32 v2, v2, v4
	v_sub_f32_e32 v3, v98, v99
	v_pk_mul_f32 v[100:101], v[80:81], v[64:65] op_sel_hi:[0,1]
	v_fma_f32 v40, v24, v36, -v26
	v_fma_f32 v41, v25, v37, v27
	v_add_f32_e32 v4, 0, v2
	v_fma_f32 v24, v4, v80, -v54
	v_fma_f32 v25, v4, v83, v55
	v_add_f32_e32 v4, v14, v0
	v_add_f32_e32 v5, v101, v1
	ds_write_b64 v9, v[24:25] offset:8704
	v_pk_mul_f32 v[52:53], v[88:89], v[102:103]
	v_mul_f32_e32 v14, v4, v5
	v_mul_f32_e32 v15, v5, v2
	v_pk_mov_b32 v[4:5], v[2:3], v[4:5] op_sel:[1,0]
	v_pk_mul_f32 v[38:39], v[88:89], v[104:105]
	v_fma_f32 v24, v2, v4, -v14
	v_fma_f32 v25, v3, v5, v15
	v_fma_f32 v87, v49, v89, v85
	ds_write_b64 v9, v[24:25] offset:26112
	v_pk_add_f32 v[24:25], v[52:53], v[52:53] op_sel:[1,0] op_sel_hi:[1,0]
	v_mul_f32_e32 v48, v88, v62
	v_mul_f32_e32 v49, v89, v59
	v_mul_f32_e32 v19, v65, v62
	v_pk_add_f32 v[4:5], v[38:39], v[38:39] op_sel:[0,1] op_sel_hi:[0,1] neg_lo:[0,1] neg_hi:[0,1]
	v_mul_f32_e32 v14, v29, v24
	v_mul_f32_e32 v15, v44, v25
	v_fma_f32 v24, v44, v4, -v14
	v_fma_f32 v25, v29, v5, v15
	v_sub_f32_e32 v2, v16, v34
	v_sub_f32_e32 v3, v48, v49
	v_pk_add_f32 v[4:5], v[18:19], v[22:23]
	v_pk_mul_f32 v[66:67], v[82:83], v[74:75] op_sel:[0,1]
	v_fma_f32 v74, v82, v76, -v67
	v_mul_f32_e32 v14, v4, v5
	v_mul_f32_e32 v15, v5, v2
	v_pk_mov_b32 v[4:5], v[2:3], v[4:5] op_sel:[1,0]
	v_fma_f32 v67, v83, v76, v66
	v_fma_f32 v16, v2, v4, -v14
	v_fma_f32 v17, v3, v5, v15
	v_sub_f32_e32 v2, v20, v42
	v_sub_f32_e32 v3, v33, v31
	v_mov_b32_e32 v77, v67
	v_sub_f32_e32 v4, v43, v21
	v_sub_f32_e32 v5, v32, v30
	v_pk_add_f32 v[14:15], v[2:3], v[4:5]
	v_pk_add_f32 v[2:3], v[2:3], v[4:5] neg_lo:[0,1] neg_hi:[0,1]
	v_mov_b32_e32 v76, v74
	ds_write_b64 v9, v[16:17] offset:30464
	v_mul_f32_e32 v16, v3, v67
	v_mul_f32_e32 v17, v3, v74
	v_pk_mul_f32 v[68:69], v[90:91], v[76:77]
	v_fma_f32 v18, v14, v74, -v16
	v_fma_f32 v19, v14, v77, v17
	v_pk_mul_f32 v[64:65], v[88:89], v[76:77]
	v_mov_b32_e32 v5, v15
	v_pk_add_f32 v[16:17], v[68:69], v[68:69] op_sel:[0,1] op_sel_hi:[0,1]
	v_mul_f32_e32 v14, v15, v16
	v_mul_f32_e32 v15, v2, v17
	v_pk_add_f32 v[16:17], v[64:65], v[64:65] op_sel:[0,1] op_sel_hi:[0,1] neg_lo:[0,1] neg_hi:[0,1]
	v_fma_f32 v2, v2, v16, -v14
	v_fma_f32 v3, v5, v17, v15
	v_mov_b32_e32 v1, v122
	ds_write_b64 v9, v[86:87] offset:17408
	ds_write_b64 v9, v[70:71] offset:19584
	ds_write_b64 v9, v[50:51] offset:21760
	ds_write_b64 v9, v[40:41] offset:23936
	ds_write_b64 v9, v[24:25] offset:28288
	ds_write_b64 v9, v[18:19] offset:15232
	ds_write_b64 v9, v[2:3] offset:32640
	s_waitcnt lgkmcnt(0)
	s_barrier
	s_cselect_b32 s95, s28, s88
	v_ashrrev_i32_e32 v2, 31, v1
	v_lshrrev_b32_e32 v2, 28, v2
	v_and_b32_e32 v7, 15, v1
	v_add_u32_e32 v1, v1, v2
	v_ashrrev_i32_e32 v1, 4, v1
	v_lshlrev_b32_e32 v2, 11, v1
	v_lshl_add_u32 v1, v1, 7, v2
	v_lshl_or_b32 v1, v7, 3, v1
	ds_read2_b64 v[20:23], v1 offset1:17
	ds_read2_b64 v[24:27], v1 offset0:68 offset1:85
	ds_read2_b64 v[28:31], v1 offset0:136 offset1:153
	ds_read2_b64 v[32:35], v1 offset0:170 offset1:187
	ds_read2_b64 v[36:39], v1 offset0:204 offset1:221
	ds_read2_b64 v[40:43], v1 offset0:238 offset1:255
	ds_read2_b64 v[44:47], v1 offset0:34 offset1:51
	ds_read2_b64 v[48:51], v1 offset0:102 offset1:119
	s_waitcnt lgkmcnt(5)
	v_pk_add_f32 v[18:19], v[28:29], v[20:21]
	v_pk_add_f32 v[28:29], v[20:21], v[28:29] neg_lo:[0,1] neg_hi:[0,1]
	s_waitcnt lgkmcnt(2)
	v_pk_mov_b32 v[68:69], v[34:35], v[42:43] op_sel:[1,0]
	s_waitcnt lgkmcnt(1)
	v_pk_add_f32 v[64:65], v[46:47], v[34:35]
	s_waitcnt lgkmcnt(0)
	v_sub_f32_e32 v34, v46, v34
	v_sub_f32_e32 v35, v51, v43
	v_pk_add_f32 v[20:21], v[24:25], v[36:37] neg_lo:[0,1] neg_hi:[0,1]
	v_pk_add_f32 v[52:53], v[36:37], v[24:25]
	v_pk_add_f32 v[54:55], v[22:23], v[30:31]
	v_pk_add_f32 v[56:57], v[26:27], v[38:39]
	v_pk_add_f32 v[66:67], v[50:51], v[42:43]
	v_sub_f32_e32 v68, v47, v68
	v_sub_f32_e32 v69, v50, v69
	v_sub_f32_e32 v46, v34, v35
	v_pk_mov_b32 v[24:25], v[20:21], v[20:21] op_sel:[1,0]
	v_add_f32_e32 v36, v28, v21
	v_sub_f32_e32 v37, v29, v20
	v_pk_add_f32 v[34:35], v[34:35], v[34:35] op_sel:[0,1] op_sel_hi:[0,1]
	v_pk_add_f32 v[4:5], v[54:55], v[56:57]
	v_pk_add_f32 v[42:43], v[64:65], v[66:67] neg_lo:[0,1] neg_hi:[0,1]
	v_pk_add_f32 v[54:55], v[54:55], v[56:57] neg_lo:[0,1] neg_hi:[0,1]
	v_pk_add_f32 v[20:21], v[68:69], v[68:69] op_sel:[0,1] op_sel_hi:[0,1] neg_lo:[0,1] neg_hi:[0,1]
	v_pk_mul_f32 v[34:35], v[34:35], s[0:1]
	v_pk_add_f32 v[58:59], v[44:45], v[32:33]
	v_pk_add_f32 v[60:61], v[48:49], v[40:41]
	v_pk_add_f32 v[16:17], v[64:65], v[66:67]
	v_add_f32_e32 v50, v68, v69
	v_pk_mul_f32 v[56:57], v[54:55], s[20:21] op_sel_hi:[1,0]
	v_mul_f32_e32 v42, 0x3f3504f3, v42
	v_mul_f32_e32 v64, 0x3f3504f3, v43
	v_mul_f32_e32 v67, 0xbf3504f3, v43
	v_fma_f32 v68, v20, s70, v34
	v_fma_f32 v69, v21, s71, -v35
	v_pk_add_f32 v[2:3], v[18:19], v[52:53]
	v_pk_add_f32 v[62:63], v[58:59], v[60:61] neg_lo:[0,1] neg_hi:[0,1]
	v_cvt_f32_i32_e32 v7, v7
	v_mov_b32_e32 v20, v18
	v_sub_f32_e32 v18, v64, v42
	v_sub_f32_e32 v19, v19, v53
	v_sub_f32_e32 v20, v20, v52
	v_sub_f32_e32 v21, v57, v56
	v_mov_b32_e32 v35, v42
	v_pk_add_f32 v[42:43], v[18:19], v[62:63] op_sel:[1,0] op_sel_hi:[0,1]
	v_mov_b32_e32 v53, v62
	v_sub_f32_e32 v34, v59, v61
	v_sub_f32_e32 v35, v67, v35
	v_sub_f32_e32 v62, v44, v32
	v_sub_f32_e32 v63, v22, v30
	v_sub_f32_e32 v64, v49, v41
	v_sub_f32_e32 v65, v27, v39
	v_mul_f32_e32 v9, 0x3f6c835e, v50
	v_mul_f32_e32 v11, 0x3ec3ef15, v46
	v_add_f32_e32 v7, v7, v7
	v_sub_f32_e32 v22, v45, v33
	v_sub_f32_e32 v23, v23, v31
	v_sub_f32_e32 v27, v26, v38
	v_sub_f32_e32 v26, v48, v40
	v_pk_add_f32 v[32:33], v[62:63], v[64:65] neg_lo:[0,1] neg_hi:[0,1]
	v_mul_f32_e32 v7, 0x3b800000, v7
	v_pk_add_f32 v[66:67], v[62:63], v[64:65]
	v_pk_add_f32 v[30:31], v[22:23], v[26:27] neg_lo:[0,1] neg_hi:[0,1]
	v_pk_add_f32 v[22:23], v[22:23], v[26:27]
	v_mov_b32_e32 v39, v29
	v_mov_b32_e32 v27, v25
	v_mul_f32_e32 v7, 0.5, v7
	v_mul_f32_e32 v26, 0x3ec3ef15, v33
	v_pk_mul_f32 v[40:41], v[32:33], s[20:21]
	v_mul_f32_e32 v33, s73, v32
	v_mul_f32_e32 v32, s72, v50
	v_sub_f32_e32 v24, v28, v24
	v_sub_f32_e32 v25, v11, v9
	v_pk_mul_f32 v[28:29], v[66:67], s[70:71] op_sel:[1,0]
	v_pk_add_f32 v[14:15], v[58:59], v[60:61]
	v_sin_f32_e32 v58, v7
	v_cos_f32_e32 v76, v7
	v_mul_f32_e32 v38, 0x3f6c835e, v23
	v_mul_f32_e32 v7, 0x3f3504f3, v66
	v_mul_f32_e32 v13, 0x3f3504f3, v30
	v_pk_fma_f32 v[40:41], v[22:23], s[36:37], v[40:41] neg_lo:[0,0,1] neg_hi:[0,0,1]
	v_fma_f32 v23, v22, s31, -v33
	v_fma_f32 v22, v46, s30, -v32
	v_fma_f32 v32, v31, s0, v28
	v_fma_f32 v33, v31, s1, -v29
	v_pk_add_f32 v[26:27], v[38:39], v[26:27]
	v_add_f32_e32 v28, v13, v7
	v_fma_f32 v29, v30, s20, -v7
	v_pk_add_f32 v[30:31], v[36:37], v[28:29]
	v_pk_add_f32 v[38:39], v[32:33], v[68:69]
	v_xor_b32_e32 v77, 0x80000000, v58
	v_pk_add_f32 v[44:45], v[38:39], v[30:31]
	v_pk_fma_f32 v[54:55], v[54:55], s[20:21], v[56:57] op_sel:[0,0,1] op_sel_hi:[1,0,0]
	v_pk_mul_f32 v[50:51], v[58:59], v[44:45] op_sel_hi:[0,1]
	v_fma_f32 v62, v76, v44, v51
	v_fma_f32 v63, v76, v45, -v50
	v_mov_b32_e32 v59, v76
	v_pk_add_f32 v[70:71], v[2:3], v[14:15]
	v_pk_add_f32 v[72:73], v[4:5], v[16:17]
	v_mul_f32_e32 v44, v58, v58
	v_mul_f32_e32 v45, v59, v77
	v_pk_add_f32 v[74:75], v[72:73], v[70:71]
	v_add_f32_e32 v56, v18, v54
	v_sub_f32_e32 v53, v19, v53
	v_pk_fma_f32 v[50:51], v[76:77], v[76:77], v[44:45] op_sel_hi:[0,1,1] neg_lo:[0,0,1] neg_hi:[0,0,1]
	v_pk_fma_f32 v[44:45], v[76:77], v[76:77], v[44:45] op_sel_hi:[0,1,1]
	v_pk_add_f32 v[60:61], v[20:21], v[34:35]
	ds_write2_b64 v1, v[74:75], v[62:63] offset1:17
	v_pk_add_f32 v[20:21], v[20:21], v[34:35] neg_lo:[0,1] neg_hi:[0,1]
	v_add_f32_e32 v34, v60, v56
	v_add_f32_e32 v35, v61, v53
	v_mov_b32_e32 v62, v50
	v_mov_b32_e32 v63, v45
	v_mul_f32_e32 v74, v45, v45
	v_mul_f32_e32 v75, v45, v50
	v_pk_mul_f32 v[44:45], v[34:35], v[44:45] op_sel:[1,1] op_sel_hi:[0,1]
	v_pk_fma_f32 v[78:79], v[50:51], v[62:63], v[74:75] op_sel_hi:[0,1,1] neg_lo:[0,0,1] neg_hi:[0,0,1]
	v_pk_fma_f32 v[74:75], v[50:51], v[62:63], v[74:75] op_sel_hi:[0,1,1]
	v_fma_f32 v88, v34, v50, -v44
	v_fma_f32 v89, v35, v50, v45
	v_pk_mul_f32 v[44:45], v[62:63], v[74:75] op_sel:[0,1]
	v_pk_add_f32 v[54:55], v[54:55], v[18:19] neg_lo:[0,1] neg_hi:[0,1]
	v_fma_f32 v50, v62, v78, -v45
	v_fma_f32 v45, v63, v78, v44
	v_pk_add_f32 v[18:19], v[42:43], v[54:55]
	v_pk_add_f32 v[32:33], v[32:33], v[68:69] neg_lo:[0,1] neg_hi:[0,1]
	v_mov_b32_e32 v69, v45
	v_sub_f32_e32 v42, v42, v54
	v_mov_b32_e32 v77, v58
	v_mov_b32_e32 v80, v78
	v_mov_b32_e32 v81, v75
	v_pk_add_f32 v[90:91], v[20:21], v[20:21] op_sel:[0,1] op_sel_hi:[0,1]
	v_mul_f32_e32 v43, v42, v50
	v_mul_f32_e32 v42, v42, v45
	v_pk_mul_f32 v[64:65], v[76:77], v[62:63]
	v_pk_mul_f32 v[66:67], v[58:59], v[62:63]
	v_mov_b32_e32 v68, v50
	v_fma_f32 v44, v90, v50, -v42
	v_pk_mul_f32 v[50:51], v[80:81], v[74:75] op_sel:[0,1]
	v_pk_add_f32 v[30:31], v[30:31], v[38:39] neg_lo:[0,1] neg_hi:[0,1]
	v_pk_add_f32 v[38:39], v[40:41], v[24:25]
	v_pk_add_f32 v[46:47], v[26:27], v[22:23]
	v_fma_f32 v45, v91, v69, v43
	v_pk_fma_f32 v[54:55], v[78:79], v[80:81], v[50:51] op_sel:[0,0,1] op_sel_hi:[0,1,0] neg_lo:[0,0,1] neg_hi:[0,0,1]
	v_pk_fma_f32 v[50:51], v[78:79], v[80:81], v[50:51] op_sel:[0,0,1] op_sel_hi:[0,1,0]
	v_mov_b32_e32 v92, v64
	v_pk_mov_b32 v[64:65], v[64:65], v[66:67] op_sel:[1,0]
	v_pk_add_f32 v[48:49], v[38:39], v[46:47]
	v_pk_add_f32 v[42:43], v[70:71], v[72:73] neg_lo:[0,1] neg_hi:[0,1]
	v_pk_mov_b32 v[72:73], v[50:51], v[54:55] op_sel:[1,0]
	v_add_f32_e32 v66, v92, v64
	v_sub_f32_e32 v64, v92, v64
	v_sub_f32_e32 v65, v67, v65
	v_pk_mul_f32 v[82:83], v[76:77], v[80:81]
	v_pk_mul_f32 v[84:85], v[58:59], v[80:81]
	v_pk_add_f32 v[28:29], v[36:37], v[28:29] neg_lo:[0,1] neg_hi:[0,1]
	v_mov_b32_e32 v70, v54
	v_mov_b32_e32 v71, v51
	v_pk_mul_f32 v[58:59], v[58:59], v[72:73] op_sel_hi:[0,1]
	v_pk_mul_f32 v[94:95], v[48:49], v[64:65] op_sel:[0,1]
	v_pk_mov_b32 v[86:87], v[74:75], v[78:79] op_sel:[1,0]
	v_pk_add_f32 v[34:35], v[28:29], v[32:33] op_sel:[0,1] op_sel_hi:[1,0]
	v_pk_add_f32 v[28:29], v[28:29], v[32:33] op_sel:[0,1] op_sel_hi:[1,0] neg_lo:[0,1] neg_hi:[0,1]
	v_fma_f32 v74, v76, v70, v58
	v_fma_f32 v59, v76, v71, -v59
	v_fma_f32 v96, v48, v66, -v95
	v_fma_f32 v97, v49, v66, v94
	v_mov_b32_e32 v98, v82
	v_mov_b32_e32 v99, v85
	v_pk_mov_b32 v[82:83], v[82:83], v[84:85] op_sel:[1,0]
	v_mov_b32_e32 v77, v59
	v_pk_mul_f32 v[48:49], v[80:81], v[64:65] op_sel:[0,1]
	v_pk_add_f32 v[84:85], v[98:99], v[82:83]
	v_sub_f32_e32 v83, v99, v83
	v_mov_b32_e32 v93, v65
	v_fma_f32 v64, v80, v66, -v49
	v_fma_f32 v49, v81, v66, v48
	v_mul_f32_e32 v36, v29, v83
	v_mul_f32_e32 v37, v34, v83
	v_mul_f32_e32 v58, v31, v59
	v_mul_f32_e32 v59, v31, v74
	v_mov_b32_e32 v92, v66
	v_mov_b32_e32 v66, v64
	v_mov_b32_e32 v67, v49
	v_mov_b32_e32 v98, v84
	v_mov_b32_e32 v99, v83
	v_fma_f32 v82, v34, v84, -v36
	v_fma_f32 v83, v29, v84, v37
	v_fma_f32 v74, v30, v74, -v58
	v_fma_f32 v75, v30, v77, v59
	v_pk_mul_f32 v[50:51], v[42:43], v[50:51] op_sel:[1,1] op_sel_hi:[0,1]
	v_pk_mul_f32 v[90:91], v[62:63], v[70:71]
	v_pk_mul_f32 v[62:63], v[62:63], v[72:73]
	ds_write2_b64 v1, v[88:89], v[96:97] offset0:34 offset1:51
	v_pk_mul_f32 v[88:89], v[92:93], v[70:71]
	v_pk_mul_f32 v[92:93], v[92:93], v[72:73]
	v_pk_mul_f32 v[94:95], v[80:81], v[70:71]
	v_pk_mul_f32 v[96:97], v[80:81], v[72:73]
	v_pk_mul_f32 v[32:33], v[70:71], v[98:99]
	v_pk_mul_f32 v[36:37], v[72:73], v[98:99]
	v_pk_mul_f32 v[30:31], v[70:71], v[68:69]
	v_pk_mul_f32 v[58:59], v[72:73], v[68:69]
	v_pk_mul_f32 v[68:69], v[70:71], v[66:67]
	v_pk_mul_f32 v[70:71], v[72:73], v[66:67]
	v_fma_f32 v72, v42, v54, -v50
	v_fma_f32 v73, v43, v54, v51
	v_sub_f32_e32 v42, v60, v56
	v_sub_f32_e32 v43, v53, v61
	v_pk_add_f32 v[50:51], v[62:63], v[62:63] op_sel:[0,1] op_sel_hi:[0,1]
	v_pk_mul_f32 v[50:51], v[42:43], v[50:51] op_sel:[1,0] op_sel_hi:[0,1]
	v_pk_add_f32 v[52:53], v[90:91], v[90:91] op_sel:[0,1] op_sel_hi:[0,1] neg_lo:[0,1] neg_hi:[0,1]
	v_fma_f32 v54, v42, v52, -v50
	v_fma_f32 v55, v43, v53, v51
	v_pk_add_f32 v[2:3], v[2:3], v[14:15] neg_lo:[0,1] neg_hi:[0,1]
	v_sub_f32_e32 v38, v38, v46
	v_sub_f32_e32 v39, v47, v39
	v_pk_add_f32 v[42:43], v[92:93], v[92:93] op_sel:[0,1] op_sel_hi:[0,1]
	v_pk_add_f32 v[4:5], v[4:5], v[16:17] neg_lo:[0,1] neg_hi:[0,1]
	v_pk_mul_f32 v[42:43], v[38:39], v[42:43] op_sel:[1,0] op_sel_hi:[0,1]
	v_pk_add_f32 v[46:47], v[88:89], v[88:89] op_sel:[0,1] op_sel_hi:[0,1] neg_lo:[0,1] neg_hi:[0,1]
	v_pk_add_f32 v[14:15], v[2:3], v[4:5] op_sel:[0,1] op_sel_hi:[1,0]
	v_pk_add_f32 v[2:3], v[2:3], v[4:5] op_sel:[0,1] op_sel_hi:[1,0] neg_lo:[0,1] neg_hi:[0,1]
	v_fma_f32 v50, v38, v46, -v42
	v_fma_f32 v51, v39, v47, v43
	v_pk_mul_f32 v[16:17], v[2:3], v[86:87] op_sel:[1,0]
	v_fma_f32 v38, v14, v78, -v16
	v_fma_f32 v39, v14, v81, v17
	v_mov_b32_e32 v5, v15
	v_pk_add_f32 v[16:17], v[96:97], v[96:97] op_sel:[0,1] op_sel_hi:[0,1]
	v_mul_f32_e32 v14, v15, v16
	v_mul_f32_e32 v15, v2, v17
	v_pk_add_f32 v[16:17], v[94:95], v[94:95] op_sel:[0,1] op_sel_hi:[0,1] neg_lo:[0,1] neg_hi:[0,1]
	v_fma_f32 v2, v2, v16, -v14
	v_fma_f32 v3, v5, v17, v15
	v_pk_add_f32 v[16:17], v[36:37], v[36:37] op_sel:[0,1] op_sel_hi:[0,1]
	v_mul_f32_e32 v14, v35, v16
	v_mul_f32_e32 v15, v28, v17
	v_pk_add_f32 v[16:17], v[32:33], v[32:33] op_sel:[0,1] op_sel_hi:[0,1] neg_lo:[0,1] neg_hi:[0,1]
	v_fma_f32 v28, v28, v16, -v14
	v_fma_f32 v29, v35, v17, v15
	v_pk_add_f32 v[14:15], v[58:59], v[58:59] op_sel:[0,1] op_sel_hi:[0,1]
	ds_write2_b64 v1, v[2:3], v[28:29] offset0:204 offset1:221
	v_sub_f32_e32 v2, v20, v21
	v_sub_f32_e32 v3, v30, v31
	v_mul_f32_e32 v4, v18, v14
	v_mul_f32_e32 v5, v2, v15
	v_pk_mov_b32 v[14:15], v[2:3], v[18:19] op_sel:[1,0]
	v_fma_f32 v16, v2, v14, -v4
	v_fma_f32 v17, v3, v15, v5
	v_sub_f32_e32 v2, v24, v40
	v_sub_f32_e32 v3, v26, v22
	v_sub_f32_e32 v4, v41, v25
	v_sub_f32_e32 v5, v27, v23
	ds_write2_b64 v1, v[72:73], v[74:75] offset0:136 offset1:153
	v_pk_add_f32 v[14:15], v[4:5], v[2:3]
	v_sub_f32_e32 v18, v2, v4
	v_sub_f32_e32 v2, v5, v3
	v_mul_f32_e32 v3, v2, v64
	v_mul_f32_e32 v2, v2, v49
	v_fma_f32 v4, v14, v64, -v2
	v_fma_f32 v5, v14, v67, v3
	ds_write2_b64 v1, v[44:45], v[4:5] offset0:102 offset1:119
	v_pk_add_f32 v[4:5], v[70:71], v[70:71] op_sel:[0,1] op_sel_hi:[0,1]
	v_mul_f32_e32 v2, v15, v4
	v_mul_f32_e32 v3, v18, v5
	v_pk_add_f32 v[4:5], v[68:69], v[68:69] op_sel:[0,1] op_sel_hi:[0,1] neg_lo:[0,1] neg_hi:[0,1]
	v_fma_f32 v14, v18, v4, -v2
	v_fma_f32 v15, v15, v5, v3
	ds_write2_b64 v1, v[54:55], v[50:51] offset0:170 offset1:187
	ds_write2_b64 v1, v[38:39], v[82:83] offset0:68 offset1:85
	ds_write2_b64 v1, v[16:17], v[14:15] offset0:238 offset1:255
	v_mov_b32_e32 v1, v122
	s_waitcnt lgkmcnt(0)
	s_barrier
	s_cselect_b32 s94, s89, s24
	v_mul_lo_u32 v1, v1, s33
	ds_read2_b64 v[2:5], v1 offset1:1
	ds_read2_b64 v[14:17], v1 offset0:8 offset1:9
	ds_read2_b64 v[18:21], v1 offset0:10 offset1:11
	ds_read2_b64 v[22:25], v1 offset0:12 offset1:13
	ds_read2_b64 v[26:29], v1 offset0:14 offset1:15
	ds_read2_b64 v[30:33], v1 offset0:2 offset1:3
	ds_read2_b64 v[34:37], v1 offset0:4 offset1:5
	ds_read2_b64 v[38:41], v1 offset0:6 offset1:7
	s_waitcnt lgkmcnt(7)
	v_mov_b32_e32 v1, v4
	v_mov_b32_e32 v42, v2
	v_mov_b32_e32 v43, v4
	v_mov_b32_e32 v4, v5
	v_mov_b32_e32 v5, v3
	s_waitcnt lgkmcnt(6)
	v_mov_b32_e32 v44, v14
	v_mov_b32_e32 v45, v16
	v_mov_b32_e32 v16, v17
	v_mov_b32_e32 v17, v15
	v_pk_add_f32 v[46:47], v[2:3], v[14:15] neg_lo:[0,1] neg_hi:[0,1]
	v_pk_add_f32 v[2:3], v[2:3], v[14:15]
	s_waitcnt lgkmcnt(1)
	v_mov_b32_e32 v7, v36
	v_mov_b32_e32 v15, v36
	v_mov_b32_e32 v36, v37
	v_mov_b32_e32 v37, v35
	v_mov_b32_e32 v48, v22
	v_mov_b32_e32 v49, v24
	v_mov_b32_e32 v24, v25
	v_mov_b32_e32 v25, v23
	v_mov_b32_e32 v14, v34
	v_pk_add_f32 v[50:51], v[34:35], v[22:23] neg_lo:[0,1] neg_hi:[0,1]
	v_pk_add_f32 v[22:23], v[34:35], v[22:23]
	v_pk_mov_b32 v[34:35], v[0:1], v[4:5] op_sel:[1,0]
	v_pk_mov_b32 v[52:53], v[44:45], v[16:17] op_sel:[1,0]
	v_pk_add_f32 v[42:43], v[42:43], v[44:45]
	v_pk_add_f32 v[4:5], v[4:5], v[16:17]
	v_pk_mov_b32 v[16:17], v[6:7], v[36:37] op_sel:[1,0]
	v_pk_mov_b32 v[44:45], v[48:49], v[24:25] op_sel:[1,0]
	v_pk_add_f32 v[14:15], v[14:15], v[48:49]
	v_pk_add_f32 v[24:25], v[36:37], v[24:25]
	v_pk_add_f32 v[48:49], v[2:3], v[22:23] neg_lo:[0,1] neg_hi:[0,1]
	v_pk_add_f32 v[2:3], v[2:3], v[22:23]
	v_pk_add_f32 v[22:23], v[34:35], v[52:53]
	v_pk_add_f32 v[34:35], v[34:35], v[52:53] neg_lo:[0,1] neg_hi:[0,1]
	v_pk_add_f32 v[36:37], v[16:17], v[44:45]
	v_pk_add_f32 v[16:17], v[16:17], v[44:45] neg_lo:[0,1] neg_hi:[0,1]
	v_add_f32_e32 v1, v46, v51
	v_sub_f32_e32 v7, v47, v50
	v_sub_f32_e32 v9, v46, v51
	v_add_f32_e32 v11, v47, v50
	v_pk_add_f32 v[4:5], v[4:5], v[24:25]
	v_add_f32_e32 v13, v34, v17
	v_sub_f32_e32 v50, v35, v16
	v_sub_f32_e32 v51, v34, v17
	v_add_f32_e32 v52, v35, v16
	v_pk_add_f32 v[16:17], v[30:31], v[18:19] neg_lo:[0,1] neg_hi:[0,1]
	v_pk_add_f32 v[24:25], v[30:31], v[18:19]
	v_pk_add_f32 v[14:15], v[42:43], v[14:15]
	v_pk_add_f32 v[42:43], v[22:23], v[36:37]
	v_pk_add_f32 v[22:23], v[22:23], v[36:37] neg_lo:[0,1] neg_hi:[0,1]
	s_waitcnt lgkmcnt(0)
	v_pk_add_f32 v[34:35], v[38:39], v[26:27] neg_lo:[0,1] neg_hi:[0,1]
	v_pk_add_f32 v[36:37], v[38:39], v[26:27]
	v_add_f32_e32 v44, v30, v18
	v_add_f32_e32 v45, v32, v20
	v_add_f32_e32 v18, v33, v21
	v_add_f32_e32 v19, v31, v19
	v_add_f32_e32 v30, v38, v26
	v_add_f32_e32 v31, v40, v28
	v_add_f32_e32 v26, v41, v29
	v_add_f32_e32 v27, v39, v27
	v_pk_add_f32 v[38:39], v[24:25], v[36:37] neg_lo:[0,1] neg_hi:[0,1]
	v_pk_add_f32 v[24:25], v[24:25], v[36:37]
	v_add_f32_e32 v36, v16, v35
	v_sub_f32_e32 v37, v17, v34
	v_sub_f32_e32 v46, v16, v35
	v_add_f32_e32 v47, v17, v34
	v_pk_add_f32 v[16:17], v[32:33], v[20:21]
	v_pk_add_f32 v[20:21], v[32:33], v[20:21] neg_lo:[0,1] neg_hi:[0,1]
	v_pk_add_f32 v[32:33], v[40:41], v[28:29]
	v_pk_add_f32 v[28:29], v[40:41], v[28:29] neg_lo:[0,1] neg_hi:[0,1]
	v_pk_add_f32 v[18:19], v[18:19], v[26:27]
	v_add_f32_e32 v26, v20, v29
	v_mul_f32_e32 v22, 0x3f3504f3, v22
	v_pk_add_f32 v[34:35], v[16:17], v[32:33]
	v_pk_add_f32 v[16:17], v[16:17], v[32:33] neg_lo:[0,1] neg_hi:[0,1]
	v_sub_f32_e32 v27, v21, v28
	v_sub_f32_e32 v20, v20, v29
	v_add_f32_e32 v21, v21, v28
	v_fmamk_f32 v29, v23, 0x3f3504f3, v22
	v_fma_f32 v33, v23, s20, -v22
	v_mul_f32_e32 v22, 0x3f3504f3, v36
	v_mul_f32_e32 v40, 0x3ec3ef15, v26
	v_mul_f32_e32 v26, 0xbf6c835e, v26
	v_pk_add_f32 v[30:31], v[44:45], v[30:31]
	v_mul_f32_e32 v28, 0x3f6c835e, v13
	v_mul_f32_e32 v13, 0x3ec3ef15, v13
	v_fmamk_f32 v32, v37, 0x3f3504f3, v22
	v_fma_f32 v36, v37, s20, -v22
	v_mul_f32_e32 v37, 0xbf3504f3, v46
	v_fmac_f32_e32 v40, 0x3f6c835e, v27
	v_fmac_f32_e32 v26, 0x3ec3ef15, v27
	v_mul_f32_e32 v27, 0xbf3504f3, v16
	v_mul_f32_e32 v16, 0x3ec3ef15, v21
	v_fmac_f32_e32 v28, 0x3ec3ef15, v50
	v_fma_f32 v13, v50, s21, -v13
	v_mul_f32_e32 v41, 0x3ec3ef15, v51
	v_mul_f32_e32 v45, 0xbf6c835e, v51
	v_fmamk_f32 v51, v47, 0x3f3504f3, v37
	v_fmac_f32_e32 v37, 0xbf3504f3, v47
	v_fmamk_f32 v44, v17, 0x3f3504f3, v27
	v_fmac_f32_e32 v27, 0xbf3504f3, v17
	v_fma_f32 v47, v20, s76, -v16
	v_mul_f32_e32 v53, 0xbf6c835e, v21
	v_pk_add_f32 v[16:17], v[2:3], v[24:25]
	v_pk_add_f32 v[2:3], v[2:3], v[24:25] neg_lo:[0,1] neg_hi:[0,1]
	v_pk_add_f32 v[22:23], v[14:15], v[30:31] neg_lo:[0,1] neg_hi:[0,1]
	v_pk_add_f32 v[24:25], v[42:43], v[34:35] neg_lo:[0,1] neg_hi:[0,1]
	v_pk_add_f32 v[4:5], v[4:5], v[18:19] neg_lo:[0,1] neg_hi:[0,1]
	v_fmac_f32_e32 v53, 0x3ec3ef15, v20
	v_pk_add_f32 v[20:21], v[42:43], v[34:35]
	v_pk_add_f32 v[70:71], v[2:3], v[24:25] op_sel:[0,1] op_sel_hi:[1,0]
	v_pk_add_f32 v[2:3], v[2:3], v[24:25] op_sel:[0,1] op_sel_hi:[1,0] neg_lo:[0,1] neg_hi:[0,1]
	v_pk_add_f32 v[72:73], v[22:23], v[4:5] neg_lo:[0,1] neg_hi:[0,1]
	v_pk_add_f32 v[4:5], v[22:23], v[4:5]
	v_add_f32_e32 v23, v1, v32
	v_add_f32_e32 v25, v7, v36
	v_sub_f32_e32 v1, v1, v32
	v_sub_f32_e32 v7, v7, v36
	v_add_f32_e32 v30, v28, v40
	v_add_f32_e32 v31, v13, v26
	v_sub_f32_e32 v35, v28, v40
	v_sub_f32_e32 v13, v13, v26
	v_fmac_f32_e32 v41, 0x3f6c835e, v52
	v_fmac_f32_e32 v45, 0x3ec3ef15, v52
	v_add_f32_e32 v22, v30, v23
	v_add_f32_e32 v24, v31, v25
	v_sub_f32_e32 v26, v23, v30
	v_sub_f32_e32 v28, v25, v31
	v_add_f32_e32 v30, v13, v1
	v_sub_f32_e32 v32, v7, v35
	v_sub_f32_e32 v34, v1, v13
	v_add_f32_e32 v36, v35, v7
	v_add_f32_e32 v1, v48, v39
	v_sub_f32_e32 v7, v49, v38
	v_sub_f32_e32 v13, v48, v39
	v_add_f32_e32 v23, v49, v38
	v_add_f32_e32 v25, v29, v44
	v_add_f32_e32 v31, v33, v27
	v_sub_f32_e32 v29, v29, v44
	v_sub_f32_e32 v27, v33, v27
	v_add_f32_e32 v38, v1, v25
	v_add_f32_e32 v40, v7, v31
	v_sub_f32_e32 v42, v1, v25
	v_sub_f32_e32 v44, v7, v31
	v_add_f32_e32 v46, v13, v27
	v_sub_f32_e32 v48, v23, v29
	v_sub_f32_e32 v50, v13, v27
	v_add_f32_e32 v52, v23, v29
	v_add_f32_e32 v1, v9, v51
	v_add_f32_e32 v7, v11, v37
	v_sub_f32_e32 v9, v9, v51
	v_sub_f32_e32 v11, v11, v37
	v_add_f32_e32 v13, v41, v47
	v_add_f32_e32 v23, v45, v53
	v_sub_f32_e32 v25, v41, v47
	v_sub_f32_e32 v27, v45, v53
	v_pk_add_f32 v[14:15], v[20:21], v[16:17]
	v_pk_add_f32 v[16:17], v[16:17], v[20:21] neg_lo:[0,1] neg_hi:[0,1]
	v_add_f32_e32 v54, v13, v1
	v_add_f32_e32 v56, v23, v7
	v_sub_f32_e32 v58, v1, v13
	v_sub_f32_e32 v60, v7, v23
	v_add_f32_e32 v62, v27, v9
	v_sub_f32_e32 v64, v11, v25
	v_sub_f32_e32 v66, v9, v27
	v_add_f32_e32 v68, v25, v11
	s_mov_b32 s29, 0
	v_mov_b32_e32 v18, v70
	v_mov_b32_e32 v19, v3
	v_mov_b32_e32 v20, v72
	v_mov_b32_e32 v21, v5
	v_pk_mov_b32 v[70:71], v[2:3], v[70:71] op_sel:[1,0]
	v_pk_mov_b32 v[72:73], v[4:5], v[72:73] op_sel:[1,0]
	v_mov_b32_e32 v39, v38
	v_mov_b32_e32 v43, v42
	v_mov_b32_e32 v47, v46
	v_mov_b32_e32 v49, v48
	v_mov_b32_e32 v51, v50
	v_mov_b32_e32 v53, v52
	v_mov_b32_e32 v23, v22
	v_mov_b32_e32 v27, v26
	v_mov_b32_e32 v31, v30
	v_mov_b32_e32 v33, v32
	v_mov_b32_e32 v35, v34
	v_mov_b32_e32 v37, v36
	v_mov_b32_e32 v55, v54
	v_mov_b32_e32 v59, v58
	v_mov_b32_e32 v63, v62
	v_mov_b32_e32 v65, v64
	v_mov_b32_e32 v67, v66
	v_mov_b32_e32 v69, v68
	v_mov_b32_e32 v13, v12
	v_mov_b32_e32 v7, v6
	v_mov_b32_e32 v9, v8
	v_mov_b32_e32 v11, v10
	v_pk_mov_b32 v[74:75], v[14:15], v[14:15] op_sel:[1,0]
	v_mov_b32_e32 v25, v24
	v_mov_b32_e32 v41, v40
	v_mov_b32_e32 v57, v56
	v_pk_mov_b32 v[76:77], v[16:17], v[16:17] op_sel:[1,0]
	v_mov_b32_e32 v29, v28
	v_mov_b32_e32 v45, v44
	v_mov_b32_e32 v61, v60
	s_mov_b64 s[0:1], 0
	s_branch .LBB0_348
.LBB0_347:
	v_mov_b32_e32 v102, v1
	s_barrier
	v_pk_add_f32 v[108:109], v[80:81], v[96:97]
	v_ashrrev_i32_e32 v103, 31, v102
	v_lshrrev_b32_e32 v103, 24, v103
	v_and_b32_e32 v115, 0xff, v102
	v_add_lshl_u32 v102, v102, v103, 4
	v_and_or_b32 v102, v102, s87, v115
	v_ashrrev_i32_e32 v103, 4, v102
	v_cvt_f32_i32_e32 v115, v115
	v_lshlrev_b32_e32 v102, 3, v102
	v_pk_add_f32 v[132:133], v[88:89], v[112:113]
	v_lshl_add_u32 v127, v103, 3, v102
	v_pk_add_f32 v[102:103], v[108:109], v[132:133] neg_lo:[0,1] neg_hi:[0,1]
	v_pk_add_f32 v[116:117], v[2:3], v[90:91]
	v_mul_f32_e32 v138, 0x3f3504f3, v102
	v_add_f32_e32 v102, v115, v115
	v_mul_f32_e32 v102, 0x39800000, v102
	v_pk_add_f32 v[118:119], v[82:83], v[98:99]
	v_pk_add_f32 v[104:105], v[4:5], v[92:93]
	v_pk_add_f32 v[106:107], v[84:85], v[100:101]
	v_pk_add_f32 v[120:121], v[78:79], v[94:95]
	v_pk_add_f32 v[128:129], v[86:87], v[110:111]
	v_mul_f32_e32 v102, 0.5, v102
	v_pk_add_f32 v[134:135], v[104:105], v[106:107] neg_lo:[0,1] neg_hi:[0,1]
	v_sin_f32_e32 v140, v102
	v_mul_f32_e32 v142, 0x3f3504f3, v103
	v_mul_f32_e32 v145, 0xbf3504f3, v103
	v_cos_f32_e32 v146, v102
	v_pk_add_f32 v[102:103], v[116:117], v[118:119]
	v_pk_add_f32 v[104:105], v[104:105], v[106:107]
	v_pk_add_f32 v[106:107], v[120:121], v[128:129]
	v_pk_add_f32 v[108:109], v[108:109], v[132:133]
	v_pk_add_f32 v[132:133], v[102:103], v[106:107]
	v_pk_add_f32 v[148:149], v[104:105], v[108:109]
	v_pk_add_f32 v[90:91], v[2:3], v[90:91] neg_lo:[0,1] neg_hi:[0,1]
	v_pk_add_f32 v[150:151], v[132:133], v[148:149]
	v_pk_add_f32 v[2:3], v[82:83], v[98:99] neg_lo:[0,1] neg_hi:[0,1]
	v_pk_mul_f32 v[136:137], v[134:135], s[20:21] op_sel_hi:[1,0]
	ds_write_b64 v127, v[150:151]
	v_pk_mov_b32 v[98:99], v[2:3], v[2:3] op_sel:[1,0]
	v_add_f32_e32 v150, v90, v3
	v_sub_f32_e32 v151, v91, v2
	v_pk_fma_f32 v[134:135], v[134:135], s[20:21], v[136:137] op_sel:[0,0,1] op_sel_hi:[1,0,0]
	v_sub_f32_e32 v2, v116, v118
	v_sub_f32_e32 v3, v137, v136
	v_sub_f32_e32 v82, v142, v138
	v_sub_f32_e32 v83, v117, v119
	v_mov_b32_e32 v117, v138
	v_sub_f32_e32 v136, v78, v94
	v_sub_f32_e32 v137, v4, v92
	v_mov_b32_e32 v139, v85
	v_sub_f32_e32 v92, v79, v95
	v_sub_f32_e32 v93, v5, v93
	v_mov_b32_e32 v5, v84
	v_sub_f32_e32 v84, v86, v110
	v_sub_f32_e32 v85, v5, v100
	v_sub_f32_e32 v4, v81, v97
	v_sub_f32_e32 v5, v78, v94
	v_sub_f32_e32 v78, v80, v96
	v_sub_f32_e32 v79, v79, v95
	v_pk_mov_b32 v[80:81], v[88:89], v[86:87] op_sel:[1,0]
	v_sub_f32_e32 v138, v87, v111
	v_sub_f32_e32 v139, v139, v101
	v_sub_f32_e32 v80, v80, v113
	v_sub_f32_e32 v81, v81, v110
	v_sub_f32_e32 v100, v88, v112
	v_sub_f32_e32 v101, v87, v111
	v_pk_add_f32 v[86:87], v[78:79], v[80:81] neg_lo:[0,1] neg_hi:[0,1]
	v_pk_add_f32 v[142:143], v[4:5], v[100:101]
	v_pk_add_f32 v[80:81], v[78:79], v[80:81]
	v_mov_b32_e32 v78, v86
	v_mul_f32_e32 v86, 0x3ec3ef15, v86
	v_pk_add_f32 v[88:89], v[136:137], v[138:139] neg_lo:[0,1] neg_hi:[0,1]
	v_pk_add_f32 v[94:95], v[92:93], v[84:85]
	v_pk_add_f32 v[96:97], v[4:5], v[100:101] neg_lo:[0,1] neg_hi:[0,1]
	v_mul_f32_e32 v84, 0x3f6c835e, v142
	v_mov_b32_e32 v101, v91
	v_mov_b32_e32 v91, v86
	v_add_f32_e32 v86, v137, v139
	s_mov_b32 s40, s21
	s_mov_b32 s41, s71
	v_pk_add_f32 v[130:131], v[120:121], v[128:129] neg_lo:[0,1] neg_hi:[0,1]
	v_mul_f32_e32 v100, 0x3ec3ef15, v89
	v_pk_mul_f32 v[88:89], v[88:89], s[20:21]
	s_mov_b32 s70, s20
	v_mov_b32_e32 v111, v99
	v_mov_b32_e32 v99, v84
	v_sub_f32_e32 v84, v93, v85
	s_mov_b32 s38, s71
	s_mov_b32 s39, s21
	v_pk_mul_f32 v[92:93], v[86:87], s[40:41] op_sel_hi:[0,1]
	v_sub_f32_e32 v116, v121, v129
	v_sub_f32_e32 v117, v145, v117
	v_pk_add_f32 v[118:119], v[82:83], v[130:131] op_sel:[1,0] op_sel_hi:[0,1]
	v_mov_b32_e32 v120, v134
	v_pk_add_f32 v[134:135], v[134:135], v[82:83] neg_lo:[0,1] neg_hi:[0,1]
	v_mov_b32_e32 v79, v81
	v_mul_f32_e32 v110, 0x3f6c835e, v95
	v_mul_f32_e32 v115, 0x3f3504f3, v143
	v_mul_f32_e32 v112, s72, v142
	v_mul_f32_e32 v113, s73, v97
	v_pk_fma_f32 v[4:5], v[94:95], s[70:71], v[88:89] neg_lo:[0,0,1] neg_hi:[0,0,1]
	v_fma_f32 v94, v84, s38, v92
	v_fma_f32 v95, v84, s39, -v93
	v_pk_mul_f32 v[80:81], v[80:81], s[38:39] op_sel_hi:[0,1]
	v_add_f32_e32 v128, v82, v120
	v_sub_f32_e32 v121, v83, v130
	v_pk_add_f32 v[130:131], v[2:3], v[116:117]
	v_pk_add_f32 v[82:83], v[2:3], v[116:117] neg_lo:[0,1] neg_hi:[0,1]
	v_pk_add_f32 v[2:3], v[118:119], v[134:135]
	v_mul_f32_e32 v119, 0x3f3504f3, v87
	v_fma_f32 v85, v87, s20, -v115
	v_fma_f32 v86, v96, s40, v80
	v_fma_f32 v87, v96, s41, -v81
	v_add_f32_e32 v84, v119, v115
	v_pk_add_f32 v[80:81], v[150:151], v[84:85]
	v_pk_add_f32 v[92:93], v[94:95], v[86:87]
	v_xor_b32_e32 v147, 0x80000000, v140
	v_pk_add_f32 v[96:97], v[80:81], v[92:93]
	v_pk_add_f32 v[88:89], v[100:101], v[110:111]
	v_pk_mul_f32 v[110:111], v[96:97], v[140:141] op_sel_hi:[1,0]
	v_pk_fma_f32 v[78:79], v[78:79], s[30:31], v[112:113] neg_lo:[0,0,1] neg_hi:[0,0,1]
	v_fma_f32 v112, v96, v146, v111
	v_fma_f32 v113, v97, v146, -v110
	v_mov_b32_e32 v141, v146
	v_mul_f32_e32 v96, v140, v140
	v_mul_f32_e32 v97, v141, v147
	v_pk_fma_f32 v[110:111], v[146:147], v[146:147], v[96:97] op_sel_hi:[0,1,1] neg_lo:[0,0,1] neg_hi:[0,0,1]
	v_pk_fma_f32 v[96:97], v[146:147], v[146:147], v[96:97] op_sel_hi:[0,1,1]
	v_add_f32_e32 v116, v130, v128
	v_add_f32_e32 v117, v131, v121
	ds_write_b64 v127, v[112:113] offset:2176
	v_mov_b32_e32 v112, v110
	v_mov_b32_e32 v113, v97
	v_mul_f32_e32 v142, v97, v97
	v_mul_f32_e32 v143, v97, v110
	v_pk_mul_f32 v[96:97], v[116:117], v[96:97] op_sel:[1,1] op_sel_hi:[0,1]
	v_pk_fma_f32 v[144:145], v[110:111], v[112:113], v[142:143] op_sel_hi:[0,1,1] neg_lo:[0,0,1] neg_hi:[0,0,1]
	v_pk_fma_f32 v[142:143], v[110:111], v[112:113], v[142:143] op_sel_hi:[0,1,1]
	v_fma_f32 v160, v116, v110, -v96
	v_fma_f32 v161, v117, v110, v97
	v_pk_mul_f32 v[110:111], v[112:113], v[142:143] op_sel:[0,1]
	v_fma_f32 v116, v112, v144, -v111
	v_fma_f32 v111, v113, v144, v110
	v_pk_add_f32 v[84:85], v[150:151], v[84:85] neg_lo:[0,1] neg_hi:[0,1]
	v_mov_b32_e32 v151, v111
	v_sub_f32_e32 v118, v118, v134
	ds_write_b64 v127, v[160:161] offset:4352
	v_mov_b32_e32 v150, v116
	v_pk_add_f32 v[160:161], v[82:83], v[82:83] op_sel:[0,1] op_sel_hi:[0,1]
	v_mul_f32_e32 v110, v118, v111
	v_mul_f32_e32 v111, v118, v116
	v_fma_f32 v116, v160, v116, -v110
	v_fma_f32 v117, v161, v151, v111
	v_mov_b32_e32 v152, v144
	v_mov_b32_e32 v153, v143
	ds_write_b64 v127, v[116:117] offset:13056
	v_pk_mul_f32 v[116:117], v[152:153], v[142:143] op_sel:[0,1]
	v_mov_b32_e32 v147, v140
	v_pk_fma_f32 v[118:119], v[144:145], v[152:153], v[116:117] op_sel:[0,0,1] op_sel_hi:[0,1,0] neg_lo:[0,0,1] neg_hi:[0,0,1]
	v_pk_fma_f32 v[116:117], v[144:145], v[152:153], v[116:117] op_sel:[0,0,1] op_sel_hi:[0,1,0]
	v_pk_mov_b32 v[134:135], v[116:117], v[118:119] op_sel:[1,0]
	v_pk_mul_f32 v[138:139], v[140:141], v[112:113]
	v_pk_mul_f32 v[156:157], v[140:141], v[152:153]
	v_pk_add_f32 v[110:111], v[132:133], v[148:149] neg_lo:[0,1] neg_hi:[0,1]
	v_mov_b32_e32 v132, v118
	v_mov_b32_e32 v133, v117
	v_pk_mul_f32 v[140:141], v[140:141], v[134:135] op_sel_hi:[0,1]
	v_pk_mov_b32 v[158:159], v[142:143], v[144:145] op_sel:[1,0]
	v_fma_f32 v142, v146, v132, v140
	v_fma_f32 v141, v146, v133, -v141
	v_pk_add_f32 v[80:81], v[80:81], v[92:93] neg_lo:[0,1] neg_hi:[0,1]
	v_pk_mul_f32 v[136:137], v[146:147], v[112:113]
	v_pk_mul_f32 v[154:155], v[146:147], v[152:153]
	v_mov_b32_e32 v147, v141
	v_mul_f32_e32 v140, v81, v141
	v_mul_f32_e32 v141, v81, v142
	v_pk_mul_f32 v[116:117], v[110:111], v[116:117] op_sel:[1,1] op_sel_hi:[0,1]
	v_pk_add_f32 v[90:91], v[90:91], v[98:99] neg_lo:[0,1] neg_hi:[0,1]
	v_pk_mul_f32 v[148:149], v[112:113], v[132:133]
	v_pk_mul_f32 v[112:113], v[112:113], v[134:135]
	v_fma_f32 v142, v80, v142, -v140
	v_fma_f32 v143, v80, v147, v141
	v_fma_f32 v146, v110, v118, -v116
	v_fma_f32 v147, v111, v118, v117
	v_pk_add_f32 v[92:93], v[4:5], v[90:91]
	v_pk_add_f32 v[98:99], v[88:89], v[78:79]
	v_mov_b32_e32 v160, v136
	v_pk_mov_b32 v[136:137], v[136:137], v[138:139] op_sel:[1,0]
	v_sub_f32_e32 v110, v130, v128
	v_sub_f32_e32 v111, v121, v131
	v_pk_add_f32 v[112:113], v[112:113], v[112:113] op_sel:[0,1] op_sel_hi:[0,1]
	v_pk_add_f32 v[100:101], v[98:99], v[92:93]
	v_add_f32_e32 v138, v160, v136
	v_sub_f32_e32 v136, v160, v136
	v_sub_f32_e32 v137, v139, v137
	v_pk_mul_f32 v[112:113], v[110:111], v[112:113] op_sel:[1,0] op_sel_hi:[0,1]
	v_pk_add_f32 v[116:117], v[148:149], v[148:149] op_sel:[0,1] op_sel_hi:[0,1] neg_lo:[0,1] neg_hi:[0,1]
	v_pk_mul_f32 v[162:163], v[100:101], v[136:137] op_sel:[0,1]
	v_fma_f32 v118, v110, v116, -v112
	v_fma_f32 v119, v111, v117, v113
	v_fma_f32 v164, v100, v138, -v163
	v_fma_f32 v165, v101, v138, v162
	v_mul_f32_e32 v162, v138, v132
	v_mul_f32_e32 v163, v137, v133
	v_mul_f32_e32 v160, v138, v134
	v_mul_f32_e32 v161, v137, v135
	v_sub_f32_e32 v92, v92, v98
	v_sub_f32_e32 v93, v99, v93
	v_pk_add_f32 v[98:99], v[160:161], v[160:161] op_sel:[0,1] op_sel_hi:[0,1]
	v_pk_mul_f32 v[98:99], v[92:93], v[98:99] op_sel:[1,0] op_sel_hi:[0,1]
	v_pk_add_f32 v[110:111], v[162:163], v[162:163] op_sel:[0,1] op_sel_hi:[0,1] neg_lo:[0,1] neg_hi:[0,1]
	v_fma_f32 v112, v92, v110, -v98
	v_fma_f32 v113, v93, v111, v99
	v_pk_add_f32 v[98:99], v[104:105], v[108:109] neg_lo:[0,1] neg_hi:[0,1]
	v_pk_add_f32 v[92:93], v[102:103], v[106:107] neg_lo:[0,1] neg_hi:[0,1]
	v_pk_add_f32 v[86:87], v[94:95], v[86:87] neg_lo:[0,1] neg_hi:[0,1]
	v_pk_add_f32 v[102:103], v[92:93], v[98:99] op_sel:[0,1] op_sel_hi:[1,0]
	v_pk_add_f32 v[92:93], v[92:93], v[98:99] op_sel:[0,1] op_sel_hi:[1,0] neg_lo:[0,1] neg_hi:[0,1]
	v_pk_add_f32 v[94:95], v[84:85], v[86:87] op_sel:[0,1] op_sel_hi:[1,0]
	v_pk_mul_f32 v[104:105], v[92:93], v[158:159] op_sel:[1,0]
	v_pk_add_f32 v[84:85], v[84:85], v[86:87] op_sel:[0,1] op_sel_hi:[1,0] neg_lo:[0,1] neg_hi:[0,1]
	v_pk_mul_f32 v[166:167], v[152:153], v[134:135]
	v_mov_b32_e32 v168, v154
	v_pk_mov_b32 v[154:155], v[154:155], v[156:157] op_sel:[1,0]
	v_fma_f32 v106, v102, v144, -v104
	v_fma_f32 v107, v102, v153, v105
	ds_write_b64 v127, v[164:165] offset:6528
	v_pk_mul_f32 v[164:165], v[152:153], v[132:133]
	v_add_f32_e32 v156, v168, v154
	v_sub_f32_e32 v155, v157, v155
	v_mov_b32_e32 v99, v103
	v_pk_add_f32 v[104:105], v[166:167], v[166:167] op_sel:[0,1] op_sel_hi:[0,1]
	v_mul_f32_e32 v96, v85, v155
	v_mul_f32_e32 v97, v94, v155
	v_mul_f32_e32 v102, v103, v104
	v_mul_f32_e32 v103, v92, v105
	v_pk_add_f32 v[104:105], v[164:165], v[164:165] op_sel:[0,1] op_sel_hi:[0,1] neg_lo:[0,1] neg_hi:[0,1]
	v_mov_b32_e32 v168, v156
	v_mov_b32_e32 v169, v155
	v_fma_f32 v154, v94, v156, -v96
	v_fma_f32 v155, v85, v156, v97
	v_fma_f32 v92, v92, v104, -v102
	v_fma_f32 v93, v99, v105, v103
	v_pk_mul_f32 v[96:97], v[134:135], v[168:169]
	ds_write_b64 v127, v[154:155] offset:10880
	v_pk_mul_f32 v[86:87], v[132:133], v[168:169]
	ds_write_b64 v127, v[146:147] offset:17408
	ds_write_b64 v127, v[142:143] offset:19584
	ds_write_b64 v127, v[92:93] offset:26112
	v_mov_b32_e32 v93, v95
	v_pk_add_f32 v[96:97], v[96:97], v[96:97] op_sel:[0,1] op_sel_hi:[0,1]
	v_mul_f32_e32 v94, v95, v96
	v_mul_f32_e32 v95, v84, v97
	v_pk_add_f32 v[86:87], v[86:87], v[86:87] op_sel:[0,1] op_sel_hi:[0,1] neg_lo:[0,1] neg_hi:[0,1]
	v_fma_f32 v84, v84, v86, -v94
	v_fma_f32 v85, v93, v87, v95
	v_pk_mul_f32 v[80:81], v[132:133], v[150:151]
	ds_write_b64 v127, v[84:85] offset:28288
	v_mov_b32_e32 v85, v80
	v_pk_mul_f32 v[140:141], v[134:135], v[150:151]
	v_sub_f32_e32 v80, v82, v83
	v_sub_f32_e32 v81, v85, v81
	v_pk_add_f32 v[84:85], v[140:141], v[140:141] op_sel:[0,1] op_sel_hi:[0,1]
	v_mul_f32_e32 v82, v2, v84
	v_mul_f32_e32 v83, v80, v85
	v_pk_mov_b32 v[2:3], v[80:81], v[2:3] op_sel:[1,0]
	v_pk_mul_f32 v[100:101], v[152:153], v[136:137] op_sel:[0,1]
	v_fma_f32 v84, v80, v2, -v82
	v_fma_f32 v85, v81, v3, v83
	v_fma_f32 v136, v152, v138, -v101
	v_fma_f32 v101, v153, v138, v100
	v_sub_f32_e32 v2, v5, v91
	v_sub_f32_e32 v3, v88, v78
	v_sub_f32_e32 v4, v90, v4
	v_sub_f32_e32 v5, v89, v79
	v_mov_b32_e32 v139, v101
	v_pk_add_f32 v[78:79], v[4:5], v[2:3]
	v_pk_add_f32 v[2:3], v[4:5], v[2:3] neg_lo:[0,1] neg_hi:[0,1]
	v_mov_b32_e32 v138, v136
	v_mul_f32_e32 v80, v3, v101
	v_mul_f32_e32 v81, v3, v136
	v_pk_mul_f32 v[134:135], v[134:135], v[138:139]
	v_fma_f32 v82, v78, v136, -v80
	v_fma_f32 v83, v78, v139, v81
	v_pk_mul_f32 v[132:133], v[132:133], v[138:139]
	v_mov_b32_e32 v5, v79
	v_pk_add_f32 v[80:81], v[134:135], v[134:135] op_sel:[0,1] op_sel_hi:[0,1]
	v_mul_f32_e32 v78, v79, v80
	v_mul_f32_e32 v79, v2, v81
	v_pk_add_f32 v[80:81], v[132:133], v[132:133] op_sel:[0,1] op_sel_hi:[0,1] neg_lo:[0,1] neg_hi:[0,1]
	v_fma_f32 v2, v2, v80, -v78
	v_fma_f32 v3, v5, v81, v79
	ds_write_b64 v127, v[118:119] offset:21760
	ds_write_b64 v127, v[2:3] offset:32640
	v_mov_b32_e32 v2, v1
	ds_write_b64 v127, v[112:113] offset:23936
	ds_write_b64 v127, v[106:107] offset:8704
	ds_write_b64 v127, v[84:85] offset:30464
	ds_write_b64 v127, v[82:83] offset:15232
	s_waitcnt lgkmcnt(0)
	s_barrier
	s_mov_b32 s2, s20
	v_ashrrev_i32_e32 v3, 31, v2
	v_lshrrev_b32_e32 v3, 28, v3
	v_and_b32_e32 v115, 15, v2
	v_add_u32_e32 v2, v2, v3
	v_ashrrev_i32_e32 v2, 4, v2
	v_lshlrev_b32_e32 v3, 11, v2
	v_lshl_add_u32 v2, v2, 7, v3
	v_lshl_or_b32 v127, v115, 3, v2
	ds_read2_b64 v[84:87], v127 offset1:17
	ds_read2_b64 v[88:91], v127 offset0:68 offset1:85
	ds_read2_b64 v[92:95], v127 offset0:136 offset1:153
	ds_read2_b64 v[96:99], v127 offset0:170 offset1:187
	ds_read2_b64 v[100:103], v127 offset0:204 offset1:221
	ds_read2_b64 v[104:107], v127 offset0:238 offset1:255
	ds_read2_b64 v[108:111], v127 offset0:34 offset1:51
	ds_read2_b64 v[116:119], v127 offset0:102 offset1:119
	s_waitcnt lgkmcnt(5)
	v_pk_add_f32 v[82:83], v[92:93], v[84:85]
	s_waitcnt lgkmcnt(2)
	v_pk_mov_b32 v[140:141], v[98:99], v[106:107] op_sel:[1,0]
	s_waitcnt lgkmcnt(1)
	v_pk_add_f32 v[136:137], v[110:111], v[98:99]
	s_waitcnt lgkmcnt(0)
	v_pk_add_f32 v[138:139], v[118:119], v[106:107]
	v_mov_b32_e32 v99, v107
	v_pk_add_f32 v[106:107], v[136:137], v[138:139] neg_lo:[0,1] neg_hi:[0,1]
	v_sub_f32_e32 v140, v111, v140
	v_sub_f32_e32 v141, v118, v141
	v_pk_add_f32 v[80:81], v[136:137], v[138:139]
	v_mul_f32_e32 v136, 0x3f3504f3, v107
	v_mul_f32_e32 v139, 0xbf3504f3, v107
	v_cvt_f32_i32_e32 v107, v115
	v_sub_f32_e32 v98, v110, v98
	v_sub_f32_e32 v99, v119, v99
	v_pk_add_f32 v[92:93], v[84:85], v[92:93] neg_lo:[0,1] neg_hi:[0,1]
	v_add_f32_e32 v107, v107, v107
	v_pk_add_f32 v[84:85], v[88:89], v[100:101] neg_lo:[0,1] neg_hi:[0,1]
	v_pk_add_f32 v[112:113], v[100:101], v[88:89]
	v_pk_add_f32 v[120:121], v[86:87], v[94:95]
	v_pk_add_f32 v[128:129], v[90:91], v[102:103]
	v_sub_f32_e32 v110, v98, v99
	v_mul_f32_e32 v107, 0x3b800000, v107
	v_pk_mov_b32 v[88:89], v[84:85], v[84:85] op_sel:[1,0]
	v_add_f32_e32 v100, v92, v85
	v_sub_f32_e32 v101, v93, v84
	v_pk_add_f32 v[98:99], v[98:99], v[98:99] op_sel:[0,1] op_sel_hi:[0,1]
	v_pk_add_f32 v[4:5], v[120:121], v[128:129]
	v_pk_add_f32 v[130:131], v[108:109], v[96:97]
	v_pk_add_f32 v[132:133], v[116:117], v[104:105]
	v_pk_add_f32 v[120:121], v[120:121], v[128:129] neg_lo:[0,1] neg_hi:[0,1]
	v_mul_f32_e32 v107, 0.5, v107
	v_pk_add_f32 v[84:85], v[140:141], v[140:141] op_sel:[0,1] op_sel_hi:[0,1] neg_lo:[0,1] neg_hi:[0,1]
	v_pk_mul_f32 v[98:99], v[98:99], s[38:39]
	v_pk_add_f32 v[78:79], v[130:131], v[132:133]
	v_pk_add_f32 v[134:135], v[130:131], v[132:133] neg_lo:[0,1] neg_hi:[0,1]
	v_add_f32_e32 v118, v140, v141
	v_pk_mul_f32 v[128:129], v[120:121], s[20:21] op_sel_hi:[1,0]
	v_mul_f32_e32 v106, 0x3f3504f3, v106
	v_sin_f32_e32 v130, v107
	s_nop 1
	v_cos_f32_e32 v148, v107
	s_nop 1
	v_fma_f32 v140, v84, s40, v98
	v_fma_f32 v141, v85, s41, -v99
	v_pk_add_f32 v[2:3], v[82:83], v[112:113]
	v_mov_b32_e32 v84, v82
	v_sub_f32_e32 v82, v136, v106
	v_sub_f32_e32 v83, v83, v113
	v_sub_f32_e32 v84, v84, v112
	v_sub_f32_e32 v85, v129, v128
	v_mov_b32_e32 v99, v106
	v_pk_add_f32 v[106:107], v[82:83], v[134:135] op_sel:[1,0] op_sel_hi:[0,1]
	v_mov_b32_e32 v113, v134
	v_sub_f32_e32 v98, v131, v133
	v_sub_f32_e32 v99, v139, v99
	v_sub_f32_e32 v134, v108, v96
	v_sub_f32_e32 v135, v86, v94
	v_sub_f32_e32 v136, v117, v105
	v_sub_f32_e32 v137, v91, v103
	v_mul_f32_e32 v115, 0x3f6c835e, v118
	v_mul_f32_e32 v150, 0x3ec3ef15, v110
	v_sub_f32_e32 v86, v109, v97
	v_sub_f32_e32 v87, v87, v95
	v_sub_f32_e32 v91, v90, v102
	v_sub_f32_e32 v90, v116, v104
	v_pk_add_f32 v[96:97], v[134:135], v[136:137] neg_lo:[0,1] neg_hi:[0,1]
	v_pk_fma_f32 v[120:121], v[120:121], s[20:21], v[128:129] op_sel:[0,0,1] op_sel_hi:[1,0,0]
	v_pk_add_f32 v[138:139], v[134:135], v[136:137]
	v_pk_add_f32 v[94:95], v[86:87], v[90:91] neg_lo:[0,1] neg_hi:[0,1]
	v_pk_add_f32 v[86:87], v[86:87], v[90:91]
	v_mov_b32_e32 v103, v93
	v_mov_b32_e32 v91, v89
	v_mov_b32_e32 v112, v120
	v_pk_add_f32 v[120:121], v[120:121], v[82:83] neg_lo:[0,1] neg_hi:[0,1]
	v_mul_f32_e32 v90, 0x3ec3ef15, v97
	v_pk_mul_f32 v[104:105], v[96:97], s[20:21]
	v_mul_f32_e32 v97, s73, v96
	v_mul_f32_e32 v96, s72, v118
	v_sub_f32_e32 v88, v92, v88
	v_sub_f32_e32 v89, v150, v115
	v_pk_mul_f32 v[92:93], v[138:139], s[40:41] op_sel:[1,0]
	v_add_f32_e32 v128, v82, v112
	v_sub_f32_e32 v113, v83, v113
	v_pk_add_f32 v[82:83], v[106:107], v[120:121]
	v_mul_f32_e32 v102, 0x3f6c835e, v87
	v_mul_f32_e32 v107, 0x3f3504f3, v138
	v_mul_f32_e32 v108, 0x3f3504f3, v94
	v_pk_fma_f32 v[104:105], v[86:87], s[70:71], v[104:105] neg_lo:[0,0,1] neg_hi:[0,0,1]
	v_fma_f32 v87, v86, s31, -v97
	v_fma_f32 v86, v110, s30, -v96
	v_fma_f32 v96, v95, s38, v92
	v_fma_f32 v97, v95, s39, -v93
	v_pk_add_f32 v[90:91], v[102:103], v[90:91]
	v_add_f32_e32 v92, v108, v107
	v_fma_f32 v93, v94, s20, -v107
	v_pk_add_f32 v[94:95], v[100:101], v[92:93]
	v_pk_add_f32 v[102:103], v[96:97], v[140:141]
	v_xor_b32_e32 v149, 0x80000000, v130
	v_pk_add_f32 v[108:109], v[102:103], v[94:95]
	v_pk_add_f32 v[142:143], v[2:3], v[78:79]
	v_pk_mul_f32 v[118:119], v[130:131], v[108:109] op_sel_hi:[0,1]
	v_fma_f32 v134, v148, v108, v119
	v_fma_f32 v135, v148, v109, -v118
	v_mov_b32_e32 v131, v148
	v_pk_add_f32 v[144:145], v[4:5], v[80:81]
	v_mul_f32_e32 v108, v130, v130
	v_mul_f32_e32 v109, v131, v149
	v_pk_add_f32 v[146:147], v[144:145], v[142:143]
	v_pk_fma_f32 v[118:119], v[148:149], v[148:149], v[108:109] op_sel_hi:[0,1,1] neg_lo:[0,0,1] neg_hi:[0,0,1]
	v_pk_fma_f32 v[108:109], v[148:149], v[148:149], v[108:109] op_sel_hi:[0,1,1]
	v_pk_add_f32 v[132:133], v[84:85], v[98:99]
	ds_write2_b64 v127, v[146:147], v[134:135] offset1:17
	v_pk_add_f32 v[84:85], v[84:85], v[98:99] neg_lo:[0,1] neg_hi:[0,1]
	v_add_f32_e32 v98, v132, v128
	v_add_f32_e32 v99, v133, v113
	v_mov_b32_e32 v134, v118
	v_mov_b32_e32 v135, v109
	v_mul_f32_e32 v146, v109, v109
	v_mul_f32_e32 v147, v109, v118
	v_pk_mul_f32 v[108:109], v[98:99], v[108:109] op_sel:[1,1] op_sel_hi:[0,1]
	v_pk_fma_f32 v[150:151], v[118:119], v[134:135], v[146:147] op_sel_hi:[0,1,1] neg_lo:[0,0,1] neg_hi:[0,0,1]
	v_pk_fma_f32 v[146:147], v[118:119], v[134:135], v[146:147] op_sel_hi:[0,1,1]
	v_fma_f32 v160, v98, v118, -v108
	v_fma_f32 v161, v99, v118, v109
	v_pk_mul_f32 v[108:109], v[134:135], v[146:147] op_sel:[0,1]
	v_pk_add_f32 v[96:97], v[96:97], v[140:141] neg_lo:[0,1] neg_hi:[0,1]
	v_fma_f32 v118, v134, v150, -v109
	v_fma_f32 v109, v135, v150, v108
	v_sub_f32_e32 v106, v106, v120
	v_mov_b32_e32 v141, v109
	v_mov_b32_e32 v149, v130
	v_mov_b32_e32 v152, v150
	v_mov_b32_e32 v153, v147
	v_pk_add_f32 v[162:163], v[84:85], v[84:85] op_sel:[0,1] op_sel_hi:[0,1]
	v_mul_f32_e32 v107, v106, v118
	v_mul_f32_e32 v106, v106, v109
	v_pk_mul_f32 v[136:137], v[148:149], v[134:135]
	v_pk_mul_f32 v[138:139], v[130:131], v[134:135]
	v_mov_b32_e32 v140, v118
	v_fma_f32 v108, v162, v118, -v106
	v_pk_mul_f32 v[118:119], v[152:153], v[146:147] op_sel:[0,1]
	v_pk_add_f32 v[94:95], v[94:95], v[102:103] neg_lo:[0,1] neg_hi:[0,1]
	v_pk_add_f32 v[102:103], v[104:105], v[88:89]
	v_pk_add_f32 v[110:111], v[90:91], v[86:87]
	v_fma_f32 v109, v163, v141, v107
	v_pk_fma_f32 v[120:121], v[150:151], v[152:153], v[118:119] op_sel:[0,0,1] op_sel_hi:[0,1,0] neg_lo:[0,0,1] neg_hi:[0,0,1]
	v_pk_fma_f32 v[118:119], v[150:151], v[152:153], v[118:119] op_sel:[0,0,1] op_sel_hi:[0,1,0]
	v_mov_b32_e32 v164, v136
	v_pk_mov_b32 v[136:137], v[136:137], v[138:139] op_sel:[1,0]
	v_pk_add_f32 v[116:117], v[102:103], v[110:111]
	v_pk_add_f32 v[106:107], v[142:143], v[144:145] neg_lo:[0,1] neg_hi:[0,1]
	v_pk_mov_b32 v[144:145], v[118:119], v[120:121] op_sel:[1,0]
	v_add_f32_e32 v138, v164, v136
	v_sub_f32_e32 v136, v164, v136
	v_sub_f32_e32 v137, v139, v137
	v_pk_mul_f32 v[154:155], v[148:149], v[152:153]
	v_pk_mul_f32 v[156:157], v[130:131], v[152:153]
	v_pk_add_f32 v[92:93], v[100:101], v[92:93] neg_lo:[0,1] neg_hi:[0,1]
	v_mov_b32_e32 v142, v120
	v_mov_b32_e32 v143, v119
	v_pk_mul_f32 v[130:131], v[130:131], v[144:145] op_sel_hi:[0,1]
	v_pk_mul_f32 v[166:167], v[116:117], v[136:137] op_sel:[0,1]
	v_pk_mov_b32 v[158:159], v[146:147], v[150:151] op_sel:[1,0]
	v_pk_add_f32 v[98:99], v[92:93], v[96:97] op_sel:[0,1] op_sel_hi:[1,0]
	v_pk_add_f32 v[92:93], v[92:93], v[96:97] op_sel:[0,1] op_sel_hi:[1,0] neg_lo:[0,1] neg_hi:[0,1]
	v_fma_f32 v146, v148, v142, v130
	v_fma_f32 v131, v148, v143, -v131
	v_fma_f32 v168, v116, v138, -v167
	v_fma_f32 v169, v117, v138, v166
	v_mov_b32_e32 v170, v154
	v_pk_mov_b32 v[154:155], v[154:155], v[156:157] op_sel:[1,0]
	v_mov_b32_e32 v149, v131
	v_pk_mul_f32 v[116:117], v[152:153], v[136:137] op_sel:[0,1]
	v_add_f32_e32 v156, v170, v154
	v_sub_f32_e32 v155, v157, v155
	v_mov_b32_e32 v165, v137
	v_fma_f32 v136, v152, v138, -v117
	v_fma_f32 v117, v153, v138, v116
	v_mul_f32_e32 v100, v93, v155
	v_mul_f32_e32 v101, v98, v155
	v_mul_f32_e32 v130, v95, v131
	v_mul_f32_e32 v131, v95, v146
	v_mov_b32_e32 v164, v138
	v_mov_b32_e32 v138, v136
	v_mov_b32_e32 v139, v117
	v_mov_b32_e32 v170, v156
	v_mov_b32_e32 v171, v155
	v_fma_f32 v154, v98, v156, -v100
	v_fma_f32 v155, v93, v156, v101
	v_fma_f32 v146, v94, v146, -v130
	v_fma_f32 v147, v94, v149, v131
	v_pk_mul_f32 v[118:119], v[106:107], v[118:119] op_sel:[1,1] op_sel_hi:[0,1]
	v_pk_mul_f32 v[162:163], v[134:135], v[142:143]
	v_pk_mul_f32 v[134:135], v[134:135], v[144:145]
	ds_write2_b64 v127, v[160:161], v[168:169] offset0:34 offset1:51
	v_pk_mul_f32 v[160:161], v[164:165], v[142:143]
	v_pk_mul_f32 v[164:165], v[164:165], v[144:145]
	v_pk_mul_f32 v[166:167], v[152:153], v[142:143]
	v_pk_mul_f32 v[168:169], v[152:153], v[144:145]
	v_pk_mul_f32 v[96:97], v[142:143], v[170:171]
	v_pk_mul_f32 v[100:101], v[144:145], v[170:171]
	v_pk_mul_f32 v[94:95], v[142:143], v[140:141]
	v_pk_mul_f32 v[130:131], v[144:145], v[140:141]
	v_pk_mul_f32 v[140:141], v[142:143], v[138:139]
	v_pk_mul_f32 v[142:143], v[144:145], v[138:139]
	v_fma_f32 v144, v106, v120, -v118
	v_fma_f32 v145, v107, v120, v119
	v_sub_f32_e32 v106, v132, v128
	v_sub_f32_e32 v107, v113, v133
	v_pk_add_f32 v[112:113], v[134:135], v[134:135] op_sel:[0,1] op_sel_hi:[0,1]
	v_pk_mul_f32 v[112:113], v[106:107], v[112:113] op_sel:[1,0] op_sel_hi:[0,1]
	v_pk_add_f32 v[118:119], v[162:163], v[162:163] op_sel:[0,1] op_sel_hi:[0,1] neg_lo:[0,1] neg_hi:[0,1]
	v_fma_f32 v120, v106, v118, -v112
	v_fma_f32 v121, v107, v119, v113
	v_pk_add_f32 v[2:3], v[2:3], v[78:79] neg_lo:[0,1] neg_hi:[0,1]
	v_sub_f32_e32 v102, v102, v110
	v_sub_f32_e32 v103, v111, v103
	v_pk_add_f32 v[106:107], v[164:165], v[164:165] op_sel:[0,1] op_sel_hi:[0,1]
	v_pk_add_f32 v[4:5], v[4:5], v[80:81] neg_lo:[0,1] neg_hi:[0,1]
	v_pk_mul_f32 v[106:107], v[102:103], v[106:107] op_sel:[1,0] op_sel_hi:[0,1]
	v_pk_add_f32 v[110:111], v[160:161], v[160:161] op_sel:[0,1] op_sel_hi:[0,1] neg_lo:[0,1] neg_hi:[0,1]
	v_pk_add_f32 v[78:79], v[2:3], v[4:5] op_sel:[0,1] op_sel_hi:[1,0]
	v_pk_add_f32 v[2:3], v[2:3], v[4:5] op_sel:[0,1] op_sel_hi:[1,0] neg_lo:[0,1] neg_hi:[0,1]
	v_fma_f32 v112, v102, v110, -v106
	v_fma_f32 v113, v103, v111, v107
	v_pk_mul_f32 v[80:81], v[2:3], v[158:159] op_sel:[1,0]
	v_fma_f32 v102, v78, v150, -v80
	v_fma_f32 v103, v78, v153, v81
	v_mov_b32_e32 v5, v79
	v_pk_add_f32 v[80:81], v[168:169], v[168:169] op_sel:[0,1] op_sel_hi:[0,1]
	v_mul_f32_e32 v78, v79, v80
	v_mul_f32_e32 v79, v2, v81
	v_pk_add_f32 v[80:81], v[166:167], v[166:167] op_sel:[0,1] op_sel_hi:[0,1] neg_lo:[0,1] neg_hi:[0,1]
	v_fma_f32 v2, v2, v80, -v78
	v_fma_f32 v3, v5, v81, v79
	v_pk_add_f32 v[80:81], v[100:101], v[100:101] op_sel:[0,1] op_sel_hi:[0,1]
	v_mul_f32_e32 v78, v99, v80
	v_mul_f32_e32 v79, v92, v81
	v_pk_add_f32 v[80:81], v[96:97], v[96:97] op_sel:[0,1] op_sel_hi:[0,1] neg_lo:[0,1] neg_hi:[0,1]
	v_fma_f32 v92, v92, v80, -v78
	v_fma_f32 v93, v99, v81, v79
	v_pk_add_f32 v[78:79], v[130:131], v[130:131] op_sel:[0,1] op_sel_hi:[0,1]
	ds_write2_b64 v127, v[2:3], v[92:93] offset0:204 offset1:221
	v_sub_f32_e32 v2, v84, v85
	v_sub_f32_e32 v3, v94, v95
	v_mul_f32_e32 v4, v82, v78
	v_mul_f32_e32 v5, v2, v79
	v_pk_mov_b32 v[78:79], v[2:3], v[82:83] op_sel:[1,0]
	v_fma_f32 v80, v2, v78, -v4
	v_fma_f32 v81, v3, v79, v5
	v_sub_f32_e32 v2, v88, v104
	v_sub_f32_e32 v3, v90, v86
	v_sub_f32_e32 v4, v105, v89
	v_sub_f32_e32 v5, v91, v87
	ds_write2_b64 v127, v[144:145], v[146:147] offset0:136 offset1:153
	v_pk_add_f32 v[78:79], v[4:5], v[2:3]
	v_sub_f32_e32 v82, v2, v4
	v_sub_f32_e32 v2, v5, v3
	v_mul_f32_e32 v3, v2, v136
	v_mul_f32_e32 v2, v2, v117
	v_fma_f32 v4, v78, v136, -v2
	v_fma_f32 v5, v78, v139, v3
	ds_write2_b64 v127, v[108:109], v[4:5] offset0:102 offset1:119
	v_pk_add_f32 v[4:5], v[142:143], v[142:143] op_sel:[0,1] op_sel_hi:[0,1]
	v_mul_f32_e32 v2, v79, v4
	v_mul_f32_e32 v3, v82, v5
	v_pk_add_f32 v[4:5], v[140:141], v[140:141] op_sel:[0,1] op_sel_hi:[0,1] neg_lo:[0,1] neg_hi:[0,1]
	v_fma_f32 v78, v82, v4, -v2
	v_fma_f32 v79, v79, v5, v3
	ds_write2_b64 v127, v[120:121], v[112:113] offset0:170 offset1:187
	v_mov_b32_e32 v2, v1
	ds_write2_b64 v127, v[102:103], v[154:155] offset0:68 offset1:85
	ds_write2_b64 v127, v[80:81], v[78:79] offset0:238 offset1:255
	s_waitcnt lgkmcnt(0)
	s_barrier
	s_mov_b32 s77, s71
	v_mul_lo_u32 v102, v2, s33
	ds_read2_b64 v[2:5], v102 offset1:1
	ds_read2_b64 v[78:81], v102 offset0:2 offset1:3
	ds_read2_b64 v[82:85], v102 offset0:9 offset1:10
	ds_read2_b64 v[86:89], v102 offset0:4 offset1:5
	ds_read2_b64 v[90:93], v102 offset0:6 offset1:7
	ds_read2_b64 v[94:97], v102 offset0:13 offset1:14
	ds_read2_b64 v[98:101], v102 offset0:8 offset1:15
	ds_read2_b64 v[102:105], v102 offset0:11 offset1:12
	s_waitcnt lgkmcnt(5)
	v_add_f32_e32 v106, v4, v82
	s_waitcnt lgkmcnt(3)
	s_waitcnt lgkmcnt(2)
	v_add_f32_e32 v108, v88, v94
	s_waitcnt lgkmcnt(1)
	v_pk_add_f32 v[132:133], v[2:3], v[98:99]
	v_pk_add_f32 v[2:3], v[2:3], v[98:99] neg_lo:[0,1] neg_hi:[0,1]
	s_waitcnt lgkmcnt(0)
	v_pk_add_f32 v[98:99], v[86:87], v[104:105]
	v_pk_add_f32 v[86:87], v[86:87], v[104:105] neg_lo:[0,1] neg_hi:[0,1]
	v_add_f32_e32 v107, v106, v108
	v_sub_f32_e32 v106, v106, v108
	v_mov_b32_e32 v128, v79
	v_add_f32_e32 v134, v2, v87
	v_sub_f32_e32 v135, v3, v86
	v_add_f32_e32 v108, v80, v102
	v_add_f32_e32 v109, v92, v100
	v_mov_b32_e32 v130, v91
	v_add_f32_e32 v115, v5, v83
	v_add_f32_e32 v110, v81, v103
	v_add_f32_e32 v111, v93, v101
	v_mov_b32_e32 v112, v81
	v_add_f32_e32 v136, v79, v85
	v_add_f32_e32 v137, v78, v84
	v_mov_b32_e32 v79, v4
	v_sub_f32_e32 v4, v128, v85
	v_sub_f32_e32 v5, v5, v83
	v_add_f32_e32 v119, v89, v95
	v_sub_f32_e32 v80, v80, v102
	v_sub_f32_e32 v81, v93, v101
	v_sub_f32_e32 v78, v78, v84
	v_sub_f32_e32 v79, v79, v82
	v_add_f32_e32 v82, v91, v97
	v_add_f32_e32 v83, v90, v96
	v_mov_b32_e32 v91, v88
	v_sub_f32_e32 v88, v130, v97
	v_sub_f32_e32 v89, v89, v95
	v_mov_b32_e32 v117, v100
	v_pk_add_f32 v[100:101], v[80:81], v[80:81] op_sel_hi:[0,1] neg_lo:[0,1] neg_hi:[0,1]
	v_sub_f32_e32 v84, v90, v96
	v_sub_f32_e32 v85, v91, v94
	v_sub_f32_e32 v112, v112, v103
	v_sub_f32_e32 v113, v92, v117
	v_pk_add_f32 v[96:97], v[78:79], v[88:89] neg_lo:[0,1] neg_hi:[0,1]
	v_pk_add_f32 v[128:129], v[4:5], v[84:85]
	v_add_f32_e32 v80, v80, v81
	v_add_f32_e32 v81, v78, v88
	v_mov_b32_e32 v131, v4
	v_sub_f32_e32 v4, v5, v85
	v_add_f32_e32 v78, v79, v89
	v_pk_add_f32 v[102:103], v[112:113], v[112:113] op_sel:[0,1] op_sel_hi:[1,0]
	v_mov_b32_e32 v130, v112
	v_pk_mov_b32 v[112:113], v[112:113], v[84:85] op_sel:[1,0]
	v_pk_mul_f32 v[84:85], v[4:5], s[38:39] op_sel_hi:[0,1]
	v_pk_mul_f32 v[78:79], v[78:79], s[40:41] op_sel_hi:[0,1]
	v_pk_add_f32 v[112:113], v[130:131], v[112:113] neg_lo:[0,1] neg_hi:[0,1]
	v_sub_f32_e32 v118, v115, v119
	v_pk_add_f32 v[92:93], v[108:109], v[108:109] op_sel:[0,1] op_sel_hi:[1,0]
	v_sub_f32_e32 v108, v108, v109
	v_add_f32_e32 v88, v2, v87
	v_add_f32_e32 v89, v84, v78
	v_fma_f32 v130, v4, s38, v78
	v_fma_f32 v131, v4, s39, -v79
	v_mul_f32_e32 v109, 0x3f3504f3, v106
	v_mul_f32_e32 v117, 0x3f3504f3, v118
	v_mul_f32_e32 v120, 0x3f3504f3, v108
	v_mul_f32_e32 v104, 0x3ec3ef15, v97
	v_mul_f32_e32 v84, 0x3f6c835e, v129
	v_sub_f32_e32 v4, v85, v79
	v_sub_f32_e32 v5, v3, v86
	v_sub_f32_e32 v78, v132, v98
	v_sub_f32_e32 v79, v117, v109
	v_add_f32_e32 v84, v84, v104
	v_add_f32_e32 v85, v3, v86
	v_pk_mul_f32 v[104:105], v[80:81], s[72:73]
	v_pk_mul_f32 v[108:109], v[80:81], s[74:75]
	v_pk_mul_f32 v[80:81], v[80:81], s[38:39] op_sel_hi:[0,1]
	v_fma_f32 v150, v112, s40, v80
	v_fma_f32 v151, v112, s41, -v81
	v_pk_add_f32 v[80:81], v[110:111], v[110:111] op_sel:[0,1] op_sel_hi:[0,1] neg_lo:[0,1] neg_hi:[0,1]
	v_pk_fma_f32 v[140:141], v[112:113], s[72:73], v[108:109] neg_lo:[0,0,1] neg_hi:[0,0,1]
	v_fmac_f32_e32 v109, 0x3f3504f3, v113
	v_pk_fma_f32 v[104:105], v[112:113], s[74:75], v[104:105]
	v_pk_mul_f32 v[112:113], v[80:81], s[2:3]
	v_mov_b32_e32 v121, v99
	v_mov_b32_e32 v144, v102
	v_sub_f32_e32 v152, v112, v120
	v_sub_f32_e32 v153, v133, v121
	v_pk_fma_f32 v[80:81], v[80:81], s[2:3], v[120:121] op_sel_hi:[1,1,0] neg_lo:[0,0,1] neg_hi:[0,0,1]
	v_pk_mul_f32 v[102:103], v[102:103], s[38:39] op_sel_hi:[0,1]
	v_mul_f32_e32 v3, s77, v101
	v_pk_add_f32 v[138:139], v[132:133], v[98:99] neg_lo:[0,1] neg_hi:[0,1]
	v_add_f32_e32 v90, v133, v99
	v_add_f32_e32 v91, v136, v82
	v_pk_add_f32 v[94:95], v[136:137], v[82:83] neg_lo:[0,1] neg_hi:[0,1]
	v_mov_b32_e32 v143, v101
	v_pk_mov_b32 v[148:149], v[100:101], v[128:129] op_sel:[1,0]
	v_sub_f32_e32 v2, v2, v87
	v_sub_f32_e32 v3, v3, v103
	v_pk_fma_f32 v[86:87], v[100:101], s[76:77], v[102:103] op_sel:[1,0,0] neg_lo:[0,0,1] neg_hi:[0,0,1]
	v_pk_mov_b32 v[100:101], v[136:137], v[110:111] op_sel:[1,0]
	v_fmamk_f32 v118, v106, 0x3f3504f3, v117
	v_mov_b32_e32 v145, v96
	v_mov_b32_e32 v154, v82
	v_add_f32_e32 v98, v132, v98
	v_add_f32_e32 v99, v115, v119
	v_add_f32_e32 v82, v100, v83
	v_add_f32_e32 v83, v101, v111
	v_sub_f32_e32 v110, v138, v94
	v_add_f32_e32 v111, v139, v95
	v_pk_mul_f32 v[116:117], v[96:97], s[20:21]
	v_pk_mul_f32 v[96:97], v[144:145], s[74:75]
	v_pk_mul_f32 v[144:145], v[144:145], s[72:73]
	v_sub_f32_e32 v112, v136, v154
	v_sub_f32_e32 v113, v113, v120
	v_add_f32_e32 v94, v152, v118
	v_sub_f32_e32 v121, v153, v95
	v_mov_b32_e32 v142, v128
	v_pk_fma_f32 v[146:147], v[128:129], s[70:71], v[116:117] neg_lo:[0,0,1] neg_hi:[0,0,1]
	v_pk_fma_f32 v[128:129], v[128:129], s[2:3], v[116:117] op_sel_hi:[0,1,0] neg_lo:[0,0,1] neg_hi:[0,0,1]
	v_add_f32_e32 v100, v90, v91
	v_add_f32_e32 v101, v99, v83
	v_mov_b32_e32 v106, v98
	v_mov_b32_e32 v102, v82
	v_pk_add_f32 v[82:83], v[98:99], v[82:83] neg_lo:[0,1] neg_hi:[0,1]
	v_pk_add_f32 v[98:99], v[130:131], v[150:151]
	v_pk_add_f32 v[130:131], v[78:79], v[112:113]
	s_mov_b32 s42, s71
	s_mov_b32 s43, s3
	v_fma_f32 v116, v142, s78, -v116
	v_fma_f32 v117, v143, s79, -v144
	v_pk_fma_f32 v[142:143], v[148:149], s[30:31], v[144:145] neg_lo:[0,0,1] neg_hi:[0,0,1]
	v_add_f32_e32 v80, v118, v80
	v_add_f32_e32 v81, v79, v81
	v_add_f32_e32 v94, v130, v94
	v_add_f32_e32 v95, v131, v121
	v_pk_fma_f32 v[96:97], v[148:149], s[42:43], v[96:97] neg_lo:[0,0,1] neg_hi:[0,0,1]
	v_add_f32_e32 v102, v106, v102
	v_add_f32_e32 v103, v107, v92
	v_sub_f32_e32 v80, v130, v80
	v_sub_f32_e32 v81, v121, v81
	v_add_f32_e32 v120, v2, v128
	v_add_f32_e32 v121, v85, v129
	v_pk_add_f32 v[128:129], v[84:85], v[142:143]
	v_pk_add_f32 v[130:131], v[146:147], v[2:3]
	v_mov_b32_e32 v146, v84
	v_mov_b32_e32 v3, v84
	v_pk_add_f32 v[132:133], v[100:101], v[100:101] op_sel:[1,0] op_sel_hi:[1,0]
	v_mov_b32_e32 v106, v90
	v_pk_mov_b32 v[90:91], v[90:91], v[92:93] op_sel:[1,0]
	v_add_f32_e32 v92, v134, v109
	v_add_f32_e32 v93, v135, v141
	v_sub_f32_e32 v84, v147, v96
	v_sub_f32_e32 v85, v85, v97
	v_pk_add_f32 v[96:97], v[130:131], v[128:129]
	v_pk_add_f32 v[130:131], v[102:103], v[102:103] op_sel:[1,0] op_sel_hi:[1,0]
	v_pk_mul_f32 v[132:133], v[74:75], v[132:133]
	v_pk_add_f32 v[88:89], v[88:89], v[104:105] op_sel:[0,1] op_sel_hi:[1,0] neg_lo:[0,1] neg_hi:[0,1]
	v_pk_add_f32 v[104:105], v[98:99], v[92:93]
	v_fma_f32 v134, v14, v130, -v132
	v_fma_f32 v135, v15, v131, v133
	v_pk_add_f32 v[90:91], v[106:107], v[90:91] neg_lo:[0,1] neg_hi:[0,1]
	v_pk_mul_f32 v[130:131], v[24:25], v[104:105] op_sel:[0,1] op_sel_hi:[1,0]
	v_pk_add_f32 v[4:5], v[4:5], v[140:141] neg_lo:[0,1] neg_hi:[0,1]
	v_fma_f32 v132, v22, v104, -v130
	v_fma_f32 v105, v23, v105, v131
	v_pk_mul_f32 v[130:131], v[40:41], v[94:95] op_sel:[0,1] op_sel_hi:[1,0]
	v_pk_add_f32 v[92:93], v[92:93], v[98:99] neg_lo:[0,1] neg_hi:[0,1]
	v_pk_add_f32 v[98:99], v[4:5], v[88:89]
	v_sub_f32_e32 v107, v5, v89
	v_fma_f32 v136, v38, v94, -v130
	v_fma_f32 v95, v39, v95, v131
	v_pk_mul_f32 v[130:131], v[56:57], v[96:97] op_sel:[0,1] op_sel_hi:[1,0]
	v_pk_add_f32 v[140:141], v[90:91], v[90:91] op_sel:[0,1] op_sel_hi:[0,1] neg_lo:[0,1] neg_hi:[0,1]
	v_mov_b32_e32 v109, v107
	v_sub_f32_e32 v78, v79, v113
	v_sub_f32_e32 v79, v118, v152
	v_fma_f32 v138, v54, v96, -v130
	v_fma_f32 v97, v55, v97, v131
	v_pk_add_f32 v[130:131], v[82:83], v[82:83] op_sel:[0,1] op_sel_hi:[0,1]
	v_pk_mul_f32 v[140:141], v[70:71], v[140:141]
	v_pk_add_f32 v[112:113], v[110:111], v[78:79]
	v_pk_add_f32 v[78:79], v[110:111], v[78:79] neg_lo:[0,1] neg_hi:[0,1]
	v_fma_f32 v142, v18, v130, -v140
	v_fma_f32 v143, v19, v131, v141
	v_mul_f32_e32 v106, v32, v107
	v_mul_f32_e32 v107, v33, v98
	v_pk_add_f32 v[86:87], v[146:147], v[86:87]
	v_pk_add_f32 v[2:3], v[2:3], v[116:117] neg_lo:[0,1] neg_hi:[0,1]
	v_fma_f32 v130, v30, v98, -v106
	v_fma_f32 v107, v31, v109, v107
	v_pk_add_f32 v[86:87], v[120:121], v[86:87] neg_lo:[0,1] neg_hi:[0,1]
	v_pk_add_f32 v[116:117], v[84:85], v[2:3]
	v_sub_f32_e32 v121, v85, v3
	v_mul_f32_e32 v108, v48, v79
	v_mul_f32_e32 v109, v49, v112
	v_pk_add_f32 v[100:101], v[100:101], v[100:101] op_sel:[0,1] op_sel_hi:[0,1] neg_lo:[0,1] neg_hi:[0,1]
	v_fma_f32 v140, v46, v112, -v108
	v_fma_f32 v109, v47, v79, v109
	v_mul_f32_e32 v110, v64, v121
	v_mul_f32_e32 v111, v65, v116
	v_pk_add_f32 v[102:103], v[102:103], v[102:103] op_sel:[0,1] op_sel_hi:[0,1] neg_lo:[0,1] neg_hi:[0,1]
	v_pk_mul_f32 v[100:101], v[76:77], v[100:101]
	v_fma_f32 v120, v62, v116, -v110
	v_fma_f32 v111, v63, v121, v111
	v_fma_f32 v128, v16, v102, -v100
	v_fma_f32 v129, v17, v103, v101
	v_sub_f32_e32 v4, v88, v4
	v_pk_mul_f32 v[100:101], v[28:29], v[92:93] op_sel:[0,1] op_sel_hi:[1,0]
	v_pk_add_f32 v[90:91], v[90:91], v[90:91] op_sel:[1,0] op_sel_hi:[1,0]
	v_fma_f32 v102, v26, v92, -v100
	v_fma_f32 v93, v27, v93, v101
	v_pk_mul_f32 v[100:101], v[44:45], v[80:81] op_sel:[0,1] op_sel_hi:[1,0]
	v_mov_b32_e32 v88, v4
	v_sub_f32_e32 v2, v2, v84
	v_fma_f32 v144, v42, v80, -v100
	v_fma_f32 v81, v43, v81, v101
	v_pk_mul_f32 v[100:101], v[60:61], v[86:87] op_sel:[0,1] op_sel_hi:[1,0]
	v_pk_add_f32 v[82:83], v[82:83], v[82:83] op_sel:[0,1] op_sel_hi:[0,1] neg_lo:[0,1] neg_hi:[0,1]
	v_pk_mul_f32 v[90:91], v[72:73], v[90:91]
	v_mov_b32_e32 v118, v78
	v_mov_b32_e32 v84, v2
	v_fma_f32 v146, v58, v86, -v100
	v_fma_f32 v87, v59, v87, v101
	v_fma_f32 v100, v20, v82, -v90
	v_fma_f32 v101, v21, v83, v91
	v_mul_f32_e32 v5, v37, v4
	v_mul_f32_e32 v4, v36, v99
	v_fma_f32 v82, v34, v88, -v4
	v_fma_f32 v5, v35, v99, v5
	v_mul_f32_e32 v79, v53, v78
	v_mul_f32_e32 v78, v52, v113
	v_mul_f32_e32 v3, v69, v2
	v_mul_f32_e32 v2, v68, v117
	v_fma_f32 v88, v50, v118, -v78
	v_fma_f32 v90, v66, v84, -v2
	v_fma_f32 v3, v67, v117, v3
	v_mov_b32_e32 v4, v1
	v_fma_f32 v79, v51, v113, v79
	s_barrier
	v_add_f32_e32 v150, v136, v144
	v_add_f32_e32 v151, v95, v81
	v_add_f32_e32 v156, v138, v146
	v_add_f32_e32 v157, v97, v87
	v_mul_lo_u32 v115, v4, s33
	v_add_f32_e32 v158, v120, v90
	v_add_f32_e32 v159, v111, v3
	v_mov_b32_e32 v92, v81
	v_sub_f32_e32 v80, v138, v146
	v_sub_f32_e32 v81, v95, v81
	v_sub_f32_e32 v2, v111, v3
	v_sub_f32_e32 v3, v140, v88
	v_mov_b32_e32 v83, v5
	v_add_f32_e32 v116, v132, v102
	v_add_f32_e32 v117, v105, v93
	v_add_f32_e32 v152, v140, v88
	v_add_f32_e32 v153, v109, v79
	v_sub_f32_e32 v4, v109, v79
	v_sub_f32_e32 v5, v107, v5
	v_mov_b32_e32 v106, v88
	v_sub_f32_e32 v86, v97, v87
	v_sub_f32_e32 v87, v136, v144
	v_sub_f32_e32 v78, v120, v90
	v_sub_f32_e32 v79, v109, v79
	v_pk_add_f32 v[88:89], v[80:81], v[2:3]
	v_pk_add_f32 v[2:3], v[80:81], v[2:3] neg_lo:[0,1] neg_hi:[0,1]
	v_sub_f32_e32 v103, v132, v102
	v_sub_f32_e32 v102, v136, v144
	v_sub_f32_e32 v92, v95, v92
	v_sub_f32_e32 v93, v105, v93
	v_pk_add_f32 v[90:91], v[86:87], v[78:79] neg_lo:[0,1] neg_hi:[0,1]
	v_pk_add_f32 v[78:79], v[86:87], v[78:79]
	v_pk_add_f32 v[84:85], v[134:135], v[128:129]
	v_pk_add_f32 v[98:99], v[142:143], v[100:101]
	v_add_f32_e32 v118, v130, v82
	v_add_f32_e32 v119, v107, v83
	v_sub_f32_e32 v83, v130, v82
	v_sub_f32_e32 v82, v140, v106
	v_pk_add_f32 v[94:95], v[102:103], v[4:5]
	v_mul_f32_e32 v105, 0x3f3504f3, v89
	v_mul_f32_e32 v80, s74, v88
	v_mul_f32_e32 v81, s75, v3
	v_mul_f32_e32 v4, 0x3f6c835e, v90
	v_pk_add_f32 v[112:113], v[84:85], v[98:99]
	v_pk_add_f32 v[154:155], v[150:151], v[152:153]
	v_pk_add_f32 v[160:161], v[156:157], v[158:159]
	v_pk_add_f32 v[84:85], v[84:85], v[98:99] neg_lo:[0,1] neg_hi:[0,1]
	v_pk_add_f32 v[98:99], v[150:151], v[152:153] neg_lo:[0,1] neg_hi:[0,1]
	v_fma_f32 v80, v90, s72, -v80
	v_fma_f32 v81, v79, s73, -v81
	v_fma_f32 v86, v88, s80, -v4
	v_add_f32_e32 v4, v93, v83
	v_pk_add_f32 v[148:149], v[116:117], v[118:119]
	v_pk_add_f32 v[100:101], v[142:143], v[100:101] neg_lo:[0,1] neg_hi:[0,1]
	v_mov_b32_e32 v150, v116
	v_sub_f32_e32 v116, v117, v119
	v_sub_f32_e32 v117, v157, v159
	v_pk_add_f32 v[96:97], v[92:93], v[82:83] neg_lo:[0,1] neg_hi:[0,1]
	v_pk_mul_f32 v[82:83], v[4:5], s[38:39] op_sel_hi:[0,1]
	v_sub_f32_e32 v4, v103, v5
	v_pk_add_f32 v[128:129], v[134:135], v[128:129] neg_lo:[0,1] neg_hi:[0,1]
	v_mov_b32_e32 v135, v100
	v_sub_f32_e32 v150, v150, v118
	v_sub_f32_e32 v151, v156, v158
	v_pk_mul_f32 v[116:117], v[116:117], s[20:21] op_sel_hi:[1,0]
	v_fma_f32 v92, v4, s40, -v82
	v_fma_f32 v93, v4, s41, v83
	v_fma_f32 v119, v151, s3, -v117
	v_fma_f32 v152, v150, s2, v116
	v_pk_fma_f32 v[116:117], v[150:151], s[20:21], v[116:117] op_sel_hi:[1,0,1] neg_lo:[0,0,1] neg_hi:[0,0,1]
	v_pk_add_f32 v[150:151], v[84:85], v[98:99] op_sel:[0,1] op_sel_hi:[1,0] neg_lo:[0,1] neg_hi:[0,1]
	v_pk_add_f32 v[84:85], v[84:85], v[98:99] op_sel:[0,1] op_sel_hi:[1,0]
	v_mul_f32_e32 v134, 0x3f6c835e, v97
	s_mov_b32 s42, s3
	s_mov_b32 s43, s21
	v_pk_mul_f32 v[96:97], v[96:97], s[70:71]
	v_pk_mul_f32 v[4:5], v[78:79], s[40:41] op_sel_hi:[0,1]
	v_sub_f32_e32 v142, v128, v101
	v_pk_add_f32 v[100:101], v[128:129], v[100:101] op_sel:[0,1] op_sel_hi:[1,0]
	v_mov_b32_e32 v99, v85
	v_mul_f32_e32 v128, 0x3ec3ef15, v95
	v_mul_f32_e32 v85, 0x3f3504f3, v91
	v_fma_f32 v106, v94, s42, -v96
	v_fma_f32 v95, v95, s43, v97
	v_fma_f32 v78, v2, s38, -v4
	v_fma_f32 v79, v2, s39, v5
	v_mov_b32_e32 v143, v101
	v_pk_add_f32 v[88:89], v[128:129], v[134:135] neg_lo:[0,1] neg_hi:[0,1]
	v_sub_f32_e32 v104, v85, v105
	v_fmac_f32_e32 v105, 0x3f3504f3, v91
	v_pk_add_f32 v[162:163], v[112:113], v[154:155]
	v_pk_add_f32 v[164:165], v[148:149], v[160:161]
	v_pk_add_f32 v[2:3], v[142:143], v[104:105]
	v_pk_add_f32 v[4:5], v[92:93], v[78:79]
	v_add_f32_e32 v90, v106, v100
	v_add_f32_e32 v91, v95, v86
	v_pk_add_f32 v[96:97], v[88:89], v[80:81]
	v_pk_add_f32 v[166:167], v[162:163], v[164:165]
	v_mov_b32_e32 v98, v150
	v_add_f32_e32 v156, v116, v119
	v_add_f32_e32 v157, v117, v152
	v_pk_add_f32 v[82:83], v[2:3], v[4:5]
	v_pk_add_f32 v[102:103], v[96:97], v[90:91]
	v_pk_add_f32 v[158:159], v[98:99], v[156:157]
	ds_write2_b64 v115, v[166:167], v[82:83] offset1:1
	ds_write2_b64 v115, v[158:159], v[102:103] offset0:2 offset1:3
	v_pk_add_f32 v[82:83], v[112:113], v[154:155] neg_lo:[0,1] neg_hi:[0,1]
	v_pk_add_f32 v[102:103], v[148:149], v[160:161] neg_lo:[0,1] neg_hi:[0,1]
	v_pk_add_f32 v[78:79], v[92:93], v[78:79] neg_lo:[0,1] neg_hi:[0,1]
	v_pk_add_f32 v[108:109], v[82:83], v[102:103] op_sel:[0,1] op_sel_hi:[1,0] neg_lo:[0,1] neg_hi:[0,1]
	v_pk_add_f32 v[82:83], v[82:83], v[102:103] op_sel:[0,1] op_sel_hi:[1,0]
	v_pk_add_f32 v[102:103], v[142:143], v[104:105] neg_lo:[0,1] neg_hi:[0,1]
	v_pk_add_f32 v[92:93], v[102:103], v[78:79] op_sel:[0,1] op_sel_hi:[1,0] neg_lo:[0,1] neg_hi:[0,1]
	v_pk_add_f32 v[78:79], v[102:103], v[78:79] op_sel:[0,1] op_sel_hi:[1,0]
	v_mov_b32_e32 v102, v108
	v_mov_b32_e32 v103, v83
	v_mov_b32_e32 v104, v92
	v_mov_b32_e32 v105, v79
	ds_write2_b64 v115, v[102:103], v[104:105] offset0:4 offset1:5
	v_mov_b32_e32 v85, v151
	v_sub_f32_e32 v102, v152, v117
	v_sub_f32_e32 v103, v116, v119
	v_sub_f32_e32 v86, v95, v86
	v_sub_f32_e32 v87, v88, v80
	v_sub_f32_e32 v80, v100, v106
	v_sub_f32_e32 v81, v89, v81
	v_pk_add_f32 v[104:105], v[84:85], v[102:103] neg_lo:[0,1] neg_hi:[0,1]
	v_pk_add_f32 v[84:85], v[84:85], v[102:103]
	v_pk_add_f32 v[88:89], v[80:81], v[86:87] neg_lo:[0,1] neg_hi:[0,1]
	v_pk_add_f32 v[80:81], v[80:81], v[86:87]
	v_mov_b32_e32 v86, v104
	v_mov_b32_e32 v87, v85
	v_mov_b32_e32 v94, v88
	v_mov_b32_e32 v95, v81
	ds_write2_b64 v115, v[86:87], v[94:95] offset0:6 offset1:7
	v_pk_add_f32 v[86:87], v[162:163], v[164:165] neg_lo:[0,1] neg_hi:[0,1]
	v_pk_add_f32 v[2:3], v[2:3], v[4:5] neg_lo:[0,1] neg_hi:[0,1]
	ds_write2_b64 v115, v[86:87], v[2:3] offset0:8 offset1:9
	v_pk_add_f32 v[2:3], v[98:99], v[156:157] neg_lo:[0,1] neg_hi:[0,1]
	v_sub_f32_e32 v4, v90, v96
	v_sub_f32_e32 v5, v97, v91
	ds_write2_b64 v115, v[2:3], v[4:5] offset0:10 offset1:11
	v_mov_b32_e32 v83, v109
	v_mov_b32_e32 v79, v93
	v_mov_b32_e32 v85, v105
	v_mov_b32_e32 v81, v89
	v_mov_b32_e32 v2, v1
	ds_write2_b64 v115, v[82:83], v[78:79] offset0:12 offset1:13
	ds_write2_b64 v115, v[84:85], v[80:81] offset0:14 offset1:15
	s_waitcnt lgkmcnt(0)
	s_barrier
	s_nop 0
	v_ashrrev_i32_e32 v3, 31, v2
	v_lshrrev_b32_e32 v3, 28, v3
	v_and_b32_e32 v106, 15, v2
	v_add_u32_e32 v2, v2, v3
	v_ashrrev_i32_e32 v2, 4, v2
	v_lshlrev_b32_e32 v3, 11, v2
	v_lshl_add_u32 v2, v2, 7, v3
	v_lshl_or_b32 v115, v106, 3, v2
	ds_read2_b64 v[2:5], v115 offset1:17
	ds_read2_b64 v[78:81], v115 offset0:34 offset1:51
	ds_read2_b64 v[82:85], v115 offset0:68 offset1:85
	ds_read2_b64 v[86:89], v115 offset0:102 offset1:119
	ds_read2_b64 v[90:93], v115 offset0:136 offset1:153
	ds_read2_b64 v[94:97], v115 offset0:170 offset1:187
	ds_read2_b64 v[98:101], v115 offset0:204 offset1:221
	ds_read2_b64 v[102:105], v115 offset0:238 offset1:255
	s_waitcnt lgkmcnt(4)
	v_mov_b32_e32 v158, v86
	v_cvt_f32_i32_e32 v106, v106
	v_mov_b32_e32 v159, v85
	v_pk_mov_b32 v[84:85], v[86:87], v[84:85] op_sel:[1,0]
	v_add_f32_e32 v106, v106, v106
	v_mul_f32_e32 v106, 0x3b800000, v106
	v_mul_f32_e32 v106, 0.5, v106
	v_sin_f32_e32 v107, v106
	v_cos_f32_e32 v106, v106
	v_mul_f32_e32 v110, v107, v107
	v_mul_f32_e32 v108, v106, v107
	v_pk_fma_f32 v[110:111], v[106:107], v[106:107], v[110:111] op_sel_hi:[1,1,0] neg_lo:[0,0,1] neg_hi:[0,0,1]
	v_add_f32_e32 v108, v108, v108
	v_mov_b32_e32 v112, v110
	v_mov_b32_e32 v113, v106
	v_mov_b32_e32 v109, v107
	v_pk_mul_f32 v[116:117], v[112:113], v[110:111] op_sel_hi:[1,0]
	v_pk_mul_f32 v[120:121], v[108:109], v[110:111] op_sel_hi:[1,0]
	v_pk_fma_f32 v[134:135], v[108:109], v[108:109], v[116:117] op_sel_hi:[1,0,1] neg_lo:[1,0,0] neg_hi:[1,0,0]
	v_pk_fma_f32 v[128:129], v[112:113], v[108:109], v[120:121] op_sel_hi:[1,0,1]
	v_mov_b32_e32 v136, v134
	v_mov_b32_e32 v137, v106
	v_mov_b32_e32 v142, v108
	v_mov_b32_e32 v143, v128
	v_mul_f32_e32 v119, v113, v108
	v_mov_b32_e32 v130, v128
	v_mov_b32_e32 v131, v107
	v_pk_mul_f32 v[138:139], v[136:137], v[134:135] op_sel_hi:[1,0]
	v_mov_b32_e32 v111, v134
	v_pk_mul_f32 v[146:147], v[142:143], v[134:135] op_sel_hi:[1,0]
	v_pk_mul_f32 v[148:149], v[130:131], v[110:111]
	v_pk_mul_f32 v[144:145], v[128:129], v[142:143] op_sel_hi:[0,1]
	v_add_f32_e32 v118, v147, v147
	v_add_f32_e32 v119, v119, v121
	v_pk_fma_f32 v[120:121], v[136:137], v[142:143], v[148:149]
	v_fma_f32 v116, -v130, v128, v138
	v_fma_f32 v117, -v131, v108, v117
	v_mul_f32_e32 v132, v134, v129
	v_mul_f32_e32 v148, v128, v135
	v_pk_mul_f32 v[150:151], v[130:131], v[134:135] op_sel_hi:[1,0]
	v_pk_fma_f32 v[130:131], v[130:131], v[128:129], v[138:139] op_sel_hi:[1,0,1] neg_lo:[1,0,0] neg_hi:[1,0,0]
	v_pk_fma_f32 v[138:139], v[134:135], v[110:111], v[144:145] op_sel_hi:[0,1,1] neg_lo:[0,0,1] neg_hi:[0,0,1]
	v_pk_fma_f32 v[144:145], v[110:111], v[128:129], v[146:147] op_sel_hi:[1,0,1]
	v_add_f32_e32 v132, v132, v148
	v_add_f32_e32 v133, v147, v147
	v_mov_b32_e32 v149, v106
	v_pk_mul_f32 v[142:143], v[128:129], v[128:129] op_sel_hi:[0,1]
	v_pk_fma_f32 v[136:137], v[136:137], v[128:129], v[150:151] op_sel_hi:[1,0,1]
	v_mov_b32_e32 v148, v130
	v_mul_f32_e32 v106, v145, v110
	v_mul_f32_e32 v107, v107, v130
	v_pk_fma_f32 v[142:143], v[134:135], v[134:135], v[142:143] op_sel_hi:[0,1,1] neg_lo:[0,0,1] neg_hi:[0,0,1]
	v_fma_f32 v106, v148, v108, v106
	v_fma_f32 v107, v149, v145, v107
	v_pk_mov_b32 v[150:151], v[144:145], v[128:129] op_sel:[1,0]
	v_mov_b32_e32 v149, v134
	v_pk_mul_f32 v[152:153], v[150:151], v[132:133]
	v_pk_mul_f32 v[150:151], v[150:151], v[142:143] op_sel:[0,1] op_sel_hi:[1,0]
	v_pk_mul_f32 v[136:137], v[136:137], v[138:139]
	v_pk_fma_f32 v[138:139], v[148:149], v[142:143], v[152:153] op_sel:[0,1,0] op_sel_hi:[1,0,1] neg_lo:[0,0,1] neg_hi:[0,0,1]
	v_pk_fma_f32 v[148:149], v[148:149], v[132:133], v[150:151]
	v_mov_b32_e32 v150, v78
	v_mov_b32_e32 v151, v5
	v_pk_mov_b32 v[4:5], v[78:79], v[4:5] op_sel:[1,0]
	v_pk_mul_f32 v[140:141], v[108:109], v[128:129] op_sel_hi:[1,0]
	v_pk_mul_f32 v[146:147], v[108:109], v[144:145] op_sel:[0,1]
	v_pk_mul_f32 v[78:79], v[4:5], v[108:109]
	v_pk_mul_f32 v[108:109], v[150:151], v[108:109]
	v_mul_f32_e32 v118, v134, v118
	v_mul_f32_e32 v119, v130, v119
	v_fma_f32 v152, v150, v112, -v78
	v_fma_f32 v79, v151, v113, v79
	v_fma_f32 v151, v5, v113, -v109
	v_fma_f32 v4, v4, v112, v108
	v_pk_fma_f32 v[140:141], v[112:113], v[134:135], v[140:141] op_sel_hi:[1,0,1] neg_lo:[0,0,1] neg_hi:[0,0,1]
	v_pk_fma_f32 v[146:147], v[112:113], v[130:131], v[146:147] op_sel_hi:[1,0,1] neg_lo:[0,0,1] neg_hi:[0,0,1]
	v_fma_f32 v116, v128, v116, v118
	v_fma_f32 v117, v145, v117, v119
	v_pk_mul_f32 v[118:119], v[144:145], v[120:121] op_sel:[1,0]
	v_mul_f32_e32 v150, v81, v129
	v_pk_mul_f32 v[86:87], v[84:85], v[120:121]
	v_pk_mul_f32 v[120:121], v[158:159], v[120:121]
	v_pk_fma_f32 v[118:119], v[130:131], v[140:141], v[118:119] op_sel_hi:[0,1,1] neg_lo:[0,0,1] neg_hi:[0,0,1]
	v_fma_f32 v112, v80, v135, -v150
	v_mov_b32_e32 v154, v82
	v_mov_b32_e32 v155, v81
	v_pk_mov_b32 v[80:81], v[82:83], v[80:81] op_sel:[1,0]
	v_fma_f32 v160, v158, v140, -v86
	v_fma_f32 v87, v159, v141, v87
	v_fma_f32 v159, v85, v141, -v121
	v_fma_f32 v84, v84, v140, v120
	v_mov_b32_e32 v141, v83
	v_mul_f32_e32 v83, v82, v128
	v_mul_f32_e32 v82, v89, v132
	v_mul_f32_e32 v86, v89, v143
	v_pk_mul_f32 v[110:111], v[128:129], v[144:145] op_sel:[0,1]
	v_pk_mul_f32 v[80:81], v[80:81], v[128:129]
	v_mov_b32_e32 v140, v88
	v_fma_f32 v88, v88, v132, v86
	s_waitcnt lgkmcnt(2)
	v_mov_b32_e32 v132, v94
	v_mov_b32_e32 v133, v93
	v_pk_mov_b32 v[92:93], v[94:95], v[92:93] op_sel:[1,0]
	v_pk_fma_f32 v[110:111], v[134:135], v[130:131], v[110:111] op_sel_hi:[1,0,1] neg_lo:[0,0,1] neg_hi:[0,0,1]
	v_fma_f32 v156, v154, v134, -v80
	v_fma_f32 v81, v155, v135, v81
	v_pk_mov_b32 v[134:135], v[142:143], v[134:135] op_sel:[1,0]
	v_pk_mul_f32 v[94:95], v[92:93], v[106:107]
	v_pk_mul_f32 v[106:107], v[132:133], v[106:107]
	v_fma_f32 v128, v140, v134, -v82
	v_fma_f32 v83, v141, v135, v83
	v_fma_f32 v134, v132, v146, -v94
	v_fma_f32 v95, v133, v147, v95
	v_fma_f32 v133, v93, v147, -v107
	v_fma_f32 v92, v92, v146, v106
	v_pk_mov_b32 v[142:143], v[110:111], v[130:131] op_sel:[1,0]
	v_mul_f32_e32 v146, v97, v117
	v_mul_f32_e32 v147, v90, v145
	v_pk_fma_f32 v[136:137], v[130:131], v[144:145], v[136:137]
	v_fma_f32 v162, v96, v142, -v146
	v_fma_f32 v141, v91, v143, v147
	v_mov_b32_e32 v143, v97
	s_waitcnt lgkmcnt(1)
	v_mul_f32_e32 v97, v96, v117
	v_mul_f32_e32 v96, v99, v116
	v_fma_f32 v116, v98, v110, -v96
	v_fma_f32 v97, v143, v111, v97
	s_waitcnt lgkmcnt(0)
	v_mov_b32_e32 v142, v102
	v_mov_b32_e32 v143, v101
	v_pk_mov_b32 v[100:101], v[102:103], v[100:101] op_sel:[1,0]
	v_pk_mul_f32 v[102:103], v[100:101], v[136:137]
	v_pk_mul_f32 v[136:137], v[142:143], v[136:137]
	v_fma_f32 v146, v142, v118, -v102
	v_fma_f32 v103, v143, v119, v103
	v_fma_f32 v143, v101, v119, -v137
	v_fma_f32 v100, v100, v118, v136
	v_mov_b32_e32 v137, v99
	v_mul_f32_e32 v99, v98, v149
	v_mul_f32_e32 v98, v105, v148
	v_fma_f32 v164, v104, v138, -v98
	v_fma_f32 v99, v137, v139, v99
	v_pk_mov_b32 v[136:137], v[90:91], v[104:105] op_sel:[1,0]
	v_mul_f32_e32 v136, v136, v145
	v_mul_f32_e32 v137, v137, v148
	v_fma_f32 v104, v90, v130, -v136
	v_fma_f32 v91, v105, v138, v137
	v_mov_b32_e32 v105, v91
	v_add_f32_e32 v136, v112, v162
	v_add_f32_e32 v137, v3, v141
	v_mov_b32_e32 v155, v81
	v_mov_b32_e32 v111, v97
	v_mov_b32_e32 v131, v88
	v_add_f32_e32 v138, v128, v164
	v_add_f32_e32 v139, v83, v99
	v_add_f32_e32 v106, v151, v133
	v_add_f32_e32 v107, v4, v92
	v_add_f32_e32 v108, v159, v143
	v_add_f32_e32 v109, v84, v100
	v_add_f32_e32 v118, v152, v134
	v_add_f32_e32 v119, v79, v95
	v_sub_f32_e32 v78, v4, v92
	v_sub_f32_e32 v79, v79, v95
	v_sub_f32_e32 v5, v4, v92
	v_sub_f32_e32 v4, v112, v162
	v_sub_f32_e32 v88, v88, v91
	v_sub_f32_e32 v89, v160, v146
	v_add_f32_e32 v120, v160, v146
	v_add_f32_e32 v121, v87, v103
	v_sub_f32_e32 v86, v84, v100
	v_sub_f32_e32 v87, v87, v103
	v_sub_f32_e32 v80, v81, v97
	v_sub_f32_e32 v81, v152, v134
	v_sub_f32_e32 v85, v84, v100
	v_sub_f32_e32 v84, v128, v164
	v_pk_add_f32 v[90:91], v[4:5], v[88:89]
	v_pk_add_f32 v[4:5], v[4:5], v[88:89] neg_lo:[0,1] neg_hi:[0,1]
	v_add_f32_e32 v130, v2, v104
	v_add_f32_e32 v131, v131, v105
	v_sub_f32_e32 v132, v152, v134
	v_sub_f32_e32 v133, v151, v133
	v_sub_f32_e32 v94, v160, v146
	v_sub_f32_e32 v95, v159, v143
	v_pk_add_f32 v[96:97], v[80:81], v[84:85] neg_lo:[0,1] neg_hi:[0,1]
	v_pk_add_f32 v[80:81], v[80:81], v[84:85]
	v_sub_f32_e32 v2, v2, v104
	v_sub_f32_e32 v3, v3, v141
	v_sub_f32_e32 v82, v83, v99
	v_sub_f32_e32 v83, v156, v116
	v_pk_add_f32 v[92:93], v[132:133], v[86:87]
	v_pk_add_f32 v[100:101], v[78:79], v[94:95] neg_lo:[0,1] neg_hi:[0,1]
	v_mul_f32_e32 v103, 0x3f3504f3, v91
	v_mul_f32_e32 v84, s74, v90
	v_mul_f32_e32 v85, s75, v5
	v_mul_f32_e32 v78, 0x3f6c835e, v96
	v_add_f32_e32 v110, v156, v116
	v_add_f32_e32 v111, v155, v111
	v_sub_f32_e32 v98, v2, v82
	v_pk_add_f32 v[104:105], v[2:3], v[82:83]
	v_mul_f32_e32 v2, 0x3ec3ef15, v93
	v_mul_f32_e32 v82, 0x3f6c835e, v101
	v_fma_f32 v84, v96, s72, -v84
	v_fma_f32 v85, v81, s73, -v85
	v_fma_f32 v88, v90, s80, -v78
	v_add_f32_e32 v78, v79, v95
	v_pk_add_f32 v[2:3], v[2:3], v[82:83] neg_lo:[0,1] neg_hi:[0,1]
	v_pk_mul_f32 v[78:79], v[78:79], s[38:39] op_sel_hi:[0,1]
	v_sub_f32_e32 v82, v133, v87
	v_pk_add_f32 v[148:149], v[106:107], v[108:109]
	v_pk_add_f32 v[166:167], v[110:111], v[130:131]
	v_sub_f32_e32 v116, v130, v110
	v_sub_f32_e32 v117, v118, v120
	v_mov_b32_e32 v140, v107
	v_mov_b32_e32 v156, v109
	v_fma_f32 v86, v82, s40, -v78
	v_fma_f32 v87, v82, s41, v79
	v_sub_f32_e32 v106, v106, v108
	v_sub_f32_e32 v107, v136, v138
	v_sub_f32_e32 v108, v119, v121
	v_sub_f32_e32 v109, v111, v131
	v_pk_mul_f32 v[100:101], v[100:101], s[70:71]
	v_pk_mul_f32 v[78:79], v[80:81], s[40:41] op_sel_hi:[0,1]
	v_pk_mul_f32 v[108:109], v[108:109], s[20:21] op_sel_hi:[1,0]
	v_mul_f32_e32 v94, 0x3f3504f3, v97
	v_fma_f32 v112, v92, s42, -v100
	v_fma_f32 v93, v93, s43, v101
	v_fma_f32 v80, v4, s38, -v78
	v_fma_f32 v81, v4, s39, v79
	v_pk_add_f32 v[144:145], v[118:119], v[120:121]
	v_pk_add_f32 v[154:155], v[136:137], v[138:139]
	v_mov_b32_e32 v99, v105
	v_sub_f32_e32 v140, v140, v156
	v_sub_f32_e32 v141, v137, v139
	v_fma_f32 v111, v107, s3, -v109
	v_fma_f32 v118, v106, s2, v108
	v_sub_f32_e32 v102, v94, v103
	v_fmac_f32_e32 v103, 0x3f3504f3, v97
	v_pk_add_f32 v[168:169], v[148:149], v[154:155]
	v_pk_add_f32 v[170:171], v[144:145], v[166:167]
	v_pk_fma_f32 v[106:107], v[106:107], s[20:21], v[108:109] op_sel_hi:[1,0,1] neg_lo:[0,0,1] neg_hi:[0,0,1]
	v_sub_f32_e32 v108, v116, v140
	v_pk_add_f32 v[130:131], v[116:117], v[140:141]
	v_pk_add_f32 v[4:5], v[98:99], v[102:103]
	v_pk_add_f32 v[78:79], v[86:87], v[80:81]
	v_add_f32_e32 v90, v112, v104
	v_add_f32_e32 v91, v93, v88
	v_pk_add_f32 v[94:95], v[2:3], v[84:85]
	v_pk_add_f32 v[172:173], v[170:171], v[168:169]
	v_mov_b32_e32 v109, v131
	v_add_f32_e32 v120, v106, v111
	v_add_f32_e32 v121, v107, v118
	v_pk_add_f32 v[82:83], v[4:5], v[78:79]
	v_pk_add_f32 v[96:97], v[94:95], v[90:91]
	v_pk_add_f32 v[136:137], v[108:109], v[120:121]
	ds_write2_b64 v115, v[172:173], v[82:83] offset1:17
	ds_write2_b64 v115, v[136:137], v[96:97] offset0:34 offset1:51
	v_sub_f32_e32 v82, v166, v144
	v_sub_f32_e32 v83, v148, v154
	v_sub_f32_e32 v96, v145, v167
	v_sub_f32_e32 v97, v155, v149
	v_pk_add_f32 v[98:99], v[98:99], v[102:103] neg_lo:[0,1] neg_hi:[0,1]
	v_pk_add_f32 v[80:81], v[86:87], v[80:81] neg_lo:[0,1] neg_hi:[0,1]
	v_sub_f32_e32 v100, v82, v96
	v_pk_add_f32 v[128:129], v[82:83], v[96:97]
	v_pk_add_f32 v[86:87], v[98:99], v[80:81] op_sel:[0,1] op_sel_hi:[1,0] neg_lo:[0,1] neg_hi:[0,1]
	v_pk_add_f32 v[80:81], v[98:99], v[80:81] op_sel:[0,1] op_sel_hi:[1,0]
	v_mov_b32_e32 v101, v129
	v_mov_b32_e32 v98, v86
	v_mov_b32_e32 v99, v81
	ds_write2_b64 v115, v[100:101], v[98:99] offset0:68 offset1:85
	v_sub_f32_e32 v131, v141, v117
	v_mov_b32_e32 v113, v85
	v_sub_f32_e32 v98, v118, v107
	v_sub_f32_e32 v99, v106, v111
	v_sub_f32_e32 v88, v93, v88
	v_sub_f32_e32 v89, v2, v84
	v_sub_f32_e32 v2, v104, v112
	v_sub_f32_e32 v3, v3, v113
	v_pk_add_f32 v[100:101], v[130:131], v[98:99] neg_lo:[0,1] neg_hi:[0,1]
	v_pk_add_f32 v[98:99], v[130:131], v[98:99]
	v_pk_add_f32 v[84:85], v[2:3], v[88:89] neg_lo:[0,1] neg_hi:[0,1]
	v_pk_add_f32 v[2:3], v[2:3], v[88:89]
	v_mov_b32_e32 v102, v100
	v_mov_b32_e32 v103, v99
	v_mov_b32_e32 v88, v84
	v_mov_b32_e32 v89, v3
	ds_write2_b64 v115, v[102:103], v[88:89] offset0:102 offset1:119
	v_sub_f32_e32 v88, v170, v168
	v_sub_f32_e32 v89, v169, v171
	v_pk_add_f32 v[4:5], v[4:5], v[78:79] neg_lo:[0,1] neg_hi:[0,1]
	ds_write2_b64 v115, v[88:89], v[4:5] offset0:136 offset1:153
	v_pk_add_f32 v[4:5], v[108:109], v[120:121] neg_lo:[0,1] neg_hi:[0,1]
	v_sub_f32_e32 v78, v90, v94
	v_sub_f32_e32 v79, v95, v91
	ds_write2_b64 v115, v[4:5], v[78:79] offset0:170 offset1:187
	v_sub_f32_e32 v129, v97, v83
	v_mov_b32_e32 v99, v101
	v_mov_b32_e32 v3, v85
	v_mov_b32_e32 v81, v87
	ds_write2_b64 v115, v[98:99], v[2:3] offset0:238 offset1:255
	v_mov_b32_e32 v2, v1
	ds_write2_b64 v115, v[128:129], v[80:81] offset0:204 offset1:221
	s_waitcnt lgkmcnt(0)
	s_barrier
	s_nop 0
	v_ashrrev_i32_e32 v3, 31, v2
	v_lshrrev_b32_e32 v3, 24, v3
	v_and_b32_e32 v4, 0xff, v2
	v_add_lshl_u32 v2, v2, v3, 4
	v_and_or_b32 v2, v2, s87, v4
	v_ashrrev_i32_e32 v3, 4, v2
	v_lshlrev_b32_e32 v2, 3, v2
	v_lshl_add_u32 v5, v3, 3, v2
	ds_read_b64 v[2:3], v5
	ds_read_b64 v[82:83], v5 offset:2176
	ds_read_b64 v[84:85], v5 offset:4352
	ds_read_b64 v[78:79], v5 offset:6528
	ds_read_b64 v[86:87], v5 offset:8704
	ds_read_b64 v[88:89], v5 offset:10880
	ds_read_b64 v[90:91], v5 offset:13056
	ds_read_b64 v[92:93], v5 offset:15232
	ds_read_b64 v[80:81], v5 offset:17408
	ds_read_b64 v[94:95], v5 offset:19584
	ds_read_b64 v[96:97], v5 offset:21760
	ds_read_b64 v[98:99], v5 offset:23936
	ds_read_b64 v[100:101], v5 offset:26112
	ds_read_b64 v[102:103], v5 offset:28288
	ds_read_b64 v[104:105], v5 offset:30464
	ds_read_b64 v[106:107], v5 offset:32640
	s_waitcnt lgkmcnt(9)
	v_mov_b32_e32 v164, v90
	v_cvt_f32_i32_e32 v4, v4
	v_mov_b32_e32 v165, v89
	v_pk_mov_b32 v[88:89], v[90:91], v[88:89] op_sel:[1,0]
	v_add_f32_e32 v4, v4, v4
	v_mul_f32_e32 v4, 0x39800000, v4
	v_mul_f32_e32 v4, 0.5, v4
	v_sin_f32_e32 v109, v4
	s_nop 0
	v_cos_f32_e32 v108, v4
	s_nop 0
	v_add_u32_e32 v4, s29, v1
	s_waitcnt lgkmcnt(4)
	v_mul_f32_e32 v112, v109, v109
	v_mul_f32_e32 v1, v108, v109
	v_add_f32_e32 v110, v1, v1
	v_pk_fma_f32 v[112:113], v[108:109], v[108:109], v[112:113] op_sel_hi:[1,1,0] neg_lo:[0,0,1] neg_hi:[0,0,1]
	v_mov_b32_e32 v111, v109
	v_mov_b32_e32 v116, v112
	v_mov_b32_e32 v117, v108
	v_pk_mul_f32 v[120:121], v[110:111], v[110:111] op_sel_hi:[1,0]
	v_pk_mul_f32 v[132:133], v[110:111], v[112:113] op_sel_hi:[1,0]
	v_pk_fma_f32 v[128:129], v[116:117], v[112:113], v[120:121] op_sel_hi:[1,0,1] neg_lo:[0,0,1] neg_hi:[0,0,1]
	v_pk_fma_f32 v[134:135], v[116:117], v[110:111], v[132:133] op_sel_hi:[1,0,1]
	v_mul_f32_e32 v151, v117, v112
	v_mul_f32_e32 v153, v117, v110
	v_mul_f32_e32 v148, v134, v112
	v_mul_f32_e32 v149, v109, v128
	v_mul_f32_e32 v152, v128, v134
	v_mul_f32_e32 v144, v128, v110
	v_mul_f32_e32 v145, v108, v134
	v_mul_f32_e32 v150, v128, v128
	v_fma_f32 v140, v128, v110, v148
	v_fma_f32 v141, v108, v134, v149
	v_mul_f32_e32 v142, v134, v134
	v_pk_mul_f32 v[136:137], v[116:117], v[128:129] op_sel_hi:[1,0]
	v_pk_mul_f32 v[138:139], v[110:111], v[134:135] op_sel_hi:[1,0]
	v_mul_f32_e32 v120, v128, v129
	v_add_f32_e32 v130, v152, v152
	v_add_f32_e32 v131, v153, v133
	v_mul_f32_e32 v132, v134, v135
	v_pk_fma_f32 v[146:147], v[116:117], v[128:129], v[138:139] op_sel_hi:[1,0,1] neg_lo:[0,0,1] neg_hi:[0,0,1]
	v_sub_f32_e32 v118, v150, v142
	v_sub_f32_e32 v119, v151, v121
	v_mov_b32_e32 v151, v137
	v_sub_f32_e32 v136, v136, v138
	v_sub_f32_e32 v137, v150, v142
	v_sub_f32_e32 v120, v120, v132
	v_sub_f32_e32 v121, v150, v142
	v_mul_f32_e32 v154, v128, v135
	v_mul_f32_e32 v156, v134, v129
	v_sub_f32_e32 v158, v150, v142
	v_sub_f32_e32 v159, v151, v139
	v_add_f32_e32 v132, v144, v148
	v_add_f32_e32 v133, v152, v152
	v_add_f32_e32 v138, v152, v152
	v_add_f32_e32 v139, v145, v149
	v_mov_b32_e32 v149, v108
	v_add_f32_e32 v142, v154, v156
	v_add_f32_e32 v143, v152, v152
	v_mov_b32_e32 v148, v158
	v_mul_f32_e32 v108, v133, v112
	v_mul_f32_e32 v109, v109, v158
	v_fma_f32 v108, v148, v110, v108
	v_fma_f32 v109, v149, v133, v109
	v_pk_mov_b32 v[150:151], v[132:133], v[134:135] op_sel:[1,0]
	v_mul_f32_e32 v130, v128, v130
	v_mul_f32_e32 v131, v158, v131
	v_mov_b32_e32 v149, v128
	v_pk_mul_f32 v[152:153], v[150:151], v[142:143]
	v_pk_mul_f32 v[150:151], v[150:151], v[120:121]
	v_fma_f32 v118, v134, v118, v130
	v_fma_f32 v119, v133, v119, v131
	v_pk_mul_f32 v[130:131], v[132:133], v[140:141] op_sel:[1,0]
	v_pk_mul_f32 v[90:91], v[88:89], v[140:141]
	v_pk_mul_f32 v[140:141], v[164:165], v[140:141]
	v_pk_fma_f32 v[130:131], v[158:159], v[146:147], v[130:131] op_sel_hi:[0,1,1] neg_lo:[0,0,1] neg_hi:[0,0,1]
	v_pk_mul_f32 v[136:137], v[138:139], v[136:137]
	v_pk_fma_f32 v[138:139], v[148:149], v[120:121], v[152:153] neg_lo:[0,0,1] neg_hi:[0,0,1]
	v_pk_fma_f32 v[148:149], v[148:149], v[142:143], v[150:151]
	v_mov_b32_e32 v150, v84
	v_mov_b32_e32 v151, v83
	v_pk_mov_b32 v[82:83], v[84:85], v[82:83] op_sel:[1,0]
	v_mov_b32_e32 v156, v86
	v_fma_f32 v166, v164, v146, -v90
	v_fma_f32 v91, v165, v147, v91
	v_fma_f32 v165, v89, v147, -v141
	v_fma_f32 v88, v88, v146, v140
	v_mov_b32_e32 v147, v87
	v_pk_mul_f32 v[144:145], v[110:111], v[132:133] op_sel:[0,1]
	v_pk_mul_f32 v[112:113], v[134:135], v[132:133] op_sel:[0,1]
	v_pk_mul_f32 v[84:85], v[82:83], v[110:111]
	v_pk_mul_f32 v[110:111], v[150:151], v[110:111]
	v_mov_b32_e32 v157, v79
	v_mul_f32_e32 v160, v87, v134
	v_mul_f32_e32 v161, v78, v135
	v_mov_b32_e32 v121, v128
	v_mul_f32_e32 v87, v86, v134
	v_mul_f32_e32 v86, v93, v142
	v_pk_fma_f32 v[144:145], v[116:117], v[158:159], v[144:145] op_sel_hi:[1,0,1] neg_lo:[0,0,1] neg_hi:[0,0,1]
	v_pk_fma_f32 v[112:113], v[128:129], v[158:159], v[112:113] op_sel_hi:[1,0,1] neg_lo:[0,0,1] neg_hi:[0,0,1]
	v_fma_f32 v152, v150, v116, -v84
	v_fma_f32 v85, v151, v117, v85
	v_pk_fma_f32 v[150:151], v[82:83], v[116:117], v[110:111] neg_lo:[0,0,1] neg_hi:[0,0,1]
	v_fma_f32 v82, v82, v116, v110
	v_pk_fma_f32 v[162:163], v[156:157], v[128:129], v[160:161] neg_lo:[0,0,1] neg_hi:[0,0,1]
	v_pk_fma_f32 v[156:157], v[156:157], v[128:129], v[160:161]
	v_fma_f32 v128, v92, v120, -v86
	v_fma_f32 v87, v147, v121, v87
	v_mov_b32_e32 v143, v120
	v_mov_b32_e32 v120, v96
	v_mov_b32_e32 v121, v95
	v_pk_mov_b32 v[94:95], v[96:97], v[94:95] op_sel:[1,0]
	v_pk_mul_f32 v[96:97], v[94:95], v[108:109]
	v_pk_mul_f32 v[108:109], v[120:121], v[108:109]
	v_pk_mul_f32 v[92:93], v[92:93], v[142:143]
	v_fma_f32 v142, v120, v144, -v96
	v_fma_f32 v97, v121, v145, v97
	v_pk_fma_f32 v[120:121], v[94:95], v[144:145], v[108:109] neg_lo:[0,0,1] neg_hi:[0,0,1]
	v_pk_fma_f32 v[94:95], v[94:95], v[144:145], v[108:109]
	v_pk_mov_b32 v[146:147], v[112:113], v[158:159] op_sel:[1,0]
	v_mul_f32_e32 v168, v99, v119
	v_mul_f32_e32 v169, v80, v133
	v_pk_fma_f32 v[136:137], v[158:159], v[132:133], v[136:137]
	v_fma_f32 v170, v98, v146, -v168
	v_fma_f32 v145, v81, v147, v169
	v_mov_b32_e32 v147, v99
	s_waitcnt lgkmcnt(3)
	v_mul_f32_e32 v99, v98, v119
	v_mul_f32_e32 v98, v101, v118
	v_fma_f32 v118, v100, v112, -v98
	v_fma_f32 v119, v147, v113, -v99
	v_fma_f32 v99, v147, v113, v99
	s_waitcnt lgkmcnt(1)
	v_mov_b32_e32 v146, v104
	v_mov_b32_e32 v147, v103
	v_pk_mov_b32 v[102:103], v[104:105], v[102:103] op_sel:[1,0]
	v_mul_f32_e32 v154, v78, v129
	v_mul_f32_e32 v155, v79, v135
	v_pk_mul_f32 v[104:105], v[102:103], v[136:137]
	v_pk_mul_f32 v[136:137], v[146:147], v[136:137]
	v_fma_f32 v168, v146, v130, -v104
	v_fma_f32 v105, v147, v131, v105
	v_fma_f32 v147, v103, v131, -v137
	v_fma_f32 v102, v102, v130, v136
	v_mov_b32_e32 v137, v101
	s_waitcnt lgkmcnt(0)
	v_mov_b32_e32 v136, v106
	v_mul_f32_e32 v101, v100, v149
	v_mul_f32_e32 v100, v107, v148
	v_pk_mov_b32 v[108:109], v[120:121], v[94:95] op_sel:[1,0]
	v_pk_fma_f32 v[172:173], v[136:137], v[138:139], v[100:101] neg_lo:[0,0,1] neg_hi:[0,0,1]
	v_mov_b32_e32 v113, v99
	v_pk_mov_b32 v[174:175], v[80:81], v[106:107] op_sel:[1,0]
	v_mul_f32_e32 v132, v174, v133
	v_mul_f32_e32 v133, v175, v148
	v_mov_b32_e32 v159, v138
	v_sub_f32_e32 v98, v157, v99
	v_sub_f32_e32 v99, v128, v172
	v_pk_fma_f32 v[100:101], v[136:137], v[138:139], v[100:101]
	v_fma_f32 v106, v80, v158, -v132
	v_fma_f32 v81, v107, v159, v133
	v_fma_f32 v78, v78, v129, -v155
	v_add_f32_e32 v93, v92, v93
	v_mov_b32_e32 v160, v162
	v_mov_b32_e32 v161, v157
	v_mov_b32_e32 v167, v91
	v_mov_b32_e32 v143, v97
	v_mov_b32_e32 v169, v105
	v_add_f32_e32 v112, v160, v118
	v_add_f32_e32 v113, v161, v113
	v_add_f32_e32 v132, v128, v172
	v_add_f32_e32 v133, v87, v101
	v_mov_b32_e32 v146, v97
	v_sub_f32_e32 v90, v151, v121
	v_sub_f32_e32 v91, v91, v105
	v_add_f32_e32 v96, v151, v108
	v_add_f32_e32 v97, v82, v109
	v_add_f32_e32 v104, v165, v147
	v_add_f32_e32 v105, v88, v102
	v_add_f32_e32 v108, v152, v142
	v_add_f32_e32 v109, v85, v143
	v_pk_add_f32 v[110:111], v[166:167], v[168:169]
	v_mov_b32_e32 v79, v93
	v_add_f32_e32 v92, v2, v106
	v_add_f32_e32 v93, v93, v81
	v_add_f32_e32 v116, v78, v170
	v_add_f32_e32 v117, v3, v145
	v_sub_f32_e32 v82, v82, v94
	v_sub_f32_e32 v83, v166, v168
	v_mov_b32_e32 v143, v102
	v_pk_add_f32 v[94:95], v[108:109], v[110:111]
	v_pk_add_f32 v[102:103], v[96:97], v[104:105]
	v_mov_b32_e32 v171, v81
	v_pk_add_f32 v[80:81], v[116:117], v[132:133]
	v_pk_add_f32 v[120:121], v[112:113], v[92:93]
	v_mov_b32_e32 v153, v88
	v_pk_add_f32 v[138:139], v[102:103], v[80:81]
	v_pk_add_f32 v[140:141], v[94:95], v[120:121]
	v_mov_b32_e32 v164, v85
	v_pk_add_f32 v[88:89], v[152:153], v[142:143] neg_lo:[0,1] neg_hi:[0,1]
	v_add_f32_e32 v5, v82, v83
	v_pk_add_f32 v[142:143], v[140:141], v[138:139]
	v_pk_add_f32 v[84:85], v[164:165], v[146:147] neg_lo:[0,1] neg_hi:[0,1]
	v_mul_f32_e32 v129, 0x3f3504f3, v5
	v_pk_mul_f32 v[142:143], v[142:143], s[84:85] op_sel_hi:[1,0]
	v_ashrrev_i32_e32 v5, 31, v4
	v_pk_add_f32 v[78:79], v[78:79], v[170:171] neg_lo:[0,1] neg_hi:[0,1]
	v_cvt_pk_bf16_f32 v107, v142, v143
	v_lshl_add_u64 v[4:5], v[4:5], 2, s[94:95]
	v_pk_mov_b32 v[100:101], v[100:101], v[118:119] op_sel:[1,0]
	v_pk_add_f32 v[118:119], v[84:85], v[84:85] op_sel:[0,1] op_sel_hi:[0,1]
	v_mov_b32_e32 v131, v98
	v_mov_b32_e32 v135, v99
	global_store_dword v[4:5], v107, off
	v_pk_mul_f32 v[118:119], v[118:119], s[38:39]
	v_pk_add_f32 v[142:143], v[90:91], v[90:91] op_sel:[0,1] op_sel_hi:[0,1] neg_lo:[0,1] neg_hi:[0,1]
	v_pk_add_f32 v[98:99], v[98:99], v[98:99] op_sel:[0,1] op_sel_hi:[0,1]
	v_sub_f32_e32 v1, v88, v89
	v_add_f32_e32 v136, v78, v79
	v_sub_f32_e32 v131, v131, v135
	v_sub_f32_e32 v2, v2, v106
	v_sub_f32_e32 v3, v3, v145
	v_sub_f32_e32 v86, v87, v100
	v_sub_f32_e32 v87, v162, v101
	v_fma_f32 v144, v142, s40, -v118
	v_fma_f32 v145, v143, s41, v119
	v_pk_mul_f32 v[98:99], v[98:99], s[40:41]
	v_pk_add_f32 v[78:79], v[78:79], v[78:79] op_sel:[0,1] op_sel_hi:[0,1] neg_lo:[0,1] neg_hi:[0,1]
	v_mul_f32_e32 v115, 0x3f3504f3, v1
	v_mul_f32_e32 v128, 0x3f6c835e, v131
	v_sub_f32_e32 v100, v2, v86
	v_pk_add_f32 v[106:107], v[2:3], v[86:87]
	v_fma_f32 v118, v78, s38, -v98
	v_fma_f32 v119, v79, s39, v99
	v_fma_f32 v134, v136, s80, -v128
	v_mov_b32_e32 v101, v107
	v_sub_f32_e32 v128, v115, v129
	v_fmac_f32_e32 v129, 0x3f3504f3, v1
	v_pk_add_f32 v[78:79], v[100:101], v[128:129]
	v_pk_add_f32 v[98:99], v[144:145], v[118:119]
	v_pk_add_f32 v[142:143], v[78:79], v[98:99]
	v_pk_mul_f32 v[142:143], v[142:143], s[84:85] op_sel_hi:[1,0]
	v_cvt_pk_bf16_f32 v1, v142, v143
	v_sub_f32_e32 v142, v92, v112
	v_sub_f32_e32 v143, v108, v110
	v_mov_b32_e32 v146, v97
	v_mov_b32_e32 v148, v105
	v_sub_f32_e32 v92, v109, v111
	v_sub_f32_e32 v93, v113, v93
	v_mov_b32_e32 v149, v133
	v_sub_f32_e32 v96, v96, v104
	v_sub_f32_e32 v97, v116, v132
	v_pk_mul_f32 v[92:93], v[92:93], s[20:21] op_sel_hi:[1,0]
	v_sub_f32_e32 v146, v146, v148
	v_sub_f32_e32 v147, v117, v149
	v_fma_f32 v105, v97, s3, -v93
	v_fma_f32 v108, v96, s2, v92
	v_pk_fma_f32 v[92:93], v[96:97], s[20:21], v[92:93] op_sel_hi:[1,0,1] neg_lo:[0,0,1] neg_hi:[0,0,1]
	v_sub_f32_e32 v96, v142, v146
	v_pk_add_f32 v[112:113], v[142:143], v[146:147]
	v_add_f32_e32 v110, v92, v105
	v_add_f32_e32 v111, v93, v108
	v_mov_b32_e32 v97, v113
	v_pk_add_f32 v[116:117], v[96:97], v[110:111]
	global_store_dword v[4:5], v1, off offset:1024
	v_pk_mul_f32 v[116:117], v[116:117], s[84:85] op_sel_hi:[1,0]
	v_cvt_pk_bf16_f32 v1, v116, v117
	v_add_f32_e32 v88, v88, v89
	v_add_f32_e32 v89, v90, v91
	v_sub_f32_e32 v82, v82, v83
	v_sub_f32_e32 v83, v84, v85
	v_mul_f32_e32 v2, 0x3ec3ef15, v89
	v_pk_mul_f32 v[84:85], v[82:83], s[70:71]
	v_mov_b32_e32 v137, v82
	v_mul_f32_e32 v86, 0x3f6c835e, v83
	v_pk_mul_f32 v[82:83], v[136:137], s[74:75]
	v_fma_f32 v90, v88, s42, -v84
	v_fma_f32 v85, v89, s43, v85
	v_fma_f32 v82, v131, s72, -v82
	v_fma_f32 v83, v88, s73, -v83
	v_pk_add_f32 v[2:3], v[2:3], v[86:87] neg_lo:[0,1] neg_hi:[0,1]
	v_add_f32_e32 v86, v90, v106
	v_add_f32_e32 v87, v85, v134
	v_pk_add_f32 v[88:89], v[2:3], v[82:83]
	global_store_dword v[4:5], v1, off offset:2048
	v_pk_add_f32 v[116:117], v[88:89], v[86:87]
	v_mov_b32_e32 v130, v94
	v_pk_mul_f32 v[116:117], v[116:117], s[84:85] op_sel_hi:[1,0]
	v_mov_b32_e32 v131, v80
	v_cvt_pk_bf16_f32 v1, v116, v117
	v_sub_f32_e32 v116, v120, v130
	v_sub_f32_e32 v117, v102, v131
	v_sub_f32_e32 v80, v95, v121
	v_sub_f32_e32 v81, v81, v103
	global_store_dword v[4:5], v1, off offset:3072
	v_sub_f32_e32 v94, v116, v80
	v_pk_add_f32 v[102:103], v[116:117], v[80:81]
	v_sub_f32_e32 v1, v81, v117
	v_mul_f32_e32 v80, s84, v94
	v_mul_f32_e32 v81, s84, v103
	s_movk_i32 s2, 0x1000
	v_cvt_pk_bf16_f32 v91, v80, v81
	v_add_co_u32_e32 v80, vcc, s2, v4
	v_pk_add_f32 v[100:101], v[100:101], v[128:129] neg_lo:[0,1] neg_hi:[0,1]
	v_pk_add_f32 v[116:117], v[144:145], v[118:119] neg_lo:[0,1] neg_hi:[0,1]
	v_addc_co_u32_e32 v81, vcc, 0, v5, vcc
	s_nop 1
	v_pk_add_f32 v[118:119], v[100:101], v[116:117] op_sel:[0,1] op_sel_hi:[1,0] neg_lo:[0,1] neg_hi:[0,1]
	v_pk_add_f32 v[100:101], v[100:101], v[116:117] op_sel:[0,1] op_sel_hi:[1,0]
	v_add_co_u32_e32 v94, vcc, s27, v4
	s_nop 1
	v_addc_co_u32_e32 v95, vcc, 0, v5, vcc
	v_mul_f32_e32 v116, s84, v118
	v_mul_f32_e32 v117, s84, v101
	global_store_dword v[94:95], v91, off offset:-4096
	v_cvt_pk_bf16_f32 v91, v116, v117
	v_pk_add_f32 v[116:117], v[146:147], v[142:143] neg_lo:[0,1] neg_hi:[0,1]
	v_mov_b32_e32 v109, v92
	v_mov_b32_e32 v104, v93
	v_mov_b32_e32 v113, v117
	v_pk_add_f32 v[92:93], v[108:109], v[104:105] neg_lo:[0,1] neg_hi:[0,1]
	global_store_dword v[80:81], v91, off offset:1024
	v_pk_add_f32 v[104:105], v[112:113], v[92:93] neg_lo:[0,1] neg_hi:[0,1]
	v_pk_add_f32 v[92:93], v[112:113], v[92:93]
	v_mul_f32_e32 v108, s84, v104
	v_mul_f32_e32 v109, s84, v93
	v_cvt_pk_bf16_f32 v91, v108, v109
	global_store_dword v[80:81], v91, off offset:2048
	v_mov_b32_e32 v135, v82
	v_mov_b32_e32 v107, v3
	v_mov_b32_e32 v91, v83
	v_sub_f32_e32 v84, v85, v134
	v_sub_f32_e32 v85, v2, v135
	v_pk_add_f32 v[2:3], v[106:107], v[90:91] neg_lo:[0,1] neg_hi:[0,1]
	v_pk_add_f32 v[78:79], v[78:79], v[98:99] neg_lo:[0,1] neg_hi:[0,1]
	v_pk_add_f32 v[82:83], v[2:3], v[84:85] neg_lo:[0,1] neg_hi:[0,1]
	v_pk_add_f32 v[2:3], v[2:3], v[84:85]
	v_mul_f32_e32 v84, s84, v82
	v_mul_f32_e32 v85, s84, v3
	v_pk_mul_f32 v[78:79], v[78:79], s[84:85] op_sel_hi:[1,0]
	v_cvt_pk_bf16_f32 v3, v84, v85
	global_store_dword v[80:81], v3, off offset:3072
	v_mov_b32_e32 v81, v139
	v_mov_b32_e32 v139, v141
	v_sub_f32_e32 v80, v140, v138
	v_sub_f32_e32 v81, v81, v139
	v_mul_f32_e32 v1, 0x39000000, v1
	v_pk_mul_f32 v[80:81], v[80:81], s[84:85] op_sel_hi:[1,0]
	v_add_co_u32_e32 v4, vcc, s86, v4
	v_cvt_pk_bf16_f32 v3, v80, v81
	global_store_dword v[94:95], v3, off
	v_cvt_pk_bf16_f32 v3, v78, v79
	v_pk_add_f32 v[78:79], v[96:97], v[110:111] neg_lo:[0,1] neg_hi:[0,1]
	global_store_dword v[94:95], v3, off offset:1024
	v_pk_mul_f32 v[78:79], v[78:79], s[84:85] op_sel_hi:[1,0]
	v_addc_co_u32_e32 v5, vcc, 0, v5, vcc
	s_nop 0
	v_cvt_pk_bf16_f32 v3, v78, v79
	v_mov_b32_e32 v79, v89
	v_mov_b32_e32 v89, v87
	v_sub_f32_e32 v78, v86, v88
	v_sub_f32_e32 v79, v79, v89
	global_store_dword v[94:95], v3, off offset:2048
	v_pk_mul_f32 v[78:79], v[78:79], s[84:85] op_sel_hi:[1,0]
	s_addk_i32 s29, 0x1000
	v_cvt_pk_bf16_f32 v3, v78, v79
	global_store_dword v[94:95], v3, off offset:3072
	v_mul_f32_e32 v3, 0x39000000, v102
	v_cvt_pk_bf16_f32 v1, v3, v1
	global_store_dword v[4:5], v1, off
	v_mul_f32_e32 v1, 0x39000000, v100
	v_mul_f32_e32 v3, 0x39000000, v119
	v_cvt_pk_bf16_f32 v1, v1, v3
	global_store_dword v[4:5], v1, off offset:1024
	v_mul_f32_e32 v1, 0x39000000, v92
	v_mul_f32_e32 v3, 0x39000000, v105
	v_cvt_pk_bf16_f32 v1, v1, v3
	s_add_u32 s0, s0, 0x4000
	global_store_dword v[4:5], v1, off offset:2048
	v_mul_f32_e32 v1, 0x39000000, v2
	v_mul_f32_e32 v2, 0x39000000, v83
	s_addc_u32 s1, s1, 0
	v_cvt_pk_bf16_f32 v1, v1, v2
	s_cmp_eq_u32 s0, 0x10000
	global_store_dword v[4:5], v1, off offset:3072
	s_cbranch_scc1 .LBB0_412

.LBB0_444:
	s_or_b64 exec, exec, s[22:23]
	v_cvt_f32_u32_e32 v40, v40
	v_cndmask_b32_e64 v60, 0, v114, s[62:63]
	s_waitcnt vmcnt(1)
	v_fmac_f32_e32 v60, v1, v25
	v_cndmask_b32_e64 v71, 0, v114, s[64:65]
	v_mul_f32_e32 v40, 0x39800000, v40
	v_mul_f32_e32 v40, 0.5, v40
	v_sin_f32_e32 v59, v40
	v_cos_f32_e32 v58, v40
	v_cvt_f32_u32_e32 v40, v24
	v_sub_f32_e32 v24, v60, v57
	s_waitcnt vmcnt(0)
	v_fmac_f32_e32 v71, v1, v37
	v_pk_mul_f32 v[24:25], v[58:59], v[24:25] op_sel_hi:[1,0] neg_hi:[0,1]
	v_mul_f32_e32 v40, 0x39800000, v40
	v_mul_f32_e32 v40, 0.5, v40
	v_sin_f32_e32 v59, v40
	v_cos_f32_e32 v58, v40
	v_cvt_f32_u32_e32 v40, v26
	v_cndmask_b32_e64 v37, 0, v114, s[60:61]
	v_fmac_f32_e32 v37, v1, v56
	v_sub_f32_e32 v26, v37, v27
	v_mul_f32_e32 v40, 0x39800000, v40
	v_mul_f32_e32 v40, 0.5, v40
	v_sin_f32_e32 v57, v40
	v_cos_f32_e32 v56, v40
	v_cvt_f32_u32_e32 v40, v38
	v_cndmask_b32_e64 v37, 0, v114, s[58:59]
	v_fmac_f32_e32 v37, v1, v39
	v_sub_f32_e32 v38, v37, v55
	v_mul_f32_e32 v40, 0x39800000, v40
	v_mul_f32_e32 v40, 0.5, v40
	v_pk_mul_f32 v[38:39], v[56:57], v[38:39] op_sel_hi:[1,0] neg_hi:[0,1]
	v_sin_f32_e32 v57, v40
	v_cos_f32_e32 v56, v40
	v_cvt_f32_u32_e32 v40, v30
	v_cndmask_b32_e64 v37, 0, v114, s[56:57]
	v_fmac_f32_e32 v37, v1, v54
	v_sub_f32_e32 v30, v37, v31
	v_mul_f32_e32 v40, 0x39800000, v40
	v_mul_f32_e32 v40, 0.5, v40
	v_sin_f32_e32 v55, v40
	v_cos_f32_e32 v54, v40
	v_cvt_f32_u32_e32 v40, v32
	v_cndmask_b32_e64 v37, 0, v114, s[0:1]
	v_fmac_f32_e32 v37, v1, v33
	v_sub_f32_e32 v32, v37, v53
	v_mul_f32_e32 v40, 0x39800000, v40
	v_mul_f32_e32 v40, 0.5, v40
	v_pk_mul_f32 v[32:33], v[54:55], v[32:33] op_sel_hi:[1,0] neg_hi:[0,1]
	v_sin_f32_e32 v55, v40
	v_cos_f32_e32 v54, v40
	v_cvt_f32_u32_e32 v40, v34
	v_cndmask_b32_e64 v37, 0, v114, s[54:55]
	v_fmac_f32_e32 v37, v1, v52
	v_sub_f32_e32 v34, v37, v35
	v_mul_f32_e32 v40, 0x39800000, v40
	v_mul_f32_e32 v40, 0.5, v40
	v_sin_f32_e32 v53, v40
	v_cos_f32_e32 v52, v40
	v_cvt_f32_u32_e32 v40, v28
	v_cndmask_b32_e64 v37, 0, v114, s[52:53]
	v_fmac_f32_e32 v37, v1, v50
	v_sub_f32_e32 v28, v37, v51
	v_mul_f32_e32 v37, 0x39800000, v40
	v_pk_mul_f32 v[50:51], v[52:53], v[28:29] op_sel_hi:[1,0] neg_hi:[0,1]
	v_cndmask_b32_e64 v28, 0, v114, s[50:51]
	v_mul_f32_e32 v37, 0.5, v37
	v_sin_f32_e32 v53, v37
	v_cos_f32_e32 v52, v37
	v_fmac_f32_e32 v28, v1, v29
	v_cvt_f32_u32_e32 v29, v22
	v_cvt_f32_u32_e32 v16, v16
	v_sub_f32_e32 v28, v28, v23
	v_pk_mul_f32 v[34:35], v[54:55], v[34:35] op_sel_hi:[1,0] neg_hi:[0,1]
	v_pk_mul_f32 v[22:23], v[52:53], v[28:29] op_sel_hi:[1,0] neg_hi:[0,1]
	v_mul_f32_e32 v29, 0x39800000, v29
	v_mul_f32_e32 v29, 0.5, v29
	v_mul_f32_e32 v16, 0x39800000, v16
	v_sin_f32_e32 v55, v29
	v_cos_f32_e32 v54, v29
	v_cvt_f32_u32_e32 v18, v18
	v_mul_f32_e32 v16, 0.5, v16
	v_cndmask_b32_e64 v37, 0, v114, s[48:49]
	v_sin_f32_e32 v61, v16
	v_cos_f32_e32 v60, v16
	v_cvt_f32_u32_e32 v16, v14
	v_fmac_f32_e32 v37, v1, v48
	v_cvt_f32_u32_e32 v29, v20
	v_sub_f32_e32 v20, v37, v49
	v_cndmask_b32_e64 v37, 0, v114, s[46:47]
	v_pk_mul_f32 v[48:49], v[54:55], v[20:21] op_sel_hi:[1,0] neg_hi:[0,1]
	v_fmac_f32_e32 v37, v1, v21
	v_cndmask_b32_e64 v21, 0, v114, s[44:45]
	v_mul_f32_e32 v18, 0x39800000, v18
	v_fmac_f32_e32 v21, v1, v46
	v_mul_f32_e32 v18, 0.5, v18
	v_mul_f32_e32 v16, 0x39800000, v16
	v_sub_f32_e32 v40, v37, v47
	v_sin_f32_e32 v47, v18
	v_cos_f32_e32 v46, v18
	v_sub_f32_e32 v18, v21, v19
	v_cndmask_b32_e64 v19, 0, v114, s[42:43]
	v_mul_f32_e32 v16, 0.5, v16
	v_fmac_f32_e32 v19, v1, v17
	v_sin_f32_e32 v17, v16
	v_cos_f32_e32 v16, v16
	v_sub_f32_e32 v14, v19, v45
	v_cndmask_b32_e64 v19, 0, v114, s[40:41]
	v_cvt_f32_u32_e32 v2, v2
	v_fmac_f32_e32 v19, v1, v15
	v_pk_mul_f32 v[62:63], v[60:61], v[14:15] op_sel_hi:[1,0] neg_hi:[0,1]
	v_cvt_f32_u32_e32 v15, v4
	v_sub_f32_e32 v4, v19, v44
	v_cndmask_b32_e64 v19, 0, v114, s[38:39]
	v_pk_mul_f32 v[44:45], v[16:17], v[4:5] op_sel_hi:[1,0] neg_hi:[0,1]
	v_fmac_f32_e32 v19, v1, v5
	v_cndmask_b32_e32 v5, 0, v114, vcc
	v_fmac_f32_e32 v5, v1, v3
	v_mul_f32_e32 v1, 0x39800000, v2
	v_mul_f32_e32 v1, 0.5, v1
	v_sin_f32_e32 v69, v1
	v_cos_f32_e32 v68, v1
	v_cvt_f32_u32_e32 v1, v36
	v_mul_f32_e32 v15, 0x39800000, v15
	v_mul_f32_e32 v29, 0x39800000, v29
	v_mul_f32_e32 v15, 0.5, v15
	v_mul_f32_e32 v1, 0x39800000, v1
	v_mul_f32_e32 v1, 0.5, v1
	v_sin_f32_e32 v3, v1
	v_cos_f32_e32 v2, v1
	v_mov_b32_e32 v1, v122
	v_mul_f32_e32 v29, 0.5, v29
	v_sin_f32_e32 v65, v15
	v_cos_f32_e32 v64, v15
	s_barrier
	v_pk_mul_f32 v[30:31], v[56:57], v[30:31] op_sel_hi:[1,0] neg_hi:[0,1]
	v_ashrrev_i32_e32 v15, 31, v1
	v_sin_f32_e32 v57, v29
	v_cos_f32_e32 v56, v29
	v_lshrrev_b32_e32 v15, 24, v15
	v_sub_f32_e32 v70, v5, v43
	v_and_b32_e32 v5, 0xff, v1
	v_add_lshl_u32 v1, v1, v15, 4
	v_and_or_b32 v1, v1, s87, v5
	v_pk_mul_f32 v[26:27], v[58:59], v[26:27] op_sel_hi:[1,0] neg_hi:[0,1]
	v_ashrrev_i32_e32 v15, 4, v1
	v_lshlrev_b32_e32 v1, 3, v1
	v_pk_mul_f32 v[58:59], v[56:57], v[40:41] op_sel_hi:[1,0] neg_hi:[0,1]
	v_sub_f32_e32 v36, v71, v41
	v_lshl_add_u32 v1, v15, 3, v1
	v_pk_fma_f32 v[40:41], v[56:57], v[40:41], v[26:27] op_sel_hi:[1,0,1] neg_hi:[0,1,0]
	v_pk_fma_f32 v[56:57], v[16:17], v[4:5], v[32:33] op_sel_hi:[1,0,1] neg_hi:[0,1,0]
	v_sub_f32_e32 v42, v19, v42
	v_cvt_f32_i32_e32 v15, v5
	v_pk_mul_f32 v[66:67], v[64:65], v[42:43] op_sel_hi:[1,0] neg_hi:[0,1]
	v_pk_fma_f32 v[42:43], v[64:65], v[42:43], v[34:35] op_sel_hi:[1,0,1] neg_hi:[0,1,0]
	v_pk_mul_f32 v[36:37], v[2:3], v[36:37] op_sel_hi:[1,0] neg_hi:[0,1]
	v_pk_fma_f32 v[60:61], v[60:61], v[14:15], v[30:31] op_sel_hi:[1,0,1] neg_hi:[0,1,0]
	v_add_f32_e32 v14, v15, v15
	v_pk_add_f32 v[4:5], v[42:43], v[40:41] neg_lo:[0,1] neg_hi:[0,1]
	v_mul_f32_e32 v14, 0x39800000, v14
	v_pk_fma_f32 v[72:73], v[68:69], v[70:71], v[50:51] op_sel_hi:[1,0,1] neg_hi:[0,1,0]
	v_pk_fma_f32 v[74:75], v[46:47], v[18:19], v[38:39] op_sel_hi:[1,0,1] neg_hi:[0,1,0]
	v_pk_fma_f32 v[20:21], v[54:55], v[20:21], v[24:25] op_sel_hi:[1,0,1] neg_hi:[0,1,0]
	v_mul_f32_e32 v14, 0.5, v14
	v_pk_mul_f32 v[76:77], v[4:5], s[20:21] op_sel_hi:[1,0]
	v_pk_fma_f32 v[28:29], v[52:53], v[28:29], v[36:37] op_sel_hi:[1,0,1] neg_hi:[0,1,0]
	v_sin_f32_e32 v64, v14
	v_pk_fma_f32 v[78:79], v[4:5], s[20:21], v[76:77] op_sel:[0,0,1] op_sel_hi:[1,0,0]
	v_cos_f32_e32 v80, v14
	v_pk_add_f32 v[2:3], v[72:73], v[74:75]
	v_pk_add_f32 v[4:5], v[42:43], v[40:41]
	v_pk_add_f32 v[14:15], v[56:57], v[20:21]
	v_pk_add_f32 v[16:17], v[60:61], v[28:29]
	v_pk_add_f32 v[28:29], v[60:61], v[28:29] neg_lo:[0,1] neg_hi:[0,1]
	v_pk_add_f32 v[40:41], v[2:3], v[14:15]
	v_mul_f32_e32 v19, 0x3f3504f3, v28
	v_pk_add_f32 v[42:43], v[4:5], v[16:17]
	v_pk_fma_f32 v[50:51], v[68:69], v[70:71], v[50:51] op_sel_hi:[1,0,1] neg_lo:[0,0,1] neg_hi:[0,1,1]
	v_pk_add_f32 v[52:53], v[40:41], v[42:43]
	v_pk_fma_f32 v[38:39], v[46:47], v[18:19], v[38:39] op_sel_hi:[1,0,1] neg_lo:[0,0,1] neg_hi:[0,1,1]
	ds_write_b64 v1, v[52:53]
	v_pk_mov_b32 v[46:47], v[38:39], v[38:39] op_sel:[1,0]
	v_add_f32_e32 v52, v50, v39
	v_sub_f32_e32 v53, v51, v38
	v_pk_add_f32 v[54:55], v[56:57], v[20:21] neg_lo:[0,1] neg_hi:[0,1]
	v_mul_f32_e32 v20, 0x3f3504f3, v29
	v_mul_f32_e32 v29, 0xbf3504f3, v29
	v_sub_f32_e32 v38, v72, v74
	v_sub_f32_e32 v39, v77, v76
	v_sub_f32_e32 v28, v57, v21
	v_sub_f32_e32 v29, v29, v19
	v_sub_f32_e32 v18, v20, v19
	v_sub_f32_e32 v19, v73, v75
	v_mov_b32_e32 v21, v54
	v_pk_add_f32 v[56:57], v[18:19], v[54:55] op_sel:[1,0] op_sel_hi:[0,1]
	v_add_f32_e32 v54, v18, v78
	v_sub_f32_e32 v61, v19, v21
	v_pk_add_f32 v[68:69], v[38:39], v[28:29]
	v_pk_add_f32 v[20:21], v[38:39], v[28:29] neg_lo:[0,1] neg_hi:[0,1]
	v_sub_f32_e32 v38, v44, v32
	v_sub_f32_e32 v39, v66, v34
	v_sub_f32_e32 v34, v45, v33
	v_sub_f32_e32 v35, v67, v35
	v_mov_b32_e32 v75, v27
	v_sub_f32_e32 v27, v58, v26
	v_sub_f32_e32 v26, v48, v24
	v_sub_f32_e32 v72, v49, v25
	v_sub_f32_e32 v73, v59, v75
	v_sub_f32_e32 v58, v63, v31
	v_sub_f32_e32 v59, v44, v32
	v_mov_b32_e32 v66, v22
	s_and_b64 s[0:1], s[96:97], exec
	v_sub_f32_e32 v30, v62, v30
	v_sub_f32_e32 v31, v45, v33
	v_sub_f32_e32 v22, v23, v37
	v_sub_f32_e32 v23, v48, v24
	v_readlane_b32 s0, v244, 15
	v_sub_f32_e32 v66, v66, v36
	v_sub_f32_e32 v67, v49, v25
	v_pk_add_f32 v[32:33], v[30:31], v[22:23] neg_lo:[0,1] neg_hi:[0,1]
	s_cselect_b32 s41, s88, s0
	v_readlane_b32 s0, v244, 13
	v_pk_add_f32 v[74:75], v[58:59], v[66:67]
	v_mov_b32_e32 v62, v32
	v_mul_f32_e32 v32, 0x3ec3ef15, v32
	s_cselect_b32 s40, s24, s0
	v_pk_add_f32 v[24:25], v[38:39], v[72:73] neg_lo:[0,1] neg_hi:[0,1]
	v_pk_add_f32 v[36:37], v[34:35], v[26:27]
	v_pk_add_f32 v[30:31], v[30:31], v[22:23]
	v_mul_f32_e32 v26, 0x3f6c835e, v74
	v_mov_b32_e32 v49, v51
	v_mov_b32_e32 v51, v32
	s_mov_b32 s0, s71
	s_mov_b32 s1, s21
	v_add_f32_e32 v32, v39, v73
	s_mov_b32 s22, s21
	s_mov_b32 s23, s71
	v_pk_add_f32 v[70:71], v[78:79], v[18:19] neg_lo:[0,1] neg_hi:[0,1]
	v_mul_f32_e32 v44, 0x3ec3ef15, v25
	v_mul_f32_e32 v48, 0x3f6c835e, v37
	v_pk_add_f32 v[58:59], v[58:59], v[66:67] neg_lo:[0,1] neg_hi:[0,1]
	v_pk_mul_f32 v[24:25], v[24:25], s[20:21]
	v_mov_b32_e32 v63, v31
	s_mov_b32 s70, s20
	v_mov_b32_e32 v45, v47
	v_mov_b32_e32 v47, v26
	v_sub_f32_e32 v26, v35, v27
	v_pk_mul_f32 v[34:35], v[32:33], s[22:23] op_sel_hi:[0,1]
	v_pk_mul_f32 v[30:31], v[30:31], s[0:1] op_sel_hi:[0,1]
	v_add_f32_e32 v28, v68, v54
	v_add_f32_e32 v29, v69, v61
	v_pk_add_f32 v[18:19], v[56:57], v[70:71]
	v_mul_f32_e32 v55, 0x3f3504f3, v75
	v_mul_f32_e32 v57, 0x3f3504f3, v33
	v_pk_fma_f32 v[22:23], v[36:37], s[70:71], v[24:25] neg_lo:[0,0,1] neg_hi:[0,0,1]
	v_pk_add_f32 v[36:37], v[48:49], v[44:45]
	v_fma_f32 v38, v26, s0, v34
	v_fma_f32 v39, v26, s1, -v35
	v_fma_f32 v48, v58, s22, v30
	v_fma_f32 v49, v58, s23, -v31
	v_add_f32_e32 v26, v57, v55
	v_fma_f32 v27, v33, s20, -v55
	v_pk_add_f32 v[32:33], v[52:53], v[26:27]
	v_pk_add_f32 v[30:31], v[38:39], v[48:49]
	v_pk_add_f32 v[44:45], v[50:51], v[46:47] neg_lo:[0,1] neg_hi:[0,1]
	v_pk_add_f32 v[50:51], v[32:33], v[30:31]
	v_xor_b32_e32 v81, 0x80000000, v64
	v_mul_f32_e32 v66, s72, v74
	v_mul_f32_e32 v67, s73, v59
	v_pk_mul_f32 v[58:59], v[50:51], v[64:65] op_sel_hi:[1,0]
	v_pk_fma_f32 v[24:25], v[62:63], s[30:31], v[66:67] neg_lo:[0,0,1] neg_hi:[0,0,1]
	v_fma_f32 v62, v50, v80, v59
	v_fma_f32 v63, v51, v80, -v58
	v_mov_b32_e32 v65, v80
	v_mul_f32_e32 v50, v64, v64
	v_mul_f32_e32 v51, v65, v81
	ds_write_b64 v1, v[62:63] offset:2176
	v_pk_fma_f32 v[58:59], v[80:81], v[80:81], v[50:51] op_sel_hi:[0,1,1] neg_lo:[0,0,1] neg_hi:[0,0,1]
	v_pk_fma_f32 v[50:51], v[80:81], v[80:81], v[50:51] op_sel_hi:[0,1,1]
	v_mov_b32_e32 v62, v58
	v_mov_b32_e32 v63, v51
	v_mul_f32_e32 v74, v51, v51
	v_mul_f32_e32 v75, v51, v58
	v_pk_mul_f32 v[50:51], v[28:29], v[50:51] op_sel:[1,1] op_sel_hi:[0,1]
	v_pk_fma_f32 v[76:77], v[58:59], v[62:63], v[74:75] op_sel_hi:[0,1,1] neg_lo:[0,0,1] neg_hi:[0,0,1]
	v_pk_fma_f32 v[74:75], v[58:59], v[62:63], v[74:75] op_sel_hi:[0,1,1]
	v_fma_f32 v88, v28, v58, -v50
	v_fma_f32 v89, v29, v58, v51
	v_pk_mul_f32 v[50:51], v[62:63], v[74:75] op_sel:[0,1]
	v_pk_add_f32 v[26:27], v[52:53], v[26:27] neg_lo:[0,1] neg_hi:[0,1]
	v_fma_f32 v52, v62, v76, -v51
	v_fma_f32 v51, v63, v76, v50
	v_mov_b32_e32 v59, v51
	v_sub_f32_e32 v56, v56, v70
	v_mov_b32_e32 v78, v76
	v_mov_b32_e32 v79, v75
	ds_write_b64 v1, v[88:89] offset:4352
	v_mov_b32_e32 v58, v52
	v_pk_add_f32 v[88:89], v[20:21], v[20:21] op_sel:[0,1] op_sel_hi:[0,1]
	v_mul_f32_e32 v50, v56, v51
	v_mul_f32_e32 v51, v56, v52
	v_fma_f32 v52, v88, v52, -v50
	v_fma_f32 v53, v89, v59, v51
	v_pk_add_f32 v[40:41], v[40:41], v[42:43] neg_lo:[0,1] neg_hi:[0,1]
	v_pk_mul_f32 v[42:43], v[78:79], v[74:75] op_sel:[0,1]
	v_pk_fma_f32 v[50:51], v[76:77], v[78:79], v[42:43] op_sel:[0,0,1] op_sel_hi:[0,1,0] neg_lo:[0,0,1] neg_hi:[0,0,1]
	v_pk_fma_f32 v[42:43], v[76:77], v[78:79], v[42:43] op_sel:[0,0,1] op_sel_hi:[0,1,0]
	v_pk_mov_b32 v[56:57], v[42:43], v[50:51] op_sel:[1,0]
	v_mov_b32_e32 v81, v64
	v_pk_mul_f32 v[72:73], v[64:65], v[62:63]
	v_pk_mul_f32 v[84:85], v[64:65], v[78:79]
	ds_write_b64 v1, v[52:53] offset:13056
	v_mov_b32_e32 v52, v50
	v_mov_b32_e32 v53, v43
	v_pk_mul_f32 v[64:65], v[64:65], v[56:57] op_sel_hi:[0,1]
	v_fma_f32 v70, v80, v52, v64
	v_fma_f32 v65, v80, v53, -v65
	v_pk_add_f32 v[30:31], v[32:33], v[30:31] neg_lo:[0,1] neg_hi:[0,1]
	v_pk_mov_b32 v[86:87], v[74:75], v[76:77] op_sel:[1,0]
	v_mov_b32_e32 v75, v65
	v_mul_f32_e32 v64, v31, v65
	v_mul_f32_e32 v65, v31, v70
	v_pk_mul_f32 v[42:43], v[40:41], v[42:43] op_sel:[1,1] op_sel_hi:[0,1]
	v_pk_mul_f32 v[66:67], v[80:81], v[62:63]
	v_pk_mul_f32 v[82:83], v[80:81], v[78:79]
	v_pk_mul_f32 v[80:81], v[62:63], v[52:53]
	v_pk_mul_f32 v[62:63], v[62:63], v[56:57]
	v_fma_f32 v70, v30, v70, -v64
	v_fma_f32 v71, v30, v75, v65
	v_fma_f32 v64, v40, v50, -v42
	v_fma_f32 v65, v41, v50, v43
	v_pk_add_f32 v[34:35], v[22:23], v[44:45]
	v_pk_add_f32 v[46:47], v[36:37], v[24:25]
	v_mov_b32_e32 v88, v66
	v_pk_mov_b32 v[66:67], v[66:67], v[72:73] op_sel:[1,0]
	v_sub_f32_e32 v40, v68, v54
	v_sub_f32_e32 v41, v61, v69
	v_pk_add_f32 v[42:43], v[62:63], v[62:63] op_sel:[0,1] op_sel_hi:[0,1]
	v_pk_add_f32 v[32:33], v[46:47], v[34:35]
	v_add_f32_e32 v72, v88, v66
	v_sub_f32_e32 v66, v88, v66
	v_sub_f32_e32 v67, v73, v67
	v_pk_mul_f32 v[42:43], v[40:41], v[42:43] op_sel:[1,0] op_sel_hi:[0,1]
	v_pk_add_f32 v[50:51], v[80:81], v[80:81] op_sel:[0,1] op_sel_hi:[0,1] neg_lo:[0,1] neg_hi:[0,1]
	v_pk_mul_f32 v[90:91], v[32:33], v[66:67] op_sel:[0,1]
	v_fma_f32 v54, v40, v50, -v42
	v_fma_f32 v55, v41, v51, v43
	v_fma_f32 v92, v32, v72, -v91
	v_fma_f32 v93, v33, v72, v90
	v_mul_f32_e32 v90, v72, v52
	v_mul_f32_e32 v91, v67, v53
	v_mul_f32_e32 v88, v72, v56
	v_mul_f32_e32 v89, v67, v57
	v_sub_f32_e32 v34, v34, v46
	v_sub_f32_e32 v35, v47, v35
	v_pk_add_f32 v[40:41], v[88:89], v[88:89] op_sel:[0,1] op_sel_hi:[0,1]
	v_pk_add_f32 v[2:3], v[2:3], v[14:15] neg_lo:[0,1] neg_hi:[0,1]
	v_pk_add_f32 v[4:5], v[4:5], v[16:17] neg_lo:[0,1] neg_hi:[0,1]
	v_pk_mul_f32 v[40:41], v[34:35], v[40:41] op_sel:[1,0] op_sel_hi:[0,1]
	v_pk_add_f32 v[42:43], v[90:91], v[90:91] op_sel:[0,1] op_sel_hi:[0,1] neg_lo:[0,1] neg_hi:[0,1]
	v_pk_add_f32 v[14:15], v[2:3], v[4:5] op_sel:[0,1] op_sel_hi:[1,0]
	v_pk_add_f32 v[2:3], v[2:3], v[4:5] op_sel:[0,1] op_sel_hi:[1,0] neg_lo:[0,1] neg_hi:[0,1]
	v_pk_add_f32 v[28:29], v[38:39], v[48:49] neg_lo:[0,1] neg_hi:[0,1]
	v_fma_f32 v46, v34, v42, -v40
	v_fma_f32 v47, v35, v43, v41
	v_pk_mul_f32 v[16:17], v[2:3], v[86:87] op_sel:[1,0]
	v_pk_add_f32 v[38:39], v[26:27], v[28:29] op_sel:[0,1] op_sel_hi:[1,0]
	v_pk_add_f32 v[26:27], v[26:27], v[28:29] op_sel:[0,1] op_sel_hi:[1,0] neg_lo:[0,1] neg_hi:[0,1]
	v_pk_mul_f32 v[94:95], v[78:79], v[56:57]
	v_mov_b32_e32 v96, v82
	v_pk_mov_b32 v[82:83], v[82:83], v[84:85] op_sel:[1,0]
	v_fma_f32 v34, v14, v76, -v16
	v_fma_f32 v35, v14, v79, v17
	ds_write_b64 v1, v[92:93] offset:6528
	v_pk_mul_f32 v[92:93], v[78:79], v[52:53]
	v_add_f32_e32 v84, v96, v82
	v_sub_f32_e32 v83, v85, v83
	v_mov_b32_e32 v5, v15
	v_pk_add_f32 v[16:17], v[94:95], v[94:95] op_sel:[0,1] op_sel_hi:[0,1]
	v_mov_b32_e32 v96, v84
	v_mov_b32_e32 v97, v83
	v_mul_f32_e32 v48, v27, v83
	v_mul_f32_e32 v49, v38, v83
	v_mul_f32_e32 v14, v15, v16
	v_mul_f32_e32 v15, v2, v17
	v_pk_add_f32 v[16:17], v[92:93], v[92:93] op_sel:[0,1] op_sel_hi:[0,1] neg_lo:[0,1] neg_hi:[0,1]
	v_fma_f32 v82, v38, v84, -v48
	v_fma_f32 v83, v27, v84, v49
	v_pk_mul_f32 v[48:49], v[56:57], v[96:97]
	v_fma_f32 v2, v2, v16, -v14
	v_fma_f32 v3, v5, v17, v15
	v_pk_mul_f32 v[28:29], v[52:53], v[96:97]
	v_pk_add_f32 v[14:15], v[48:49], v[48:49] op_sel:[0,1] op_sel_hi:[0,1]
	ds_write_b64 v1, v[82:83] offset:10880
	ds_write_b64 v1, v[64:65] offset:17408
	ds_write_b64 v1, v[70:71] offset:19584
	ds_write_b64 v1, v[2:3] offset:26112
	v_mul_f32_e32 v4, v39, v14
	v_mul_f32_e32 v5, v26, v15
	v_pk_add_f32 v[14:15], v[28:29], v[28:29] op_sel:[0,1] op_sel_hi:[0,1] neg_lo:[0,1] neg_hi:[0,1]
	v_pk_mul_f32 v[30:31], v[52:53], v[58:59]
	v_fma_f32 v16, v26, v14, -v4
	v_fma_f32 v17, v39, v15, v5
	v_pk_mul_f32 v[58:59], v[56:57], v[58:59]
	v_sub_f32_e32 v2, v20, v21
	v_sub_f32_e32 v3, v30, v31
	v_pk_add_f32 v[14:15], v[58:59], v[58:59] op_sel:[0,1] op_sel_hi:[0,1]
	v_mul_f32_e32 v4, v18, v14
	v_mul_f32_e32 v5, v2, v15
	v_pk_mov_b32 v[14:15], v[2:3], v[18:19] op_sel:[1,0]
	ds_write_b64 v1, v[16:17] offset:28288
	v_fma_f32 v16, v2, v14, -v4
	v_fma_f32 v17, v3, v15, v5
	v_pk_mul_f32 v[32:33], v[78:79], v[66:67] op_sel:[0,1]
	v_fma_f32 v66, v78, v72, -v33
	v_fma_f32 v33, v79, v72, v32
	v_sub_f32_e32 v2, v23, v45
	v_sub_f32_e32 v3, v36, v24
	v_sub_f32_e32 v4, v44, v22
	v_sub_f32_e32 v5, v37, v25
	v_mov_b32_e32 v73, v33
	v_pk_add_f32 v[14:15], v[4:5], v[2:3]
	v_pk_add_f32 v[2:3], v[4:5], v[2:3] neg_lo:[0,1] neg_hi:[0,1]
	v_mov_b32_e32 v72, v66
	ds_write_b64 v1, v[16:17] offset:30464
	v_mul_f32_e32 v16, v3, v33
	v_mul_f32_e32 v17, v3, v66
	v_pk_mul_f32 v[56:57], v[56:57], v[72:73]
	v_fma_f32 v18, v14, v66, -v16
	v_fma_f32 v19, v14, v73, v17
	v_pk_mul_f32 v[52:53], v[52:53], v[72:73]
	v_mov_b32_e32 v5, v15
	v_pk_add_f32 v[16:17], v[56:57], v[56:57] op_sel:[0,1] op_sel_hi:[0,1]
	v_mul_f32_e32 v14, v15, v16
	v_mul_f32_e32 v15, v2, v17
	v_pk_add_f32 v[16:17], v[52:53], v[52:53] op_sel:[0,1] op_sel_hi:[0,1] neg_lo:[0,1] neg_hi:[0,1]
	v_fma_f32 v2, v2, v16, -v14
	v_fma_f32 v3, v5, v17, v15
	ds_write_b64 v1, v[54:55] offset:21760
	ds_write_b64 v1, v[46:47] offset:23936
	ds_write_b64 v1, v[34:35] offset:8704
	ds_write_b64 v1, v[18:19] offset:15232
	ds_write_b64 v1, v[2:3] offset:32640
	v_mov_b32_e32 v1, v122
	s_waitcnt lgkmcnt(0)
	s_barrier
	s_mov_b32 s43, 0
	v_ashrrev_i32_e32 v2, 31, v1
	v_lshrrev_b32_e32 v2, 28, v2
	v_and_b32_e32 v70, 15, v1
	v_add_u32_e32 v1, v1, v2
	v_ashrrev_i32_e32 v1, 4, v1
	v_lshlrev_b32_e32 v2, 11, v1
	v_lshl_add_u32 v1, v1, 7, v2
	v_lshl_or_b32 v1, v70, 3, v1
	ds_read2_b64 v[20:23], v1 offset1:17
	ds_read2_b64 v[24:27], v1 offset0:68 offset1:85
	ds_read2_b64 v[28:31], v1 offset0:136 offset1:153
	ds_read2_b64 v[32:35], v1 offset0:170 offset1:187
	ds_read2_b64 v[36:39], v1 offset0:204 offset1:221
	ds_read2_b64 v[40:43], v1 offset0:238 offset1:255
	ds_read2_b64 v[44:47], v1 offset0:34 offset1:51
	ds_read2_b64 v[48:51], v1 offset0:102 offset1:119
	s_waitcnt lgkmcnt(5)
	v_pk_add_f32 v[18:19], v[28:29], v[20:21]
	s_waitcnt lgkmcnt(2)
	v_pk_mov_b32 v[68:69], v[34:35], v[42:43] op_sel:[1,0]
	s_waitcnt lgkmcnt(1)
	v_pk_add_f32 v[64:65], v[46:47], v[34:35]
	s_waitcnt lgkmcnt(0)
	v_pk_add_f32 v[66:67], v[50:51], v[42:43]
	v_mov_b32_e32 v35, v43
	v_pk_add_f32 v[42:43], v[64:65], v[66:67] neg_lo:[0,1] neg_hi:[0,1]
	v_sub_f32_e32 v68, v47, v68
	v_sub_f32_e32 v69, v50, v69
	v_pk_add_f32 v[16:17], v[64:65], v[66:67]
	v_mul_f32_e32 v64, 0x3f3504f3, v43
	v_mul_f32_e32 v67, 0xbf3504f3, v43
	v_cvt_f32_i32_e32 v43, v70
	v_sub_f32_e32 v34, v46, v34
	v_sub_f32_e32 v35, v51, v35
	v_pk_add_f32 v[28:29], v[20:21], v[28:29] neg_lo:[0,1] neg_hi:[0,1]
	v_add_f32_e32 v43, v43, v43
	v_pk_add_f32 v[20:21], v[24:25], v[36:37] neg_lo:[0,1] neg_hi:[0,1]
	v_pk_add_f32 v[52:53], v[36:37], v[24:25]
	v_pk_add_f32 v[54:55], v[22:23], v[30:31]
	v_pk_add_f32 v[56:57], v[26:27], v[38:39]
	v_sub_f32_e32 v46, v34, v35
	v_mul_f32_e32 v43, 0x3b800000, v43
	v_pk_mov_b32 v[24:25], v[20:21], v[20:21] op_sel:[1,0]
	v_add_f32_e32 v36, v28, v21
	v_sub_f32_e32 v37, v29, v20
	v_pk_add_f32 v[34:35], v[34:35], v[34:35] op_sel:[0,1] op_sel_hi:[0,1]
	v_pk_add_f32 v[4:5], v[54:55], v[56:57]
	v_pk_add_f32 v[58:59], v[44:45], v[32:33]
	v_pk_add_f32 v[60:61], v[48:49], v[40:41]
	v_pk_add_f32 v[54:55], v[54:55], v[56:57] neg_lo:[0,1] neg_hi:[0,1]
	v_mul_f32_e32 v43, 0.5, v43
	v_pk_add_f32 v[20:21], v[68:69], v[68:69] op_sel:[0,1] op_sel_hi:[0,1] neg_lo:[0,1] neg_hi:[0,1]
	v_pk_mul_f32 v[34:35], v[34:35], s[0:1]
	v_pk_add_f32 v[14:15], v[58:59], v[60:61]
	v_pk_add_f32 v[62:63], v[58:59], v[60:61] neg_lo:[0,1] neg_hi:[0,1]
	v_add_f32_e32 v50, v68, v69
	v_pk_mul_f32 v[56:57], v[54:55], s[20:21] op_sel_hi:[1,0]
	v_mul_f32_e32 v42, 0x3f3504f3, v42
	v_sin_f32_e32 v58, v43
	s_nop 1
	v_cos_f32_e32 v76, v43
	s_nop 1
	v_fma_f32 v68, v20, s22, v34
	v_fma_f32 v69, v21, s23, -v35
	v_pk_add_f32 v[2:3], v[18:19], v[52:53]
	v_mov_b32_e32 v20, v18
	v_sub_f32_e32 v18, v64, v42
	v_sub_f32_e32 v19, v19, v53
	v_sub_f32_e32 v20, v20, v52
	v_sub_f32_e32 v21, v57, v56
	v_mov_b32_e32 v35, v42
	v_pk_add_f32 v[42:43], v[18:19], v[62:63] op_sel:[1,0] op_sel_hi:[0,1]
	v_mov_b32_e32 v53, v62
	v_sub_f32_e32 v34, v59, v61
	v_sub_f32_e32 v35, v67, v35
	v_sub_f32_e32 v62, v44, v32
	v_sub_f32_e32 v63, v22, v30
	v_sub_f32_e32 v64, v49, v41
	v_sub_f32_e32 v65, v27, v39
	v_mul_f32_e32 v78, 0x3f6c835e, v50
	v_mul_f32_e32 v79, 0x3ec3ef15, v46
	v_sub_f32_e32 v22, v45, v33
	v_sub_f32_e32 v23, v23, v31
	v_sub_f32_e32 v27, v26, v38
	v_sub_f32_e32 v26, v48, v40
	v_pk_add_f32 v[32:33], v[62:63], v[64:65] neg_lo:[0,1] neg_hi:[0,1]
	v_pk_fma_f32 v[54:55], v[54:55], s[20:21], v[56:57] op_sel:[0,0,1] op_sel_hi:[1,0,0]
	v_pk_add_f32 v[66:67], v[62:63], v[64:65]
	v_pk_add_f32 v[30:31], v[22:23], v[26:27] neg_lo:[0,1] neg_hi:[0,1]
	v_pk_add_f32 v[22:23], v[22:23], v[26:27]
	v_mov_b32_e32 v39, v29
	v_mov_b32_e32 v27, v25
	v_mov_b32_e32 v52, v54
	v_pk_add_f32 v[54:55], v[54:55], v[18:19] neg_lo:[0,1] neg_hi:[0,1]
	v_mul_f32_e32 v26, 0x3ec3ef15, v33
	v_pk_mul_f32 v[40:41], v[32:33], s[20:21]
	v_mul_f32_e32 v33, s73, v32
	v_mul_f32_e32 v32, s72, v50
	v_sub_f32_e32 v24, v28, v24
	v_sub_f32_e32 v25, v79, v78
	v_pk_mul_f32 v[28:29], v[66:67], s[22:23] op_sel:[1,0]
	v_add_f32_e32 v56, v18, v52
	v_sub_f32_e32 v53, v19, v53
	v_pk_add_f32 v[18:19], v[42:43], v[54:55]
	v_mul_f32_e32 v38, 0x3f6c835e, v23
	v_mul_f32_e32 v43, 0x3f3504f3, v66
	v_mul_f32_e32 v44, 0x3f3504f3, v30
	v_pk_fma_f32 v[40:41], v[22:23], s[70:71], v[40:41] neg_lo:[0,0,1] neg_hi:[0,0,1]
	v_fma_f32 v23, v22, s31, -v33
	v_fma_f32 v22, v46, s30, -v32
	v_fma_f32 v32, v31, s0, v28
	v_fma_f32 v33, v31, s1, -v29
	v_pk_add_f32 v[26:27], v[38:39], v[26:27]
	v_add_f32_e32 v28, v44, v43
	v_fma_f32 v29, v30, s20, -v43
	v_pk_add_f32 v[30:31], v[36:37], v[28:29]
	v_pk_add_f32 v[38:39], v[32:33], v[68:69]
	v_xor_b32_e32 v77, 0x80000000, v58
	v_pk_add_f32 v[44:45], v[38:39], v[30:31]
	v_pk_add_f32 v[70:71], v[2:3], v[14:15]
	v_pk_mul_f32 v[50:51], v[58:59], v[44:45] op_sel_hi:[0,1]
	v_fma_f32 v62, v76, v44, v51
	v_fma_f32 v63, v76, v45, -v50
	v_mov_b32_e32 v59, v76
	v_pk_add_f32 v[72:73], v[4:5], v[16:17]
	v_mul_f32_e32 v44, v58, v58
	v_mul_f32_e32 v45, v59, v77
	v_pk_add_f32 v[74:75], v[72:73], v[70:71]
	v_pk_fma_f32 v[50:51], v[76:77], v[76:77], v[44:45] op_sel_hi:[0,1,1] neg_lo:[0,0,1] neg_hi:[0,0,1]
	v_pk_fma_f32 v[44:45], v[76:77], v[76:77], v[44:45] op_sel_hi:[0,1,1]
	v_pk_add_f32 v[60:61], v[20:21], v[34:35]
	ds_write2_b64 v1, v[74:75], v[62:63] offset1:17
	v_pk_add_f32 v[20:21], v[20:21], v[34:35] neg_lo:[0,1] neg_hi:[0,1]
	v_add_f32_e32 v34, v60, v56
	v_add_f32_e32 v35, v61, v53
	v_mov_b32_e32 v62, v50
	v_mov_b32_e32 v63, v45
	v_mul_f32_e32 v74, v45, v45
	v_mul_f32_e32 v75, v45, v50
	v_pk_mul_f32 v[44:45], v[34:35], v[44:45] op_sel:[1,1] op_sel_hi:[0,1]
	v_pk_fma_f32 v[78:79], v[50:51], v[62:63], v[74:75] op_sel_hi:[0,1,1] neg_lo:[0,0,1] neg_hi:[0,0,1]
	v_pk_fma_f32 v[74:75], v[50:51], v[62:63], v[74:75] op_sel_hi:[0,1,1]
	v_fma_f32 v88, v34, v50, -v44
	v_fma_f32 v89, v35, v50, v45
	v_pk_mul_f32 v[44:45], v[62:63], v[74:75] op_sel:[0,1]
	v_pk_add_f32 v[32:33], v[32:33], v[68:69] neg_lo:[0,1] neg_hi:[0,1]
	v_fma_f32 v50, v62, v78, -v45
	v_fma_f32 v45, v63, v78, v44
	v_sub_f32_e32 v42, v42, v54
	v_mov_b32_e32 v69, v45
	v_mov_b32_e32 v77, v58
	v_mov_b32_e32 v80, v78
	v_mov_b32_e32 v81, v75
	v_pk_add_f32 v[90:91], v[20:21], v[20:21] op_sel:[0,1] op_sel_hi:[0,1]
	v_mul_f32_e32 v43, v42, v50
	v_mul_f32_e32 v42, v42, v45
	v_pk_mul_f32 v[64:65], v[76:77], v[62:63]
	v_pk_mul_f32 v[66:67], v[58:59], v[62:63]
	v_mov_b32_e32 v68, v50
	v_fma_f32 v44, v90, v50, -v42
	v_pk_mul_f32 v[50:51], v[80:81], v[74:75] op_sel:[0,1]
	v_pk_add_f32 v[30:31], v[30:31], v[38:39] neg_lo:[0,1] neg_hi:[0,1]
	v_pk_add_f32 v[38:39], v[40:41], v[24:25]
	v_pk_add_f32 v[46:47], v[26:27], v[22:23]
	v_fma_f32 v45, v91, v69, v43
	v_pk_fma_f32 v[54:55], v[78:79], v[80:81], v[50:51] op_sel:[0,0,1] op_sel_hi:[0,1,0] neg_lo:[0,0,1] neg_hi:[0,0,1]
	v_pk_fma_f32 v[50:51], v[78:79], v[80:81], v[50:51] op_sel:[0,0,1] op_sel_hi:[0,1,0]
	v_mov_b32_e32 v92, v64
	v_pk_mov_b32 v[64:65], v[64:65], v[66:67] op_sel:[1,0]
	v_pk_add_f32 v[48:49], v[38:39], v[46:47]
	v_pk_add_f32 v[42:43], v[70:71], v[72:73] neg_lo:[0,1] neg_hi:[0,1]
	v_pk_mov_b32 v[72:73], v[50:51], v[54:55] op_sel:[1,0]
	v_add_f32_e32 v66, v92, v64
	v_sub_f32_e32 v64, v92, v64
	v_sub_f32_e32 v65, v67, v65
	v_pk_mul_f32 v[82:83], v[76:77], v[80:81]
	v_pk_mul_f32 v[84:85], v[58:59], v[80:81]
	v_pk_add_f32 v[28:29], v[36:37], v[28:29] neg_lo:[0,1] neg_hi:[0,1]
	v_mov_b32_e32 v70, v54
	v_mov_b32_e32 v71, v51
	v_pk_mul_f32 v[58:59], v[58:59], v[72:73] op_sel_hi:[0,1]
	v_pk_mul_f32 v[94:95], v[48:49], v[64:65] op_sel:[0,1]
	v_pk_mov_b32 v[86:87], v[74:75], v[78:79] op_sel:[1,0]
	v_pk_add_f32 v[34:35], v[28:29], v[32:33] op_sel:[0,1] op_sel_hi:[1,0]
	v_pk_add_f32 v[28:29], v[28:29], v[32:33] op_sel:[0,1] op_sel_hi:[1,0] neg_lo:[0,1] neg_hi:[0,1]
	v_fma_f32 v74, v76, v70, v58
	v_fma_f32 v59, v76, v71, -v59
	v_fma_f32 v96, v48, v66, -v95
	v_fma_f32 v97, v49, v66, v94
	v_mov_b32_e32 v98, v82
	v_mov_b32_e32 v99, v85
	v_pk_mov_b32 v[82:83], v[82:83], v[84:85] op_sel:[1,0]
	v_mov_b32_e32 v77, v59
	v_pk_mul_f32 v[48:49], v[80:81], v[64:65] op_sel:[0,1]
	v_pk_add_f32 v[84:85], v[98:99], v[82:83]
	v_sub_f32_e32 v83, v99, v83
	v_mov_b32_e32 v93, v65
	v_fma_f32 v64, v80, v66, -v49
	v_fma_f32 v49, v81, v66, v48
	v_mul_f32_e32 v36, v29, v83
	v_mul_f32_e32 v37, v34, v83
	v_mul_f32_e32 v58, v31, v59
	v_mul_f32_e32 v59, v31, v74
	v_mov_b32_e32 v92, v66
	v_mov_b32_e32 v66, v64
	v_mov_b32_e32 v67, v49
	v_mov_b32_e32 v98, v84
	v_mov_b32_e32 v99, v83
	v_fma_f32 v82, v34, v84, -v36
	v_fma_f32 v83, v29, v84, v37
	v_fma_f32 v74, v30, v74, -v58
	v_fma_f32 v75, v30, v77, v59
	v_pk_mul_f32 v[50:51], v[42:43], v[50:51] op_sel:[1,1] op_sel_hi:[0,1]
	v_pk_mul_f32 v[90:91], v[62:63], v[70:71]
	v_pk_mul_f32 v[62:63], v[62:63], v[72:73]
	ds_write2_b64 v1, v[88:89], v[96:97] offset0:34 offset1:51
	v_pk_mul_f32 v[88:89], v[92:93], v[70:71]
	v_pk_mul_f32 v[92:93], v[92:93], v[72:73]
	v_pk_mul_f32 v[94:95], v[80:81], v[70:71]
	v_pk_mul_f32 v[96:97], v[80:81], v[72:73]
	v_pk_mul_f32 v[32:33], v[70:71], v[98:99]
	v_pk_mul_f32 v[36:37], v[72:73], v[98:99]
	v_pk_mul_f32 v[30:31], v[70:71], v[68:69]
	v_pk_mul_f32 v[58:59], v[72:73], v[68:69]
	v_pk_mul_f32 v[68:69], v[70:71], v[66:67]
	v_pk_mul_f32 v[70:71], v[72:73], v[66:67]
	v_fma_f32 v72, v42, v54, -v50
	v_fma_f32 v73, v43, v54, v51
	v_sub_f32_e32 v42, v60, v56
	v_sub_f32_e32 v43, v53, v61
	v_pk_add_f32 v[50:51], v[62:63], v[62:63] op_sel:[0,1] op_sel_hi:[0,1]
	v_pk_mul_f32 v[50:51], v[42:43], v[50:51] op_sel:[1,0] op_sel_hi:[0,1]
	v_pk_add_f32 v[52:53], v[90:91], v[90:91] op_sel:[0,1] op_sel_hi:[0,1] neg_lo:[0,1] neg_hi:[0,1]
	v_fma_f32 v54, v42, v52, -v50
	v_fma_f32 v55, v43, v53, v51
	v_pk_add_f32 v[2:3], v[2:3], v[14:15] neg_lo:[0,1] neg_hi:[0,1]
	v_sub_f32_e32 v38, v38, v46
	v_sub_f32_e32 v39, v47, v39
	v_pk_add_f32 v[42:43], v[92:93], v[92:93] op_sel:[0,1] op_sel_hi:[0,1]
	v_pk_add_f32 v[4:5], v[4:5], v[16:17] neg_lo:[0,1] neg_hi:[0,1]
	v_pk_mul_f32 v[42:43], v[38:39], v[42:43] op_sel:[1,0] op_sel_hi:[0,1]
	v_pk_add_f32 v[46:47], v[88:89], v[88:89] op_sel:[0,1] op_sel_hi:[0,1] neg_lo:[0,1] neg_hi:[0,1]
	v_pk_add_f32 v[14:15], v[2:3], v[4:5] op_sel:[0,1] op_sel_hi:[1,0]
	v_pk_add_f32 v[2:3], v[2:3], v[4:5] op_sel:[0,1] op_sel_hi:[1,0] neg_lo:[0,1] neg_hi:[0,1]
	v_fma_f32 v50, v38, v46, -v42
	v_fma_f32 v51, v39, v47, v43
	v_pk_mul_f32 v[16:17], v[2:3], v[86:87] op_sel:[1,0]
	v_fma_f32 v38, v14, v78, -v16
	v_fma_f32 v39, v14, v81, v17
	v_mov_b32_e32 v5, v15
	v_pk_add_f32 v[16:17], v[96:97], v[96:97] op_sel:[0,1] op_sel_hi:[0,1]
	v_mul_f32_e32 v14, v15, v16
	v_mul_f32_e32 v15, v2, v17
	v_pk_add_f32 v[16:17], v[94:95], v[94:95] op_sel:[0,1] op_sel_hi:[0,1] neg_lo:[0,1] neg_hi:[0,1]
	v_fma_f32 v2, v2, v16, -v14
	v_fma_f32 v3, v5, v17, v15
	v_pk_add_f32 v[16:17], v[36:37], v[36:37] op_sel:[0,1] op_sel_hi:[0,1]
	v_mul_f32_e32 v14, v35, v16
	v_mul_f32_e32 v15, v28, v17
	v_pk_add_f32 v[16:17], v[32:33], v[32:33] op_sel:[0,1] op_sel_hi:[0,1] neg_lo:[0,1] neg_hi:[0,1]
	v_fma_f32 v28, v28, v16, -v14
	v_fma_f32 v29, v35, v17, v15
	v_pk_add_f32 v[14:15], v[58:59], v[58:59] op_sel:[0,1] op_sel_hi:[0,1]
	ds_write2_b64 v1, v[2:3], v[28:29] offset0:204 offset1:221
	v_sub_f32_e32 v2, v20, v21
	v_sub_f32_e32 v3, v30, v31
	v_mul_f32_e32 v4, v18, v14
	v_mul_f32_e32 v5, v2, v15
	v_pk_mov_b32 v[14:15], v[2:3], v[18:19] op_sel:[1,0]
	v_fma_f32 v16, v2, v14, -v4
	v_fma_f32 v17, v3, v15, v5
	v_sub_f32_e32 v2, v24, v40
	v_sub_f32_e32 v3, v26, v22
	v_sub_f32_e32 v4, v41, v25
	v_sub_f32_e32 v5, v27, v23
	ds_write2_b64 v1, v[72:73], v[74:75] offset0:136 offset1:153
	v_pk_add_f32 v[14:15], v[4:5], v[2:3]
	v_sub_f32_e32 v18, v2, v4
	v_sub_f32_e32 v2, v5, v3
	v_mul_f32_e32 v3, v2, v64
	v_mul_f32_e32 v2, v2, v49
	v_fma_f32 v4, v14, v64, -v2
	v_fma_f32 v5, v14, v67, v3
	ds_write2_b64 v1, v[44:45], v[4:5] offset0:102 offset1:119
	v_pk_add_f32 v[4:5], v[70:71], v[70:71] op_sel:[0,1] op_sel_hi:[0,1]
	v_mul_f32_e32 v2, v15, v4
	v_mul_f32_e32 v3, v18, v5
	v_pk_add_f32 v[4:5], v[68:69], v[68:69] op_sel:[0,1] op_sel_hi:[0,1] neg_lo:[0,1] neg_hi:[0,1]
	v_fma_f32 v14, v18, v4, -v2
	v_fma_f32 v15, v15, v5, v3
	ds_write2_b64 v1, v[54:55], v[50:51] offset0:170 offset1:187
	ds_write2_b64 v1, v[38:39], v[82:83] offset0:68 offset1:85
	ds_write2_b64 v1, v[16:17], v[14:15] offset0:238 offset1:255
	v_mov_b32_e32 v1, v122
	s_waitcnt lgkmcnt(0)
	s_barrier
	s_and_b64 s[0:1], s[96:97], exec
	v_mul_lo_u32 v1, v1, s33
	ds_read2_b64 v[2:5], v1 offset1:1
	ds_read2_b64 v[14:17], v1 offset0:8 offset1:9
	ds_read2_b64 v[18:21], v1 offset0:10 offset1:11
	ds_read2_b64 v[22:25], v1 offset0:12 offset1:13
	ds_read2_b64 v[26:29], v1 offset0:14 offset1:15
	ds_read2_b64 v[30:33], v1 offset0:2 offset1:3
	ds_read2_b64 v[34:37], v1 offset0:4 offset1:5
	ds_read2_b64 v[38:41], v1 offset0:6 offset1:7
	s_waitcnt lgkmcnt(7)
	v_mov_b32_e32 v1, v4
	v_mov_b32_e32 v42, v2
	v_mov_b32_e32 v43, v4
	v_mov_b32_e32 v4, v5
	v_mov_b32_e32 v5, v3
	s_waitcnt lgkmcnt(6)
	v_mov_b32_e32 v44, v14
	v_mov_b32_e32 v45, v16
	v_mov_b32_e32 v16, v17
	v_mov_b32_e32 v17, v15
	v_pk_add_f32 v[46:47], v[2:3], v[14:15] neg_lo:[0,1] neg_hi:[0,1]
	v_pk_add_f32 v[2:3], v[2:3], v[14:15]
	s_waitcnt lgkmcnt(1)
	v_mov_b32_e32 v15, v36
	v_mov_b32_e32 v49, v36
	v_mov_b32_e32 v36, v37
	v_mov_b32_e32 v37, v35
	v_mov_b32_e32 v50, v22
	v_mov_b32_e32 v51, v24
	v_mov_b32_e32 v24, v25
	v_mov_b32_e32 v25, v23
	v_mov_b32_e32 v48, v34
	v_pk_add_f32 v[52:53], v[34:35], v[22:23] neg_lo:[0,1] neg_hi:[0,1]
	v_pk_add_f32 v[22:23], v[34:35], v[22:23]
	v_pk_mov_b32 v[34:35], v[0:1], v[4:5] op_sel:[1,0]
	v_pk_mov_b32 v[54:55], v[44:45], v[16:17] op_sel:[1,0]
	v_pk_add_f32 v[4:5], v[4:5], v[16:17]
	v_pk_mov_b32 v[14:15], v[14:15], v[36:37] op_sel:[1,0]
	v_pk_mov_b32 v[16:17], v[50:51], v[24:25] op_sel:[1,0]
	v_pk_add_f32 v[42:43], v[42:43], v[44:45]
	v_pk_add_f32 v[44:45], v[48:49], v[50:51]
	v_pk_add_f32 v[24:25], v[36:37], v[24:25]
	v_pk_add_f32 v[48:49], v[2:3], v[22:23] neg_lo:[0,1] neg_hi:[0,1]
	v_pk_add_f32 v[2:3], v[2:3], v[22:23]
	v_pk_add_f32 v[22:23], v[34:35], v[54:55]
	v_pk_add_f32 v[34:35], v[34:35], v[54:55] neg_lo:[0,1] neg_hi:[0,1]
	v_pk_add_f32 v[36:37], v[14:15], v[16:17]
	v_pk_add_f32 v[14:15], v[14:15], v[16:17] neg_lo:[0,1] neg_hi:[0,1]
	v_add_f32_e32 v1, v46, v53
	v_sub_f32_e32 v50, v47, v52
	v_sub_f32_e32 v51, v46, v53
	v_add_f32_e32 v53, v47, v52
	v_pk_add_f32 v[16:17], v[42:43], v[44:45]
	v_pk_add_f32 v[4:5], v[4:5], v[24:25]
	v_add_f32_e32 v52, v34, v15
	v_sub_f32_e32 v54, v35, v14
	v_sub_f32_e32 v55, v34, v15
	v_add_f32_e32 v56, v35, v14
	v_pk_add_f32 v[14:15], v[30:31], v[18:19] neg_lo:[0,1] neg_hi:[0,1]
	v_pk_add_f32 v[24:25], v[30:31], v[18:19]
	v_pk_add_f32 v[42:43], v[22:23], v[36:37]
	v_pk_add_f32 v[22:23], v[22:23], v[36:37] neg_lo:[0,1] neg_hi:[0,1]
	s_waitcnt lgkmcnt(0)
	v_pk_add_f32 v[34:35], v[38:39], v[26:27] neg_lo:[0,1] neg_hi:[0,1]
	v_pk_add_f32 v[36:37], v[38:39], v[26:27]
	v_add_f32_e32 v44, v30, v18
	v_add_f32_e32 v45, v32, v20
	v_add_f32_e32 v18, v33, v21
	v_add_f32_e32 v19, v31, v19
	v_add_f32_e32 v30, v38, v26
	v_add_f32_e32 v31, v40, v28
	v_add_f32_e32 v26, v41, v29
	v_add_f32_e32 v27, v39, v27
	v_pk_add_f32 v[38:39], v[24:25], v[36:37] neg_lo:[0,1] neg_hi:[0,1]
	v_pk_add_f32 v[24:25], v[24:25], v[36:37]
	v_add_f32_e32 v36, v14, v35
	v_sub_f32_e32 v37, v15, v34
	v_sub_f32_e32 v46, v14, v35
	v_add_f32_e32 v47, v15, v34
	v_pk_add_f32 v[14:15], v[32:33], v[20:21]
	v_pk_add_f32 v[20:21], v[32:33], v[20:21] neg_lo:[0,1] neg_hi:[0,1]
	v_pk_add_f32 v[32:33], v[40:41], v[28:29]
	v_mul_f32_e32 v22, 0x3f3504f3, v22
	v_pk_add_f32 v[28:29], v[40:41], v[28:29] neg_lo:[0,1] neg_hi:[0,1]
	v_pk_add_f32 v[34:35], v[14:15], v[32:33]
	v_pk_add_f32 v[14:15], v[14:15], v[32:33] neg_lo:[0,1] neg_hi:[0,1]
	v_fmamk_f32 v33, v23, 0x3f3504f3, v22
	v_fma_f32 v40, v23, s20, -v22
	v_mul_f32_e32 v22, 0x3f3504f3, v36
	v_pk_add_f32 v[30:31], v[44:45], v[30:31]
	v_pk_add_f32 v[18:19], v[18:19], v[26:27]
	v_add_f32_e32 v26, v20, v29
	v_sub_f32_e32 v27, v21, v28
	v_sub_f32_e32 v20, v20, v29
	v_add_f32_e32 v21, v21, v28
	v_mul_f32_e32 v28, 0x3f6c835e, v52
	v_mul_f32_e32 v29, 0x3ec3ef15, v52
	v_mul_f32_e32 v41, 0x3ec3ef15, v55
	v_mul_f32_e32 v45, 0xbf6c835e, v55
	v_fmamk_f32 v32, v37, 0x3f3504f3, v22
	v_fma_f32 v36, v37, s20, -v22
	v_mul_f32_e32 v37, 0xbf3504f3, v46
	v_fmac_f32_e32 v28, 0x3ec3ef15, v54
	v_fma_f32 v29, v54, s21, -v29
	v_fmac_f32_e32 v41, 0x3f6c835e, v56
	v_fmac_f32_e32 v45, 0x3ec3ef15, v56
	v_fmamk_f32 v54, v47, 0x3f3504f3, v37
	v_fmac_f32_e32 v37, 0xbf3504f3, v47
	v_mul_f32_e32 v44, 0x3ec3ef15, v26
	v_mul_f32_e32 v46, 0xbf6c835e, v26
	v_mul_f32_e32 v47, 0xbf3504f3, v14
	v_mul_f32_e32 v14, 0x3ec3ef15, v21
	v_mul_f32_e32 v56, 0xbf6c835e, v21
	v_fmac_f32_e32 v44, 0x3f6c835e, v27
	v_fmac_f32_e32 v46, 0x3ec3ef15, v27
	v_fma_f32 v55, v20, s76, -v14
	v_fmac_f32_e32 v56, 0x3ec3ef15, v20
	v_pk_add_f32 v[20:21], v[2:3], v[24:25]
	v_pk_add_f32 v[2:3], v[2:3], v[24:25] neg_lo:[0,1] neg_hi:[0,1]
	v_pk_add_f32 v[22:23], v[42:43], v[34:35]
	v_pk_add_f32 v[24:25], v[16:17], v[30:31] neg_lo:[0,1] neg_hi:[0,1]
	v_pk_add_f32 v[26:27], v[42:43], v[34:35] neg_lo:[0,1] neg_hi:[0,1]
	v_pk_add_f32 v[4:5], v[4:5], v[18:19] neg_lo:[0,1] neg_hi:[0,1]
	v_fmamk_f32 v52, v15, 0x3f3504f3, v47
	v_fmac_f32_e32 v47, 0xbf3504f3, v15
	v_pk_add_f32 v[14:15], v[22:23], v[20:21]
	v_pk_add_f32 v[16:17], v[20:21], v[22:23] neg_lo:[0,1] neg_hi:[0,1]
	v_pk_add_f32 v[70:71], v[2:3], v[26:27] op_sel:[0,1] op_sel_hi:[1,0]
	v_pk_add_f32 v[2:3], v[2:3], v[26:27] op_sel:[0,1] op_sel_hi:[1,0] neg_lo:[0,1] neg_hi:[0,1]
	v_pk_add_f32 v[72:73], v[24:25], v[4:5] neg_lo:[0,1] neg_hi:[0,1]
	v_pk_add_f32 v[4:5], v[24:25], v[4:5]
	v_add_f32_e32 v23, v1, v32
	v_add_f32_e32 v25, v50, v36
	v_sub_f32_e32 v1, v1, v32
	v_sub_f32_e32 v27, v50, v36
	v_add_f32_e32 v26, v28, v44
	v_add_f32_e32 v30, v29, v46
	v_sub_f32_e32 v31, v28, v44
	v_sub_f32_e32 v29, v29, v46
	v_add_f32_e32 v22, v26, v23
	v_add_f32_e32 v24, v30, v25
	v_sub_f32_e32 v26, v23, v26
	v_sub_f32_e32 v28, v25, v30
	v_add_f32_e32 v30, v29, v1
	v_sub_f32_e32 v32, v27, v31
	v_sub_f32_e32 v34, v1, v29
	v_add_f32_e32 v36, v31, v27
	v_add_f32_e32 v1, v48, v39
	v_sub_f32_e32 v23, v49, v38
	v_sub_f32_e32 v25, v48, v39
	v_add_f32_e32 v27, v49, v38
	v_add_f32_e32 v29, v33, v52
	v_add_f32_e32 v31, v40, v47
	v_sub_f32_e32 v33, v33, v52
	v_sub_f32_e32 v35, v40, v47
	v_add_f32_e32 v38, v1, v29
	v_add_f32_e32 v40, v23, v31
	v_sub_f32_e32 v42, v1, v29
	v_sub_f32_e32 v44, v23, v31
	v_add_f32_e32 v46, v25, v35
	v_sub_f32_e32 v48, v27, v33
	v_sub_f32_e32 v50, v25, v35
	v_add_f32_e32 v52, v27, v33
	v_add_f32_e32 v1, v51, v54
	v_add_f32_e32 v23, v53, v37
	v_sub_f32_e32 v25, v51, v54
	v_sub_f32_e32 v27, v53, v37
	v_add_f32_e32 v29, v41, v55
	v_add_f32_e32 v31, v45, v56
	v_sub_f32_e32 v33, v41, v55
	v_sub_f32_e32 v35, v45, v56
	v_add_f32_e32 v54, v29, v1
	v_add_f32_e32 v56, v31, v23
	v_sub_f32_e32 v58, v1, v29
	v_sub_f32_e32 v60, v23, v31
	v_add_f32_e32 v62, v35, v25
	v_sub_f32_e32 v64, v27, v33
	v_sub_f32_e32 v66, v25, v35
	v_add_f32_e32 v68, v33, v27
	v_readlane_b32 s0, v244, 11
	v_mov_b32_e32 v18, v70
	v_mov_b32_e32 v19, v3
	v_mov_b32_e32 v20, v72
	v_mov_b32_e32 v21, v5
	s_cselect_b32 s29, s12, s28
	s_cselect_b32 s42, s0, s89
	v_pk_mov_b32 v[70:71], v[2:3], v[70:71] op_sel:[1,0]
	v_pk_mov_b32 v[72:73], v[4:5], v[72:73] op_sel:[1,0]
	v_mov_b32_e32 v39, v38
	v_mov_b32_e32 v43, v42
	v_mov_b32_e32 v47, v46
	v_mov_b32_e32 v49, v48
	v_mov_b32_e32 v51, v50
	v_mov_b32_e32 v53, v52
	v_mov_b32_e32 v23, v22
	v_mov_b32_e32 v27, v26
	v_mov_b32_e32 v31, v30
	v_mov_b32_e32 v33, v32
	v_mov_b32_e32 v35, v34
	v_mov_b32_e32 v37, v36
	v_mov_b32_e32 v55, v54
	v_mov_b32_e32 v59, v58
	v_mov_b32_e32 v63, v62
	v_mov_b32_e32 v65, v64
	v_mov_b32_e32 v67, v66
	v_mov_b32_e32 v69, v68
	v_pk_mov_b32 v[74:75], v[14:15], v[14:15] op_sel:[1,0]
	v_mov_b32_e32 v25, v24
	v_mov_b32_e32 v41, v40
	v_mov_b32_e32 v57, v56
	v_pk_mov_b32 v[76:77], v[16:17], v[16:17] op_sel:[1,0]
	v_mov_b32_e32 v29, v28
	v_mov_b32_e32 v45, v44
	v_mov_b32_e32 v61, v60
	s_mov_b64 s[34:35], 0
	s_branch .LBB0_446

.LBB0_510:
	v_cvt_f32_i32_e32 v105, v105
	v_cvt_f32_i32_e32 v104, v104
	v_cvt_f32_i32_e32 v119, v108
	v_cvt_f32_i32_e32 v121, v118
	v_mul_f32_e32 v105, 0x39800000, v105
	v_mul_f32_e32 v105, 0.5, v105
	v_mul_f32_e32 v109, 0x39800000, v104
	v_sin_f32_e32 v104, v105
	v_cos_f32_e32 v202, v105
	v_mul_f32_e32 v109, 0.5, v109
	v_sin_f32_e32 v204, v109
	v_pk_mul_f32 v[206:207], v[106:107], v[104:105] op_sel:[1,0] op_sel_hi:[0,0]
	v_fma_f32 v104, v106, v202, v206
	v_fma_f32 v107, v107, v202, -v207
	v_cos_f32_e32 v202, v109
	v_pk_mul_f32 v[204:205], v[112:113], v[204:205] op_sel:[1,0] op_sel_hi:[0,0]
	v_cvt_f32_i32_e32 v117, v117
	v_cvt_f32_i32_e32 v183, v120
	v_fma_f32 v108, v112, v202, v204
	v_fma_f32 v113, v113, v202, -v205
	v_mul_f32_e32 v109, 0x39800000, v119
	v_mul_f32_e32 v109, 0.5, v109
	v_sin_f32_e32 v112, v109
	s_nop 0
	v_cos_f32_e32 v202, v109
	s_nop 0
	v_cvt_f32_i32_e32 v179, v179
	v_pk_mul_f32 v[204:205], v[114:115], v[112:113] op_sel:[1,0] op_sel_hi:[0,0]
	v_fma_f32 v118, v114, v202, v204
	v_fma_f32 v119, v115, v202, -v205
	v_mul_f32_e32 v112, 0x39800000, v121
	v_mul_f32_e32 v114, 0.5, v112
	v_sin_f32_e32 v112, v114
	s_nop 0
	v_cos_f32_e32 v202, v114
	s_nop 0
	v_cvt_f32_i32_e32 v121, v116
	v_pk_mul_f32 v[204:205], v[102:103], v[112:113] op_sel:[1,0] op_sel_hi:[0,0]
	v_fma_f32 v114, v102, v202, v204
	v_mul_f32_e32 v112, 0x39800000, v117
	v_mul_f32_e32 v115, 0.5, v112
	v_sin_f32_e32 v112, v115
	s_nop 0
	v_fma_f32 v103, v103, v202, -v205
	v_cos_f32_e32 v202, v115
	s_nop 0
	v_pk_mul_f32 v[204:205], v[100:101], v[112:113] op_sel:[1,0] op_sel_hi:[0,0]
	v_fma_f32 v116, v100, v202, v204
	v_fma_f32 v101, v101, v202, -v205
	v_mul_f32_e32 v100, 0x39800000, v121
	v_mul_f32_e32 v100, 0.5, v100
	v_sin_f32_e32 v112, v100
	s_nop 0
	v_cos_f32_e32 v202, v100
	s_nop 0
	s_mov_b32 s0, s71
	v_pk_mul_f32 v[204:205], v[98:99], v[112:113] op_sel:[1,0] op_sel_hi:[0,0]
	v_fma_f32 v120, v98, v202, v204
	v_fma_f32 v99, v99, v202, -v205
	v_cvt_f32_i32_e32 v204, v182
	v_mul_f32_e32 v98, 0x39800000, v183
	v_mul_f32_e32 v112, 0.5, v98
	v_sin_f32_e32 v98, v112
	s_nop 0
	v_cos_f32_e32 v112, v112
	s_nop 0
	s_mov_b32 s1, s21
	v_pk_mul_f32 v[182:183], v[96:97], v[98:99] op_sel:[1,0] op_sel_hi:[0,0]
	v_fma_f32 v202, v96, v112, v182
	v_fma_f32 v97, v97, v112, -v183
	v_cvt_f32_i32_e32 v112, v181
	v_mul_f32_e32 v96, 0x39800000, v204
	v_mul_f32_e32 v98, 0.5, v96
	v_sin_f32_e32 v96, v98
	v_cos_f32_e32 v98, v98
	v_mov_b32_e32 v203, v97
	v_cvt_f32_i32_e32 v204, v180
	v_pk_mul_f32 v[182:183], v[94:95], v[96:97] op_sel:[1,0] op_sel_hi:[0,0]
	v_fma_f32 v96, v94, v98, v182
	v_fma_f32 v95, v95, v98, -v183
	v_mul_f32_e32 v97, 0x39800000, v112
	v_mul_f32_e32 v97, 0.5, v97
	v_sin_f32_e32 v98, v97
	s_nop 0
	v_cos_f32_e32 v112, v97
	s_nop 0
	s_mov_b32 s22, s21
	v_pk_mul_f32 v[180:181], v[92:93], v[98:99] op_sel:[1,0] op_sel_hi:[0,0]
	v_fma_f32 v182, v92, v112, v180
	v_fma_f32 v93, v93, v112, -v181
	v_mul_f32_e32 v92, 0x39800000, v204
	v_mul_f32_e32 v92, 0.5, v92
	v_sin_f32_e32 v98, v92
	v_cos_f32_e32 v112, v92
	v_add_f32_e32 v220, v182, v104
	v_add_f32_e32 v221, v93, v107
	v_pk_mul_f32 v[180:181], v[90:91], v[98:99] op_sel:[1,0] op_sel_hi:[0,0]
	v_fma_f32 v204, v90, v112, v180
	v_fma_f32 v181, v91, v112, -v181
	v_mul_f32_e32 v90, 0x39800000, v179
	v_mul_f32_e32 v91, 0.5, v90
	v_sin_f32_e32 v90, v91
	s_nop 0
	v_cos_f32_e32 v98, v91
	s_nop 0
	v_cvt_f32_i32_e32 v112, v177
	v_pk_mul_f32 v[90:91], v[88:89], v[90:91] op_sel:[1,0] op_sel_hi:[0,0]
	v_fma_f32 v206, v88, v98, v90
	v_fma_f32 v89, v89, v98, -v91
	v_cvt_f32_i32_e32 v91, v176
	v_mul_f32_e32 v88, 0x39800000, v112
	v_mul_f32_e32 v90, 0.5, v88
	v_sin_f32_e32 v88, v90
	v_cos_f32_e32 v90, v90
	v_mov_b32_e32 v207, v89
	v_pk_add_f32 v[216:217], v[206:207], v[118:119]
	v_pk_mul_f32 v[88:89], v[86:87], v[88:89] op_sel:[1,0] op_sel_hi:[0,0]
	v_fma_f32 v176, v86, v90, v88
	v_fma_f32 v209, v87, v90, -v89
	v_mul_f32_e32 v86, 0x39800000, v91
	v_mul_f32_e32 v87, 0.5, v86
	v_sin_f32_e32 v86, v87
	s_nop 0
	v_cos_f32_e32 v88, v87
	s_nop 0
	v_cvt_f32_i32_e32 v89, v175
	v_pk_mul_f32 v[86:87], v[84:85], v[86:87] op_sel:[1,0] op_sel_hi:[0,0]
	v_add_f32_e32 v224, v176, v114
	v_add_f32_e32 v225, v209, v103
	v_fma_f32 v210, v84, v88, v86
	v_fma_f32 v213, v85, v88, -v87
	v_mul_f32_e32 v84, 0x39800000, v89
	v_mul_f32_e32 v85, 0.5, v84
	v_sin_f32_e32 v84, v85
	s_nop 0
	v_cos_f32_e32 v86, v85
	s_nop 0
	v_cvt_f32_i32_e32 v87, v174
	v_pk_mul_f32 v[84:85], v[4:5], v[84:85] op_sel:[1,0] op_sel_hi:[0,0]
	v_add_f32_e32 v218, v210, v116
	v_add_f32_e32 v219, v213, v101
	v_fma_f32 v174, v4, v86, v84
	v_mul_f32_e32 v87, 0x39800000, v87
	v_mul_f32_e32 v87, 0.5, v87
	v_fma_f32 v215, v5, v86, -v85
	v_mov_b32_e32 v5, v127
	v_sin_f32_e32 v88, v87
	v_cos_f32_e32 v4, v87
	v_cvt_f32_i32_e32 v5, v5
	v_pk_mul_f32 v[84:85], v[2:3], v[88:89] op_sel:[1,0] op_sel_hi:[0,0]
	s_barrier
	v_fma_f32 v88, v2, v4, v84
	v_fma_f32 v89, v3, v4, -v85
	s_nop 0
	v_mul_f32_e32 v2, 0x39800000, v5
	v_mul_f32_e32 v3, 0.5, v2
	v_sin_f32_e32 v2, v3
	s_nop 0
	v_cos_f32_e32 v4, v3
	s_nop 0
	v_mov_b32_e32 v3, v78
	v_ashrrev_i32_e32 v84, 31, v3
	v_lshrrev_b32_e32 v84, 24, v84
	v_and_b32_e32 v5, 0xff, v3
	v_add_lshl_u32 v3, v3, v84, 4
	v_and_or_b32 v3, v3, s87, v5
	v_ashrrev_i32_e32 v84, 4, v3
	v_lshlrev_b32_e32 v3, 3, v3
	v_lshl_add_u32 v179, v84, 3, v3
	v_pk_add_f32 v[90:91], v[88:89], v[202:203]
	v_cvt_f32_i32_e32 v3, v5
	v_add_f32_e32 v84, v174, v120
	v_add_f32_e32 v85, v215, v99
	v_add_f32_e32 v86, v204, v108
	v_add_f32_e32 v87, v181, v113
	v_pk_add_f32 v[202:203], v[88:89], v[202:203] neg_lo:[0,1] neg_hi:[0,1]
	v_add_f32_e32 v3, v3, v3
	v_mul_f32_e32 v3, 0x39800000, v3
	v_mul_f32_e32 v3, 0.5, v3
	v_sin_f32_e32 v100, v3
	v_cos_f32_e32 v230, v3
	v_pk_mul_f32 v[2:3], v[110:111], v[2:3] op_sel:[1,0] op_sel_hi:[0,0]
	v_fma_f32 v232, v110, v4, v2
	v_fma_f32 v111, v111, v4, -v3
	v_pk_add_f32 v[226:227], v[84:85], v[86:87] neg_lo:[0,1] neg_hi:[0,1]
	v_add_f32_e32 v234, v96, v232
	v_add_f32_e32 v235, v95, v111
	v_pk_add_f32 v[2:3], v[90:91], v[216:217]
	v_pk_add_f32 v[4:5], v[84:85], v[86:87]
	v_pk_add_f32 v[84:85], v[218:219], v[220:221]
	v_pk_add_f32 v[86:87], v[224:225], v[234:235]
	v_pk_add_f32 v[236:237], v[2:3], v[84:85]
	v_pk_add_f32 v[238:239], v[4:5], v[86:87]
	v_pk_add_f32 v[88:89], v[206:207], v[118:119] neg_lo:[0,1] neg_hi:[0,1]
	v_pk_mul_f32 v[228:229], v[226:227], s[20:21] op_sel_hi:[1,0]
	v_pk_add_f32 v[240:241], v[236:237], v[238:239]
	v_pk_mov_b32 v[118:119], v[88:89], v[88:89] op_sel:[1,0]
	v_add_f32_e32 v206, v202, v89
	v_sub_f32_e32 v207, v203, v88
	v_pk_fma_f32 v[226:227], v[226:227], s[20:21], v[228:229] op_sel:[0,0,1] op_sel_hi:[1,0,0]
	ds_write_b64 v179, v[240:241]
	v_sub_f32_e32 v121, v174, v120
	v_sub_f32_e32 v120, v210, v116
	v_sub_f32_e32 v112, v93, v107
	v_sub_f32_e32 v113, v181, v113
	v_sub_f32_e32 v109, v204, v108
	v_sub_f32_e32 v108, v182, v104
	v_mov_b32_e32 v233, v107
	v_sub_f32_e32 v106, v176, v114
	v_sub_f32_e32 v107, v213, v101
	v_sub_f32_e32 v94, v95, v111
	v_sub_f32_e32 v95, v182, v104
	v_sub_f32_e32 v102, v209, v103
	v_sub_f32_e32 v103, v210, v116
	v_sub_f32_e32 v92, v96, v232
	v_sub_f32_e32 v93, v93, v233
	v_pk_add_f32 v[104:105], v[106:107], v[94:95] neg_lo:[0,1] neg_hi:[0,1]
	v_sub_f32_e32 v98, v213, v101
	v_sub_f32_e32 v99, v215, v99
	v_pk_add_f32 v[96:97], v[102:103], v[92:93]
	v_pk_add_f32 v[106:107], v[106:107], v[94:95]
	v_mov_b32_e32 v94, v104
	v_mul_f32_e32 v104, 0x3ec3ef15, v104
	v_pk_add_f32 v[110:111], v[120:121], v[112:113] neg_lo:[0,1] neg_hi:[0,1]
	v_pk_add_f32 v[114:115], v[98:99], v[108:109]
	v_pk_add_f32 v[102:103], v[102:103], v[92:93] neg_lo:[0,1] neg_hi:[0,1]
	v_mul_f32_e32 v98, 0x3f6c835e, v96
	v_mov_b32_e32 v175, v203
	v_mov_b32_e32 v203, v104
	v_add_f32_e32 v104, v121, v113
	s_mov_b32 s23, s71
	v_mul_f32_e32 v116, 0x3ec3ef15, v111
	v_mul_f32_e32 v174, 0x3f6c835e, v115
	v_mul_f32_e32 v101, 0x3f3504f3, v97
	v_mov_b32_e32 v95, v107
	v_mov_b32_e32 v117, v119
	v_mov_b32_e32 v119, v98
	v_sub_f32_e32 v98, v99, v109
	v_pk_mul_f32 v[108:109], v[104:105], s[22:23] op_sel_hi:[0,1]
	v_pk_mul_f32 v[106:107], v[106:107], s[0:1] op_sel_hi:[0,1]
	v_mul_f32_e32 v120, 0x3f3504f3, v105
	v_pk_mul_f32 v[92:93], v[110:111], s[20:21]
	v_mul_f32_e32 v110, s72, v96
	v_mul_f32_e32 v111, s73, v103
	v_pk_add_f32 v[96:97], v[174:175], v[116:117]
	v_fma_f32 v112, v98, s0, v108
	v_fma_f32 v113, v98, s1, -v109
	v_fma_f32 v116, v102, s22, v106
	v_fma_f32 v117, v102, s23, -v107
	v_add_f32_e32 v98, v120, v101
	v_fma_f32 v99, v105, s20, -v101
	v_pk_add_f32 v[104:105], v[206:207], v[98:99]
	v_pk_add_f32 v[102:103], v[112:113], v[116:117]
	v_xor_b32_e32 v231, 0x80000000, v100
	v_pk_add_f32 v[106:107], v[104:105], v[102:103]
	v_pk_add_f32 v[224:225], v[224:225], v[234:235] neg_lo:[0,1] neg_hi:[0,1]
	v_pk_fma_f32 v[94:95], v[94:95], s[30:31], v[110:111] neg_lo:[0,0,1] neg_hi:[0,0,1]
	v_pk_add_f32 v[110:111], v[202:203], v[118:119] neg_lo:[0,1] neg_hi:[0,1]
	v_pk_mul_f32 v[118:119], v[100:101], v[106:107] op_sel_hi:[0,1]
	v_mul_f32_e32 v235, 0x3f3504f3, v224
	v_fma_f32 v120, v230, v106, v119
	v_fma_f32 v121, v230, v107, -v118
	v_pk_add_f32 v[222:223], v[218:219], v[220:221] neg_lo:[0,1] neg_hi:[0,1]
	v_mul_f32_e32 v218, 0x3f3504f3, v225
	v_mov_b32_e32 v224, v219
	v_mov_b32_e32 v101, v230
	v_mul_f32_e32 v225, 0xbf3504f3, v225
	v_mov_b32_e32 v88, v90
	v_sub_f32_e32 v90, v218, v235
	v_sub_f32_e32 v91, v91, v217
	v_mov_b32_e32 v219, v222
	v_mul_f32_e32 v106, v100, v100
	v_mul_f32_e32 v107, v101, v231
	v_sub_f32_e32 v88, v88, v216
	v_sub_f32_e32 v89, v229, v228
	v_sub_f32_e32 v220, v224, v221
	v_sub_f32_e32 v221, v225, v235
	v_pk_add_f32 v[216:217], v[90:91], v[222:223] op_sel:[1,0] op_sel_hi:[0,1]
	v_add_f32_e32 v222, v90, v226
	v_sub_f32_e32 v219, v91, v219
	v_pk_fma_f32 v[118:119], v[230:231], v[230:231], v[106:107] op_sel_hi:[0,1,1] neg_lo:[0,0,1] neg_hi:[0,0,1]
	v_pk_fma_f32 v[106:107], v[230:231], v[230:231], v[106:107] op_sel_hi:[0,1,1]
	v_pk_add_f32 v[224:225], v[88:89], v[220:221]
	v_pk_add_f32 v[226:227], v[226:227], v[90:91] neg_lo:[0,1] neg_hi:[0,1]
	v_pk_add_f32 v[90:91], v[88:89], v[220:221] neg_lo:[0,1] neg_hi:[0,1]
	v_add_f32_e32 v220, v224, v222
	v_add_f32_e32 v221, v225, v219
	ds_write_b64 v179, v[120:121] offset:2176
	v_mov_b32_e32 v120, v118
	v_mov_b32_e32 v121, v107
	v_mul_f32_e32 v180, v107, v107
	v_mul_f32_e32 v181, v107, v118
	v_pk_mul_f32 v[106:107], v[220:221], v[106:107] op_sel:[1,1] op_sel_hi:[0,1]
	v_pk_fma_f32 v[182:183], v[118:119], v[120:121], v[180:181] op_sel_hi:[0,1,1] neg_lo:[0,0,1] neg_hi:[0,0,1]
	v_pk_fma_f32 v[180:181], v[118:119], v[120:121], v[180:181] op_sel_hi:[0,1,1]
	v_fma_f32 v212, v220, v118, -v106
	v_fma_f32 v213, v221, v118, v107
	v_pk_mul_f32 v[118:119], v[120:121], v[180:181] op_sel:[0,1]
	v_pk_add_f32 v[98:99], v[206:207], v[98:99] neg_lo:[0,1] neg_hi:[0,1]
	v_fma_f32 v206, v120, v182, -v119
	v_fma_f32 v119, v121, v182, v118
	v_pk_add_f32 v[88:89], v[216:217], v[226:227]
	ds_write_b64 v179, v[212:213] offset:4352
	v_mov_b32_e32 v213, v119
	v_sub_f32_e32 v216, v216, v226
	v_mov_b32_e32 v212, v206
	v_pk_add_f32 v[214:215], v[90:91], v[90:91] op_sel:[0,1] op_sel_hi:[0,1]
	v_mul_f32_e32 v118, v216, v119
	v_mul_f32_e32 v119, v216, v206
	v_mov_b32_e32 v202, v182
	v_mov_b32_e32 v203, v181
	v_fma_f32 v206, v214, v206, -v118
	v_fma_f32 v207, v215, v213, v119
	v_pk_mov_b32 v[210:211], v[180:181], v[182:183] op_sel:[1,0]
	v_pk_mul_f32 v[180:181], v[202:203], v[180:181] op_sel:[0,1]
	ds_write_b64 v179, v[206:207] offset:13056
	v_pk_fma_f32 v[206:207], v[182:183], v[202:203], v[180:181] op_sel:[0,0,1] op_sel_hi:[0,1,0] neg_lo:[0,0,1] neg_hi:[0,0,1]
	v_pk_fma_f32 v[180:181], v[182:183], v[202:203], v[180:181] op_sel:[0,0,1] op_sel_hi:[0,1,0]
	s_mov_b32 s70, s20
	v_mov_b32_e32 v231, v100
	v_pk_mov_b32 v[216:217], v[180:181], v[206:207] op_sel:[1,0]
	v_pk_fma_f32 v[92:93], v[114:115], s[70:71], v[92:93] neg_lo:[0,0,1] neg_hi:[0,0,1]
	v_pk_mul_f32 v[174:175], v[230:231], v[120:121]
	v_pk_mul_f32 v[176:177], v[100:101], v[120:121]
	v_pk_mul_f32 v[208:209], v[100:101], v[202:203]
	v_mov_b32_e32 v214, v206
	v_mov_b32_e32 v215, v181
	v_pk_mul_f32 v[100:101], v[100:101], v[216:217] op_sel_hi:[0,1]
	v_pk_add_f32 v[108:109], v[92:93], v[110:111]
	v_pk_add_f32 v[114:115], v[96:97], v[94:95]
	v_pk_mul_f32 v[204:205], v[230:231], v[202:203]
	v_pk_add_f32 v[106:107], v[112:113], v[116:117] neg_lo:[0,1] neg_hi:[0,1]
	v_fma_f32 v220, v230, v214, v100
	v_fma_f32 v101, v230, v215, -v101
	v_mov_b32_e32 v230, v174
	v_pk_mov_b32 v[174:175], v[174:175], v[176:177] op_sel:[1,0]
	v_pk_add_f32 v[102:103], v[104:105], v[102:103] neg_lo:[0,1] neg_hi:[0,1]
	v_pk_add_f32 v[104:105], v[114:115], v[108:109]
	v_pk_add_f32 v[112:113], v[98:99], v[106:107] op_sel:[0,1] op_sel_hi:[1,0]
	v_pk_add_f32 v[98:99], v[98:99], v[106:107] op_sel:[0,1] op_sel_hi:[1,0] neg_lo:[0,1] neg_hi:[0,1]
	v_pk_add_f32 v[118:119], v[236:237], v[238:239] neg_lo:[0,1] neg_hi:[0,1]
	v_add_f32_e32 v176, v230, v174
	v_sub_f32_e32 v174, v230, v174
	v_sub_f32_e32 v175, v177, v175
	v_mov_b32_e32 v238, v204
	v_pk_mov_b32 v[204:205], v[204:205], v[208:209] op_sel:[1,0]
	v_pk_mul_f32 v[232:233], v[104:105], v[174:175] op_sel:[0,1]
	v_add_f32_e32 v208, v238, v204
	v_sub_f32_e32 v205, v209, v205
	v_fma_f32 v234, v104, v176, -v233
	v_fma_f32 v235, v105, v176, v232
	v_mul_f32_e32 v116, v99, v205
	v_mul_f32_e32 v117, v112, v205
	v_mov_b32_e32 v227, v101
	v_pk_mul_f32 v[104:105], v[202:203], v[174:175] op_sel:[0,1]
	v_mov_b32_e32 v239, v205
	v_fma_f32 v204, v112, v208, -v116
	v_fma_f32 v205, v99, v208, v117
	v_mov_b32_e32 v231, v175
	v_fma_f32 v174, v202, v176, -v105
	v_fma_f32 v105, v203, v176, v104
	v_mul_f32_e32 v100, v103, v101
	v_mul_f32_e32 v101, v103, v220
	v_mov_b32_e32 v230, v176
	v_mov_b32_e32 v176, v174
	v_mov_b32_e32 v177, v105
	v_mov_b32_e32 v238, v208
	ds_write_b64 v179, v[204:205] offset:10880
	v_fma_f32 v204, v102, v220, -v100
	v_fma_f32 v205, v102, v227, v101
	v_pk_mul_f32 v[180:181], v[118:119], v[180:181] op_sel:[1,1] op_sel_hi:[0,1]
	v_pk_mul_f32 v[228:229], v[120:121], v[214:215]
	v_pk_mul_f32 v[120:121], v[120:121], v[216:217]
	ds_write_b64 v179, v[234:235] offset:6528
	v_pk_mul_f32 v[232:233], v[230:231], v[214:215]
	v_pk_mul_f32 v[234:235], v[202:203], v[214:215]
	v_pk_mul_f32 v[106:107], v[214:215], v[238:239]
	v_pk_mul_f32 v[100:101], v[214:215], v[212:213]
	v_pk_mul_f32 v[208:209], v[214:215], v[176:177]
	v_fma_f32 v214, v118, v206, -v180
	v_fma_f32 v215, v119, v206, v181
	v_sub_f32_e32 v118, v224, v222
	v_sub_f32_e32 v119, v219, v225
	v_pk_add_f32 v[120:121], v[120:121], v[120:121] op_sel:[0,1] op_sel_hi:[0,1]
	v_pk_mul_f32 v[120:121], v[118:119], v[120:121] op_sel:[1,0] op_sel_hi:[0,1]
	v_pk_add_f32 v[180:181], v[228:229], v[228:229] op_sel:[0,1] op_sel_hi:[0,1] neg_lo:[0,1] neg_hi:[0,1]
	ds_write_b64 v179, v[214:215] offset:17408
	ds_write_b64 v179, v[204:205] offset:19584
	v_fma_f32 v204, v118, v180, -v120
	v_fma_f32 v205, v119, v181, v121
	v_pk_mul_f32 v[230:231], v[230:231], v[216:217]
	v_sub_f32_e32 v108, v108, v114
	v_sub_f32_e32 v109, v115, v109
	v_pk_add_f32 v[114:115], v[230:231], v[230:231] op_sel:[0,1] op_sel_hi:[0,1]
	v_pk_add_f32 v[2:3], v[2:3], v[84:85] neg_lo:[0,1] neg_hi:[0,1]
	v_pk_add_f32 v[4:5], v[4:5], v[86:87] neg_lo:[0,1] neg_hi:[0,1]
	v_pk_mul_f32 v[114:115], v[108:109], v[114:115] op_sel:[1,0] op_sel_hi:[0,1]
	v_pk_add_f32 v[118:119], v[232:233], v[232:233] op_sel:[0,1] op_sel_hi:[0,1] neg_lo:[0,1] neg_hi:[0,1]
	v_pk_add_f32 v[84:85], v[2:3], v[4:5] op_sel:[0,1] op_sel_hi:[1,0]
	v_pk_add_f32 v[2:3], v[2:3], v[4:5] op_sel:[0,1] op_sel_hi:[1,0] neg_lo:[0,1] neg_hi:[0,1]
	v_fma_f32 v120, v108, v118, -v114
	v_fma_f32 v121, v109, v119, v115
	v_pk_mul_f32 v[86:87], v[2:3], v[210:211] op_sel:[1,0]
	v_pk_mul_f32 v[236:237], v[202:203], v[216:217]
	v_fma_f32 v108, v84, v182, -v86
	v_fma_f32 v109, v84, v203, v87
	v_mov_b32_e32 v5, v85
	v_pk_add_f32 v[86:87], v[236:237], v[236:237] op_sel:[0,1] op_sel_hi:[0,1]
	v_mul_f32_e32 v84, v85, v86
	v_mul_f32_e32 v85, v2, v87
	v_pk_add_f32 v[86:87], v[234:235], v[234:235] op_sel:[0,1] op_sel_hi:[0,1] neg_lo:[0,1] neg_hi:[0,1]
	v_pk_mul_f32 v[116:117], v[216:217], v[238:239]
	v_fma_f32 v2, v2, v86, -v84
	v_fma_f32 v3, v5, v87, v85
	v_pk_add_f32 v[84:85], v[116:117], v[116:117] op_sel:[0,1] op_sel_hi:[0,1]
	ds_write_b64 v179, v[2:3] offset:26112
	v_mul_f32_e32 v4, v113, v84
	v_mul_f32_e32 v5, v98, v85
	v_pk_add_f32 v[84:85], v[106:107], v[106:107] op_sel:[0,1] op_sel_hi:[0,1] neg_lo:[0,1] neg_hi:[0,1]
	v_fma_f32 v86, v98, v84, -v4
	v_fma_f32 v87, v113, v85, v5
	v_pk_mul_f32 v[102:103], v[216:217], v[212:213]
	v_sub_f32_e32 v2, v90, v91
	v_sub_f32_e32 v3, v100, v101
	v_pk_add_f32 v[84:85], v[102:103], v[102:103] op_sel:[0,1] op_sel_hi:[0,1]
	v_mul_f32_e32 v4, v88, v84
	v_mul_f32_e32 v5, v2, v85
	v_pk_mov_b32 v[84:85], v[2:3], v[88:89] op_sel:[1,0]
	ds_write_b64 v179, v[86:87] offset:28288
	v_fma_f32 v86, v2, v84, -v4
	v_fma_f32 v87, v3, v85, v5
	v_sub_f32_e32 v2, v93, v111
	v_sub_f32_e32 v3, v96, v94
	v_sub_f32_e32 v4, v110, v92
	v_sub_f32_e32 v5, v97, v95
	v_pk_add_f32 v[84:85], v[4:5], v[2:3]
	v_pk_add_f32 v[2:3], v[4:5], v[2:3] neg_lo:[0,1] neg_hi:[0,1]
	ds_write_b64 v179, v[86:87] offset:30464
	v_mul_f32_e32 v86, v3, v105
	v_mul_f32_e32 v87, v3, v174
	v_pk_mul_f32 v[212:213], v[216:217], v[176:177]
	v_fma_f32 v88, v84, v174, -v86
	v_fma_f32 v89, v84, v177, v87
	v_mov_b32_e32 v5, v85
	v_pk_add_f32 v[86:87], v[212:213], v[212:213] op_sel:[0,1] op_sel_hi:[0,1]
	v_mul_f32_e32 v84, v85, v86
	v_mul_f32_e32 v85, v2, v87
	v_pk_add_f32 v[86:87], v[208:209], v[208:209] op_sel:[0,1] op_sel_hi:[0,1] neg_lo:[0,1] neg_hi:[0,1]
	v_fma_f32 v2, v2, v86, -v84
	v_fma_f32 v3, v5, v87, v85
	ds_write_b64 v179, v[204:205] offset:21760
	ds_write_b64 v179, v[2:3] offset:32640
	v_mov_b32_e32 v2, v78
	ds_write_b64 v179, v[120:121] offset:23936
	ds_write_b64 v179, v[108:109] offset:8704
	ds_write_b64 v179, v[88:89] offset:15232
	s_waitcnt lgkmcnt(0)
	s_barrier
	s_mov_b32 s2, s20
	v_ashrrev_i32_e32 v3, 31, v2
	v_lshrrev_b32_e32 v3, 28, v3
	v_and_b32_e32 v179, 15, v2
	v_add_u32_e32 v2, v2, v3
	v_ashrrev_i32_e32 v2, 4, v2
	v_lshlrev_b32_e32 v3, 11, v2
	v_lshl_add_u32 v2, v2, 7, v3
	v_lshl_or_b32 v242, v179, 3, v2
	ds_read2_b64 v[90:93], v242 offset1:17
	ds_read2_b64 v[94:97], v242 offset0:68 offset1:85
	ds_read2_b64 v[98:101], v242 offset0:136 offset1:153
	ds_read2_b64 v[102:105], v242 offset0:170 offset1:187
	ds_read2_b64 v[106:109], v242 offset0:204 offset1:221
	ds_read2_b64 v[110:113], v242 offset0:238 offset1:255
	ds_read2_b64 v[114:117], v242 offset0:34 offset1:51
	ds_read2_b64 v[118:121], v242 offset0:102 offset1:119
	s_waitcnt lgkmcnt(5)
	v_pk_add_f32 v[88:89], v[98:99], v[90:91]
	s_waitcnt lgkmcnt(2)
	v_pk_mov_b32 v[210:211], v[104:105], v[112:113] op_sel:[1,0]
	s_waitcnt lgkmcnt(1)
	v_pk_add_f32 v[206:207], v[116:117], v[104:105]
	s_waitcnt lgkmcnt(0)
	v_pk_add_f32 v[208:209], v[120:121], v[112:113]
	v_mov_b32_e32 v105, v113
	v_pk_add_f32 v[112:113], v[206:207], v[208:209] neg_lo:[0,1] neg_hi:[0,1]
	v_sub_f32_e32 v210, v117, v210
	v_sub_f32_e32 v211, v120, v211
	v_pk_add_f32 v[86:87], v[206:207], v[208:209]
	v_mul_f32_e32 v206, 0x3f3504f3, v113
	v_mul_f32_e32 v209, 0xbf3504f3, v113
	v_cvt_f32_i32_e32 v113, v179
	v_sub_f32_e32 v104, v116, v104
	v_sub_f32_e32 v105, v121, v105
	v_pk_add_f32 v[98:99], v[90:91], v[98:99] neg_lo:[0,1] neg_hi:[0,1]
	v_add_f32_e32 v113, v113, v113
	v_pk_add_f32 v[90:91], v[94:95], v[106:107] neg_lo:[0,1] neg_hi:[0,1]
	v_pk_add_f32 v[174:175], v[106:107], v[94:95]
	v_pk_add_f32 v[176:177], v[92:93], v[100:101]
	v_pk_add_f32 v[180:181], v[96:97], v[108:109]
	v_sub_f32_e32 v116, v104, v105
	v_mul_f32_e32 v113, 0x3b800000, v113
	v_pk_mov_b32 v[94:95], v[90:91], v[90:91] op_sel:[1,0]
	v_add_f32_e32 v106, v98, v91
	v_sub_f32_e32 v107, v99, v90
	v_pk_add_f32 v[104:105], v[104:105], v[104:105] op_sel:[0,1] op_sel_hi:[0,1]
	v_pk_add_f32 v[4:5], v[176:177], v[180:181]
	v_pk_add_f32 v[182:183], v[114:115], v[102:103]
	v_pk_add_f32 v[202:203], v[118:119], v[110:111]
	v_pk_add_f32 v[176:177], v[176:177], v[180:181] neg_lo:[0,1] neg_hi:[0,1]
	v_mul_f32_e32 v113, 0.5, v113
	v_pk_add_f32 v[90:91], v[210:211], v[210:211] op_sel:[0,1] op_sel_hi:[0,1] neg_lo:[0,1] neg_hi:[0,1]
	v_pk_mul_f32 v[104:105], v[104:105], s[0:1]
	v_pk_add_f32 v[84:85], v[182:183], v[202:203]
	v_pk_add_f32 v[204:205], v[182:183], v[202:203] neg_lo:[0,1] neg_hi:[0,1]
	v_add_f32_e32 v120, v210, v211
	v_pk_mul_f32 v[180:181], v[176:177], s[20:21] op_sel_hi:[1,0]
	v_mul_f32_e32 v112, 0x3f3504f3, v112
	v_sin_f32_e32 v182, v113
	s_nop 1
	v_cos_f32_e32 v218, v113
	s_nop 1
	v_fma_f32 v210, v90, s22, v104
	v_fma_f32 v211, v91, s23, -v105
	v_pk_add_f32 v[2:3], v[88:89], v[174:175]
	v_mov_b32_e32 v90, v88
	v_sub_f32_e32 v88, v206, v112
	v_sub_f32_e32 v89, v89, v175
	v_sub_f32_e32 v90, v90, v174
	v_sub_f32_e32 v91, v181, v180
	v_mov_b32_e32 v105, v112
	v_pk_add_f32 v[112:113], v[88:89], v[204:205] op_sel:[1,0] op_sel_hi:[0,1]
	v_mov_b32_e32 v175, v204
	v_sub_f32_e32 v104, v183, v203
	v_sub_f32_e32 v105, v209, v105
	v_sub_f32_e32 v204, v114, v102
	v_sub_f32_e32 v205, v92, v100
	v_sub_f32_e32 v206, v119, v111
	v_sub_f32_e32 v207, v97, v109
	v_mul_f32_e32 v179, 0x3f6c835e, v120
	v_mul_f32_e32 v220, 0x3ec3ef15, v116
	v_sub_f32_e32 v92, v115, v103
	v_sub_f32_e32 v93, v93, v101
	v_sub_f32_e32 v97, v96, v108
	v_sub_f32_e32 v96, v118, v110
	v_pk_add_f32 v[102:103], v[204:205], v[206:207] neg_lo:[0,1] neg_hi:[0,1]
	v_pk_fma_f32 v[176:177], v[176:177], s[20:21], v[180:181] op_sel:[0,0,1] op_sel_hi:[1,0,0]
	v_pk_add_f32 v[208:209], v[204:205], v[206:207]
	v_pk_add_f32 v[100:101], v[92:93], v[96:97] neg_lo:[0,1] neg_hi:[0,1]
	v_pk_add_f32 v[92:93], v[92:93], v[96:97]
	v_mov_b32_e32 v109, v99
	v_mov_b32_e32 v97, v95
	v_mov_b32_e32 v174, v176
	v_pk_add_f32 v[176:177], v[176:177], v[88:89] neg_lo:[0,1] neg_hi:[0,1]
	v_mul_f32_e32 v96, 0x3ec3ef15, v103
	v_pk_mul_f32 v[110:111], v[102:103], s[20:21]
	v_mul_f32_e32 v103, s73, v102
	v_mul_f32_e32 v102, s72, v120
	v_sub_f32_e32 v94, v98, v94
	v_sub_f32_e32 v95, v220, v179
	v_pk_mul_f32 v[98:99], v[208:209], s[22:23] op_sel:[1,0]
	v_add_f32_e32 v180, v88, v174
	v_sub_f32_e32 v175, v89, v175
	v_pk_add_f32 v[88:89], v[112:113], v[176:177]
	v_mul_f32_e32 v108, 0x3f6c835e, v93
	v_mul_f32_e32 v113, 0x3f3504f3, v208
	v_mul_f32_e32 v114, 0x3f3504f3, v100
	v_pk_fma_f32 v[110:111], v[92:93], s[70:71], v[110:111] neg_lo:[0,0,1] neg_hi:[0,0,1]
	v_fma_f32 v93, v92, s31, -v103
	v_fma_f32 v92, v116, s30, -v102
	v_fma_f32 v102, v101, s0, v98
	v_fma_f32 v103, v101, s1, -v99
	v_pk_add_f32 v[96:97], v[108:109], v[96:97]
	v_add_f32_e32 v98, v114, v113
	v_fma_f32 v99, v100, s20, -v113
	v_pk_add_f32 v[100:101], v[106:107], v[98:99]
	v_pk_add_f32 v[108:109], v[102:103], v[210:211]
	v_xor_b32_e32 v219, 0x80000000, v182
	v_pk_add_f32 v[114:115], v[108:109], v[100:101]
	v_pk_add_f32 v[212:213], v[2:3], v[84:85]
	v_pk_mul_f32 v[120:121], v[182:183], v[114:115] op_sel_hi:[0,1]
	v_fma_f32 v204, v218, v114, v121
	v_fma_f32 v205, v218, v115, -v120
	v_mov_b32_e32 v183, v218
	v_pk_add_f32 v[214:215], v[4:5], v[86:87]
	v_mul_f32_e32 v114, v182, v182
	v_mul_f32_e32 v115, v183, v219
	v_pk_add_f32 v[216:217], v[214:215], v[212:213]
	v_pk_fma_f32 v[120:121], v[218:219], v[218:219], v[114:115] op_sel_hi:[0,1,1] neg_lo:[0,0,1] neg_hi:[0,0,1]
	v_pk_fma_f32 v[114:115], v[218:219], v[218:219], v[114:115] op_sel_hi:[0,1,1]
	v_pk_add_f32 v[202:203], v[90:91], v[104:105]
	ds_write2_b64 v242, v[216:217], v[204:205] offset1:17
	v_pk_add_f32 v[90:91], v[90:91], v[104:105] neg_lo:[0,1] neg_hi:[0,1]
	v_add_f32_e32 v104, v202, v180
	v_add_f32_e32 v105, v203, v175
	v_mov_b32_e32 v204, v120
	v_mov_b32_e32 v205, v115
	v_mul_f32_e32 v216, v115, v115
	v_mul_f32_e32 v217, v115, v120
	v_pk_mul_f32 v[114:115], v[104:105], v[114:115] op_sel:[1,1] op_sel_hi:[0,1]
	v_pk_fma_f32 v[220:221], v[120:121], v[204:205], v[216:217] op_sel_hi:[0,1,1] neg_lo:[0,0,1] neg_hi:[0,0,1]
	v_pk_fma_f32 v[216:217], v[120:121], v[204:205], v[216:217] op_sel_hi:[0,1,1]
	v_fma_f32 v230, v104, v120, -v114
	v_fma_f32 v231, v105, v120, v115
	v_pk_mul_f32 v[114:115], v[204:205], v[216:217] op_sel:[0,1]
	v_pk_add_f32 v[102:103], v[102:103], v[210:211] neg_lo:[0,1] neg_hi:[0,1]
	v_fma_f32 v120, v204, v220, -v115
	v_fma_f32 v115, v205, v220, v114
	v_sub_f32_e32 v112, v112, v176
	v_mov_b32_e32 v211, v115
	v_mov_b32_e32 v219, v182
	v_mov_b32_e32 v222, v220
	v_mov_b32_e32 v223, v217
	v_pk_add_f32 v[232:233], v[90:91], v[90:91] op_sel:[0,1] op_sel_hi:[0,1]
	v_mul_f32_e32 v113, v112, v120
	v_mul_f32_e32 v112, v112, v115
	v_pk_mul_f32 v[206:207], v[218:219], v[204:205]
	v_pk_mul_f32 v[208:209], v[182:183], v[204:205]
	v_mov_b32_e32 v210, v120
	v_fma_f32 v114, v232, v120, -v112
	v_pk_mul_f32 v[120:121], v[222:223], v[216:217] op_sel:[0,1]
	v_pk_add_f32 v[100:101], v[100:101], v[108:109] neg_lo:[0,1] neg_hi:[0,1]
	v_pk_add_f32 v[108:109], v[110:111], v[94:95]
	v_pk_add_f32 v[116:117], v[96:97], v[92:93]
	v_fma_f32 v115, v233, v211, v113
	v_pk_fma_f32 v[176:177], v[220:221], v[222:223], v[120:121] op_sel:[0,0,1] op_sel_hi:[0,1,0] neg_lo:[0,0,1] neg_hi:[0,0,1]
	v_pk_fma_f32 v[120:121], v[220:221], v[222:223], v[120:121] op_sel:[0,0,1] op_sel_hi:[0,1,0]
	v_mov_b32_e32 v234, v206
	v_pk_mov_b32 v[206:207], v[206:207], v[208:209] op_sel:[1,0]
	v_pk_add_f32 v[118:119], v[108:109], v[116:117]
	v_pk_add_f32 v[112:113], v[212:213], v[214:215] neg_lo:[0,1] neg_hi:[0,1]
	v_pk_mov_b32 v[214:215], v[120:121], v[176:177] op_sel:[1,0]
	v_add_f32_e32 v208, v234, v206
	v_sub_f32_e32 v206, v234, v206
	v_sub_f32_e32 v207, v209, v207
	v_pk_mul_f32 v[224:225], v[218:219], v[222:223]
	v_pk_mul_f32 v[226:227], v[182:183], v[222:223]
	v_pk_add_f32 v[98:99], v[106:107], v[98:99] neg_lo:[0,1] neg_hi:[0,1]
	v_mov_b32_e32 v212, v176
	v_mov_b32_e32 v213, v121
	v_pk_mul_f32 v[182:183], v[182:183], v[214:215] op_sel_hi:[0,1]
	v_pk_mul_f32 v[236:237], v[118:119], v[206:207] op_sel:[0,1]
	v_pk_mov_b32 v[228:229], v[216:217], v[220:221] op_sel:[1,0]
	v_pk_add_f32 v[104:105], v[98:99], v[102:103] op_sel:[0,1] op_sel_hi:[1,0]
	v_pk_add_f32 v[98:99], v[98:99], v[102:103] op_sel:[0,1] op_sel_hi:[1,0] neg_lo:[0,1] neg_hi:[0,1]
	v_fma_f32 v216, v218, v212, v182
	v_fma_f32 v183, v218, v213, -v183
	v_fma_f32 v238, v118, v208, -v237
	v_fma_f32 v239, v119, v208, v236
	v_mov_b32_e32 v240, v224
	v_pk_mov_b32 v[224:225], v[224:225], v[226:227] op_sel:[1,0]
	v_mov_b32_e32 v219, v183
	v_pk_mul_f32 v[118:119], v[222:223], v[206:207] op_sel:[0,1]
	v_add_f32_e32 v226, v240, v224
	v_sub_f32_e32 v225, v227, v225
	v_mov_b32_e32 v235, v207
	v_fma_f32 v206, v222, v208, -v119
	v_fma_f32 v119, v223, v208, v118
	v_mul_f32_e32 v106, v99, v225
	v_mul_f32_e32 v107, v104, v225
	v_mul_f32_e32 v182, v101, v183
	v_mul_f32_e32 v183, v101, v216
	v_mov_b32_e32 v234, v208
	v_mov_b32_e32 v208, v206
	v_mov_b32_e32 v209, v119
	v_mov_b32_e32 v240, v226
	v_mov_b32_e32 v241, v225
	v_fma_f32 v224, v104, v226, -v106
	v_fma_f32 v225, v99, v226, v107
	v_fma_f32 v216, v100, v216, -v182
	v_fma_f32 v217, v100, v219, v183
	v_pk_mul_f32 v[120:121], v[112:113], v[120:121] op_sel:[1,1] op_sel_hi:[0,1]
	v_pk_mul_f32 v[232:233], v[204:205], v[212:213]
	v_pk_mul_f32 v[204:205], v[204:205], v[214:215]
	ds_write2_b64 v242, v[230:231], v[238:239] offset0:34 offset1:51
	v_pk_mul_f32 v[230:231], v[234:235], v[212:213]
	v_pk_mul_f32 v[234:235], v[234:235], v[214:215]
	v_pk_mul_f32 v[236:237], v[222:223], v[212:213]
	v_pk_mul_f32 v[238:239], v[222:223], v[214:215]
	v_pk_mul_f32 v[102:103], v[212:213], v[240:241]
	v_pk_mul_f32 v[106:107], v[214:215], v[240:241]
	v_pk_mul_f32 v[100:101], v[212:213], v[210:211]
	v_pk_mul_f32 v[182:183], v[214:215], v[210:211]
	v_pk_mul_f32 v[210:211], v[212:213], v[208:209]
	v_pk_mul_f32 v[212:213], v[214:215], v[208:209]
	v_fma_f32 v214, v112, v176, -v120
	v_fma_f32 v215, v113, v176, v121
	v_sub_f32_e32 v112, v202, v180
	v_sub_f32_e32 v113, v175, v203
	v_pk_add_f32 v[120:121], v[204:205], v[204:205] op_sel:[0,1] op_sel_hi:[0,1]
	v_pk_mul_f32 v[120:121], v[112:113], v[120:121] op_sel:[1,0] op_sel_hi:[0,1]
	v_pk_add_f32 v[174:175], v[232:233], v[232:233] op_sel:[0,1] op_sel_hi:[0,1] neg_lo:[0,1] neg_hi:[0,1]
	v_fma_f32 v176, v112, v174, -v120
	v_fma_f32 v177, v113, v175, v121
	v_pk_add_f32 v[2:3], v[2:3], v[84:85] neg_lo:[0,1] neg_hi:[0,1]
	v_sub_f32_e32 v108, v108, v116
	v_sub_f32_e32 v109, v117, v109
	v_pk_add_f32 v[112:113], v[234:235], v[234:235] op_sel:[0,1] op_sel_hi:[0,1]
	v_pk_add_f32 v[4:5], v[4:5], v[86:87] neg_lo:[0,1] neg_hi:[0,1]
	v_pk_mul_f32 v[112:113], v[108:109], v[112:113] op_sel:[1,0] op_sel_hi:[0,1]
	v_pk_add_f32 v[116:117], v[230:231], v[230:231] op_sel:[0,1] op_sel_hi:[0,1] neg_lo:[0,1] neg_hi:[0,1]
	v_pk_add_f32 v[84:85], v[2:3], v[4:5] op_sel:[0,1] op_sel_hi:[1,0]
	v_pk_add_f32 v[2:3], v[2:3], v[4:5] op_sel:[0,1] op_sel_hi:[1,0] neg_lo:[0,1] neg_hi:[0,1]
	v_fma_f32 v120, v108, v116, -v112
	v_fma_f32 v121, v109, v117, v113
	v_pk_mul_f32 v[86:87], v[2:3], v[228:229] op_sel:[1,0]
	v_fma_f32 v108, v84, v220, -v86
	v_fma_f32 v109, v84, v223, v87
	v_mov_b32_e32 v5, v85
	v_pk_add_f32 v[86:87], v[238:239], v[238:239] op_sel:[0,1] op_sel_hi:[0,1]
	v_mul_f32_e32 v84, v85, v86
	v_mul_f32_e32 v85, v2, v87
	v_pk_add_f32 v[86:87], v[236:237], v[236:237] op_sel:[0,1] op_sel_hi:[0,1] neg_lo:[0,1] neg_hi:[0,1]
	v_fma_f32 v2, v2, v86, -v84
	v_fma_f32 v3, v5, v87, v85
	v_pk_add_f32 v[86:87], v[106:107], v[106:107] op_sel:[0,1] op_sel_hi:[0,1]
	v_mul_f32_e32 v84, v105, v86
	v_mul_f32_e32 v85, v98, v87
	v_pk_add_f32 v[86:87], v[102:103], v[102:103] op_sel:[0,1] op_sel_hi:[0,1] neg_lo:[0,1] neg_hi:[0,1]
	v_fma_f32 v98, v98, v86, -v84
	v_fma_f32 v99, v105, v87, v85
	v_pk_add_f32 v[84:85], v[182:183], v[182:183] op_sel:[0,1] op_sel_hi:[0,1]
	ds_write2_b64 v242, v[2:3], v[98:99] offset0:204 offset1:221
	v_sub_f32_e32 v2, v90, v91
	v_sub_f32_e32 v3, v100, v101
	v_mul_f32_e32 v4, v88, v84
	v_mul_f32_e32 v5, v2, v85
	v_pk_mov_b32 v[84:85], v[2:3], v[88:89] op_sel:[1,0]
	v_fma_f32 v86, v2, v84, -v4
	v_fma_f32 v87, v3, v85, v5
	v_sub_f32_e32 v2, v94, v110
	v_sub_f32_e32 v3, v96, v92
	v_sub_f32_e32 v4, v111, v95
	v_sub_f32_e32 v5, v97, v93
	ds_write2_b64 v242, v[214:215], v[216:217] offset0:136 offset1:153
	v_pk_add_f32 v[84:85], v[4:5], v[2:3]
	v_sub_f32_e32 v88, v2, v4
	v_sub_f32_e32 v2, v5, v3
	v_mul_f32_e32 v3, v2, v206
	v_mul_f32_e32 v2, v2, v119
	v_fma_f32 v4, v84, v206, -v2
	v_fma_f32 v5, v84, v209, v3
	ds_write2_b64 v242, v[114:115], v[4:5] offset0:102 offset1:119
	v_pk_add_f32 v[4:5], v[212:213], v[212:213] op_sel:[0,1] op_sel_hi:[0,1]
	v_mul_f32_e32 v2, v85, v4
	v_mul_f32_e32 v3, v88, v5
	v_pk_add_f32 v[4:5], v[210:211], v[210:211] op_sel:[0,1] op_sel_hi:[0,1] neg_lo:[0,1] neg_hi:[0,1]
	v_fma_f32 v84, v88, v4, -v2
	v_fma_f32 v85, v85, v5, v3
	ds_write2_b64 v242, v[176:177], v[120:121] offset0:170 offset1:187
	v_mov_b32_e32 v2, v78
	ds_write2_b64 v242, v[108:109], v[224:225] offset0:68 offset1:85
	ds_write2_b64 v242, v[86:87], v[84:85] offset0:238 offset1:255
	s_waitcnt lgkmcnt(0)
	s_barrier
	s_mov_b32 s77, s71
	v_mul_lo_u32 v108, v2, s33
	ds_read2_b64 v[2:5], v108 offset1:1
	ds_read2_b64 v[84:87], v108 offset0:2 offset1:3
	ds_read2_b64 v[88:91], v108 offset0:9 offset1:10
	ds_read2_b64 v[92:95], v108 offset0:4 offset1:5
	ds_read2_b64 v[96:99], v108 offset0:6 offset1:7
	ds_read2_b64 v[100:103], v108 offset0:13 offset1:14
	ds_read2_b64 v[104:107], v108 offset0:8 offset1:15
	ds_read2_b64 v[108:111], v108 offset0:11 offset1:12
	s_waitcnt lgkmcnt(5)
	v_add_f32_e32 v112, v4, v88
	s_waitcnt lgkmcnt(3)
	s_waitcnt lgkmcnt(2)
	v_add_f32_e32 v114, v94, v100
	s_waitcnt lgkmcnt(1)
	v_pk_add_f32 v[202:203], v[2:3], v[104:105]
	v_pk_add_f32 v[2:3], v[2:3], v[104:105] neg_lo:[0,1] neg_hi:[0,1]
	s_waitcnt lgkmcnt(0)
	v_pk_add_f32 v[104:105], v[92:93], v[110:111]
	v_pk_add_f32 v[92:93], v[92:93], v[110:111] neg_lo:[0,1] neg_hi:[0,1]
	v_add_f32_e32 v113, v112, v114
	v_sub_f32_e32 v112, v112, v114
	v_mov_b32_e32 v180, v85
	v_add_f32_e32 v204, v2, v93
	v_sub_f32_e32 v205, v3, v92
	v_add_f32_e32 v114, v86, v108
	v_add_f32_e32 v115, v98, v106
	v_mov_b32_e32 v182, v97
	v_add_f32_e32 v175, v5, v89
	v_add_f32_e32 v116, v87, v109
	v_add_f32_e32 v117, v99, v107
	v_mov_b32_e32 v118, v87
	v_add_f32_e32 v206, v85, v91
	v_add_f32_e32 v207, v84, v90
	v_mov_b32_e32 v85, v4
	v_sub_f32_e32 v4, v180, v91
	v_sub_f32_e32 v5, v5, v89
	v_add_f32_e32 v179, v95, v101
	v_sub_f32_e32 v86, v86, v108
	v_sub_f32_e32 v87, v99, v107
	v_sub_f32_e32 v84, v84, v90
	v_sub_f32_e32 v85, v85, v88
	v_add_f32_e32 v88, v97, v103
	v_add_f32_e32 v89, v96, v102
	v_mov_b32_e32 v97, v94
	v_sub_f32_e32 v94, v182, v103
	v_sub_f32_e32 v95, v95, v101
	v_mov_b32_e32 v121, v106
	v_pk_add_f32 v[106:107], v[86:87], v[86:87] op_sel_hi:[0,1] neg_lo:[0,1] neg_hi:[0,1]
	v_sub_f32_e32 v90, v96, v102
	v_sub_f32_e32 v91, v97, v100
	v_sub_f32_e32 v118, v118, v109
	v_sub_f32_e32 v119, v98, v121
	v_pk_add_f32 v[102:103], v[84:85], v[94:95] neg_lo:[0,1] neg_hi:[0,1]
	v_pk_add_f32 v[180:181], v[4:5], v[90:91]
	v_add_f32_e32 v86, v86, v87
	v_add_f32_e32 v87, v84, v94
	v_mov_b32_e32 v183, v4
	v_sub_f32_e32 v4, v5, v91
	v_add_f32_e32 v84, v85, v95
	v_pk_add_f32 v[108:109], v[118:119], v[118:119] op_sel:[0,1] op_sel_hi:[1,0]
	v_mov_b32_e32 v182, v118
	v_pk_mov_b32 v[118:119], v[118:119], v[90:91] op_sel:[1,0]
	v_pk_mul_f32 v[90:91], v[4:5], s[0:1] op_sel_hi:[0,1]
	v_pk_mul_f32 v[84:85], v[84:85], s[22:23] op_sel_hi:[0,1]
	v_pk_add_f32 v[118:119], v[182:183], v[118:119] neg_lo:[0,1] neg_hi:[0,1]
	v_sub_f32_e32 v174, v175, v179
	v_pk_add_f32 v[98:99], v[114:115], v[114:115] op_sel:[0,1] op_sel_hi:[1,0]
	v_sub_f32_e32 v114, v114, v115
	v_add_f32_e32 v94, v2, v93
	v_add_f32_e32 v95, v90, v84
	v_fma_f32 v182, v4, s0, v84
	v_fma_f32 v183, v4, s1, -v85
	v_mul_f32_e32 v115, 0x3f3504f3, v112
	v_mul_f32_e32 v121, 0x3f3504f3, v174
	v_mul_f32_e32 v176, 0x3f3504f3, v114
	v_mul_f32_e32 v110, 0x3ec3ef15, v103
	v_mul_f32_e32 v90, 0x3f6c835e, v181
	v_sub_f32_e32 v4, v91, v85
	v_sub_f32_e32 v5, v3, v92
	v_sub_f32_e32 v84, v202, v104
	v_sub_f32_e32 v85, v121, v115
	v_add_f32_e32 v90, v90, v110
	v_add_f32_e32 v91, v3, v92
	v_pk_mul_f32 v[110:111], v[86:87], s[72:73]
	v_pk_mul_f32 v[114:115], v[86:87], s[74:75]
	v_pk_mul_f32 v[86:87], v[86:87], s[0:1] op_sel_hi:[0,1]
	v_fma_f32 v220, v118, s22, v86
	v_fma_f32 v221, v118, s23, -v87
	v_pk_add_f32 v[86:87], v[116:117], v[116:117] op_sel:[0,1] op_sel_hi:[0,1] neg_lo:[0,1] neg_hi:[0,1]
	v_pk_fma_f32 v[210:211], v[118:119], s[72:73], v[114:115] neg_lo:[0,0,1] neg_hi:[0,0,1]
	v_fmac_f32_e32 v115, 0x3f3504f3, v119
	v_pk_fma_f32 v[110:111], v[118:119], s[74:75], v[110:111]
	v_pk_mul_f32 v[118:119], v[86:87], s[2:3]
	v_mov_b32_e32 v177, v105
	v_mov_b32_e32 v214, v108
	v_sub_f32_e32 v222, v118, v176
	v_sub_f32_e32 v223, v203, v177
	v_pk_fma_f32 v[86:87], v[86:87], s[2:3], v[176:177] op_sel_hi:[1,1,0] neg_lo:[0,0,1] neg_hi:[0,0,1]
	v_pk_mul_f32 v[108:109], v[108:109], s[0:1] op_sel_hi:[0,1]
	v_mul_f32_e32 v3, s77, v107
	v_pk_add_f32 v[208:209], v[202:203], v[104:105] neg_lo:[0,1] neg_hi:[0,1]
	v_add_f32_e32 v96, v203, v105
	v_add_f32_e32 v97, v206, v88
	v_pk_add_f32 v[100:101], v[206:207], v[88:89] neg_lo:[0,1] neg_hi:[0,1]
	v_mov_b32_e32 v213, v107
	v_pk_mov_b32 v[218:219], v[106:107], v[180:181] op_sel:[1,0]
	v_sub_f32_e32 v2, v2, v93
	v_sub_f32_e32 v3, v3, v109
	v_pk_fma_f32 v[92:93], v[106:107], s[76:77], v[108:109] op_sel:[1,0,0] neg_lo:[0,0,1] neg_hi:[0,0,1]
	v_pk_mov_b32 v[106:107], v[206:207], v[116:117] op_sel:[1,0]
	v_fmamk_f32 v174, v112, 0x3f3504f3, v121
	v_mov_b32_e32 v215, v102
	v_mov_b32_e32 v224, v88
	v_add_f32_e32 v104, v202, v104
	v_add_f32_e32 v105, v175, v179
	v_add_f32_e32 v88, v106, v89
	v_add_f32_e32 v89, v107, v117
	v_sub_f32_e32 v116, v208, v100
	v_add_f32_e32 v117, v209, v101
	v_pk_mul_f32 v[120:121], v[102:103], s[20:21]
	v_pk_mul_f32 v[102:103], v[214:215], s[74:75]
	v_pk_mul_f32 v[214:215], v[214:215], s[72:73]
	v_sub_f32_e32 v118, v206, v224
	v_sub_f32_e32 v119, v119, v176
	v_add_f32_e32 v100, v222, v174
	v_sub_f32_e32 v177, v223, v101
	v_mov_b32_e32 v212, v180
	v_pk_fma_f32 v[216:217], v[180:181], s[70:71], v[120:121] neg_lo:[0,0,1] neg_hi:[0,0,1]
	v_pk_fma_f32 v[180:181], v[180:181], s[2:3], v[120:121] op_sel_hi:[0,1,0] neg_lo:[0,0,1] neg_hi:[0,0,1]
	v_add_f32_e32 v106, v96, v97
	v_add_f32_e32 v107, v105, v89
	v_mov_b32_e32 v112, v104
	v_mov_b32_e32 v108, v88
	v_pk_add_f32 v[88:89], v[104:105], v[88:89] neg_lo:[0,1] neg_hi:[0,1]
	v_pk_add_f32 v[104:105], v[182:183], v[220:221]
	v_pk_add_f32 v[182:183], v[84:85], v[118:119]
	s_mov_b32 s38, s71
	s_mov_b32 s39, s3
	v_fma_f32 v120, v212, s78, -v120
	v_fma_f32 v121, v213, s79, -v214
	v_pk_fma_f32 v[212:213], v[218:219], s[30:31], v[214:215] neg_lo:[0,0,1] neg_hi:[0,0,1]
	v_add_f32_e32 v86, v174, v86
	v_add_f32_e32 v87, v85, v87
	v_add_f32_e32 v100, v182, v100
	v_add_f32_e32 v101, v183, v177
	v_pk_fma_f32 v[102:103], v[218:219], s[38:39], v[102:103] neg_lo:[0,0,1] neg_hi:[0,0,1]
	v_add_f32_e32 v108, v112, v108
	v_add_f32_e32 v109, v113, v98
	v_sub_f32_e32 v86, v182, v86
	v_sub_f32_e32 v87, v177, v87
	v_add_f32_e32 v176, v2, v180
	v_add_f32_e32 v177, v91, v181
	v_pk_add_f32 v[180:181], v[90:91], v[212:213]
	v_pk_add_f32 v[182:183], v[216:217], v[2:3]
	v_mov_b32_e32 v216, v90
	v_mov_b32_e32 v3, v90
	v_pk_add_f32 v[202:203], v[106:107], v[106:107] op_sel:[1,0] op_sel_hi:[1,0]
	v_mov_b32_e32 v112, v96
	v_pk_mov_b32 v[96:97], v[96:97], v[98:99] op_sel:[1,0]
	v_add_f32_e32 v98, v204, v115
	v_add_f32_e32 v99, v205, v211
	v_sub_f32_e32 v90, v217, v102
	v_sub_f32_e32 v91, v91, v103
	v_pk_add_f32 v[102:103], v[182:183], v[180:181]
	v_pk_add_f32 v[182:183], v[108:109], v[108:109] op_sel:[1,0] op_sel_hi:[1,0]
	v_pk_mul_f32 v[202:203], v[74:75], v[202:203]
	v_pk_add_f32 v[94:95], v[94:95], v[110:111] op_sel:[0,1] op_sel_hi:[1,0] neg_lo:[0,1] neg_hi:[0,1]
	v_pk_add_f32 v[110:111], v[104:105], v[98:99]
	v_fma_f32 v204, v14, v182, -v202
	v_fma_f32 v205, v15, v183, v203
	v_pk_add_f32 v[96:97], v[112:113], v[96:97] neg_lo:[0,1] neg_hi:[0,1]
	v_pk_mul_f32 v[182:183], v[24:25], v[110:111] op_sel:[0,1] op_sel_hi:[1,0]
	v_pk_add_f32 v[4:5], v[4:5], v[210:211] neg_lo:[0,1] neg_hi:[0,1]
	v_fma_f32 v202, v22, v110, -v182
	v_fma_f32 v111, v23, v111, v183
	v_pk_mul_f32 v[182:183], v[40:41], v[100:101] op_sel:[0,1] op_sel_hi:[1,0]
	v_pk_add_f32 v[98:99], v[98:99], v[104:105] neg_lo:[0,1] neg_hi:[0,1]
	v_pk_add_f32 v[104:105], v[4:5], v[94:95]
	v_sub_f32_e32 v113, v5, v95
	v_fma_f32 v206, v38, v100, -v182
	v_fma_f32 v101, v39, v101, v183
	v_pk_mul_f32 v[182:183], v[56:57], v[102:103] op_sel:[0,1] op_sel_hi:[1,0]
	v_pk_add_f32 v[210:211], v[96:97], v[96:97] op_sel:[0,1] op_sel_hi:[0,1] neg_lo:[0,1] neg_hi:[0,1]
	v_mov_b32_e32 v115, v113
	v_sub_f32_e32 v84, v85, v119
	v_sub_f32_e32 v85, v174, v222
	v_fma_f32 v208, v54, v102, -v182
	v_fma_f32 v103, v55, v103, v183
	v_pk_add_f32 v[182:183], v[88:89], v[88:89] op_sel:[0,1] op_sel_hi:[0,1]
	v_pk_mul_f32 v[210:211], v[70:71], v[210:211]
	v_pk_add_f32 v[118:119], v[116:117], v[84:85]
	v_pk_add_f32 v[84:85], v[116:117], v[84:85] neg_lo:[0,1] neg_hi:[0,1]
	v_fma_f32 v212, v18, v182, -v210
	v_fma_f32 v213, v19, v183, v211
	v_mul_f32_e32 v112, v32, v113
	v_mul_f32_e32 v113, v33, v104
	v_pk_add_f32 v[92:93], v[216:217], v[92:93]
	v_pk_add_f32 v[2:3], v[2:3], v[120:121] neg_lo:[0,1] neg_hi:[0,1]
	v_fma_f32 v182, v30, v104, -v112
	v_fma_f32 v113, v31, v115, v113
	v_pk_add_f32 v[92:93], v[176:177], v[92:93] neg_lo:[0,1] neg_hi:[0,1]
	v_pk_add_f32 v[120:121], v[90:91], v[2:3]
	v_sub_f32_e32 v177, v91, v3
	v_mul_f32_e32 v114, v48, v85
	v_mul_f32_e32 v115, v49, v118
	v_pk_add_f32 v[106:107], v[106:107], v[106:107] op_sel:[0,1] op_sel_hi:[0,1] neg_lo:[0,1] neg_hi:[0,1]
	v_fma_f32 v210, v46, v118, -v114
	v_fma_f32 v115, v47, v85, v115
	v_mul_f32_e32 v116, v64, v177
	v_mul_f32_e32 v117, v65, v120
	v_pk_add_f32 v[108:109], v[108:109], v[108:109] op_sel:[0,1] op_sel_hi:[0,1] neg_lo:[0,1] neg_hi:[0,1]
	v_pk_mul_f32 v[106:107], v[76:77], v[106:107]
	v_fma_f32 v176, v62, v120, -v116
	v_fma_f32 v117, v63, v177, v117
	v_fma_f32 v180, v16, v108, -v106
	v_fma_f32 v181, v17, v109, v107
	v_sub_f32_e32 v4, v94, v4
	v_pk_mul_f32 v[106:107], v[28:29], v[98:99] op_sel:[0,1] op_sel_hi:[1,0]
	v_pk_add_f32 v[96:97], v[96:97], v[96:97] op_sel:[1,0] op_sel_hi:[1,0]
	v_fma_f32 v108, v26, v98, -v106
	v_fma_f32 v99, v27, v99, v107
	v_pk_mul_f32 v[106:107], v[44:45], v[86:87] op_sel:[0,1] op_sel_hi:[1,0]
	v_mov_b32_e32 v94, v4
	v_sub_f32_e32 v2, v2, v90
	v_fma_f32 v214, v42, v86, -v106
	v_fma_f32 v87, v43, v87, v107
	v_pk_mul_f32 v[106:107], v[60:61], v[92:93] op_sel:[0,1] op_sel_hi:[1,0]
	v_pk_add_f32 v[88:89], v[88:89], v[88:89] op_sel:[0,1] op_sel_hi:[0,1] neg_lo:[0,1] neg_hi:[0,1]
	v_pk_mul_f32 v[96:97], v[72:73], v[96:97]
	v_mov_b32_e32 v174, v84
	v_mov_b32_e32 v90, v2
	v_fma_f32 v216, v58, v92, -v106
	v_fma_f32 v93, v59, v93, v107
	v_fma_f32 v106, v20, v88, -v96
	v_fma_f32 v107, v21, v89, v97
	v_mul_f32_e32 v5, v37, v4
	v_mul_f32_e32 v4, v36, v105
	v_fma_f32 v88, v34, v94, -v4
	v_fma_f32 v5, v35, v105, v5
	v_mul_f32_e32 v85, v53, v84
	v_mul_f32_e32 v84, v52, v119
	v_mul_f32_e32 v3, v69, v2
	v_mul_f32_e32 v2, v68, v121
	v_fma_f32 v94, v50, v174, -v84
	v_fma_f32 v96, v66, v90, -v2
	v_fma_f32 v3, v67, v121, v3
	v_mov_b32_e32 v4, v78
	v_fma_f32 v85, v51, v119, v85
	s_barrier
	v_add_f32_e32 v220, v206, v214
	v_add_f32_e32 v221, v101, v87
	v_add_f32_e32 v226, v208, v216
	v_add_f32_e32 v227, v103, v93
	v_mul_lo_u32 v179, v4, s33
	v_add_f32_e32 v228, v176, v96
	v_add_f32_e32 v229, v117, v3
	v_mov_b32_e32 v98, v87
	v_sub_f32_e32 v86, v208, v216
	v_sub_f32_e32 v87, v101, v87
	v_sub_f32_e32 v2, v117, v3
	v_sub_f32_e32 v3, v210, v94
	v_mov_b32_e32 v89, v5
	v_add_f32_e32 v120, v202, v108
	v_add_f32_e32 v121, v111, v99
	v_add_f32_e32 v222, v210, v94
	v_add_f32_e32 v223, v115, v85
	v_sub_f32_e32 v4, v115, v85
	v_sub_f32_e32 v5, v113, v5
	v_mov_b32_e32 v112, v94
	v_sub_f32_e32 v92, v103, v93
	v_sub_f32_e32 v93, v206, v214
	v_sub_f32_e32 v84, v176, v96
	v_sub_f32_e32 v85, v115, v85
	v_pk_add_f32 v[94:95], v[86:87], v[2:3]
	v_pk_add_f32 v[2:3], v[86:87], v[2:3] neg_lo:[0,1] neg_hi:[0,1]
	v_sub_f32_e32 v109, v202, v108
	v_sub_f32_e32 v108, v206, v214
	v_sub_f32_e32 v98, v101, v98
	v_sub_f32_e32 v99, v111, v99
	v_pk_add_f32 v[96:97], v[92:93], v[84:85] neg_lo:[0,1] neg_hi:[0,1]
	v_pk_add_f32 v[84:85], v[92:93], v[84:85]
	v_pk_add_f32 v[90:91], v[204:205], v[180:181]
	v_pk_add_f32 v[104:105], v[212:213], v[106:107]
	v_add_f32_e32 v174, v182, v88
	v_add_f32_e32 v175, v113, v89
	v_sub_f32_e32 v89, v182, v88
	v_sub_f32_e32 v88, v210, v112
	v_pk_add_f32 v[100:101], v[108:109], v[4:5]
	v_mul_f32_e32 v111, 0x3f3504f3, v95
	v_mul_f32_e32 v86, s74, v94
	v_mul_f32_e32 v87, s75, v3
	v_mul_f32_e32 v4, 0x3f6c835e, v96
	v_pk_add_f32 v[118:119], v[90:91], v[104:105]
	v_pk_add_f32 v[224:225], v[220:221], v[222:223]
	v_pk_add_f32 v[230:231], v[226:227], v[228:229]
	v_pk_add_f32 v[90:91], v[90:91], v[104:105] neg_lo:[0,1] neg_hi:[0,1]
	v_pk_add_f32 v[104:105], v[220:221], v[222:223] neg_lo:[0,1] neg_hi:[0,1]
	v_fma_f32 v86, v96, s72, -v86
	v_fma_f32 v87, v85, s73, -v87
	v_fma_f32 v92, v94, s80, -v4
	v_add_f32_e32 v4, v99, v89
	v_pk_add_f32 v[218:219], v[120:121], v[174:175]
	v_pk_add_f32 v[106:107], v[212:213], v[106:107] neg_lo:[0,1] neg_hi:[0,1]
	v_mov_b32_e32 v220, v120
	v_sub_f32_e32 v120, v121, v175
	v_sub_f32_e32 v121, v227, v229
	v_pk_add_f32 v[102:103], v[98:99], v[88:89] neg_lo:[0,1] neg_hi:[0,1]
	v_pk_mul_f32 v[88:89], v[4:5], s[0:1] op_sel_hi:[0,1]
	v_sub_f32_e32 v4, v109, v5
	v_pk_add_f32 v[180:181], v[204:205], v[180:181] neg_lo:[0,1] neg_hi:[0,1]
	v_mov_b32_e32 v205, v106
	v_sub_f32_e32 v220, v220, v174
	v_sub_f32_e32 v221, v226, v228
	v_pk_mul_f32 v[120:121], v[120:121], s[20:21] op_sel_hi:[1,0]
	v_fma_f32 v98, v4, s22, -v88
	v_fma_f32 v99, v4, s23, v89
	v_fma_f32 v175, v221, s3, -v121
	v_fma_f32 v222, v220, s2, v120
	v_pk_fma_f32 v[120:121], v[220:221], s[20:21], v[120:121] op_sel_hi:[1,0,1] neg_lo:[0,0,1] neg_hi:[0,0,1]
	v_pk_add_f32 v[220:221], v[90:91], v[104:105] op_sel:[0,1] op_sel_hi:[1,0] neg_lo:[0,1] neg_hi:[0,1]
	v_pk_add_f32 v[90:91], v[90:91], v[104:105] op_sel:[0,1] op_sel_hi:[1,0]
	v_mul_f32_e32 v204, 0x3f6c835e, v103
	s_mov_b32 s38, s3
	s_mov_b32 s39, s21
	v_pk_mul_f32 v[102:103], v[102:103], s[70:71]
	v_pk_mul_f32 v[4:5], v[84:85], s[22:23] op_sel_hi:[0,1]
	v_sub_f32_e32 v212, v180, v107
	v_pk_add_f32 v[106:107], v[180:181], v[106:107] op_sel:[0,1] op_sel_hi:[1,0]
	v_mov_b32_e32 v105, v91
	v_mul_f32_e32 v180, 0x3ec3ef15, v101
	v_mul_f32_e32 v91, 0x3f3504f3, v97
	v_fma_f32 v112, v100, s38, -v102
	v_fma_f32 v101, v101, s39, v103
	v_fma_f32 v84, v2, s0, -v4
	v_fma_f32 v85, v2, s1, v5
	v_mov_b32_e32 v213, v107
	v_pk_add_f32 v[94:95], v[180:181], v[204:205] neg_lo:[0,1] neg_hi:[0,1]
	v_sub_f32_e32 v110, v91, v111
	v_fmac_f32_e32 v111, 0x3f3504f3, v97
	v_pk_add_f32 v[232:233], v[118:119], v[224:225]
	v_pk_add_f32 v[234:235], v[218:219], v[230:231]
	v_pk_add_f32 v[2:3], v[212:213], v[110:111]
	v_pk_add_f32 v[4:5], v[98:99], v[84:85]
	v_add_f32_e32 v96, v112, v106
	v_add_f32_e32 v97, v101, v92
	v_pk_add_f32 v[102:103], v[94:95], v[86:87]
	v_pk_add_f32 v[236:237], v[232:233], v[234:235]
	v_mov_b32_e32 v104, v220
	v_add_f32_e32 v226, v120, v175
	v_add_f32_e32 v227, v121, v222
	v_pk_add_f32 v[88:89], v[2:3], v[4:5]
	v_pk_add_f32 v[108:109], v[102:103], v[96:97]
	v_pk_add_f32 v[228:229], v[104:105], v[226:227]
	ds_write2_b64 v179, v[236:237], v[88:89] offset1:1
	ds_write2_b64 v179, v[228:229], v[108:109] offset0:2 offset1:3
	v_pk_add_f32 v[88:89], v[118:119], v[224:225] neg_lo:[0,1] neg_hi:[0,1]
	v_pk_add_f32 v[108:109], v[218:219], v[230:231] neg_lo:[0,1] neg_hi:[0,1]
	v_pk_add_f32 v[84:85], v[98:99], v[84:85] neg_lo:[0,1] neg_hi:[0,1]
	v_pk_add_f32 v[114:115], v[88:89], v[108:109] op_sel:[0,1] op_sel_hi:[1,0] neg_lo:[0,1] neg_hi:[0,1]
	v_pk_add_f32 v[88:89], v[88:89], v[108:109] op_sel:[0,1] op_sel_hi:[1,0]
	v_pk_add_f32 v[108:109], v[212:213], v[110:111] neg_lo:[0,1] neg_hi:[0,1]
	v_pk_add_f32 v[98:99], v[108:109], v[84:85] op_sel:[0,1] op_sel_hi:[1,0] neg_lo:[0,1] neg_hi:[0,1]
	v_pk_add_f32 v[84:85], v[108:109], v[84:85] op_sel:[0,1] op_sel_hi:[1,0]
	v_mov_b32_e32 v108, v114
	v_mov_b32_e32 v109, v89
	v_mov_b32_e32 v110, v98
	v_mov_b32_e32 v111, v85
	ds_write2_b64 v179, v[108:109], v[110:111] offset0:4 offset1:5
	v_mov_b32_e32 v91, v221
	v_sub_f32_e32 v108, v222, v121
	v_sub_f32_e32 v109, v120, v175
	v_sub_f32_e32 v92, v101, v92
	v_sub_f32_e32 v93, v94, v86
	v_sub_f32_e32 v86, v106, v112
	v_sub_f32_e32 v87, v95, v87
	v_pk_add_f32 v[110:111], v[90:91], v[108:109] neg_lo:[0,1] neg_hi:[0,1]
	v_pk_add_f32 v[90:91], v[90:91], v[108:109]
	v_pk_add_f32 v[94:95], v[86:87], v[92:93] neg_lo:[0,1] neg_hi:[0,1]
	v_pk_add_f32 v[86:87], v[86:87], v[92:93]
	v_mov_b32_e32 v92, v110
	v_mov_b32_e32 v93, v91
	v_mov_b32_e32 v100, v94
	v_mov_b32_e32 v101, v87
	ds_write2_b64 v179, v[92:93], v[100:101] offset0:6 offset1:7
	v_pk_add_f32 v[92:93], v[232:233], v[234:235] neg_lo:[0,1] neg_hi:[0,1]
	v_pk_add_f32 v[2:3], v[2:3], v[4:5] neg_lo:[0,1] neg_hi:[0,1]
	ds_write2_b64 v179, v[92:93], v[2:3] offset0:8 offset1:9
	v_pk_add_f32 v[2:3], v[104:105], v[226:227] neg_lo:[0,1] neg_hi:[0,1]
	v_sub_f32_e32 v4, v96, v102
	v_sub_f32_e32 v5, v103, v97
	ds_write2_b64 v179, v[2:3], v[4:5] offset0:10 offset1:11
	v_mov_b32_e32 v89, v115
	v_mov_b32_e32 v85, v99
	v_mov_b32_e32 v91, v111
	v_mov_b32_e32 v87, v95
	v_mov_b32_e32 v2, v78
	ds_write2_b64 v179, v[88:89], v[84:85] offset0:12 offset1:13
	ds_write2_b64 v179, v[90:91], v[86:87] offset0:14 offset1:15
	s_waitcnt lgkmcnt(0)
	s_barrier
	s_nop 0
	v_ashrrev_i32_e32 v3, 31, v2
	v_lshrrev_b32_e32 v3, 28, v3
	v_and_b32_e32 v112, 15, v2
	v_add_u32_e32 v2, v2, v3
	v_ashrrev_i32_e32 v2, 4, v2
	v_lshlrev_b32_e32 v3, 11, v2
	v_lshl_add_u32 v2, v2, 7, v3
	v_lshl_or_b32 v179, v112, 3, v2
	ds_read2_b64 v[2:5], v179 offset1:17
	ds_read2_b64 v[84:87], v179 offset0:34 offset1:51
	ds_read2_b64 v[88:91], v179 offset0:68 offset1:85
	ds_read2_b64 v[92:95], v179 offset0:102 offset1:119
	ds_read2_b64 v[96:99], v179 offset0:136 offset1:153
	ds_read2_b64 v[100:103], v179 offset0:170 offset1:187
	ds_read2_b64 v[104:107], v179 offset0:204 offset1:221
	ds_read2_b64 v[108:111], v179 offset0:238 offset1:255
	s_waitcnt lgkmcnt(4)
	v_mov_b32_e32 v228, v92
	v_cvt_f32_i32_e32 v112, v112
	v_mov_b32_e32 v229, v91
	v_pk_mov_b32 v[90:91], v[92:93], v[90:91] op_sel:[1,0]
	v_add_f32_e32 v112, v112, v112
	v_mul_f32_e32 v112, 0x3b800000, v112
	v_mul_f32_e32 v112, 0.5, v112
	v_sin_f32_e32 v113, v112
	v_cos_f32_e32 v112, v112
	v_mul_f32_e32 v116, v113, v113
	v_mul_f32_e32 v114, v112, v113
	v_pk_fma_f32 v[116:117], v[112:113], v[112:113], v[116:117] op_sel_hi:[1,1,0] neg_lo:[0,0,1] neg_hi:[0,0,1]
	v_add_f32_e32 v114, v114, v114
	v_mov_b32_e32 v118, v116
	v_mov_b32_e32 v119, v112
	v_mov_b32_e32 v115, v113
	v_pk_mul_f32 v[120:121], v[118:119], v[116:117] op_sel_hi:[1,0]
	v_pk_mul_f32 v[176:177], v[114:115], v[116:117] op_sel_hi:[1,0]
	v_pk_fma_f32 v[204:205], v[114:115], v[114:115], v[120:121] op_sel_hi:[1,0,1] neg_lo:[1,0,0] neg_hi:[1,0,0]
	v_pk_fma_f32 v[180:181], v[118:119], v[114:115], v[176:177] op_sel_hi:[1,0,1]
	v_mov_b32_e32 v206, v204
	v_mov_b32_e32 v207, v112
	v_mov_b32_e32 v212, v114
	v_mov_b32_e32 v213, v180
	v_mul_f32_e32 v175, v119, v114
	v_mov_b32_e32 v182, v180
	v_mov_b32_e32 v183, v113
	v_pk_mul_f32 v[208:209], v[206:207], v[204:205] op_sel_hi:[1,0]
	v_mov_b32_e32 v117, v204
	v_pk_mul_f32 v[216:217], v[212:213], v[204:205] op_sel_hi:[1,0]
	v_pk_mul_f32 v[218:219], v[182:183], v[116:117]
	v_pk_mul_f32 v[214:215], v[180:181], v[212:213] op_sel_hi:[0,1]
	v_add_f32_e32 v174, v217, v217
	v_add_f32_e32 v175, v175, v177
	v_pk_fma_f32 v[176:177], v[206:207], v[212:213], v[218:219]
	v_fma_f32 v120, -v182, v180, v208
	v_fma_f32 v121, -v183, v114, v121
	v_mul_f32_e32 v202, v204, v181
	v_mul_f32_e32 v218, v180, v205
	v_pk_mul_f32 v[220:221], v[182:183], v[204:205] op_sel_hi:[1,0]
	v_pk_fma_f32 v[182:183], v[182:183], v[180:181], v[208:209] op_sel_hi:[1,0,1] neg_lo:[1,0,0] neg_hi:[1,0,0]
	v_pk_fma_f32 v[208:209], v[204:205], v[116:117], v[214:215] op_sel_hi:[0,1,1] neg_lo:[0,0,1] neg_hi:[0,0,1]
	v_pk_fma_f32 v[214:215], v[116:117], v[180:181], v[216:217] op_sel_hi:[1,0,1]
	v_add_f32_e32 v202, v202, v218
	v_add_f32_e32 v203, v217, v217
	v_mov_b32_e32 v219, v112
	v_pk_mul_f32 v[212:213], v[180:181], v[180:181] op_sel_hi:[0,1]
	v_pk_fma_f32 v[206:207], v[206:207], v[180:181], v[220:221] op_sel_hi:[1,0,1]
	v_mov_b32_e32 v218, v182
	v_mul_f32_e32 v112, v215, v116
	v_mul_f32_e32 v113, v113, v182
	v_pk_fma_f32 v[212:213], v[204:205], v[204:205], v[212:213] op_sel_hi:[0,1,1] neg_lo:[0,0,1] neg_hi:[0,0,1]
	v_fma_f32 v112, v218, v114, v112
	v_fma_f32 v113, v219, v215, v113
	v_pk_mov_b32 v[220:221], v[214:215], v[180:181] op_sel:[1,0]
	v_mov_b32_e32 v219, v204
	v_pk_mul_f32 v[222:223], v[220:221], v[202:203]
	v_pk_mul_f32 v[220:221], v[220:221], v[212:213] op_sel:[0,1] op_sel_hi:[1,0]
	v_pk_mul_f32 v[206:207], v[206:207], v[208:209]
	v_pk_fma_f32 v[208:209], v[218:219], v[212:213], v[222:223] op_sel:[0,1,0] op_sel_hi:[1,0,1] neg_lo:[0,0,1] neg_hi:[0,0,1]
	v_pk_fma_f32 v[218:219], v[218:219], v[202:203], v[220:221]
	v_mov_b32_e32 v220, v84
	v_mov_b32_e32 v221, v5
	v_pk_mov_b32 v[4:5], v[84:85], v[4:5] op_sel:[1,0]
	v_pk_mul_f32 v[210:211], v[114:115], v[180:181] op_sel_hi:[1,0]
	v_pk_mul_f32 v[216:217], v[114:115], v[214:215] op_sel:[0,1]
	v_pk_mul_f32 v[84:85], v[4:5], v[114:115]
	v_pk_mul_f32 v[114:115], v[220:221], v[114:115]
	v_mul_f32_e32 v174, v204, v174
	v_mul_f32_e32 v175, v182, v175
	v_pk_fma_f32 v[222:223], v[220:221], v[118:119], v[84:85] neg_lo:[0,0,1] neg_hi:[0,0,1]
	v_fma_f32 v85, v221, v119, v85
	v_fma_f32 v221, v5, v119, -v115
	v_fma_f32 v4, v4, v118, v114
	v_pk_fma_f32 v[210:211], v[118:119], v[204:205], v[210:211] op_sel_hi:[1,0,1] neg_lo:[0,0,1] neg_hi:[0,0,1]
	v_pk_fma_f32 v[216:217], v[118:119], v[182:183], v[216:217] op_sel_hi:[1,0,1] neg_lo:[0,0,1] neg_hi:[0,0,1]
	v_fma_f32 v120, v180, v120, v174
	v_fma_f32 v121, v215, v121, v175
	v_pk_mul_f32 v[174:175], v[214:215], v[176:177] op_sel:[1,0]
	v_mul_f32_e32 v220, v87, v181
	v_pk_mul_f32 v[92:93], v[90:91], v[176:177]
	v_pk_mul_f32 v[176:177], v[228:229], v[176:177]
	v_pk_fma_f32 v[174:175], v[182:183], v[210:211], v[174:175] op_sel_hi:[0,1,1] neg_lo:[0,0,1] neg_hi:[0,0,1]
	v_fma_f32 v118, v86, v205, -v220
	v_mov_b32_e32 v224, v88
	v_mov_b32_e32 v225, v87
	v_pk_mov_b32 v[86:87], v[88:89], v[86:87] op_sel:[1,0]
	v_fma_f32 v230, v228, v210, -v92
	v_fma_f32 v93, v229, v211, v93
	v_pk_fma_f32 v[228:229], v[90:91], v[210:211], v[176:177] neg_lo:[0,0,1] neg_hi:[0,0,1]
	v_fma_f32 v90, v90, v210, v176
	v_mov_b32_e32 v211, v89
	v_mul_f32_e32 v89, v88, v180
	v_mul_f32_e32 v88, v95, v202
	v_mul_f32_e32 v92, v95, v213
	v_pk_mul_f32 v[116:117], v[180:181], v[214:215] op_sel:[0,1]
	v_pk_mul_f32 v[86:87], v[86:87], v[180:181]
	v_mov_b32_e32 v210, v94
	v_fma_f32 v94, v94, v202, v92
	s_waitcnt lgkmcnt(2)
	v_mov_b32_e32 v202, v100
	v_mov_b32_e32 v203, v99
	v_pk_mov_b32 v[98:99], v[100:101], v[98:99] op_sel:[1,0]
	v_pk_fma_f32 v[116:117], v[204:205], v[182:183], v[116:117] op_sel_hi:[1,0,1] neg_lo:[0,0,1] neg_hi:[0,0,1]
	v_fma_f32 v226, v224, v204, -v86
	v_fma_f32 v87, v225, v205, v87
	v_pk_mov_b32 v[204:205], v[212:213], v[204:205] op_sel:[1,0]
	v_pk_mul_f32 v[100:101], v[98:99], v[112:113]
	v_pk_mul_f32 v[112:113], v[202:203], v[112:113]
	v_fma_f32 v180, v210, v204, -v88
	v_fma_f32 v89, v211, v205, v89
	v_fma_f32 v204, v202, v216, -v100
	v_fma_f32 v101, v203, v217, v101
	v_fma_f32 v203, v99, v217, -v113
	v_fma_f32 v98, v98, v216, v112
	v_pk_mov_b32 v[212:213], v[116:117], v[182:183] op_sel:[1,0]
	v_mul_f32_e32 v216, v103, v121
	v_mul_f32_e32 v217, v96, v215
	v_pk_fma_f32 v[206:207], v[182:183], v[214:215], v[206:207]
	v_fma_f32 v232, v102, v212, -v216
	v_fma_f32 v211, v97, v213, v217
	v_mov_b32_e32 v213, v103
	s_waitcnt lgkmcnt(1)
	v_mul_f32_e32 v103, v102, v121
	v_mul_f32_e32 v102, v105, v120
	v_fma_f32 v120, v104, v116, -v102
	v_fma_f32 v103, v213, v117, v103
	s_waitcnt lgkmcnt(0)
	v_mov_b32_e32 v212, v108
	v_mov_b32_e32 v213, v107
	v_pk_mov_b32 v[106:107], v[108:109], v[106:107] op_sel:[1,0]
	v_pk_mul_f32 v[108:109], v[106:107], v[206:207]
	v_pk_mul_f32 v[206:207], v[212:213], v[206:207]
	v_fma_f32 v216, v212, v174, -v108
	v_fma_f32 v109, v213, v175, v109
	v_fma_f32 v213, v107, v175, -v207
	v_fma_f32 v106, v106, v174, v206
	v_mov_b32_e32 v207, v105
	v_mul_f32_e32 v105, v104, v219
	v_mul_f32_e32 v104, v111, v218
	v_fma_f32 v234, v110, v208, -v104
	v_fma_f32 v105, v207, v209, v105
	v_pk_mov_b32 v[206:207], v[96:97], v[110:111] op_sel:[1,0]
	v_mul_f32_e32 v206, v206, v215
	v_mul_f32_e32 v207, v207, v218
	v_fma_f32 v110, v96, v182, -v206
	v_fma_f32 v97, v111, v208, v207
	v_mov_b32_e32 v111, v97
	v_add_f32_e32 v206, v118, v232
	v_add_f32_e32 v207, v3, v211
	v_mov_b32_e32 v233, v98
	v_mov_b32_e32 v225, v87
	v_mov_b32_e32 v117, v103
	v_mov_b32_e32 v183, v94
	v_add_f32_e32 v208, v180, v234
	v_add_f32_e32 v209, v89, v105
	v_add_f32_e32 v112, v221, v203
	v_add_f32_e32 v113, v4, v98
	v_add_f32_e32 v114, v229, v213
	v_add_f32_e32 v115, v90, v106
	v_add_f32_e32 v174, v222, v204
	v_add_f32_e32 v175, v85, v101
	v_sub_f32_e32 v84, v4, v98
	v_sub_f32_e32 v85, v85, v101
	v_mov_b32_e32 v235, v106
	v_sub_f32_e32 v5, v4, v233
	v_sub_f32_e32 v4, v118, v232
	v_sub_f32_e32 v94, v94, v97
	v_sub_f32_e32 v95, v230, v216
	v_add_f32_e32 v176, v230, v216
	v_add_f32_e32 v177, v93, v109
	v_mov_b32_e32 v220, v222
	v_sub_f32_e32 v92, v90, v106
	v_sub_f32_e32 v93, v93, v109
	v_mov_b32_e32 v231, v229
	v_sub_f32_e32 v86, v87, v103
	v_sub_f32_e32 v87, v222, v204
	v_sub_f32_e32 v91, v90, v235
	v_sub_f32_e32 v90, v180, v234
	v_pk_add_f32 v[96:97], v[4:5], v[94:95]
	v_pk_add_f32 v[4:5], v[4:5], v[94:95] neg_lo:[0,1] neg_hi:[0,1]
	v_add_f32_e32 v182, v2, v110
	v_add_f32_e32 v183, v183, v111
	v_sub_f32_e32 v202, v220, v204
	v_sub_f32_e32 v203, v221, v203
	v_sub_f32_e32 v100, v230, v216
	v_sub_f32_e32 v101, v231, v213
	v_pk_add_f32 v[102:103], v[86:87], v[90:91] neg_lo:[0,1] neg_hi:[0,1]
	v_pk_add_f32 v[86:87], v[86:87], v[90:91]
	v_sub_f32_e32 v2, v2, v110
	v_sub_f32_e32 v3, v3, v211
	v_sub_f32_e32 v88, v89, v105
	v_sub_f32_e32 v89, v226, v120
	v_pk_add_f32 v[98:99], v[202:203], v[92:93]
	v_pk_add_f32 v[106:107], v[84:85], v[100:101] neg_lo:[0,1] neg_hi:[0,1]
	v_mul_f32_e32 v109, 0x3f3504f3, v97
	v_mul_f32_e32 v90, s74, v96
	v_mul_f32_e32 v91, s75, v5
	v_mul_f32_e32 v84, 0x3f6c835e, v102
	v_add_f32_e32 v116, v226, v120
	v_add_f32_e32 v117, v225, v117
	v_sub_f32_e32 v104, v2, v88
	v_pk_add_f32 v[110:111], v[2:3], v[88:89]
	v_mul_f32_e32 v2, 0x3ec3ef15, v99
	v_mul_f32_e32 v88, 0x3f6c835e, v107
	v_fma_f32 v90, v102, s72, -v90
	v_fma_f32 v91, v87, s73, -v91
	v_fma_f32 v94, v96, s80, -v84
	v_add_f32_e32 v84, v85, v101
	v_pk_add_f32 v[2:3], v[2:3], v[88:89] neg_lo:[0,1] neg_hi:[0,1]
	v_pk_mul_f32 v[84:85], v[84:85], s[0:1] op_sel_hi:[0,1]
	v_sub_f32_e32 v88, v203, v93
	v_pk_add_f32 v[218:219], v[112:113], v[114:115]
	v_pk_add_f32 v[236:237], v[116:117], v[182:183]
	v_sub_f32_e32 v120, v182, v116
	v_sub_f32_e32 v121, v174, v176
	v_mov_b32_e32 v210, v113
	v_mov_b32_e32 v226, v115
	v_fma_f32 v92, v88, s22, -v84
	v_fma_f32 v93, v88, s23, v85
	v_sub_f32_e32 v112, v112, v114
	v_sub_f32_e32 v113, v206, v208
	v_sub_f32_e32 v114, v175, v177
	v_sub_f32_e32 v115, v117, v183
	v_pk_mul_f32 v[106:107], v[106:107], s[70:71]
	v_pk_mul_f32 v[84:85], v[86:87], s[22:23] op_sel_hi:[0,1]
	v_mov_b32_e32 v227, v209
	v_pk_mul_f32 v[114:115], v[114:115], s[20:21] op_sel_hi:[1,0]
	v_mul_f32_e32 v100, 0x3f3504f3, v103
	v_fma_f32 v118, v98, s38, -v106
	v_fma_f32 v99, v99, s39, v107
	v_fma_f32 v86, v4, s0, -v84
	v_fma_f32 v87, v4, s1, v85
	v_pk_add_f32 v[214:215], v[174:175], v[176:177]
	v_pk_add_f32 v[224:225], v[206:207], v[208:209]
	v_mov_b32_e32 v105, v111
	v_sub_f32_e32 v210, v210, v226
	v_sub_f32_e32 v211, v207, v227
	v_fma_f32 v117, v113, s3, -v115
	v_fma_f32 v174, v112, s2, v114
	v_sub_f32_e32 v108, v100, v109
	v_fmac_f32_e32 v109, 0x3f3504f3, v103
	v_pk_add_f32 v[238:239], v[218:219], v[224:225]
	v_pk_add_f32 v[240:241], v[214:215], v[236:237]
	v_pk_fma_f32 v[112:113], v[112:113], s[20:21], v[114:115] op_sel_hi:[1,0,1] neg_lo:[0,0,1] neg_hi:[0,0,1]
	v_sub_f32_e32 v114, v120, v210
	v_pk_add_f32 v[182:183], v[120:121], v[210:211]
	v_pk_add_f32 v[4:5], v[104:105], v[108:109]
	v_pk_add_f32 v[84:85], v[92:93], v[86:87]
	v_add_f32_e32 v96, v118, v110
	v_add_f32_e32 v97, v99, v94
	v_pk_add_f32 v[100:101], v[2:3], v[90:91]
	v_pk_add_f32 v[242:243], v[240:241], v[238:239]
	v_mov_b32_e32 v115, v183
	v_add_f32_e32 v176, v112, v117
	v_add_f32_e32 v177, v113, v174
	v_pk_add_f32 v[88:89], v[4:5], v[84:85]
	v_pk_add_f32 v[102:103], v[100:101], v[96:97]
	v_pk_add_f32 v[206:207], v[114:115], v[176:177]
	ds_write2_b64 v179, v[242:243], v[88:89] offset1:17
	ds_write2_b64 v179, v[206:207], v[102:103] offset0:34 offset1:51
	v_mov_b32_e32 v89, v218
	v_mov_b32_e32 v103, v224
	v_mov_b32_e32 v224, v215
	v_mov_b32_e32 v218, v237
	v_sub_f32_e32 v88, v236, v214
	v_sub_f32_e32 v89, v89, v103
	v_pk_add_f32 v[102:103], v[224:225], v[218:219] neg_lo:[0,1] neg_hi:[0,1]
	v_pk_add_f32 v[104:105], v[104:105], v[108:109] neg_lo:[0,1] neg_hi:[0,1]
	v_pk_add_f32 v[86:87], v[92:93], v[86:87] neg_lo:[0,1] neg_hi:[0,1]
	v_sub_f32_e32 v106, v88, v102
	v_pk_add_f32 v[180:181], v[88:89], v[102:103]
	v_pk_add_f32 v[92:93], v[104:105], v[86:87] op_sel:[0,1] op_sel_hi:[1,0] neg_lo:[0,1] neg_hi:[0,1]
	v_pk_add_f32 v[86:87], v[104:105], v[86:87] op_sel:[0,1] op_sel_hi:[1,0]
	v_mov_b32_e32 v107, v181
	v_mov_b32_e32 v104, v92
	v_mov_b32_e32 v105, v87
	ds_write2_b64 v179, v[106:107], v[104:105] offset0:68 offset1:85
	v_sub_f32_e32 v183, v211, v121
	v_sub_f32_e32 v104, v174, v113
	v_sub_f32_e32 v105, v112, v117
	v_sub_f32_e32 v94, v99, v94
	v_sub_f32_e32 v95, v2, v90
	v_sub_f32_e32 v2, v110, v118
	v_sub_f32_e32 v3, v3, v91
	v_pk_add_f32 v[106:107], v[182:183], v[104:105] neg_lo:[0,1] neg_hi:[0,1]
	v_pk_add_f32 v[104:105], v[182:183], v[104:105]
	v_pk_add_f32 v[90:91], v[2:3], v[94:95] neg_lo:[0,1] neg_hi:[0,1]
	v_pk_add_f32 v[2:3], v[2:3], v[94:95]
	v_mov_b32_e32 v108, v106
	v_mov_b32_e32 v109, v105
	v_mov_b32_e32 v94, v90
	v_mov_b32_e32 v95, v3
	ds_write2_b64 v179, v[108:109], v[94:95] offset0:102 offset1:119
	v_mov_b32_e32 v95, v239
	v_mov_b32_e32 v239, v241
	v_sub_f32_e32 v94, v240, v238
	v_sub_f32_e32 v95, v95, v239
	v_pk_add_f32 v[4:5], v[4:5], v[84:85] neg_lo:[0,1] neg_hi:[0,1]
	ds_write2_b64 v179, v[94:95], v[4:5] offset0:136 offset1:153
	v_pk_add_f32 v[4:5], v[114:115], v[176:177] neg_lo:[0,1] neg_hi:[0,1]
	v_sub_f32_e32 v84, v96, v100
	v_sub_f32_e32 v85, v101, v97
	ds_write2_b64 v179, v[4:5], v[84:85] offset0:170 offset1:187
	v_sub_f32_e32 v181, v103, v89
	v_mov_b32_e32 v105, v107
	v_mov_b32_e32 v3, v91
	v_add_u32_e32 v112, s43, v78
	v_mov_b32_e32 v87, v93
	ds_write2_b64 v179, v[104:105], v[2:3] offset0:238 offset1:255
	v_mov_b32_e32 v2, v78
	v_ashrrev_i32_e32 v113, 31, v112
	ds_write2_b64 v179, v[180:181], v[86:87] offset0:204 offset1:221
	s_waitcnt lgkmcnt(0)
	s_barrier
	v_lshl_add_u64 v[112:113], v[112:113], 2, s[94:95]
	v_ashrrev_i32_e32 v3, 31, v2
	s_movk_i32 s0, 0x1000
	v_lshrrev_b32_e32 v3, 24, v3
	v_add_co_u32_e32 v114, vcc, s0, v112
	v_and_b32_e32 v182, 0xff, v2
	v_add_lshl_u32 v2, v2, v3, 4
	v_addc_co_u32_e32 v115, vcc, 0, v113, vcc
	v_and_or_b32 v2, v2, s87, v182
	v_add_co_u32_e32 v202, vcc, s27, v112
	v_ashrrev_i32_e32 v3, 4, v2
	v_lshlrev_b32_e32 v2, 3, v2
	v_addc_co_u32_e32 v203, vcc, 0, v113, vcc
	v_lshl_add_u32 v2, v3, 3, v2
	v_add_co_u32_e32 v204, vcc, s86, v112
	ds_read_b64 v[84:85], v2
	ds_read_b64 v[110:111], v2 offset:2176
	ds_read_b64 v[108:109], v2 offset:4352
	ds_read_b64 v[106:107], v2 offset:6528
	ds_read_b64 v[104:105], v2 offset:8704
	ds_read_b64 v[102:103], v2 offset:10880
	ds_read_b64 v[100:101], v2 offset:13056
	ds_read_b64 v[98:99], v2 offset:15232
	ds_read_b64 v[96:97], v2 offset:17408
	ds_read_b64 v[94:95], v2 offset:19584
	ds_read_b64 v[92:93], v2 offset:21760
	ds_read_b64 v[90:91], v2 offset:23936
	ds_read_b64 v[88:89], v2 offset:26112
	ds_read_b64 v[86:87], v2 offset:28288
	ds_read_b64 v[4:5], v2 offset:30464
	ds_read_b64 v[2:3], v2 offset:32640
	v_addc_co_u32_e32 v205, vcc, 0, v113, vcc
	global_load_dword v180, v[112:113], off
	global_load_dword v179, v[112:113], off offset:1024
	global_load_dword v177, v[112:113], off offset:2048
	global_load_dword v176, v[112:113], off offset:3072
	global_load_dword v174, v[114:115], off offset:1024
	global_load_dword v121, v[114:115], off offset:2048
	global_load_dword v120, v[114:115], off offset:3072
	s_nop 0
	global_load_dword v115, v[204:205], off
	global_load_dword v175, v[202:203], off offset:-4096
	global_load_dword v119, v[202:203], off
	global_load_dword v118, v[202:203], off offset:1024
	global_load_dword v117, v[202:203], off offset:2048
	global_load_dword v116, v[202:203], off offset:3072
	global_load_dword v114, v[204:205], off offset:1024
	global_load_dword v113, v[204:205], off offset:2048
	global_load_dword v112, v[204:205], off offset:3072
	v_lshl_add_u64 v[202:203], s[40:41], 0, v[80:81]
	v_add_co_u32_e32 v206, vcc, s27, v202
	v_lshl_add_u64 v[214:215], s[40:41], 0, v[82:83]
	s_nop 0
	v_addc_co_u32_e32 v207, vcc, 0, v203, vcc
	s_nop 1
	s_waitcnt lgkmcnt(0)
	s_barrier
	global_load_dwordx4 v[202:205], v[202:203], off
	s_nop 0
	global_load_dwordx4 v[206:209], v[206:207], off
	s_nop 0
	global_load_dwordx4 v[210:213], v[214:215], off
	v_add_co_u32_e32 v214, vcc, 0x2000, v214
	s_nop 1
	v_addc_co_u32_e32 v215, vcc, 0, v215, vcc
	global_load_dwordx4 v[214:217], v[214:215], off
	s_andn2_b64 vcc, exec, s[90:91]
	s_waitcnt vmcnt(3)
	ds_write_b128 v79, v[202:205]
	s_waitcnt vmcnt(2)
	ds_write_b128 v79, v[206:209] offset:8192
	s_waitcnt vmcnt(1)
	ds_write_b128 v79, v[210:213] offset:4096
	s_waitcnt vmcnt(0)
	ds_write_b128 v79, v[214:217] offset:12288
	s_cbranch_vccnz .LBB0_512
	v_lshl_add_u64 v[80:81], s[68:69], 0, v[80:81]
	v_add_co_u32_e32 v202, vcc, 0xb04e000, v80
	s_nop 1
	v_addc_co_u32_e32 v203, vcc, 0, v81, vcc
	v_add_co_u32_e32 v80, vcc, 0xb050000, v80
	global_load_dwordx4 v[202:205], v[202:203], off
	s_nop 0
	v_addc_co_u32_e32 v81, vcc, 0, v81, vcc
	global_load_dwordx4 v[206:209], v[80:81], off
	s_waitcnt vmcnt(1)
	ds_write_b128 v79, v[202:205] offset:16384
	s_waitcnt vmcnt(0)
	ds_write_b128 v79, v[206:209] offset:24576
	v_lshl_add_u64 v[202:203], s[68:69], 0, v[82:83]
	v_add_co_u32_e32 v80, vcc, 0xb04e000, v202
	s_nop 1
	v_addc_co_u32_e32 v81, vcc, 0, v203, vcc
	v_add_co_u32_e32 v202, vcc, 0xb050000, v202
	global_load_dwordx4 v[80:83], v[80:81], off
	s_nop 0
	v_addc_co_u32_e32 v203, vcc, 0, v203, vcc
	global_load_dwordx4 v[202:205], v[202:203], off
	s_waitcnt vmcnt(1)
	ds_write_b128 v79, v[80:83] offset:20480
	s_waitcnt vmcnt(0)
	ds_write_b128 v79, v[202:205] offset:28672

.LBB0_599:
	s_ashr_i32 s0, s2, 31
	s_lshr_b32 s0, s0, 26
	s_add_i32 s0, s2, s0
	s_andn2_b32 s0, s0, 63
	s_sub_i32 s1, s2, s0
	s_bfe_i32 s22, s1, 0x80000
	s_bfe_u32 s22, s22, 0x3000c
	s_add_i32 s23, s1, s22
	s_bfe_i32 s22, s23, 0x80000
	s_sext_i32_i16 s22, s22
	s_and_b32 s22, s22, -8
	s_add_i32 s22, s22, s0
	v_readlane_b32 s0, v246, 0
	s_or_b32 s22, s22, s0
	s_and_b32 s0, s23, 0xf8
	s_sub_i32 s0, s1, s0
	s_sext_i32_i8 s0, s0
	s_lshl_b32 s23, s0, 7
	v_readlane_b32 s0, v246, 22
	s_lshl_b32 s24, s22, 7
	v_readlane_b32 s0, v245, 5
	v_readlane_b32 s1, v245, 6
	v_ashrrev_i32_e32 v1, 1, v184
	v_and_b32_e32 v1, 0xffffffc0, v1
	v_lshrrev_b32_e32 v67, 3, v184
	v_and_b32_e32 v67, 4, v67
	v_add_u32_e32 v1, s24, v1
	v_or_b32_e32 v1, v1, v67
	v_and_b32_e32 v68, 0x5f, v184
	v_or_b32_e32 v68, s23, v68
	v_lshlrev_b32_e32 v69, 2, v68
	v_lshl_add_u32 v70, v1, 12, v69
	s_add_i32 s28, s24, 0xffffe000
	s_ashr_i32 s28, s28, 12
	s_mulk_i32 s28, 0xc00
	s_addk_i32 s28, 0x800
	s_cmp_gt_i32 s22, 63
	s_cselect_b32 s28, s28, 0x6800
	v_add_lshl_u32 v71, v68, s28, 2
	v_mov_b32_e32 v218, v70
	v_add_u32_e32 v219, 0x1000, v70
	v_add_u32_e32 v220, 0x2000, v70
	v_add_u32_e32 v221, 0x3000, v70
	v_add_u32_e32 v222, 0x8000, v70
	v_add_u32_e32 v223, 0x9000, v70
	v_add_u32_e32 v224, 0xa000, v70
	v_add_u32_e32 v225, 0xb000, v70
	v_add_u32_e32 v226, 0x10000, v70
	v_add_u32_e32 v227, 0x11000, v70
	v_add_u32_e32 v228, 0x12000, v70
	v_add_u32_e32 v229, 0x13000, v70
	v_add_u32_e32 v230, 0x18000, v70
	v_add_u32_e32 v231, 0x19000, v70
	v_add_u32_e32 v232, 0x1a000, v70
	v_add_u32_e32 v233, 0x1b000, v70
	global_load_dword v234, v71, s[0:1]
	global_load_dword v235, v71, s[0:1] offset:128
	s_barrier
	v_lshrrev_b32_e32 v122, 6, v184
	v_and_b32_e32 v123, 63, v184
	v_readfirstlane_b32 s39, v122
	v_lshrrev_b32_e32 v124, 4, v123
	v_and_b32_e32 v125, 15, v123
	v_lshlrev_b32_e32 v126, 2, v124
	v_xor_b32_e32 v125, v125, v126
	v_mul_u32_u24_e32 v124, 0x14000, v124
	v_readlane_b32 s0, v246, 22
	v_readlane_b32 s1, v246, 23
	s_nop 3
	s_lshl_b32 s101, s39, 12
	s_mul_i32 s100, s39, 0x140000
	s_lshl_b32 s28, s24, 1
	s_add_u32 s100, s100, s28
	s_add_u32 s100, s100, 0xb04a000
	s_add_u32 s28, s68, s100
	s_addc_u32 s29, s69, 0
	v_xor_b32_e32 v126, 0, v125
	v_lshl_add_u32 v126, v126, 4, v124
	v_mov_b32_e32 v127, 0
	v_lshl_add_u64 v[98:99], v[126:127], 0, s[28:29]
	s_add_u32 s28, s28, 0x50000
	s_addc_u32 s29, s29, 0
	v_xor_b32_e32 v126, 1, v125
	v_lshl_add_u32 v126, v126, 4, v124
	v_mov_b32_e32 v127, 0
	v_lshl_add_u64 v[100:101], v[126:127], 0, s[28:29]
	s_add_u32 s28, s28, 0x50000
	s_addc_u32 s29, s29, 0
	v_xor_b32_e32 v126, 2, v125
	v_lshl_add_u32 v126, v126, 4, v124
	v_mov_b32_e32 v127, 0
	v_lshl_add_u64 v[102:103], v[126:127], 0, s[28:29]
	s_add_u32 s28, s28, 0x50000
	s_addc_u32 s29, s29, 0
	v_xor_b32_e32 v126, 3, v125
	v_lshl_add_u32 v126, v126, 4, v124
	v_mov_b32_e32 v127, 0
	v_lshl_add_u64 v[104:105], v[126:127], 0, s[28:29]
	v_lshrrev_b32_e32 v124, 3, v123
	v_lshrrev_b32_e32 v125, 4, v123
	v_and_b32_e32 v126, 7, v123
	s_lshl_b32 s100, s39, 5
	s_add_i32 s100, s100, s23
	s_lshl_b32 s100, s100, 11
	s_add_u32 s0, s0, s100
	s_addc_u32 s1, s1, 0
	v_and_b32_e32 v127, 7, v125
	v_xor_b32_e32 v127, v126, v127
	v_lshlrev_b32_e32 v127, 4, v127
	v_lshl_add_u32 v128, v124, 11, v127
	v_mov_b32_e32 v96, v128
	v_mov_b32_e32 v97, 0
	v_lshl_add_u64 v[106:107], v[96:97], 0, s[0:1]
	s_add_u32 s0, s0, 0x4000
	s_addc_u32 s1, s1, 0
	v_add_u32_e32 v127, 4, v125
	v_and_b32_e32 v127, 7, v127
	v_xor_b32_e32 v127, v126, v127
	v_lshlrev_b32_e32 v127, 4, v127
	v_lshl_add_u32 v128, v124, 11, v127
	v_mov_b32_e32 v96, v128
	v_mov_b32_e32 v97, 0
	v_lshl_add_u64 v[108:109], v[96:97], 0, s[0:1]
	s_add_u32 s0, s0, 0x4000
	s_addc_u32 s1, s1, 0
	v_and_b32_e32 v127, 7, v125
	v_xor_b32_e32 v127, v126, v127
	v_lshlrev_b32_e32 v127, 4, v127
	v_lshl_add_u32 v128, v124, 11, v127
	v_mov_b32_e32 v96, v128
	v_mov_b32_e32 v97, 0
	v_lshl_add_u64 v[110:111], v[96:97], 0, s[0:1]
	s_add_u32 s0, s0, 0x4000
	s_addc_u32 s1, s1, 0
	v_add_u32_e32 v127, 4, v125
	v_and_b32_e32 v127, 7, v127
	v_xor_b32_e32 v127, v126, v127
	v_lshlrev_b32_e32 v127, 4, v127
	v_lshl_add_u32 v128, v124, 11, v127
	v_mov_b32_e32 v96, v128
	v_mov_b32_e32 v97, 0
	v_lshl_add_u64 v[112:113], v[96:97], 0, s[0:1]
	s_mov_b32 s28, 0x500000
	s_mov_b32 s29, 0
	s_mov_b32 s36, 128
	s_mov_b32 s37, 0
	s_add_u32 m0, s101, 0x0
	s_nop 0
	global_load_lds_dwordx4 v[98:99], off
	v_lshl_add_u64 v[98:99], v[98:99], 0, s[28:29]
	s_add_u32 m0, s101, 0x400
	s_nop 0
	global_load_lds_dwordx4 v[100:101], off
	v_lshl_add_u64 v[100:101], v[100:101], 0, s[28:29]
	s_add_u32 m0, s101, 0x800
	s_nop 0
	global_load_lds_dwordx4 v[102:103], off
	v_lshl_add_u64 v[102:103], v[102:103], 0, s[28:29]
	s_add_u32 m0, s101, 0xc00
	s_nop 0
	global_load_lds_dwordx4 v[104:105], off
	v_lshl_add_u64 v[104:105], v[104:105], 0, s[28:29]
	s_add_u32 m0, s101, 0x4000
	s_nop 0
	global_load_lds_dwordx4 v[106:107], off
	v_lshl_add_u64 v[106:107], v[106:107], 0, s[36:37]
	s_add_u32 m0, s101, 0x4400
	s_nop 0
	global_load_lds_dwordx4 v[108:109], off
	v_lshl_add_u64 v[108:109], v[108:109], 0, s[36:37]
	s_add_u32 m0, s101, 0x4800
	s_nop 0
	global_load_lds_dwordx4 v[110:111], off
	v_lshl_add_u64 v[110:111], v[110:111], 0, s[36:37]
	s_add_u32 m0, s101, 0x4c00
	s_nop 0
	global_load_lds_dwordx4 v[112:113], off
	v_lshl_add_u64 v[112:113], v[112:113], 0, s[36:37]
	v_and_b32_e32 v122, 31, v123
	v_lshrrev_b32_e32 v124, 5, v123
	v_bfe_u32 v125, v123, 4, 1
	v_bfe_u32 v126, v123, 2, 2
	v_and_b32_e32 v127, 3, v123
	s_lshr_b32 s38, s39, 1
	s_and_b32 s39, s39, 1
	v_lshlrev_b32_e32 v96, 1, v124
	v_add_u32_e32 v96, 0, v96
	v_and_b32_e32 v96, 3, v96
	v_lshl_or_b32 v96, v126, 2, v96
	v_lshrrev_b32_e32 v97, 1, v127
	v_lshl_or_b32 v97, v125, 1, v97
	v_or_b32_e32 v97, 0, v97
	s_lshl_b32 s0, s38, 3
	v_or_b32_e32 v97, s0, v97
	v_xor_b32_e32 v97, v97, v96
	v_lshlrev_b32_e32 v96, 3, v124
	v_add3_u32 v96, v96, v126, 0
	v_lshlrev_b32_e32 v96, 8, v96
	v_lshl_add_u32 v96, v97, 4, v96
	v_and_b32_e32 v97, 1, v127
	v_lshl_add_u32 v114, v97, 3, v96
	v_lshlrev_b32_e32 v96, 1, v124
	v_add_u32_e32 v96, 1, v96
	v_and_b32_e32 v96, 3, v96
	v_lshl_or_b32 v96, v126, 2, v96
	v_lshrrev_b32_e32 v97, 1, v127
	v_lshl_or_b32 v97, v125, 1, v97
	v_or_b32_e32 v97, 0, v97
	s_lshl_b32 s0, s38, 3
	v_or_b32_e32 v97, s0, v97
	v_xor_b32_e32 v97, v97, v96
	v_lshlrev_b32_e32 v96, 3, v124
	v_add3_u32 v96, v96, v126, 4
	v_lshlrev_b32_e32 v96, 8, v96
	v_lshl_add_u32 v96, v97, 4, v96
	v_and_b32_e32 v97, 1, v127
	v_lshl_add_u32 v115, v97, 3, v96
	v_lshlrev_b32_e32 v96, 1, v124
	v_add_u32_e32 v96, 0, v96
	v_and_b32_e32 v96, 3, v96
	v_lshl_or_b32 v96, v126, 2, v96
	v_lshrrev_b32_e32 v97, 1, v127
	v_lshl_or_b32 v97, v125, 1, v97
	v_or_b32_e32 v97, 4, v97
	s_lshl_b32 s0, s38, 3
	v_or_b32_e32 v97, s0, v97
	v_xor_b32_e32 v97, v97, v96
	v_lshlrev_b32_e32 v96, 3, v124
	v_add3_u32 v96, v96, v126, 0
	v_lshlrev_b32_e32 v96, 8, v96
	v_lshl_add_u32 v96, v97, 4, v96
	v_and_b32_e32 v97, 1, v127
	v_lshl_add_u32 v116, v97, 3, v96
	v_lshlrev_b32_e32 v96, 1, v124
	v_add_u32_e32 v96, 1, v96
	v_and_b32_e32 v96, 3, v96
	v_lshl_or_b32 v96, v126, 2, v96
	v_lshrrev_b32_e32 v97, 1, v127
	v_lshl_or_b32 v97, v125, 1, v97
	v_or_b32_e32 v97, 4, v97
	s_lshl_b32 s0, s38, 3
	v_or_b32_e32 v97, s0, v97
	v_xor_b32_e32 v97, v97, v96
	v_lshlrev_b32_e32 v96, 3, v124
	v_add3_u32 v96, v96, v126, 4
	v_lshlrev_b32_e32 v96, 8, v96
	v_lshl_add_u32 v96, v97, 4, v96
	v_and_b32_e32 v97, 1, v127
	v_lshl_add_u32 v117, v97, 3, v96
	v_bfe_u32 v96, v122, 1, 3
	v_xor_b32_e32 v96, v96, v124
	v_lshlrev_b32_e32 v96, 4, v96
	v_lshl_add_u32 v96, v122, 7, v96
	s_lshl_b32 s0, s39, 13
	v_add_u32_e32 v118, s0, v96
	v_xor_b32_e32 v119, 0x20, v118
	v_xor_b32_e32 v120, 0x40, v118
	v_xor_b32_e32 v121, 0x60, v118
	v_mov_b32_e32 v2, 0
	v_mov_b32_e32 v3, v2
	v_mov_b32_e32 v4, v2
	v_mov_b32_e32 v5, v2
	v_mov_b32_e32 v6, v2
	v_mov_b32_e32 v7, v2
	v_mov_b32_e32 v8, v2
	v_mov_b32_e32 v9, v2
	v_mov_b32_e32 v10, v2
	v_mov_b32_e32 v11, v2
	v_mov_b32_e32 v12, v2
	v_mov_b32_e32 v13, v2
	v_mov_b32_e32 v14, v2
	v_mov_b32_e32 v15, v2
	v_mov_b32_e32 v16, v2
	v_mov_b32_e32 v17, v2
	v_mov_b32_e32 v18, v2
	v_mov_b32_e32 v19, v2
	v_mov_b32_e32 v20, v2
	v_mov_b32_e32 v21, v2
	v_mov_b32_e32 v22, v2
	v_mov_b32_e32 v23, v2
	v_mov_b32_e32 v24, v2
	v_mov_b32_e32 v25, v2
	v_mov_b32_e32 v26, v2
	v_mov_b32_e32 v27, v2
	v_mov_b32_e32 v28, v2
	v_mov_b32_e32 v29, v2
	v_mov_b32_e32 v30, v2
	v_mov_b32_e32 v31, v2
	v_mov_b32_e32 v32, v2
	v_mov_b32_e32 v33, v2
	v_mov_b32_e32 v34, v2
	v_mov_b32_e32 v35, v2
	v_mov_b32_e32 v36, v2
	v_mov_b32_e32 v37, v2
	v_mov_b32_e32 v38, v2
	v_mov_b32_e32 v39, v2
	v_mov_b32_e32 v40, v2
	v_mov_b32_e32 v41, v2
	v_mov_b32_e32 v42, v2
	v_mov_b32_e32 v43, v2
	v_mov_b32_e32 v44, v2
	v_mov_b32_e32 v45, v2
	v_mov_b32_e32 v46, v2
	v_mov_b32_e32 v47, v2
	v_mov_b32_e32 v48, v2
	v_mov_b32_e32 v49, v2
	v_mov_b32_e32 v50, v2
	v_mov_b32_e32 v51, v2
	v_mov_b32_e32 v52, v2
	v_mov_b32_e32 v53, v2
	v_mov_b32_e32 v54, v2
	v_mov_b32_e32 v55, v2
	v_mov_b32_e32 v56, v2
	v_mov_b32_e32 v57, v2
	v_mov_b32_e32 v58, v2
	v_mov_b32_e32 v59, v2
	v_mov_b32_e32 v60, v2
	v_mov_b32_e32 v61, v2
	v_mov_b32_e32 v62, v2
	v_mov_b32_e32 v63, v2
	v_mov_b32_e32 v64, v2
	v_mov_b32_e32 v65, v2
	v_readlane_b32 s0, v248, 6
	v_readlane_b32 s1, v248, 7
	v_readlane_b32 s38, v248, 8
	v_readlane_b32 s39, v248, 9
	s_nop 3
	s_sub_u32 s38, s38, 0x2000000
	s_subb_u32 s39, s39, 0
	s_cmp_gt_i32 s22, 63
	s_cselect_b32 s0, s38, s0
	s_cselect_b32 s1, s39, s1
	s_add_u32 s38, s0, 0x20000
	s_addc_u32 s39, s1, 0
	s_mov_b32 s100, 7
.LgemmT_p5_loop:
	s_waitcnt vmcnt(0)
	s_barrier
	ds_read_b64_tr_b16 v[66:67], v114 offset:0
	ds_read_b64_tr_b16 v[68:69], v115 offset:0
	ds_read_b64_tr_b16 v[70:71], v116 offset:0
	ds_read_b64_tr_b16 v[72:73], v117 offset:0
	ds_read_b128 v[74:77], v118 offset:16384
	ds_read_b128 v[78:81], v118 offset:20480
	ds_read_b64_tr_b16 v[82:83], v114 offset:4096
	ds_read_b64_tr_b16 v[84:85], v115 offset:4096
	ds_read_b64_tr_b16 v[86:87], v116 offset:4096
	ds_read_b64_tr_b16 v[88:89], v117 offset:4096
	ds_read_b128 v[90:93], v119 offset:16384
	ds_read_b128 v[94:97], v119 offset:20480
	s_add_u32 m0, s101, 0x8000
	s_nop 0
	global_load_lds_dwordx4 v[98:99], off
	v_lshl_add_u64 v[98:99], v[98:99], 0, s[28:29]
	s_add_u32 m0, s101, 0x8400
	s_nop 0
	global_load_lds_dwordx4 v[100:101], off
	v_lshl_add_u64 v[100:101], v[100:101], 0, s[28:29]
	s_waitcnt lgkmcnt(6)
	v_mfma_f32_32x32x16_bf16 v[50:65], v[66:69], v[74:77], v[50:65]
	v_mfma_f32_32x32x16_bf16 v[34:49], v[66:69], v[78:81], v[34:49]
	v_mfma_f32_32x32x16_bf16 v[18:33], v[70:73], v[74:77], v[18:33]
	v_mfma_f32_32x32x16_bf16 v[2:17], v[70:73], v[78:81], v[2:17]
	ds_read_b64_tr_b16 v[66:67], v114 offset:8192
	ds_read_b64_tr_b16 v[68:69], v115 offset:8192
	ds_read_b64_tr_b16 v[70:71], v116 offset:8192
	ds_read_b64_tr_b16 v[72:73], v117 offset:8192
	ds_read_b128 v[74:77], v120 offset:16384
	ds_read_b128 v[78:81], v120 offset:20480
	s_add_u32 m0, s101, 0x8800
	s_nop 0
	global_load_lds_dwordx4 v[102:103], off
	v_lshl_add_u64 v[102:103], v[102:103], 0, s[28:29]
	s_add_u32 m0, s101, 0x8c00
	s_nop 0
	global_load_lds_dwordx4 v[104:105], off
	v_lshl_add_u64 v[104:105], v[104:105], 0, s[28:29]
	s_waitcnt lgkmcnt(6)
	v_mfma_f32_32x32x16_bf16 v[50:65], v[82:85], v[90:93], v[50:65]
	v_mfma_f32_32x32x16_bf16 v[34:49], v[82:85], v[94:97], v[34:49]
	v_mfma_f32_32x32x16_bf16 v[18:33], v[86:89], v[90:93], v[18:33]
	v_mfma_f32_32x32x16_bf16 v[2:17], v[86:89], v[94:97], v[2:17]
	ds_read_b64_tr_b16 v[82:83], v114 offset:12288
	ds_read_b64_tr_b16 v[84:85], v115 offset:12288
	ds_read_b64_tr_b16 v[86:87], v116 offset:12288
	ds_read_b64_tr_b16 v[88:89], v117 offset:12288
	ds_read_b128 v[90:93], v121 offset:16384
	ds_read_b128 v[94:97], v121 offset:20480
	s_add_u32 m0, s101, 0xc010
	s_nop 0
	global_load_lds_dwordx4 v[106:107], off
	v_lshl_add_u64 v[106:107], v[106:107], 0, s[36:37]
	s_add_u32 m0, s101, 0xc410
	s_nop 0
	global_load_lds_dwordx4 v[108:109], off
	v_lshl_add_u64 v[108:109], v[108:109], 0, s[36:37]
	s_waitcnt lgkmcnt(6)
	v_mfma_f32_32x32x16_bf16 v[50:65], v[66:69], v[74:77], v[50:65]
	v_mfma_f32_32x32x16_bf16 v[34:49], v[66:69], v[78:81], v[34:49]
	v_mfma_f32_32x32x16_bf16 v[18:33], v[70:73], v[74:77], v[18:33]
	v_mfma_f32_32x32x16_bf16 v[2:17], v[70:73], v[78:81], v[2:17]
	s_add_u32 m0, s101, 0xc810
	s_nop 0
	global_load_lds_dwordx4 v[110:111], off
	v_lshl_add_u64 v[110:111], v[110:111], 0, s[36:37]
	s_add_u32 m0, s101, 0xcc10
	s_nop 0
	global_load_lds_dwordx4 v[112:113], off
	v_lshl_add_u64 v[112:113], v[112:113], 0, s[36:37]
	s_waitcnt lgkmcnt(0)
	v_mfma_f32_32x32x16_bf16 v[50:65], v[82:85], v[90:93], v[50:65]
	v_mfma_f32_32x32x16_bf16 v[34:49], v[82:85], v[94:97], v[34:49]
	v_mfma_f32_32x32x16_bf16 v[18:33], v[86:89], v[90:93], v[18:33]
	v_mfma_f32_32x32x16_bf16 v[2:17], v[86:89], v[94:97], v[2:17]
	s_waitcnt vmcnt(0)
	s_barrier
	ds_read_b64_tr_b16 v[66:67], v114 offset:32768
	ds_read_b64_tr_b16 v[68:69], v115 offset:32768
	ds_read_b64_tr_b16 v[70:71], v116 offset:32768
	ds_read_b64_tr_b16 v[72:73], v117 offset:32768
	ds_read_b128 v[74:77], v118 offset:49168
	ds_read_b128 v[78:81], v118 offset:53264
	ds_read_b64_tr_b16 v[82:83], v114 offset:36864
	ds_read_b64_tr_b16 v[84:85], v115 offset:36864
	ds_read_b64_tr_b16 v[86:87], v116 offset:36864
	ds_read_b64_tr_b16 v[88:89], v117 offset:36864
	ds_read_b128 v[90:93], v119 offset:49168
	ds_read_b128 v[94:97], v119 offset:53264
	s_add_u32 m0, s101, 0x0
	s_nop 0
	global_load_lds_dwordx4 v[98:99], off
	v_lshl_add_u64 v[98:99], v[98:99], 0, s[28:29]
	s_add_u32 m0, s101, 0x400
	s_nop 0
	global_load_lds_dwordx4 v[100:101], off
	v_lshl_add_u64 v[100:101], v[100:101], 0, s[28:29]
	s_waitcnt lgkmcnt(6)
	v_mfma_f32_32x32x16_bf16 v[50:65], v[66:69], v[74:77], v[50:65]
	v_mfma_f32_32x32x16_bf16 v[34:49], v[66:69], v[78:81], v[34:49]
	v_mfma_f32_32x32x16_bf16 v[18:33], v[70:73], v[74:77], v[18:33]
	v_mfma_f32_32x32x16_bf16 v[2:17], v[70:73], v[78:81], v[2:17]
	ds_read_b64_tr_b16 v[66:67], v114 offset:40960
	ds_read_b64_tr_b16 v[68:69], v115 offset:40960
	ds_read_b64_tr_b16 v[70:71], v116 offset:40960
	ds_read_b64_tr_b16 v[72:73], v117 offset:40960
	ds_read_b128 v[74:77], v120 offset:49168
	ds_read_b128 v[78:81], v120 offset:53264
	s_add_u32 m0, s101, 0x800
	s_nop 0
	global_load_lds_dwordx4 v[102:103], off
	v_lshl_add_u64 v[102:103], v[102:103], 0, s[28:29]
	s_add_u32 m0, s101, 0xc00
	s_nop 0
	global_load_lds_dwordx4 v[104:105], off
	v_lshl_add_u64 v[104:105], v[104:105], 0, s[28:29]
	s_waitcnt lgkmcnt(6)
	v_mfma_f32_32x32x16_bf16 v[50:65], v[82:85], v[90:93], v[50:65]
	v_mfma_f32_32x32x16_bf16 v[34:49], v[82:85], v[94:97], v[34:49]
	v_mfma_f32_32x32x16_bf16 v[18:33], v[86:89], v[90:93], v[18:33]
	v_mfma_f32_32x32x16_bf16 v[2:17], v[86:89], v[94:97], v[2:17]
	ds_read_b64_tr_b16 v[82:83], v114 offset:45056
	ds_read_b64_tr_b16 v[84:85], v115 offset:45056
	ds_read_b64_tr_b16 v[86:87], v116 offset:45056
	ds_read_b64_tr_b16 v[88:89], v117 offset:45056
	ds_read_b128 v[90:93], v121 offset:49168
	ds_read_b128 v[94:97], v121 offset:53264
	s_add_u32 m0, s101, 0x4000
	s_nop 0
	global_load_lds_dwordx4 v[106:107], off
	v_lshl_add_u64 v[106:107], v[106:107], 0, s[36:37]
	s_add_u32 m0, s101, 0x4400
	s_nop 0
	global_load_lds_dwordx4 v[108:109], off
	v_lshl_add_u64 v[108:109], v[108:109], 0, s[36:37]
	s_waitcnt lgkmcnt(6)
	v_mfma_f32_32x32x16_bf16 v[50:65], v[66:69], v[74:77], v[50:65]
	v_mfma_f32_32x32x16_bf16 v[34:49], v[66:69], v[78:81], v[34:49]
	v_mfma_f32_32x32x16_bf16 v[18:33], v[70:73], v[74:77], v[18:33]
	v_mfma_f32_32x32x16_bf16 v[2:17], v[70:73], v[78:81], v[2:17]
	s_add_u32 m0, s101, 0x4800
	s_nop 0
	global_load_lds_dwordx4 v[110:111], off
	v_lshl_add_u64 v[110:111], v[110:111], 0, s[36:37]
	s_add_u32 m0, s101, 0x4c00
	s_nop 0
	global_load_lds_dwordx4 v[112:113], off
	v_lshl_add_u64 v[112:113], v[112:113], 0, s[36:37]
	s_waitcnt lgkmcnt(0)
	v_mfma_f32_32x32x16_bf16 v[50:65], v[82:85], v[90:93], v[50:65]
	v_mfma_f32_32x32x16_bf16 v[34:49], v[82:85], v[94:97], v[34:49]
	v_mfma_f32_32x32x16_bf16 v[18:33], v[86:89], v[90:93], v[18:33]
	v_mfma_f32_32x32x16_bf16 v[2:17], v[86:89], v[94:97], v[2:17]
	s_sub_u32 s100, s100, 1
	s_cmp_lg_u32 s100, 0
	s_cbranch_scc1 .LgemmT_p5_loop
	s_waitcnt vmcnt(0)
	s_barrier
	ds_read_b64_tr_b16 v[66:67], v114 offset:0
	ds_read_b64_tr_b16 v[68:69], v115 offset:0
	ds_read_b64_tr_b16 v[70:71], v116 offset:0
	ds_read_b64_tr_b16 v[72:73], v117 offset:0
	ds_read_b128 v[74:77], v118 offset:16384
	ds_read_b128 v[78:81], v118 offset:20480
	ds_read_b64_tr_b16 v[82:83], v114 offset:4096
	ds_read_b64_tr_b16 v[84:85], v115 offset:4096
	ds_read_b64_tr_b16 v[86:87], v116 offset:4096
	ds_read_b64_tr_b16 v[88:89], v117 offset:4096
	ds_read_b128 v[90:93], v119 offset:16384
	ds_read_b128 v[94:97], v119 offset:20480
	s_add_u32 m0, s101, 0x8000
	s_nop 0
	global_load_lds_dwordx4 v[98:99], off
	v_lshl_add_u64 v[98:99], v[98:99], 0, s[28:29]
	s_add_u32 m0, s101, 0x8400
	s_nop 0
	global_load_lds_dwordx4 v[100:101], off
	v_lshl_add_u64 v[100:101], v[100:101], 0, s[28:29]
	s_waitcnt lgkmcnt(6)
	v_mfma_f32_32x32x16_bf16 v[50:65], v[66:69], v[74:77], v[50:65]
	v_mfma_f32_32x32x16_bf16 v[34:49], v[66:69], v[78:81], v[34:49]
	v_mfma_f32_32x32x16_bf16 v[18:33], v[70:73], v[74:77], v[18:33]
	v_mfma_f32_32x32x16_bf16 v[2:17], v[70:73], v[78:81], v[2:17]
	ds_read_b64_tr_b16 v[66:67], v114 offset:8192
	ds_read_b64_tr_b16 v[68:69], v115 offset:8192
	ds_read_b64_tr_b16 v[70:71], v116 offset:8192
	ds_read_b64_tr_b16 v[72:73], v117 offset:8192
	ds_read_b128 v[74:77], v120 offset:16384
	ds_read_b128 v[78:81], v120 offset:20480
	s_add_u32 m0, s101, 0x8800
	s_nop 0
	global_load_lds_dwordx4 v[102:103], off
	v_lshl_add_u64 v[102:103], v[102:103], 0, s[28:29]
	s_add_u32 m0, s101, 0x8c00
	s_nop 0
	global_load_lds_dwordx4 v[104:105], off
	v_lshl_add_u64 v[104:105], v[104:105], 0, s[28:29]
	s_waitcnt lgkmcnt(6)
	v_mfma_f32_32x32x16_bf16 v[50:65], v[82:85], v[90:93], v[50:65]
	v_mfma_f32_32x32x16_bf16 v[34:49], v[82:85], v[94:97], v[34:49]
	v_mfma_f32_32x32x16_bf16 v[18:33], v[86:89], v[90:93], v[18:33]
	v_mfma_f32_32x32x16_bf16 v[2:17], v[86:89], v[94:97], v[2:17]
	ds_read_b64_tr_b16 v[82:83], v114 offset:12288
	ds_read_b64_tr_b16 v[84:85], v115 offset:12288
	ds_read_b64_tr_b16 v[86:87], v116 offset:12288
	ds_read_b64_tr_b16 v[88:89], v117 offset:12288
	ds_read_b128 v[90:93], v121 offset:16384
	ds_read_b128 v[94:97], v121 offset:20480
	s_add_u32 m0, s101, 0xc010
	s_nop 0
	global_load_lds_dwordx4 v[106:107], off
	v_lshl_add_u64 v[106:107], v[106:107], 0, s[36:37]
	s_add_u32 m0, s101, 0xc410
	s_nop 0
	global_load_lds_dwordx4 v[108:109], off
	v_lshl_add_u64 v[108:109], v[108:109], 0, s[36:37]
	s_waitcnt lgkmcnt(6)
	v_mfma_f32_32x32x16_bf16 v[50:65], v[66:69], v[74:77], v[50:65]
	v_mfma_f32_32x32x16_bf16 v[34:49], v[66:69], v[78:81], v[34:49]
	v_mfma_f32_32x32x16_bf16 v[18:33], v[70:73], v[74:77], v[18:33]
	v_mfma_f32_32x32x16_bf16 v[2:17], v[70:73], v[78:81], v[2:17]
	s_add_u32 m0, s101, 0xc810
	s_nop 0
	global_load_lds_dwordx4 v[110:111], off
	v_lshl_add_u64 v[110:111], v[110:111], 0, s[36:37]
	s_add_u32 m0, s101, 0xcc10
	s_nop 0
	global_load_lds_dwordx4 v[112:113], off
	v_lshl_add_u64 v[112:113], v[112:113], 0, s[36:37]
	s_waitcnt lgkmcnt(0)
	v_mfma_f32_32x32x16_bf16 v[50:65], v[82:85], v[90:93], v[50:65]
	v_mfma_f32_32x32x16_bf16 v[34:49], v[82:85], v[94:97], v[34:49]
	v_mfma_f32_32x32x16_bf16 v[18:33], v[86:89], v[90:93], v[18:33]
	v_mfma_f32_32x32x16_bf16 v[2:17], v[86:89], v[94:97], v[2:17]
	s_waitcnt vmcnt(0)
	s_barrier
	ds_read_b64_tr_b16 v[66:67], v114 offset:32768
	ds_read_b64_tr_b16 v[68:69], v115 offset:32768
	ds_read_b64_tr_b16 v[70:71], v116 offset:32768
	ds_read_b64_tr_b16 v[72:73], v117 offset:32768
	ds_read_b128 v[74:77], v118 offset:49168
	ds_read_b128 v[78:81], v118 offset:53264
	ds_read_b64_tr_b16 v[82:83], v114 offset:36864
	ds_read_b64_tr_b16 v[84:85], v115 offset:36864
	ds_read_b64_tr_b16 v[86:87], v116 offset:36864
	ds_read_b64_tr_b16 v[88:89], v117 offset:36864
	ds_read_b128 v[90:93], v119 offset:49168
	ds_read_b128 v[94:97], v119 offset:53264
	global_load_dword v129, v218, s[0:1] nt
	global_load_dword v130, v219, s[0:1] nt
	global_load_dword v131, v220, s[0:1] nt
	global_load_dword v132, v221, s[0:1] nt
	global_load_dword v133, v222, s[0:1] nt
	global_load_dword v134, v223, s[0:1] nt
	global_load_dword v135, v224, s[0:1] nt
	global_load_dword v136, v225, s[0:1] nt
	global_load_dword v137, v226, s[0:1] nt
	global_load_dword v138, v227, s[0:1] nt
	global_load_dword v139, v228, s[0:1] nt
	global_load_dword v140, v229, s[0:1] nt
	global_load_dword v141, v230, s[0:1] nt
	global_load_dword v142, v231, s[0:1] nt
	global_load_dword v143, v232, s[0:1] nt
	global_load_dword v144, v233, s[0:1] nt
	s_waitcnt lgkmcnt(6)
	v_mfma_f32_32x32x16_bf16 v[50:65], v[66:69], v[74:77], v[50:65]
	v_mfma_f32_32x32x16_bf16 v[34:49], v[66:69], v[78:81], v[34:49]
	v_mfma_f32_32x32x16_bf16 v[18:33], v[70:73], v[74:77], v[18:33]
	v_mfma_f32_32x32x16_bf16 v[2:17], v[70:73], v[78:81], v[2:17]
	ds_read_b64_tr_b16 v[66:67], v114 offset:40960
	ds_read_b64_tr_b16 v[68:69], v115 offset:40960
	ds_read_b64_tr_b16 v[70:71], v116 offset:40960
	ds_read_b64_tr_b16 v[72:73], v117 offset:40960
	ds_read_b128 v[74:77], v120 offset:49168
	ds_read_b128 v[78:81], v120 offset:53264
	global_load_dword v145, v218, s[0:1] offset:128 nt
	global_load_dword v146, v219, s[0:1] offset:128 nt
	global_load_dword v147, v220, s[0:1] offset:128 nt
	global_load_dword v148, v221, s[0:1] offset:128 nt
	global_load_dword v149, v222, s[0:1] offset:128 nt
	global_load_dword v150, v223, s[0:1] offset:128 nt
	global_load_dword v151, v224, s[0:1] offset:128 nt
	global_load_dword v152, v225, s[0:1] offset:128 nt
	global_load_dword v153, v226, s[0:1] offset:128 nt
	global_load_dword v154, v227, s[0:1] offset:128 nt
	global_load_dword v155, v228, s[0:1] offset:128 nt
	global_load_dword v156, v229, s[0:1] offset:128 nt
	global_load_dword v157, v230, s[0:1] offset:128 nt
	global_load_dword v158, v231, s[0:1] offset:128 nt
	global_load_dword v159, v232, s[0:1] offset:128 nt
	global_load_dword v160, v233, s[0:1] offset:128 nt
	s_waitcnt lgkmcnt(6)
	v_mfma_f32_32x32x16_bf16 v[50:65], v[82:85], v[90:93], v[50:65]
	v_mfma_f32_32x32x16_bf16 v[34:49], v[82:85], v[94:97], v[34:49]
	v_mfma_f32_32x32x16_bf16 v[18:33], v[86:89], v[90:93], v[18:33]
	v_mfma_f32_32x32x16_bf16 v[2:17], v[86:89], v[94:97], v[2:17]
	ds_read_b64_tr_b16 v[82:83], v114 offset:45056
	ds_read_b64_tr_b16 v[84:85], v115 offset:45056
	ds_read_b64_tr_b16 v[86:87], v116 offset:45056
	ds_read_b64_tr_b16 v[88:89], v117 offset:45056
	ds_read_b128 v[90:93], v121 offset:49168
	ds_read_b128 v[94:97], v121 offset:53264
	global_load_dword v161, v218, s[38:39] nt
	global_load_dword v162, v219, s[38:39] nt
	global_load_dword v163, v220, s[38:39] nt
	global_load_dword v164, v221, s[38:39] nt
	global_load_dword v165, v222, s[38:39] nt
	global_load_dword v166, v223, s[38:39] nt
	global_load_dword v167, v224, s[38:39] nt
	global_load_dword v168, v225, s[38:39] nt
	global_load_dword v169, v226, s[38:39] nt
	global_load_dword v170, v227, s[38:39] nt
	global_load_dword v171, v228, s[38:39] nt
	global_load_dword v172, v229, s[38:39] nt
	global_load_dword v173, v230, s[38:39] nt
	global_load_dword v174, v231, s[38:39] nt
	global_load_dword v175, v232, s[38:39] nt
	global_load_dword v176, v233, s[38:39] nt
	s_waitcnt lgkmcnt(6)
	v_mfma_f32_32x32x16_bf16 v[50:65], v[66:69], v[74:77], v[50:65]
	v_mfma_f32_32x32x16_bf16 v[34:49], v[66:69], v[78:81], v[34:49]
	v_mfma_f32_32x32x16_bf16 v[18:33], v[70:73], v[74:77], v[18:33]
	v_mfma_f32_32x32x16_bf16 v[2:17], v[70:73], v[78:81], v[2:17]
	global_load_dword v177, v218, s[38:39] offset:128 nt
	global_load_dword v202, v219, s[38:39] offset:128 nt
	global_load_dword v203, v220, s[38:39] offset:128 nt
	global_load_dword v204, v221, s[38:39] offset:128 nt
	global_load_dword v205, v222, s[38:39] offset:128 nt
	global_load_dword v206, v223, s[38:39] offset:128 nt
	global_load_dword v207, v224, s[38:39] offset:128 nt
	global_load_dword v208, v225, s[38:39] offset:128 nt
	global_load_dword v209, v226, s[38:39] offset:128 nt
	global_load_dword v210, v227, s[38:39] offset:128 nt
	global_load_dword v211, v228, s[38:39] offset:128 nt
	global_load_dword v212, v229, s[38:39] offset:128 nt
	global_load_dword v213, v230, s[38:39] offset:128 nt
	global_load_dword v214, v231, s[38:39] offset:128 nt
	global_load_dword v215, v232, s[38:39] offset:128 nt
	global_load_dword v216, v233, s[38:39] offset:128 nt
	s_waitcnt lgkmcnt(0)
	v_mfma_f32_32x32x16_bf16 v[50:65], v[82:85], v[90:93], v[50:65]
	v_mfma_f32_32x32x16_bf16 v[34:49], v[82:85], v[94:97], v[34:49]
	v_mfma_f32_32x32x16_bf16 v[18:33], v[86:89], v[90:93], v[18:33]
	v_mfma_f32_32x32x16_bf16 v[2:17], v[86:89], v[94:97], v[2:17]
	v_readlane_b32 s38, v248, 2
	v_readlane_b32 s39, v248, 3
	s_nop 3
	s_add_u32 s36, s38, 0x20000
	s_addc_u32 s37, s39, 0
	s_nop 7
	s_waitcnt vmcnt(63)
	v_fmac_f32_e32 v129, v50, v234
	global_store_dword v218, v129, s[38:39]
	s_waitcnt vmcnt(63)
	v_fmac_f32_e32 v130, v51, v234
	global_store_dword v219, v130, s[38:39]
	s_waitcnt vmcnt(63)
	v_fmac_f32_e32 v131, v52, v234
	global_store_dword v220, v131, s[38:39]
	s_waitcnt vmcnt(63)
	v_fmac_f32_e32 v132, v53, v234
	global_store_dword v221, v132, s[38:39]
	s_waitcnt vmcnt(63)
	v_fmac_f32_e32 v133, v54, v234
	global_store_dword v222, v133, s[38:39]
	s_waitcnt vmcnt(63)
	v_fmac_f32_e32 v134, v55, v234
	global_store_dword v223, v134, s[38:39]
	s_waitcnt vmcnt(63)
	v_fmac_f32_e32 v135, v56, v234
	global_store_dword v224, v135, s[38:39]
	s_waitcnt vmcnt(63)
	v_fmac_f32_e32 v136, v57, v234
	global_store_dword v225, v136, s[38:39]
	s_waitcnt vmcnt(63)
	v_fmac_f32_e32 v137, v58, v234
	global_store_dword v226, v137, s[38:39]
	s_waitcnt vmcnt(63)
	v_fmac_f32_e32 v138, v59, v234
	global_store_dword v227, v138, s[38:39]
	s_waitcnt vmcnt(63)
	v_fmac_f32_e32 v139, v60, v234
	global_store_dword v228, v139, s[38:39]
	s_waitcnt vmcnt(63)
	v_fmac_f32_e32 v140, v61, v234
	global_store_dword v229, v140, s[38:39]
	s_waitcnt vmcnt(63)
	v_fmac_f32_e32 v141, v62, v234
	global_store_dword v230, v141, s[38:39]
	s_waitcnt vmcnt(63)
	v_fmac_f32_e32 v142, v63, v234
	global_store_dword v231, v142, s[38:39]
	s_waitcnt vmcnt(63)
	v_fmac_f32_e32 v143, v64, v234
	global_store_dword v232, v143, s[38:39]
	s_waitcnt vmcnt(63)
	v_fmac_f32_e32 v144, v65, v234
	global_store_dword v233, v144, s[38:39]
	s_waitcnt vmcnt(63)
	v_fmac_f32_e32 v145, v34, v235
	global_store_dword v218, v145, s[38:39] offset:128
	s_waitcnt vmcnt(63)
	v_fmac_f32_e32 v146, v35, v235
	global_store_dword v219, v146, s[38:39] offset:128
	s_waitcnt vmcnt(63)
	v_fmac_f32_e32 v147, v36, v235
	global_store_dword v220, v147, s[38:39] offset:128
	s_waitcnt vmcnt(63)
	v_fmac_f32_e32 v148, v37, v235
	global_store_dword v221, v148, s[38:39] offset:128
	s_waitcnt vmcnt(63)
	v_fmac_f32_e32 v149, v38, v235
	global_store_dword v222, v149, s[38:39] offset:128
	s_waitcnt vmcnt(63)
	v_fmac_f32_e32 v150, v39, v235
	global_store_dword v223, v150, s[38:39] offset:128
	s_waitcnt vmcnt(63)
	v_fmac_f32_e32 v151, v40, v235
	global_store_dword v224, v151, s[38:39] offset:128
	s_waitcnt vmcnt(63)
	v_fmac_f32_e32 v152, v41, v235
	global_store_dword v225, v152, s[38:39] offset:128
	s_waitcnt vmcnt(63)
	v_fmac_f32_e32 v153, v42, v235
	global_store_dword v226, v153, s[38:39] offset:128
	s_waitcnt vmcnt(63)
	v_fmac_f32_e32 v154, v43, v235
	global_store_dword v227, v154, s[38:39] offset:128
	s_waitcnt vmcnt(63)
	v_fmac_f32_e32 v155, v44, v235
	global_store_dword v228, v155, s[38:39] offset:128
	s_waitcnt vmcnt(63)
	v_fmac_f32_e32 v156, v45, v235
	global_store_dword v229, v156, s[38:39] offset:128
	s_waitcnt vmcnt(63)
	v_fmac_f32_e32 v157, v46, v235
	global_store_dword v230, v157, s[38:39] offset:128
	s_waitcnt vmcnt(63)
	v_fmac_f32_e32 v158, v47, v235
	global_store_dword v231, v158, s[38:39] offset:128
	s_waitcnt vmcnt(63)
	v_fmac_f32_e32 v159, v48, v235
	global_store_dword v232, v159, s[38:39] offset:128
	s_waitcnt vmcnt(63)
	v_fmac_f32_e32 v160, v49, v235
	global_store_dword v233, v160, s[38:39] offset:128
	s_waitcnt vmcnt(63)
	v_fmac_f32_e32 v161, v18, v234
	global_store_dword v218, v161, s[36:37]
	s_waitcnt vmcnt(63)
	v_fmac_f32_e32 v162, v19, v234
	global_store_dword v219, v162, s[36:37]
	s_waitcnt vmcnt(63)
	v_fmac_f32_e32 v163, v20, v234
	global_store_dword v220, v163, s[36:37]
	s_waitcnt vmcnt(63)
	v_fmac_f32_e32 v164, v21, v234
	global_store_dword v221, v164, s[36:37]
	s_waitcnt vmcnt(63)
	v_fmac_f32_e32 v165, v22, v234
	global_store_dword v222, v165, s[36:37]
	s_waitcnt vmcnt(63)
	v_fmac_f32_e32 v166, v23, v234
	global_store_dword v223, v166, s[36:37]
	s_waitcnt vmcnt(63)
	v_fmac_f32_e32 v167, v24, v234
	global_store_dword v224, v167, s[36:37]
	s_waitcnt vmcnt(63)
	v_fmac_f32_e32 v168, v25, v234
	global_store_dword v225, v168, s[36:37]
	s_waitcnt vmcnt(63)
	v_fmac_f32_e32 v169, v26, v234
	global_store_dword v226, v169, s[36:37]
	s_waitcnt vmcnt(63)
	v_fmac_f32_e32 v170, v27, v234
	global_store_dword v227, v170, s[36:37]
	s_waitcnt vmcnt(63)
	v_fmac_f32_e32 v171, v28, v234
	global_store_dword v228, v171, s[36:37]
	s_waitcnt vmcnt(63)
	v_fmac_f32_e32 v172, v29, v234
	global_store_dword v229, v172, s[36:37]
	s_waitcnt vmcnt(63)
	v_fmac_f32_e32 v173, v30, v234
	global_store_dword v230, v173, s[36:37]
	s_waitcnt vmcnt(63)
	v_fmac_f32_e32 v174, v31, v234
	global_store_dword v231, v174, s[36:37]
	s_waitcnt vmcnt(63)
	v_fmac_f32_e32 v175, v32, v234
	global_store_dword v232, v175, s[36:37]
	s_waitcnt vmcnt(63)
	v_fmac_f32_e32 v176, v33, v234
	global_store_dword v233, v176, s[36:37]
	s_waitcnt vmcnt(63)
	v_fmac_f32_e32 v177, v2, v235
	global_store_dword v218, v177, s[36:37] offset:128
	s_waitcnt vmcnt(63)
	v_fmac_f32_e32 v202, v3, v235
	global_store_dword v219, v202, s[36:37] offset:128
	s_waitcnt vmcnt(63)
	v_fmac_f32_e32 v203, v4, v235
	global_store_dword v220, v203, s[36:37] offset:128
	s_waitcnt vmcnt(63)
	v_fmac_f32_e32 v204, v5, v235
	global_store_dword v221, v204, s[36:37] offset:128
	s_waitcnt vmcnt(63)
	v_fmac_f32_e32 v205, v6, v235
	global_store_dword v222, v205, s[36:37] offset:128
	s_waitcnt vmcnt(63)
	v_fmac_f32_e32 v206, v7, v235
	global_store_dword v223, v206, s[36:37] offset:128
	s_waitcnt vmcnt(63)
	v_fmac_f32_e32 v207, v8, v235
	global_store_dword v224, v207, s[36:37] offset:128
	s_waitcnt vmcnt(63)
	v_fmac_f32_e32 v208, v9, v235
	global_store_dword v225, v208, s[36:37] offset:128
	s_waitcnt vmcnt(63)
	v_fmac_f32_e32 v209, v10, v235
	global_store_dword v226, v209, s[36:37] offset:128
	s_waitcnt vmcnt(63)
	v_fmac_f32_e32 v210, v11, v235
	global_store_dword v227, v210, s[36:37] offset:128
	s_waitcnt vmcnt(63)
	v_fmac_f32_e32 v211, v12, v235
	global_store_dword v228, v211, s[36:37] offset:128
	s_waitcnt vmcnt(63)
	v_fmac_f32_e32 v212, v13, v235
	global_store_dword v229, v212, s[36:37] offset:128
	s_waitcnt vmcnt(63)
	v_fmac_f32_e32 v213, v14, v235
	global_store_dword v230, v213, s[36:37] offset:128
	s_waitcnt vmcnt(63)
	v_fmac_f32_e32 v214, v15, v235
	global_store_dword v231, v214, s[36:37] offset:128
	s_waitcnt vmcnt(63)
	v_fmac_f32_e32 v215, v16, v235
	global_store_dword v232, v215, s[36:37] offset:128
	s_waitcnt vmcnt(63)
	v_fmac_f32_e32 v216, v17, v235
	global_store_dword v233, v216, s[36:37] offset:128
	v_readlane_b32 s0, v246, 1
	s_nop 1
	s_add_i32 s2, s2, s0
	s_cmpk_gt_i32 s2, 0x13f
	s_cbranch_scc0 .LBB0_599
	v_readlane_b32 s52, v245, 56
	v_readlane_b32 s54, v245, 58
	v_readlane_b32 s55, v245, 59
	v_readlane_b32 s56, v245, 60
	v_readlane_b32 s57, v245, 61
	v_readlane_b32 s58, v245, 62
	v_readlane_b32 s59, v245, 63
	v_readlane_b32 s60, v244, 0
	v_readlane_b32 s61, v244, 1
	v_readlane_b32 s62, v244, 2
	v_readlane_b32 s63, v244, 3
	v_readlane_b32 s64, v244, 4
	v_readlane_b32 s65, v244, 5
	v_readlane_b32 s66, v244, 6
	v_readlane_b32 s67, v244, 7
	s_movk_i32 s43, 0x1fff
	v_readlane_b32 s53, v245, 57

.LBB0_654:
	s_waitcnt vmcnt(1)
	v_lshlrev_b32_e32 v18, 16, v34
	v_lshlrev_b32_e32 v34, 16, v32
	v_lshlrev_b32_e32 v32, 16, v22
	v_lshlrev_b32_e32 v22, 16, v10
	v_lshlrev_b32_e32 v10, 16, v3
	v_mov_b32_e32 v3, v1
	v_lshlrev_b32_e32 v52, 16, v6
	v_lshlrev_b32_e32 v6, 16, v5
	s_barrier
	v_lshlrev_b32_e32 v48, 16, v14
	v_ashrrev_i32_e32 v5, 31, v3
	v_lshrrev_b32_e32 v5, 28, v5
	v_and_b32_e32 v41, 15, v3
	v_add_u32_e32 v3, v3, v5
	v_lshlrev_b32_e32 v14, 16, v13
	v_ashrrev_i32_e32 v3, 4, v3
	v_lshlrev_b32_e32 v36, 16, v31
	v_lshlrev_b32_e32 v44, 16, v26
	v_lshlrev_b32_e32 v26, 16, v25
	v_lshlrev_b32_e32 v5, 11, v3
	s_waitcnt vmcnt(0)
	v_lshlrev_b32_e32 v16, 16, v16
	v_lshlrev_b32_e32 v42, 16, v29
	v_lshlrev_b32_e32 v46, 16, v21
	v_lshlrev_b32_e32 v50, 16, v9
	v_lshl_add_u32 v3, v3, 7, v5
	v_pk_add_f32 v[54:55], v[10:11], v[32:33]
	v_pk_add_f32 v[10:11], v[10:11], v[32:33] neg_lo:[0,1] neg_hi:[0,1]
	v_pk_add_f32 v[32:33], v[22:23], v[36:37]
	v_mov_b32_e32 v57, v22
	v_sub_f32_e32 v58, v48, v18
	v_sub_f32_e32 v59, v14, v34
	v_sub_f32_e32 v22, v23, v37
	v_sub_f32_e32 v23, v57, v36
	v_pk_add_f32 v[36:37], v[6:7], v[26:27]
	v_sub_f32_e32 v56, v52, v44
	v_sub_f32_e32 v57, v6, v26
	v_sub_f32_e32 v6, v4, v24
	v_sub_f32_e32 v7, v7, v27
	v_pk_add_f32 v[26:27], v[14:15], v[34:35]
	v_sub_f32_e32 v14, v12, v30
	v_sub_f32_e32 v15, v15, v35
	v_mov_b32_e32 v53, v4
	v_mov_b32_e32 v45, v24
	v_sub_f32_e32 v5, v4, v24
	v_sub_f32_e32 v4, v50, v42
	v_add_f32_e32 v24, v48, v18
	v_add_f32_e32 v25, v12, v30
	v_sub_f32_e32 v19, v48, v18
	v_sub_f32_e32 v18, v8, v28
	v_sub_f32_e32 v13, v12, v30
	v_sub_f32_e32 v12, v46, v16
	v_lshl_or_b32 v96, v41, 3, v3
	v_pk_add_f32 v[34:35], v[52:53], v[44:45]
	v_mov_b32_e32 v3, v52
	v_pk_add_f32 v[52:53], v[4:5], v[18:19] neg_lo:[0,1] neg_hi:[0,1]
	v_add_f32_e32 v9, v8, v28
	v_add_f32_e32 v8, v46, v16
	v_pk_add_f32 v[16:17], v[4:5], v[18:19]
	v_pk_add_f32 v[4:5], v[36:37], v[26:27] neg_lo:[0,1] neg_hi:[0,1]
	v_pk_mul_f32 v[18:19], v[4:5], s[20:21] op_sel_hi:[1,0]
	v_pk_fma_f32 v[28:29], v[4:5], s[20:21], v[18:19] op_sel:[0,0,1] op_sel_hi:[1,0,0]
	v_cvt_f32_i32_e32 v4, v41
	v_sub_f32_e32 v45, v3, v44
	v_sub_f32_e32 v44, v2, v20
	v_add_f32_e32 v21, v2, v20
	v_add_f32_e32 v20, v50, v42
	v_pk_add_f32 v[30:31], v[34:35], v[24:25] neg_lo:[0,1] neg_hi:[0,1]
	v_pk_add_f32 v[2:3], v[20:21], v[8:9] neg_lo:[0,1] neg_hi:[0,1]
	v_add_f32_e32 v64, v10, v22
	v_mul_f32_e32 v42, 0x3f3504f3, v2
	v_add_f32_e32 v2, v4, v4
	v_mul_f32_e32 v2, 0x3b800000, v2
	v_pk_add_f32 v[4:5], v[36:37], v[26:27]
	v_pk_add_f32 v[26:27], v[34:35], v[24:25]
	v_sub_f32_e32 v65, v11, v23
	s_mov_b32 s28, s71
	s_mov_b32 s29, s21
	v_add_f32_e32 v34, v57, v15
	s_mov_b32 s70, s21
	v_pk_add_f32 v[48:49], v[44:45], v[12:13]
	v_pk_add_f32 v[12:13], v[44:45], v[12:13] neg_lo:[0,1] neg_hi:[0,1]
	v_mul_f32_e32 v2, 0.5, v2
	v_sub_f32_e32 v24, v7, v59
	v_pk_mul_f32 v[66:67], v[34:35], s[70:71] op_sel_hi:[0,1]
	v_pk_mul_f32 v[70:71], v[16:17], s[28:29] op_sel_hi:[0,1]
	v_mul_f32_e32 v41, 0x3f3504f3, v49
	v_mul_f32_e32 v43, 0x3f3504f3, v53
	v_sin_f32_e32 v44, v2
	v_fma_f32 v68, v24, s28, v66
	v_fma_f32 v69, v24, s29, -v67
	v_fma_f32 v72, v12, s70, v70
	v_fma_f32 v73, v12, s71, -v71
	v_cos_f32_e32 v60, v2
	s_nop 1
	v_add_f32_e32 v66, v43, v41
	v_fma_f32 v67, v53, s20, -v41
	v_pk_add_f32 v[70:71], v[64:65], v[66:67]
	v_pk_add_f32 v[74:75], v[68:69], v[72:73]
	v_mul_f32_e32 v46, 0x3f3504f3, v3
	v_pk_add_f32 v[76:77], v[70:71], v[74:75]
	v_mul_f32_e32 v51, 0xbf3504f3, v3
	v_xor_b32_e32 v61, 0x80000000, v44
	v_pk_add_f32 v[2:3], v[54:55], v[32:33]
	v_pk_add_f32 v[8:9], v[20:21], v[8:9]
	v_pk_add_f32 v[70:71], v[70:71], v[74:75] neg_lo:[0,1] neg_hi:[0,1]
	v_pk_mul_f32 v[74:75], v[76:77], v[44:45] op_sel_hi:[1,0]
	v_pk_add_f32 v[20:21], v[2:3], v[26:27]
	v_pk_add_f32 v[36:37], v[4:5], v[8:9]
	v_fma_f32 v78, v76, v60, v75
	v_fma_f32 v79, v77, v60, -v74
	v_pk_add_f32 v[62:63], v[20:21], v[36:37]
	v_pk_add_f32 v[14:15], v[56:57], v[14:15] neg_lo:[0,1] neg_hi:[0,1]
	v_pk_add_f32 v[6:7], v[6:7], v[58:59]
	v_readlane_b32 s4, v245, 26
	s_nop 1
	ds_write2_b64 v96, v[62:63], v[78:79] offset1:17
	v_mov_b32_e32 v74, v32
	v_sub_f32_e32 v32, v46, v42
	v_sub_f32_e32 v33, v55, v33
	v_sub_f32_e32 v24, v35, v25
	v_sub_f32_e32 v25, v51, v42
	v_mov_b32_e32 v43, v30
	v_mov_b32_e32 v53, v17
	v_mov_b32_e32 v49, v13
	v_mul_f32_e32 v12, 0x3ec3ef15, v15
	v_mul_f32_e32 v16, 0x3f6c835e, v7
	s_mov_b32 s28, s3
	s_mov_b32 s29, s76
	v_readlane_b32 s5, v245, 27
	s_nop 0
	v_mov_b32_e32 v45, v60
	v_sub_f32_e32 v19, v19, v18
	v_sub_f32_e32 v18, v54, v74
	v_pk_add_f32 v[34:35], v[32:33], v[30:31] op_sel:[1,0] op_sel_hi:[0,1]
	v_add_f32_e32 v30, v32, v28
	v_sub_f32_e32 v43, v33, v43
	v_add_f32_e32 v12, v16, v12
	v_add_f32_e32 v13, v11, v23
	v_pk_mul_f32 v[14:15], v[14:15], s[28:29]
	s_mov_b32 s70, s20
	v_pk_mul_f32 v[16:17], v[48:49], s[4:5]
	v_mul_f32_e32 v50, v44, v44
	v_mul_f32_e32 v51, v45, v61
	v_pk_add_f32 v[46:47], v[18:19], v[24:25]
	v_pk_fma_f32 v[6:7], v[6:7], s[70:71], v[14:15]
	v_pk_fma_f32 v[14:15], v[52:53], s[30:31], v[16:17]
	v_mul_f32_e32 v11, 0x3ec3ef15, v52
	v_pk_fma_f32 v[52:53], v[60:61], v[60:61], v[50:51] op_sel_hi:[0,1,1] neg_lo:[0,0,1] neg_hi:[0,0,1]
	v_pk_fma_f32 v[50:51], v[60:61], v[60:61], v[50:51] op_sel_hi:[0,1,1]
	v_pk_add_f32 v[18:19], v[18:19], v[24:25] neg_lo:[0,1] neg_hi:[0,1]
	v_add_f32_e32 v24, v46, v30
	v_add_f32_e32 v25, v47, v43
	v_mov_b32_e32 v54, v52
	v_mov_b32_e32 v55, v51
	v_mul_f32_e32 v62, v51, v51
	v_mul_f32_e32 v63, v51, v52
	v_pk_mul_f32 v[50:51], v[24:25], v[50:51] op_sel:[1,1] op_sel_hi:[0,1]
	v_pk_fma_f32 v[74:75], v[52:53], v[54:55], v[62:63] op_sel_hi:[0,1,1] neg_lo:[0,0,1] neg_hi:[0,0,1]
	v_pk_fma_f32 v[62:63], v[52:53], v[54:55], v[62:63] op_sel_hi:[0,1,1]
	v_fma_f32 v84, v24, v52, -v50
	v_fma_f32 v85, v25, v52, v51
	v_pk_add_f32 v[28:29], v[28:29], v[32:33] neg_lo:[0,1] neg_hi:[0,1]
	v_pk_add_f32 v[24:25], v[64:65], v[66:67] neg_lo:[0,1] neg_hi:[0,1]
	v_pk_mul_f32 v[66:67], v[54:55], v[62:63] op_sel:[0,1]
	v_pk_add_f32 v[50:51], v[68:69], v[72:73] neg_lo:[0,1] neg_hi:[0,1]
	v_fma_f32 v68, v54, v74, -v67
	v_fma_f32 v67, v55, v74, v66
	v_pk_add_f32 v[32:33], v[34:35], v[28:29]
	v_sub_f32_e32 v28, v34, v28
	v_mov_b32_e32 v72, v68
	v_mov_b32_e32 v73, v67
	v_pk_add_f32 v[86:87], v[18:19], v[18:19] op_sel:[0,1] op_sel_hi:[0,1]
	v_mul_f32_e32 v29, v28, v68
	v_mul_f32_e32 v28, v28, v67
	v_mov_b32_e32 v76, v74
	v_mov_b32_e32 v77, v63
	v_fma_f32 v34, v86, v68, -v28
	v_fma_f32 v35, v87, v73, v29
	v_pk_add_f32 v[20:21], v[20:21], v[36:37] neg_lo:[0,1] neg_hi:[0,1]
	v_pk_mul_f32 v[28:29], v[76:77], v[62:63] op_sel:[0,1]
	v_mov_b32_e32 v61, v44
	v_pk_fma_f32 v[36:37], v[74:75], v[76:77], v[28:29] op_sel:[0,0,1] op_sel_hi:[0,1,0] neg_lo:[0,0,1] neg_hi:[0,0,1]
	v_pk_fma_f32 v[28:29], v[74:75], v[76:77], v[28:29] op_sel:[0,0,1] op_sel_hi:[0,1,0]
	v_pk_mov_b32 v[66:67], v[28:29], v[36:37] op_sel:[1,0]
	v_pk_mul_f32 v[58:59], v[44:45], v[54:55]
	v_pk_mul_f32 v[80:81], v[44:45], v[76:77]
	v_pk_mov_b32 v[82:83], v[62:63], v[74:75] op_sel:[1,0]
	v_mov_b32_e32 v62, v36
	v_mov_b32_e32 v63, v29
	v_pk_mul_f32 v[44:45], v[44:45], v[66:67] op_sel_hi:[0,1]
	v_mul_f32_e32 v23, 0x3f6c835e, v48
	v_fma_f32 v68, v60, v62, v44
	v_fma_f32 v45, v60, v63, -v45
	v_pk_add_f32 v[10:11], v[10:11], v[22:23] neg_lo:[0,1] neg_hi:[0,1]
	v_pk_mul_f32 v[56:57], v[60:61], v[54:55]
	v_pk_mul_f32 v[78:79], v[60:61], v[76:77]
	v_mov_b32_e32 v61, v45
	v_pk_add_f32 v[16:17], v[12:13], v[14:15]
	v_pk_add_f32 v[22:23], v[6:7], v[10:11]
	v_mov_b32_e32 v88, v56
	v_mov_b32_e32 v89, v59
	v_pk_mov_b32 v[56:57], v[56:57], v[58:59] op_sel:[1,0]
	v_mul_f32_e32 v44, v71, v45
	v_mul_f32_e32 v45, v71, v68
	v_pk_mul_f32 v[28:29], v[20:21], v[28:29] op_sel:[1,1] op_sel_hi:[0,1]
	v_pk_add_f32 v[48:49], v[16:17], v[22:23]
	v_pk_mul_f32 v[86:87], v[54:55], v[62:63]
	v_pk_mul_f32 v[54:55], v[54:55], v[66:67]
	v_pk_add_f32 v[58:59], v[88:89], v[56:57]
	v_pk_add_f32 v[56:57], v[88:89], v[56:57] neg_lo:[0,1] neg_hi:[0,1]
	v_fma_f32 v68, v70, v68, -v44
	v_fma_f32 v69, v70, v61, v45
	v_fma_f32 v70, v20, v36, -v28
	v_fma_f32 v71, v21, v36, v29
	v_mov_b32_e32 v42, v46
	v_pk_mul_f32 v[90:91], v[48:49], v[56:57] op_sel:[0,1]
	v_sub_f32_e32 v20, v42, v30
	v_sub_f32_e32 v21, v43, v47
	v_pk_add_f32 v[28:29], v[54:55], v[54:55] op_sel:[0,1] op_sel_hi:[0,1]
	v_fma_f32 v92, v48, v58, -v91
	v_fma_f32 v93, v49, v58, v90
	v_pk_mul_f32 v[28:29], v[20:21], v[28:29] op_sel:[1,0] op_sel_hi:[0,1]
	v_pk_add_f32 v[30:31], v[86:87], v[86:87] op_sel:[0,1] op_sel_hi:[0,1] neg_lo:[0,1] neg_hi:[0,1]
	v_fma_f32 v36, v20, v30, -v28
	v_fma_f32 v37, v21, v31, v29
	ds_write2_b64 v96, v[84:85], v[92:93] offset0:34 offset1:51
	v_mul_f32_e32 v84, v58, v62
	v_mul_f32_e32 v85, v57, v63
	v_mul_f32_e32 v88, v58, v66
	v_mul_f32_e32 v89, v57, v67
	v_sub_f32_e32 v16, v22, v16
	v_sub_f32_e32 v17, v17, v23
	v_pk_add_f32 v[20:21], v[88:89], v[88:89] op_sel:[0,1] op_sel_hi:[0,1]
	v_pk_mul_f32 v[20:21], v[16:17], v[20:21] op_sel:[1,0] op_sel_hi:[0,1]
	v_pk_add_f32 v[22:23], v[84:85], v[84:85] op_sel:[0,1] op_sel_hi:[0,1] neg_lo:[0,1] neg_hi:[0,1]
	v_pk_add_f32 v[2:3], v[2:3], v[26:27] neg_lo:[0,1] neg_hi:[0,1]
	v_pk_add_f32 v[4:5], v[4:5], v[8:9] neg_lo:[0,1] neg_hi:[0,1]
	v_fma_f32 v28, v16, v22, -v20
	v_fma_f32 v29, v17, v23, v21
	v_pk_add_f32 v[8:9], v[2:3], v[4:5] op_sel:[0,1] op_sel_hi:[1,0]
	v_pk_add_f32 v[2:3], v[2:3], v[4:5] op_sel:[0,1] op_sel_hi:[1,0] neg_lo:[0,1] neg_hi:[0,1]
	v_pk_add_f32 v[52:53], v[24:25], v[50:51] op_sel:[0,1] op_sel_hi:[1,0]
	v_pk_add_f32 v[24:25], v[24:25], v[50:51] op_sel:[0,1] op_sel_hi:[1,0] neg_lo:[0,1] neg_hi:[0,1]
	v_mov_b32_e32 v94, v78
	v_mov_b32_e32 v95, v81
	v_pk_mov_b32 v[78:79], v[78:79], v[80:81] op_sel:[1,0]
	v_pk_mul_f32 v[16:17], v[2:3], v[82:83] op_sel:[1,0]
	v_pk_mul_f32 v[92:93], v[76:77], v[66:67]
	v_pk_add_f32 v[80:81], v[94:95], v[78:79]
	v_sub_f32_e32 v79, v95, v79
	v_fma_f32 v20, v8, v74, -v16
	v_fma_f32 v21, v8, v77, v17
	v_pk_mul_f32 v[90:91], v[76:77], v[62:63]
	v_mov_b32_e32 v94, v80
	v_mov_b32_e32 v95, v79
	v_mul_f32_e32 v64, v25, v79
	v_mul_f32_e32 v65, v52, v79
	v_mov_b32_e32 v5, v9
	v_pk_add_f32 v[16:17], v[92:93], v[92:93] op_sel:[0,1] op_sel_hi:[0,1]
	v_fma_f32 v78, v52, v80, -v64
	v_fma_f32 v79, v25, v80, v65
	v_pk_mul_f32 v[64:65], v[66:67], v[94:95]
	v_mul_f32_e32 v8, v9, v16
	v_mul_f32_e32 v9, v2, v17
	v_pk_add_f32 v[16:17], v[90:91], v[90:91] op_sel:[0,1] op_sel_hi:[0,1] neg_lo:[0,1] neg_hi:[0,1]
	v_pk_mul_f32 v[50:51], v[62:63], v[94:95]
	v_fma_f32 v2, v2, v16, -v8
	v_fma_f32 v3, v5, v17, v9
	v_pk_add_f32 v[16:17], v[64:65], v[64:65] op_sel:[0,1] op_sel_hi:[0,1]
	v_mul_f32_e32 v8, v53, v16
	v_mul_f32_e32 v9, v24, v17
	v_pk_add_f32 v[16:17], v[50:51], v[50:51] op_sel:[0,1] op_sel_hi:[0,1] neg_lo:[0,1] neg_hi:[0,1]
	ds_write2_b64 v96, v[20:21], v[78:79] offset0:68 offset1:85
	v_fma_f32 v20, v24, v16, -v8
	v_fma_f32 v21, v53, v17, v9
	v_pk_mul_f32 v[44:45], v[62:63], v[72:73]
	ds_write2_b64 v96, v[2:3], v[20:21] offset0:204 offset1:221
	v_mov_b32_e32 v3, v44
	v_mov_b32_e32 v44, v19
	v_pk_mul_f32 v[60:61], v[66:67], v[72:73]
	v_sub_f32_e32 v2, v18, v44
	v_sub_f32_e32 v3, v3, v45
	v_pk_add_f32 v[8:9], v[60:61], v[60:61] op_sel:[0,1] op_sel_hi:[0,1]
	v_mul_f32_e32 v4, v32, v8
	v_mul_f32_e32 v5, v2, v9
	v_pk_mov_b32 v[8:9], v[2:3], v[32:33] op_sel:[1,0]
	v_pk_mul_f32 v[48:49], v[76:77], v[56:57] op_sel:[0,1]
	v_fma_f32 v16, v2, v8, -v4
	v_fma_f32 v17, v3, v9, v5
	v_sub_f32_e32 v2, v10, v6
	v_sub_f32_e32 v3, v13, v15
	v_pk_mov_b32 v[4:5], v[6:7], v[12:13] op_sel:[1,0]
	v_pk_fma_f32 v[56:57], v[76:77], v[58:59], v[48:49] op_sel:[0,0,1] op_sel_hi:[1,0,0] neg_lo:[0,0,1] neg_hi:[0,0,1]
	v_pk_fma_f32 v[48:49], v[76:77], v[58:59], v[48:49] op_sel:[0,0,1] op_sel_hi:[1,0,0]
	v_sub_f32_e32 v4, v4, v11
	v_sub_f32_e32 v5, v5, v14
	v_mov_b32_e32 v59, v49
	v_pk_mov_b32 v[48:49], v[48:49], v[56:57] op_sel:[1,0]
	v_pk_add_f32 v[6:7], v[2:3], v[4:5]
	v_pk_add_f32 v[2:3], v[2:3], v[4:5] neg_lo:[0,1] neg_hi:[0,1]
	v_mov_b32_e32 v58, v56
	v_pk_mul_f32 v[8:9], v[2:3], v[48:49] op_sel:[1,0]
	v_pk_mul_f32 v[66:67], v[66:67], v[58:59]
	v_fma_f32 v10, v6, v56, -v8
	v_fma_f32 v11, v6, v59, v9
	v_pk_mul_f32 v[62:63], v[62:63], v[58:59]
	v_mov_b32_e32 v5, v7
	v_pk_add_f32 v[8:9], v[66:67], v[66:67] op_sel:[0,1] op_sel_hi:[0,1]
	v_mul_f32_e32 v6, v7, v8
	v_mul_f32_e32 v7, v2, v9
	v_pk_add_f32 v[8:9], v[62:63], v[62:63] op_sel:[0,1] op_sel_hi:[0,1] neg_lo:[0,1] neg_hi:[0,1]
	v_fma_f32 v2, v2, v8, -v6
	v_fma_f32 v3, v5, v9, v7
	ds_write2_b64 v96, v[70:71], v[68:69] offset0:136 offset1:153
	ds_write2_b64 v96, v[16:17], v[2:3] offset0:238 offset1:255
	v_mov_b32_e32 v2, v1
	ds_write2_b64 v96, v[36:37], v[28:29] offset0:170 offset1:187
	ds_write2_b64 v96, v[34:35], v[10:11] offset0:102 offset1:119
	s_waitcnt lgkmcnt(0)
	s_barrier
	v_readlane_b32 s4, v246, 28
	v_mul_lo_u32 v26, v2, s33
	ds_read2_b64 v[2:5], v26 offset0:1 offset1:2
	ds_read_b32 v32, v26
	ds_read_b64 v[30:31], v26 offset:56
	ds_read2_b64 v[6:9], v26 offset0:8 offset1:9
	ds_read2_b64 v[10:13], v26 offset0:10 offset1:11
	ds_read2_b64 v[14:17], v26 offset0:12 offset1:13
	ds_read2_b64 v[18:21], v26 offset0:3 offset1:4
	ds_read2_b64 v[22:25], v26 offset0:5 offset1:6
	ds_read2_b64 v[26:29], v26 offset0:14 offset1:15
	s_waitcnt lgkmcnt(5)
	v_add_f32_e32 v7, v32, v6
	v_sub_f32_e32 v6, v32, v6
	s_waitcnt lgkmcnt(2)
	v_add_f32_e32 v14, v20, v14
	v_sub_f32_e32 v15, v21, v15
	v_add_f32_e32 v20, v7, v14
	v_sub_f32_e32 v7, v7, v14
	v_add_f32_e32 v14, v6, v15
	v_sub_f32_e32 v6, v6, v15
	v_add_f32_e32 v15, v2, v8
	v_add_f32_e32 v21, v3, v9
	v_sub_f32_e32 v2, v2, v8
	v_sub_f32_e32 v3, v3, v9
	s_waitcnt lgkmcnt(1)
	v_add_f32_e32 v8, v22, v16
	v_add_f32_e32 v9, v23, v17
	v_sub_f32_e32 v16, v22, v16
	v_sub_f32_e32 v17, v23, v17
	v_add_f32_e32 v22, v15, v8
	v_add_f32_e32 v23, v21, v9
	v_sub_f32_e32 v8, v15, v8
	v_sub_f32_e32 v9, v21, v9
	v_add_f32_e32 v15, v2, v17
	v_sub_f32_e32 v21, v3, v16
	v_sub_f32_e32 v2, v2, v17
	v_add_f32_e32 v3, v3, v16
	v_add_f32_e32 v16, v4, v10
	v_add_f32_e32 v17, v5, v11
	v_sub_f32_e32 v4, v4, v10
	v_sub_f32_e32 v5, v5, v11
	s_waitcnt lgkmcnt(0)
	v_add_f32_e32 v10, v24, v26
	v_add_f32_e32 v11, v25, v27
	v_sub_f32_e32 v25, v25, v27
	v_sub_f32_e32 v24, v24, v26
	v_add_f32_e32 v10, v16, v10
	v_add_f32_e32 v16, v4, v25
	v_sub_f32_e32 v4, v4, v25
	v_add_f32_e32 v25, v19, v13
	v_sub_f32_e32 v13, v19, v13
	v_add_f32_e32 v19, v31, v29
	v_sub_f32_e32 v26, v30, v28
	v_sub_f32_e32 v27, v31, v29
	v_add_f32_e32 v29, v25, v19
	v_sub_f32_e32 v19, v25, v19
	v_sub_f32_e32 v25, v13, v26
	v_add_f32_e32 v13, v13, v26
	v_mul_f32_e32 v26, 0x3f6c835e, v15
	v_mul_f32_e32 v15, 0xbec3ef15, v15
	v_mul_f32_e32 v8, 0x3f3504f3, v8
	v_sub_f32_e32 v11, v17, v11
	v_sub_f32_e32 v17, v5, v24
	v_add_f32_e32 v5, v5, v24
	v_add_f32_e32 v24, v18, v12
	v_sub_f32_e32 v12, v18, v12
	v_add_f32_e32 v18, v30, v28
	v_fmac_f32_e32 v26, 0x3ec3ef15, v21
	v_fmac_f32_e32 v15, 0x3f6c835e, v21
	v_fmamk_f32 v21, v9, 0x3f3504f3, v8
	v_fma_f32 v8, v9, s20, -v8
	v_mul_f32_e32 v9, 0x3ec3ef15, v2
	v_mul_f32_e32 v2, 0xbf6c835e, v2
	v_add_f32_e32 v28, v24, v18
	v_sub_f32_e32 v18, v24, v18
	v_fmac_f32_e32 v9, 0x3f6c835e, v3
	v_fmac_f32_e32 v2, 0x3ec3ef15, v3
	v_mul_f32_e32 v3, 0x3f3504f3, v16
	v_add_f32_e32 v24, v12, v27
	v_fmac_f32_e32 v3, 0x3f3504f3, v17
	v_mul_f32_e32 v17, 0xbf3504f3, v18
	v_sub_f32_e32 v12, v12, v27
	v_mul_f32_e32 v16, 0xbf6c835e, v24
	v_fmamk_f32 v18, v19, 0x3f3504f3, v17
	v_fmac_f32_e32 v17, 0xbf3504f3, v19
	v_mul_f32_e32 v19, 0xbec3ef15, v13
	v_mul_f32_e32 v13, 0xbf6c835e, v13
	v_fmac_f32_e32 v16, 0x3ec3ef15, v25
	v_fmac_f32_e32 v19, 0xbf6c835e, v12
	v_fmac_f32_e32 v13, 0x3ec3ef15, v12
	v_add_f32_e32 v12, v20, v10
	v_sub_f32_e32 v10, v20, v10
	v_add_f32_e32 v20, v22, v28
	v_sub_f32_e32 v22, v23, v29
	v_mul_f32_e32 v4, 0xbf3504f3, v4
	v_add_f32_e32 v23, v12, v20
	v_sub_f32_e32 v12, v12, v20
	v_add_f32_e32 v20, v10, v22
	v_sub_f32_e32 v10, v10, v22
	v_add_f32_e32 v22, v14, v3
	v_sub_f32_e32 v3, v14, v3
	v_sub_f32_e32 v14, v15, v16
	v_fmac_f32_e32 v4, 0x3f3504f3, v5
	v_add_f32_e32 v16, v3, v14
	v_sub_f32_e32 v3, v3, v14
	v_add_f32_e32 v14, v7, v11
	v_sub_f32_e32 v7, v7, v11
	v_add_f32_e32 v11, v21, v18
	v_sub_f32_e32 v8, v8, v17
	v_add_f32_e32 v17, v14, v11
	v_sub_f32_e32 v11, v14, v11
	v_add_f32_e32 v14, v7, v8
	v_sub_f32_e32 v7, v7, v8
	v_add_f32_e32 v8, v6, v4
	v_sub_f32_e32 v4, v6, v4
	v_add_f32_e32 v6, v9, v19
	v_sub_f32_e32 v2, v2, v13
	v_add_f32_e32 v9, v8, v6
	v_sub_f32_e32 v6, v8, v6
	v_add_f32_e32 v8, v4, v2
	v_sub_f32_e32 v2, v4, v2
	v_lshlrev_b32_e32 v4, 2, v40
	v_mul_f32_e32 v5, 0x3ec3ef15, v24
	v_lshl_add_u32 v18, v39, 2, v4
	v_ashrrev_i32_e32 v19, 2, v39
	v_fmac_f32_e32 v5, 0x3f6c835e, v25
	v_mul_f32_e32 v13, 0x3bb504f3, v23
	v_add_u32_e32 v19, v18, v19
	v_add_f32_e32 v5, v26, v5
	s_barrier
	ds_write_b32 v19, v13
	v_or_b32_e32 v13, 16, v39
	v_add_f32_e32 v15, v22, v5
	v_ashrrev_i32_e32 v13, 2, v13
	v_mul_f32_e32 v15, 0x3bb504f3, v15
	v_add_u32_e32 v13, v18, v13
	ds_write_b32 v13, v15 offset:64
	v_or_b32_e32 v13, 32, v39
	v_ashrrev_i32_e32 v13, 2, v13
	v_mul_f32_e32 v15, 0x3bb504f3, v17
	v_add_u32_e32 v13, v18, v13
	ds_write_b32 v13, v15 offset:128
	v_or_b32_e32 v13, 48, v39
	v_ashrrev_i32_e32 v13, 2, v13
	v_mul_f32_e32 v9, 0x3bb504f3, v9
	v_add_u32_e32 v13, v18, v13
	ds_write_b32 v13, v9 offset:192
	v_or_b32_e32 v9, 64, v39
	v_ashrrev_i32_e32 v9, 2, v9
	v_mul_f32_e32 v13, 0x3bb504f3, v20
	v_add_u32_e32 v9, v18, v9
	ds_write_b32 v9, v13 offset:256
	v_or_b32_e32 v9, 0x50, v39
	v_ashrrev_i32_e32 v9, 2, v9
	v_mul_f32_e32 v13, 0x3bb504f3, v16
	v_add_u32_e32 v9, v18, v9
	ds_write_b32 v9, v13 offset:320
	v_or_b32_e32 v9, 0x60, v39
	v_ashrrev_i32_e32 v9, 2, v9
	v_mul_f32_e32 v13, 0x3bb504f3, v14
	v_add_u32_e32 v9, v18, v9
	ds_write_b32 v9, v13 offset:384
	v_or_b32_e32 v9, 0x70, v39
	v_ashrrev_i32_e32 v9, 2, v9
	v_mul_f32_e32 v8, 0x3bb504f3, v8
	v_add_u32_e32 v9, v18, v9
	ds_write_b32 v9, v8 offset:448
	v_or_b32_e32 v8, 0x80, v39
	v_ashrrev_i32_e32 v8, 2, v8
	v_mul_f32_e32 v9, 0x3bb504f3, v12
	v_add_u32_e32 v8, v18, v8
	ds_write_b32 v8, v9 offset:512
	v_or_b32_e32 v8, 0x90, v39
	v_sub_f32_e32 v5, v22, v5
	v_ashrrev_i32_e32 v8, 2, v8
	v_mul_f32_e32 v5, 0x3bb504f3, v5
	v_add_u32_e32 v8, v18, v8
	ds_write_b32 v8, v5 offset:576
	v_or_b32_e32 v5, 0xa0, v39
	v_ashrrev_i32_e32 v5, 2, v5
	v_mul_f32_e32 v8, 0x3bb504f3, v11
	v_add_u32_e32 v5, v18, v5
	ds_write_b32 v5, v8 offset:640
	v_or_b32_e32 v5, 0xb0, v39
	v_ashrrev_i32_e32 v5, 2, v5
	v_mul_f32_e32 v6, 0x3bb504f3, v6
	v_add_u32_e32 v5, v18, v5
	ds_write_b32 v5, v6 offset:704
	v_or_b32_e32 v5, 0xc0, v39
	v_ashrrev_i32_e32 v5, 2, v5
	v_mul_f32_e32 v6, 0x3bb504f3, v10
	v_add_u32_e32 v5, v18, v5
	ds_write_b32 v5, v6 offset:768
	v_or_b32_e32 v5, 0xd0, v39
	v_ashrrev_i32_e32 v5, 2, v5
	v_mul_f32_e32 v3, 0x3bb504f3, v3
	v_add_u32_e32 v5, v18, v5
	ds_write_b32 v5, v3 offset:832
	v_or_b32_e32 v3, 0xe0, v39
	v_ashrrev_i32_e32 v3, 2, v3
	v_mul_f32_e32 v5, 0x3bb504f3, v7
	v_add_u32_e32 v3, v18, v3
	v_readlane_b32 s5, v246, 29
	s_add_u32 s24, s4, s0
	ds_write_b32 v3, v5 offset:896
	v_or_b32_e32 v3, 0xf0, v38
	s_addc_u32 s35, s5, s1
	s_lshl_b64 s[28:29], s[22:23], 1
	v_lshlrev_b32_e32 v8, 3, v1
	v_lshlrev_b32_e32 v5, 2, v3
	v_ashrrev_i32_e32 v3, 2, v3
	s_add_u32 s22, s24, s28
	v_ashrrev_i32_e32 v9, 31, v8
	v_mul_f32_e32 v2, 0x3bb504f3, v2
	v_add3_u32 v3, v4, v5, v3
	s_addc_u32 s23, s35, s29
	v_lshlrev_b64 v[12:13], 1, v[8:9]
	ds_write_b32 v3, v2
	v_lshl_add_u64 v[2:3], s[22:23], 0, v[12:13]
	s_waitcnt lgkmcnt(0)
	s_barrier
	global_load_dwordx4 v[2:5], v[2:3], off
	v_bfe_i32 v6, v1, 1, 28
	v_lshlrev_b32_e32 v1, 5, v1
	v_lshl_add_u32 v9, v6, 2, v1
	ds_read2_b32 v[10:11], v9 offset1:1
	ds_read2_b32 v[14:15], v9 offset0:2 offset1:3
	ds_read2_b32 v[16:17], v9 offset0:4 offset1:5
	ds_read2_b32 v[18:19], v9 offset0:6 offset1:7
	v_readlane_b32 s4, v247, 56
	v_readlane_b32 s5, v247, 57
	s_add_u32 s0, s4, s0
	s_addc_u32 s1, s5, s1
	s_add_u32 s0, s0, s28
	s_addc_u32 s1, s1, s29
	s_and_b64 vcc, exec, s[36:37]
	s_waitcnt vmcnt(0)
	v_lshlrev_b32_e32 v6, 16, v2
	v_and_b32_e32 v7, 0xffff0000, v2
	s_waitcnt lgkmcnt(3)
	v_pk_mul_f32 v[6:7], v[10:11], v[6:7]
	v_add_u32_e32 v10, 0x800, v8
	v_cvt_pk_bf16_f32 v2, v6, v7
	v_lshlrev_b32_e32 v6, 16, v3
	v_and_b32_e32 v7, 0xffff0000, v3
	s_waitcnt lgkmcnt(2)
	v_pk_mul_f32 v[6:7], v[14:15], v[6:7]
	v_ashrrev_i32_e32 v11, 31, v10
	v_cvt_pk_bf16_f32 v3, v6, v7
	v_lshlrev_b32_e32 v6, 16, v4
	v_and_b32_e32 v7, 0xffff0000, v4
	s_waitcnt lgkmcnt(1)
	v_pk_mul_f32 v[6:7], v[16:17], v[6:7]
	v_ashrrev_i32_e32 v9, 4, v10
	v_cvt_pk_bf16_f32 v4, v6, v7
	v_lshlrev_b32_e32 v6, 16, v5
	v_and_b32_e32 v7, 0xffff0000, v5
	s_waitcnt lgkmcnt(0)
	v_pk_mul_f32 v[6:7], v[18:19], v[6:7]
	v_lshl_add_u32 v1, v9, 2, v1
	v_cvt_pk_bf16_f32 v5, v6, v7
	v_lshl_add_u64 v[6:7], s[0:1], 0, v[12:13]
	global_store_dwordx4 v[6:7], v[2:5], off
	v_lshlrev_b64 v[6:7], 1, v[10:11]
	v_add_u32_e32 v9, 0x2000, v1
	v_lshl_add_u64 v[2:3], s[22:23], 0, v[6:7]
	global_load_dwordx4 v[2:5], v[2:3], off
	ds_read2_b32 v[16:17], v9 offset1:1
	v_add_u32_e32 v11, 0x2008, v1
	v_add_u32_e32 v20, 0x2010, v1
	v_add_u32_e32 v1, 0x2018, v1
	ds_read2_b32 v[18:19], v11 offset1:1
	ds_read2_b32 v[20:21], v20 offset1:1
	ds_read2_b32 v[22:23], v1 offset1:1
	s_waitcnt vmcnt(0)
	v_lshlrev_b32_e32 v14, 16, v2
	v_and_b32_e32 v15, 0xffff0000, v2
	s_waitcnt lgkmcnt(3)
	v_pk_mul_f32 v[14:15], v[16:17], v[14:15]
	s_nop 0
	v_cvt_pk_bf16_f32 v2, v14, v15
	v_lshlrev_b32_e32 v14, 16, v3
	v_and_b32_e32 v15, 0xffff0000, v3
	s_waitcnt lgkmcnt(2)
	v_pk_mul_f32 v[14:15], v[18:19], v[14:15]
	s_nop 0
	v_cvt_pk_bf16_f32 v3, v14, v15
	v_lshlrev_b32_e32 v14, 16, v4
	v_and_b32_e32 v15, 0xffff0000, v4
	s_waitcnt lgkmcnt(1)
	v_pk_mul_f32 v[14:15], v[20:21], v[14:15]
	s_nop 0
	v_cvt_pk_bf16_f32 v4, v14, v15
	v_lshlrev_b32_e32 v14, 16, v5
	v_and_b32_e32 v15, 0xffff0000, v5
	s_waitcnt lgkmcnt(0)
	v_pk_mul_f32 v[14:15], v[22:23], v[14:15]
	s_nop 0
	v_cvt_pk_bf16_f32 v5, v14, v15
	v_lshl_add_u64 v[14:15], s[0:1], 0, v[6:7]
	global_store_dwordx4 v[14:15], v[2:5], off
	s_cbranch_vccnz .LBB0_656
	s_sub_i32 s0, s34, s2
	s_addk_i32 s0, 0x80
	s_mul_hi_i32 s1, s0, 0x14000
	s_mul_i32 s0, s0, 0x14000
	v_readlane_b32 s4, v246, 28
	v_readlane_b32 s5, v246, 29
	s_add_u32 s2, s4, s0
	s_addc_u32 s23, s5, s1
	s_add_u32 s22, s2, s28
	s_addc_u32 s23, s23, s29
	v_lshl_add_u64 v[2:3], s[22:23], 0, v[12:13]
	global_load_dwordx4 v[2:5], v[2:3], off
	v_sub_u32_e32 v9, 0, v8
	v_and_b32_e32 v14, 0xffffff00, v8
	v_and_b32_e32 v9, 0xf8, v9
	v_or_b32_e32 v11, v9, v14
	v_ashrrev_i32_e32 v15, 4, v11
	v_lshlrev_b32_e32 v15, 2, v15
	v_lshl_add_u32 v11, v11, 2, v15
	ds_read_b32 v11, v11
	v_readlane_b32 s4, v247, 56
	v_readlane_b32 s5, v247, 57
	s_add_u32 s0, s4, s0
	s_addc_u32 s1, s5, s1
	s_add_u32 s0, s0, s28
	s_addc_u32 s1, s1, s29
	v_lshl_add_u64 v[12:13], s[0:1], 0, v[12:13]
	v_and_b32_e32 v10, 0xffffff00, v10
	v_or_b32_e32 v9, v10, v9
	s_movk_i32 s2, 0xf0
	s_waitcnt vmcnt(0)
	v_lshlrev_b32_e32 v1, 16, v2
	s_waitcnt lgkmcnt(0)
	v_mul_f32_e32 v15, v11, v1
	v_and_b32_e32 v1, 0xffff0000, v2
	v_xor_b32_e32 v2, 0xf0, v8
	v_ashrrev_i32_e32 v2, 4, v2
	v_xor_b32_e32 v11, 0xf8, v8
	v_lshlrev_b32_e32 v2, 2, v2
	v_lshl_add_u32 v2, v11, 2, v2
	ds_read_b32 v2, v2 offset:28
	s_waitcnt lgkmcnt(0)
	v_mul_f32_e32 v16, v2, v1
	v_sub_u32_e32 v1, 0xfe, v8
	v_and_b32_e32 v1, 0xfe, v1
	v_or_b32_e32 v11, v1, v14
	v_ashrrev_i32_e32 v17, 4, v11
	v_lshlrev_b32_e32 v17, 2, v17
	v_lshl_add_u32 v11, v11, 2, v17
	ds_read_b32 v11, v11
	v_lshlrev_b32_e32 v2, 16, v3
	v_and_b32_e32 v3, 0xffff0000, v3
	v_or_b32_e32 v1, v1, v10
	s_waitcnt lgkmcnt(0)
	v_mul_f32_e32 v17, v11, v2
	v_sub_u32_e32 v2, 0xfd, v8
	v_and_b32_e32 v2, 0xfd, v2
	v_or_b32_e32 v11, v2, v14
	v_ashrrev_i32_e32 v18, 4, v11
	v_lshlrev_b32_e32 v18, 2, v18
	v_lshl_add_u32 v11, v11, 2, v18
	ds_read_b32 v11, v11
	v_or_b32_e32 v2, v2, v10
	s_waitcnt lgkmcnt(0)
	v_mul_f32_e32 v18, v11, v3
	v_sub_u32_e32 v3, 0xfc, v8
	v_and_b32_e32 v3, 0xfc, v3
	v_or_b32_e32 v19, v3, v14
	v_ashrrev_i32_e32 v20, 4, v19
	v_lshlrev_b32_e32 v20, 2, v20
	v_lshl_add_u32 v19, v19, 2, v20
	ds_read_b32 v19, v19
	v_lshlrev_b32_e32 v11, 16, v4
	v_or_b32_e32 v3, v3, v10
	s_waitcnt lgkmcnt(0)
	v_mul_f32_e32 v19, v19, v11
	v_and_b32_e32 v11, 0xffff0000, v4
	v_sub_u32_e32 v4, 0xfb, v8
	v_and_b32_e32 v4, 0xfb, v4
	v_or_b32_e32 v20, v4, v14
	v_ashrrev_i32_e32 v21, 4, v20
	v_lshlrev_b32_e32 v21, 2, v21
	v_lshl_add_u32 v20, v20, 2, v21
	ds_read_b32 v20, v20
	v_lshlrev_b32_e32 v21, 16, v5
	s_waitcnt lgkmcnt(0)
	v_mul_f32_e32 v20, v20, v11
	v_sub_u32_e32 v11, 0xfa, v8
	v_and_b32_e32 v11, 0xfa, v11
	v_or_b32_e32 v22, v11, v14
	v_ashrrev_i32_e32 v23, 4, v22
	v_lshlrev_b32_e32 v23, 2, v23
	v_lshl_add_u32 v22, v22, 2, v23
	ds_read_b32 v22, v22
	s_waitcnt lgkmcnt(0)
	v_mul_f32_e32 v21, v22, v21
	v_and_b32_e32 v22, 0xffff0000, v5
	v_sub_u32_e32 v5, 0xf9, v8
	v_and_b32_e32 v5, 0xf9, v5
	v_or_b32_e32 v14, v5, v14
	v_ashrrev_i32_e32 v23, 4, v14
	v_lshlrev_b32_e32 v23, 2, v23
	v_lshl_add_u32 v14, v14, 2, v23
	ds_read_b32 v14, v14
	s_waitcnt lgkmcnt(0)
	v_mul_f32_e32 v22, v14, v22
	v_cvt_pk_bf16_f32 v14, v15, v16
	v_cvt_pk_bf16_f32 v15, v17, v18
	v_cvt_pk_bf16_f32 v16, v19, v20
	v_cvt_pk_bf16_f32 v17, v21, v22
	global_store_dwordx4 v[12:13], v[14:17], off
	v_lshl_add_u64 v[12:13], s[22:23], 0, v[6:7]
	global_load_dwordx4 v[12:15], v[12:13], off
	v_ashrrev_i32_e32 v17, 4, v9
	v_lshlrev_b32_e32 v17, 2, v17
	v_lshl_add_u32 v9, v9, 2, v17
	ds_read_b32 v9, v9
	v_lshl_add_u64 v[6:7], s[0:1], 0, v[6:7]
	s_waitcnt vmcnt(0)
	v_lshlrev_b32_e32 v16, 16, v12
	s_waitcnt lgkmcnt(0)
	v_mul_f32_e32 v9, v9, v16
	v_and_b32_e32 v16, 0xf8, v8
	v_bitop3_b32 v16, v10, s2, v16 bitop3:0x36
	v_ashrrev_i32_e32 v16, 4, v16
	s_movk_i32 s2, 0xf8
	v_bitop3_b32 v8, v10, s2, v8 bitop3:0x34
	v_lshlrev_b32_e32 v16, 2, v16
	v_lshl_add_u32 v8, v8, 2, v16
	v_ashrrev_i32_e32 v16, 4, v1
	v_lshlrev_b32_e32 v16, 2, v16
	ds_read_b32 v8, v8 offset:28
	v_lshl_add_u32 v1, v1, 2, v16
	ds_read_b32 v1, v1
	v_and_b32_e32 v12, 0xffff0000, v12
	s_waitcnt lgkmcnt(1)
	v_mul_f32_e32 v8, v8, v12
	v_lshlrev_b32_e32 v12, 16, v13
	s_waitcnt lgkmcnt(0)
	v_mul_f32_e32 v1, v1, v12
	v_and_b32_e32 v12, 0xffff0000, v13
	v_ashrrev_i32_e32 v13, 4, v2
	v_lshlrev_b32_e32 v13, 2, v13
	v_lshl_add_u32 v2, v2, 2, v13
	v_ashrrev_i32_e32 v13, 4, v3
	v_lshlrev_b32_e32 v13, 2, v13
	ds_read_b32 v2, v2
	v_lshl_add_u32 v3, v3, 2, v13
	ds_read_b32 v3, v3
	s_waitcnt lgkmcnt(1)
	v_mul_f32_e32 v12, v2, v12
	v_lshlrev_b32_e32 v2, 16, v14
	s_waitcnt lgkmcnt(0)
	v_mul_f32_e32 v13, v3, v2
	v_or_b32_e32 v3, v4, v10
	v_ashrrev_i32_e32 v4, 4, v3
	v_lshlrev_b32_e32 v4, 2, v4
	v_lshl_add_u32 v3, v3, 2, v4
	ds_read_b32 v3, v3
	v_and_b32_e32 v2, 0xffff0000, v14
	s_waitcnt lgkmcnt(0)
	v_mul_f32_e32 v4, v3, v2
	v_or_b32_e32 v3, v11, v10
	v_ashrrev_i32_e32 v11, 4, v3
	v_lshlrev_b32_e32 v11, 2, v11
	v_lshl_add_u32 v3, v3, 2, v11
	ds_read_b32 v3, v3
	v_lshlrev_b32_e32 v2, 16, v15
	v_cvt_pk_bf16_f32 v4, v13, v4
	s_waitcnt lgkmcnt(0)
	v_mul_f32_e32 v11, v3, v2
	v_or_b32_e32 v3, v5, v10
	v_ashrrev_i32_e32 v5, 4, v3
	v_lshlrev_b32_e32 v5, 2, v5
	v_lshl_add_u32 v3, v3, 2, v5
	ds_read_b32 v3, v3
	v_and_b32_e32 v2, 0xffff0000, v15
	s_waitcnt lgkmcnt(0)
	v_mul_f32_e32 v5, v3, v2
	v_cvt_pk_bf16_f32 v2, v9, v8
	v_cvt_pk_bf16_f32 v3, v1, v12
	v_cvt_pk_bf16_f32 v5, v11, v5
	global_store_dwordx4 v[6:7], v[2:5], off

.LBB0_690:
	s_waitcnt vmcnt(9)
	v_lshlrev_b32_e32 v46, 16, v12
	v_lshlrev_b32_e32 v12, 16, v1
	v_mov_b32_e32 v1, v2
	v_lshlrev_b32_e32 v50, 16, v5
	s_barrier
	s_waitcnt vmcnt(1)
	v_lshlrev_b32_e32 v20, 16, v32
	v_ashrrev_i32_e32 v5, 31, v1
	v_lshrrev_b32_e32 v5, 24, v5
	v_lshlrev_b32_e32 v32, 16, v31
	v_lshlrev_b32_e32 v38, 16, v28
	v_lshlrev_b32_e32 v42, 16, v24
	v_lshlrev_b32_e32 v24, 16, v22
	v_lshlrev_b32_e32 v28, 16, v16
	v_lshlrev_b32_e32 v16, 16, v11
	v_lshlrev_b32_e32 v22, 16, v8
	v_lshlrev_b32_e32 v8, 16, v3
	v_and_b32_e32 v3, 0xff, v1
	v_add_lshl_u32 v1, v1, v5, 4
	v_and_or_b32 v1, v1, s87, v3
	s_waitcnt vmcnt(0)
	v_lshlrev_b32_e32 v18, 16, v18
	v_lshlrev_b32_e32 v40, 16, v27
	v_lshlrev_b32_e32 v44, 16, v15
	v_lshlrev_b32_e32 v48, 16, v7
	v_ashrrev_i32_e32 v5, 4, v1
	v_lshlrev_b32_e32 v1, 3, v1
	v_pk_add_f32 v[52:53], v[12:13], v[28:29]
	v_pk_add_f32 v[12:13], v[12:13], v[28:29] neg_lo:[0,1] neg_hi:[0,1]
	v_pk_add_f32 v[28:29], v[22:23], v[38:39]
	v_mov_b32_e32 v55, v22
	v_sub_f32_e32 v56, v46, v20
	v_sub_f32_e32 v57, v16, v32
	v_lshl_add_u32 v1, v5, 3, v1
	v_sub_f32_e32 v22, v23, v39
	v_sub_f32_e32 v23, v55, v38
	v_pk_add_f32 v[38:39], v[8:9], v[24:25]
	v_sub_f32_e32 v54, v50, v42
	v_sub_f32_e32 v55, v8, v24
	v_sub_f32_e32 v24, v6, v30
	v_sub_f32_e32 v25, v9, v25
	v_pk_add_f32 v[8:9], v[16:17], v[32:33]
	v_sub_f32_e32 v16, v14, v36
	v_sub_f32_e32 v17, v17, v33
	v_mov_b32_e32 v51, v6
	v_mov_b32_e32 v43, v30
	v_sub_f32_e32 v7, v6, v30
	v_sub_f32_e32 v6, v48, v40
	v_add_f32_e32 v30, v46, v20
	v_add_f32_e32 v31, v14, v36
	v_sub_f32_e32 v21, v46, v20
	v_sub_f32_e32 v20, v10, v34
	v_sub_f32_e32 v15, v14, v36
	v_sub_f32_e32 v14, v44, v18
	v_pk_add_f32 v[32:33], v[50:51], v[42:43]
	v_sub_f32_e32 v43, v50, v42
	v_sub_f32_e32 v42, v4, v26
	v_pk_add_f32 v[50:51], v[6:7], v[20:21] neg_lo:[0,1] neg_hi:[0,1]
	v_add_f32_e32 v27, v4, v26
	v_add_f32_e32 v26, v48, v40
	v_add_f32_e32 v11, v10, v34
	v_add_f32_e32 v10, v44, v18
	v_pk_add_f32 v[18:19], v[6:7], v[20:21]
	v_pk_add_f32 v[6:7], v[38:39], v[8:9] neg_lo:[0,1] neg_hi:[0,1]
	v_cvt_f32_i32_e32 v3, v3
	v_pk_add_f32 v[4:5], v[26:27], v[10:11] neg_lo:[0,1] neg_hi:[0,1]
	v_pk_mul_f32 v[20:21], v[6:7], s[20:21] op_sel_hi:[1,0]
	v_mul_f32_e32 v40, 0x3f3504f3, v4
	v_pk_fma_f32 v[34:35], v[6:7], s[20:21], v[20:21] op_sel:[0,0,1] op_sel_hi:[1,0,0]
	v_mul_f32_e32 v44, 0x3f3504f3, v5
	v_mul_f32_e32 v49, 0xbf3504f3, v5
	v_pk_add_f32 v[4:5], v[52:53], v[28:29]
	v_pk_add_f32 v[6:7], v[38:39], v[8:9]
	v_pk_add_f32 v[8:9], v[32:33], v[30:31]
	v_pk_add_f32 v[10:11], v[26:27], v[10:11]
	v_pk_add_f32 v[26:27], v[4:5], v[8:9]
	v_pk_add_f32 v[38:39], v[6:7], v[10:11]
	v_add_f32_e32 v3, v3, v3
	v_pk_add_f32 v[60:61], v[26:27], v[38:39]
	v_pk_add_f32 v[36:37], v[32:33], v[30:31] neg_lo:[0,1] neg_hi:[0,1]
	v_mul_f32_e32 v3, 0x39800000, v3
	ds_write_b64 v1, v[60:61]
	v_add_f32_e32 v60, v12, v22
	v_sub_f32_e32 v61, v13, v23
	s_mov_b32 s22, s71
	s_mov_b32 s23, s21
	v_add_f32_e32 v32, v55, v17
	s_mov_b32 s70, s21
	v_pk_add_f32 v[46:47], v[42:43], v[14:15]
	v_pk_add_f32 v[14:15], v[42:43], v[14:15] neg_lo:[0,1] neg_hi:[0,1]
	v_mul_f32_e32 v3, 0.5, v3
	v_sub_f32_e32 v30, v25, v57
	v_pk_mul_f32 v[62:63], v[32:33], s[70:71] op_sel_hi:[0,1]
	v_pk_mul_f32 v[66:67], v[18:19], s[22:23] op_sel_hi:[0,1]
	v_mul_f32_e32 v41, 0x3f3504f3, v47
	v_mul_f32_e32 v43, 0x3f3504f3, v51
	v_sin_f32_e32 v42, v3
	v_fma_f32 v64, v30, s22, v62
	v_fma_f32 v65, v30, s23, -v63
	v_fma_f32 v68, v14, s70, v66
	v_fma_f32 v69, v14, s71, -v67
	v_cos_f32_e32 v58, v3
	s_nop 1
	v_add_f32_e32 v62, v43, v41
	v_fma_f32 v63, v51, s20, -v41
	v_pk_add_f32 v[66:67], v[60:61], v[62:63]
	v_pk_add_f32 v[70:71], v[64:65], v[68:69]
	v_xor_b32_e32 v59, 0x80000000, v42
	v_pk_add_f32 v[72:73], v[66:67], v[70:71]
	v_pk_add_f32 v[66:67], v[66:67], v[70:71] neg_lo:[0,1] neg_hi:[0,1]
	v_pk_mul_f32 v[70:71], v[72:73], v[42:43] op_sel_hi:[1,0]
	v_fma_f32 v74, v72, v58, v71
	v_fma_f32 v75, v73, v58, -v70
	v_pk_add_f32 v[16:17], v[54:55], v[16:17] neg_lo:[0,1] neg_hi:[0,1]
	v_pk_add_f32 v[24:25], v[24:25], v[56:57]
	v_mov_b32_e32 v72, v28
	v_sub_f32_e32 v28, v44, v40
	v_sub_f32_e32 v29, v53, v29
	v_sub_f32_e32 v30, v33, v31
	v_sub_f32_e32 v31, v49, v40
	v_mov_b32_e32 v41, v36
	v_mov_b32_e32 v51, v19
	v_mov_b32_e32 v47, v15
	v_mul_f32_e32 v14, 0x3ec3ef15, v17
	v_mul_f32_e32 v18, 0x3f6c835e, v25
	v_mov_b32_e32 v43, v58
	v_sub_f32_e32 v21, v21, v20
	v_sub_f32_e32 v20, v52, v72
	v_pk_add_f32 v[32:33], v[28:29], v[36:37] op_sel:[1,0] op_sel_hi:[0,1]
	v_add_f32_e32 v36, v28, v34
	v_sub_f32_e32 v41, v29, v41
	v_add_f32_e32 v14, v18, v14
	v_add_f32_e32 v15, v13, v23
	v_pk_mul_f32 v[18:19], v[46:47], s[72:73]
	v_mul_f32_e32 v48, v42, v42
	v_mul_f32_e32 v49, v43, v59
	v_pk_add_f32 v[44:45], v[20:21], v[30:31]
	v_pk_fma_f32 v[18:19], v[50:51], s[30:31], v[18:19] neg_lo:[0,0,1] neg_hi:[0,0,1]
	v_mul_f32_e32 v13, 0x3ec3ef15, v50
	v_pk_fma_f32 v[50:51], v[58:59], v[58:59], v[48:49] op_sel_hi:[0,1,1] neg_lo:[0,0,1] neg_hi:[0,0,1]
	v_pk_fma_f32 v[48:49], v[58:59], v[58:59], v[48:49] op_sel_hi:[0,1,1]
	v_pk_add_f32 v[20:21], v[20:21], v[30:31] neg_lo:[0,1] neg_hi:[0,1]
	v_add_f32_e32 v30, v44, v36
	v_add_f32_e32 v31, v45, v41
	v_mov_b32_e32 v52, v50
	v_mov_b32_e32 v53, v49
	v_mul_f32_e32 v70, v49, v49
	v_mul_f32_e32 v71, v49, v50
	v_pk_mul_f32 v[48:49], v[30:31], v[48:49] op_sel:[1,1] op_sel_hi:[0,1]
	v_pk_fma_f32 v[72:73], v[50:51], v[52:53], v[70:71] op_sel_hi:[0,1,1] neg_lo:[0,0,1] neg_hi:[0,0,1]
	v_pk_fma_f32 v[70:71], v[50:51], v[52:53], v[70:71] op_sel_hi:[0,1,1]
	v_fma_f32 v82, v30, v50, -v48
	v_fma_f32 v83, v31, v50, v49
	v_pk_add_f32 v[28:29], v[34:35], v[28:29] neg_lo:[0,1] neg_hi:[0,1]
	v_pk_add_f32 v[30:31], v[60:61], v[62:63] neg_lo:[0,1] neg_hi:[0,1]
	v_pk_mul_f32 v[62:63], v[52:53], v[70:71] op_sel:[0,1]
	v_pk_add_f32 v[48:49], v[64:65], v[68:69] neg_lo:[0,1] neg_hi:[0,1]
	v_fma_f32 v64, v52, v72, -v63
	v_fma_f32 v63, v53, v72, v62
	v_pk_add_f32 v[34:35], v[32:33], v[28:29]
	v_sub_f32_e32 v28, v32, v28
	ds_write_b64 v1, v[82:83] offset:4352
	v_mov_b32_e32 v68, v64
	v_mov_b32_e32 v69, v63
	v_pk_add_f32 v[82:83], v[20:21], v[20:21] op_sel:[0,1] op_sel_hi:[0,1]
	v_mul_f32_e32 v29, v28, v64
	v_mul_f32_e32 v28, v28, v63
	ds_write_b64 v1, v[74:75] offset:2176
	v_mov_b32_e32 v74, v72
	v_mov_b32_e32 v75, v71
	v_fma_f32 v32, v82, v64, -v28
	v_fma_f32 v33, v83, v69, v29
	v_mov_b32_e32 v59, v42
	v_pk_mul_f32 v[28:29], v[74:75], v[70:71] op_sel:[0,1]
	ds_write_b64 v1, v[32:33] offset:13056
	v_pk_fma_f32 v[32:33], v[72:73], v[74:75], v[28:29] op_sel:[0,0,1] op_sel_hi:[0,1,0] neg_lo:[0,0,1] neg_hi:[0,0,1]
	v_pk_fma_f32 v[28:29], v[72:73], v[74:75], v[28:29] op_sel:[0,0,1] op_sel_hi:[0,1,0]
	v_pk_mov_b32 v[62:63], v[28:29], v[32:33] op_sel:[1,0]
	v_pk_mul_f32 v[56:57], v[42:43], v[52:53]
	v_pk_mul_f32 v[78:79], v[42:43], v[74:75]
	v_pk_add_f32 v[26:27], v[26:27], v[38:39] neg_lo:[0,1] neg_hi:[0,1]
	v_mov_b32_e32 v38, v32
	v_mov_b32_e32 v39, v29
	v_pk_mul_f32 v[42:43], v[42:43], v[62:63] op_sel_hi:[0,1]
	v_fma_f32 v64, v58, v38, v42
	v_fma_f32 v43, v58, v39, -v43
	v_pk_mul_f32 v[54:55], v[58:59], v[52:53]
	v_pk_mul_f32 v[76:77], v[58:59], v[74:75]
	v_mov_b32_e32 v59, v43
	v_pk_mul_f32 v[16:17], v[16:17], s[20:21]
	s_mov_b32 s28, s20
	s_mov_b32 s29, s71
	v_mul_f32_e32 v23, 0x3f6c835e, v46
	v_mul_f32_e32 v42, v67, v43
	v_mul_f32_e32 v43, v67, v64
	v_pk_mul_f32 v[28:29], v[26:27], v[28:29] op_sel:[1,1] op_sel_hi:[0,1]
	v_pk_fma_f32 v[16:17], v[24:25], s[28:29], v[16:17] neg_lo:[0,0,1] neg_hi:[0,0,1]
	v_pk_add_f32 v[12:13], v[12:13], v[22:23] neg_lo:[0,1] neg_hi:[0,1]
	v_pk_mov_b32 v[80:81], v[70:71], v[72:73] op_sel:[1,0]
	v_pk_mul_f32 v[70:71], v[52:53], v[38:39]
	v_pk_mul_f32 v[52:53], v[52:53], v[62:63]
	v_fma_f32 v64, v66, v64, -v42
	v_fma_f32 v65, v66, v59, v43
	v_fma_f32 v66, v26, v32, -v28
	v_fma_f32 v67, v27, v32, v29
	v_pk_add_f32 v[22:23], v[14:15], v[18:19]
	v_pk_add_f32 v[24:25], v[16:17], v[12:13]
	v_mov_b32_e32 v82, v54
	v_pk_mov_b32 v[54:55], v[54:55], v[56:57] op_sel:[1,0]
	v_sub_f32_e32 v26, v44, v36
	v_sub_f32_e32 v27, v41, v45
	v_pk_add_f32 v[28:29], v[52:53], v[52:53] op_sel:[0,1] op_sel_hi:[0,1]
	v_pk_add_f32 v[46:47], v[22:23], v[24:25]
	v_add_f32_e32 v56, v82, v54
	v_sub_f32_e32 v54, v82, v54
	v_sub_f32_e32 v55, v57, v55
	v_pk_mul_f32 v[28:29], v[26:27], v[28:29] op_sel:[1,0] op_sel_hi:[0,1]
	v_pk_add_f32 v[32:33], v[70:71], v[70:71] op_sel:[0,1] op_sel_hi:[0,1] neg_lo:[0,1] neg_hi:[0,1]
	v_pk_mul_f32 v[84:85], v[46:47], v[54:55] op_sel:[0,1]
	v_fma_f32 v36, v26, v32, -v28
	v_fma_f32 v37, v27, v33, v29
	v_fma_f32 v86, v46, v56, -v85
	v_fma_f32 v87, v47, v56, v84
	v_mul_f32_e32 v84, v56, v38
	v_mul_f32_e32 v85, v55, v39
	v_mul_f32_e32 v82, v56, v62
	v_mul_f32_e32 v83, v55, v63
	v_sub_f32_e32 v22, v24, v22
	v_sub_f32_e32 v23, v23, v25
	v_pk_add_f32 v[24:25], v[82:83], v[82:83] op_sel:[0,1] op_sel_hi:[0,1]
	v_pk_add_f32 v[4:5], v[4:5], v[8:9] neg_lo:[0,1] neg_hi:[0,1]
	v_pk_add_f32 v[6:7], v[6:7], v[10:11] neg_lo:[0,1] neg_hi:[0,1]
	v_pk_mul_f32 v[24:25], v[22:23], v[24:25] op_sel:[1,0] op_sel_hi:[0,1]
	v_pk_add_f32 v[26:27], v[84:85], v[84:85] op_sel:[0,1] op_sel_hi:[0,1] neg_lo:[0,1] neg_hi:[0,1]
	v_pk_add_f32 v[8:9], v[4:5], v[6:7] op_sel:[0,1] op_sel_hi:[1,0]
	v_pk_add_f32 v[4:5], v[4:5], v[6:7] op_sel:[0,1] op_sel_hi:[1,0] neg_lo:[0,1] neg_hi:[0,1]
	v_fma_f32 v28, v22, v26, -v24
	v_fma_f32 v29, v23, v27, v25
	v_pk_mul_f32 v[10:11], v[4:5], v[80:81] op_sel:[1,0]
	v_pk_add_f32 v[50:51], v[30:31], v[48:49] op_sel:[0,1] op_sel_hi:[1,0]
	v_pk_add_f32 v[30:31], v[30:31], v[48:49] op_sel:[0,1] op_sel_hi:[1,0] neg_lo:[0,1] neg_hi:[0,1]
	v_pk_mul_f32 v[88:89], v[74:75], v[62:63]
	v_mov_b32_e32 v90, v76
	v_pk_mov_b32 v[76:77], v[76:77], v[78:79] op_sel:[1,0]
	v_fma_f32 v22, v8, v72, -v10
	v_fma_f32 v23, v8, v75, v11
	ds_write_b64 v1, v[86:87] offset:6528
	v_pk_mul_f32 v[86:87], v[74:75], v[38:39]
	v_add_f32_e32 v78, v90, v76
	v_sub_f32_e32 v77, v79, v77
	v_mov_b32_e32 v7, v9
	v_pk_add_f32 v[10:11], v[88:89], v[88:89] op_sel:[0,1] op_sel_hi:[0,1]
	v_mov_b32_e32 v90, v78
	v_mov_b32_e32 v91, v77
	v_mul_f32_e32 v60, v31, v77
	v_mul_f32_e32 v61, v50, v77
	v_mul_f32_e32 v8, v9, v10
	v_mul_f32_e32 v9, v4, v11
	v_pk_add_f32 v[10:11], v[86:87], v[86:87] op_sel:[0,1] op_sel_hi:[0,1] neg_lo:[0,1] neg_hi:[0,1]
	v_fma_f32 v76, v50, v78, -v60
	v_fma_f32 v77, v31, v78, v61
	v_pk_mul_f32 v[60:61], v[62:63], v[90:91]
	v_fma_f32 v4, v4, v10, -v8
	v_fma_f32 v5, v7, v11, v9
	v_pk_mul_f32 v[48:49], v[38:39], v[90:91]
	v_pk_add_f32 v[8:9], v[60:61], v[60:61] op_sel:[0,1] op_sel_hi:[0,1]
	ds_write_b64 v1, v[76:77] offset:10880
	ds_write_b64 v1, v[66:67] offset:17408
	ds_write_b64 v1, v[64:65] offset:19584
	ds_write_b64 v1, v[4:5] offset:26112
	v_mul_f32_e32 v6, v51, v8
	v_mul_f32_e32 v7, v30, v9
	v_pk_add_f32 v[8:9], v[48:49], v[48:49] op_sel:[0,1] op_sel_hi:[0,1] neg_lo:[0,1] neg_hi:[0,1]
	v_pk_mul_f32 v[42:43], v[38:39], v[68:69]
	v_fma_f32 v10, v30, v8, -v6
	v_fma_f32 v11, v51, v9, v7
	v_pk_mul_f32 v[58:59], v[62:63], v[68:69]
	v_sub_f32_e32 v4, v20, v21
	v_sub_f32_e32 v5, v42, v43
	v_pk_add_f32 v[8:9], v[58:59], v[58:59] op_sel:[0,1] op_sel_hi:[0,1]
	v_mul_f32_e32 v6, v34, v8
	v_mul_f32_e32 v7, v4, v9
	v_pk_mov_b32 v[8:9], v[4:5], v[34:35] op_sel:[1,0]
	ds_write_b64 v1, v[10:11] offset:28288
	v_fma_f32 v10, v4, v8, -v6
	v_fma_f32 v11, v5, v9, v7
	v_pk_mul_f32 v[46:47], v[74:75], v[54:55] op_sel:[0,1]
	v_sub_f32_e32 v4, v12, v16
	v_sub_f32_e32 v5, v15, v19
	v_fma_f32 v54, v74, v56, -v47
	v_fma_f32 v47, v75, v56, v46
	v_sub_f32_e32 v6, v17, v13
	v_sub_f32_e32 v7, v14, v18
	v_mov_b32_e32 v57, v47
	v_pk_add_f32 v[8:9], v[4:5], v[6:7]
	v_pk_add_f32 v[4:5], v[4:5], v[6:7] neg_lo:[0,1] neg_hi:[0,1]
	v_mov_b32_e32 v56, v54
	ds_write_b64 v1, v[10:11] offset:30464
	v_mul_f32_e32 v10, v5, v47
	v_mul_f32_e32 v11, v5, v54
	v_pk_mul_f32 v[62:63], v[62:63], v[56:57]
	v_fma_f32 v12, v8, v54, -v10
	v_fma_f32 v13, v8, v57, v11
	v_pk_mul_f32 v[38:39], v[38:39], v[56:57]
	v_mov_b32_e32 v7, v9
	v_pk_add_f32 v[10:11], v[62:63], v[62:63] op_sel:[0,1] op_sel_hi:[0,1]
	v_mul_f32_e32 v8, v9, v10
	v_mul_f32_e32 v9, v4, v11
	v_pk_add_f32 v[10:11], v[38:39], v[38:39] op_sel:[0,1] op_sel_hi:[0,1] neg_lo:[0,1] neg_hi:[0,1]
	v_fma_f32 v4, v4, v10, -v8
	v_fma_f32 v5, v7, v11, v9
	ds_write_b64 v1, v[36:37] offset:21760
	ds_write_b64 v1, v[28:29] offset:23936
	ds_write_b64 v1, v[22:23] offset:8704
	ds_write_b64 v1, v[12:13] offset:15232
	ds_write_b64 v1, v[4:5] offset:32640
	v_mov_b32_e32 v1, v2
	s_waitcnt lgkmcnt(0)
	s_barrier
	v_readlane_b32 s4, v246, 28
	v_ashrrev_i32_e32 v4, 31, v1
	v_lshrrev_b32_e32 v4, 28, v4
	v_and_b32_e32 v3, 15, v1
	v_add_u32_e32 v1, v1, v4
	v_ashrrev_i32_e32 v1, 4, v1
	v_lshlrev_b32_e32 v4, 11, v1
	v_lshl_add_u32 v1, v1, 7, v4
	v_lshl_or_b32 v1, v3, 3, v1
	ds_read2_b64 v[14:17], v1 offset1:17
	ds_read2_b64 v[18:21], v1 offset0:68 offset1:85
	ds_read2_b64 v[22:25], v1 offset0:136 offset1:153
	ds_read2_b64 v[26:29], v1 offset0:170 offset1:187
	ds_read2_b64 v[30:33], v1 offset0:204 offset1:221
	ds_read2_b64 v[34:37], v1 offset0:238 offset1:255
	ds_read2_b64 v[38:41], v1 offset0:34 offset1:51
	ds_read2_b64 v[42:45], v1 offset0:102 offset1:119
	s_waitcnt lgkmcnt(5)
	v_pk_add_f32 v[12:13], v[22:23], v[14:15]
	v_pk_add_f32 v[22:23], v[14:15], v[22:23] neg_lo:[0,1] neg_hi:[0,1]
	s_waitcnt lgkmcnt(2)
	v_pk_mov_b32 v[62:63], v[28:29], v[36:37] op_sel:[1,0]
	s_waitcnt lgkmcnt(1)
	v_pk_add_f32 v[58:59], v[40:41], v[28:29]
	s_waitcnt lgkmcnt(0)
	v_sub_f32_e32 v28, v40, v28
	v_sub_f32_e32 v29, v45, v37
	v_pk_add_f32 v[14:15], v[18:19], v[30:31] neg_lo:[0,1] neg_hi:[0,1]
	v_pk_add_f32 v[46:47], v[30:31], v[18:19]
	v_pk_add_f32 v[48:49], v[16:17], v[24:25]
	v_pk_add_f32 v[50:51], v[20:21], v[32:33]
	v_pk_add_f32 v[60:61], v[44:45], v[36:37]
	v_sub_f32_e32 v62, v41, v62
	v_sub_f32_e32 v63, v44, v63
	v_sub_f32_e32 v40, v28, v29
	v_pk_mov_b32 v[18:19], v[14:15], v[14:15] op_sel:[1,0]
	v_add_f32_e32 v30, v22, v15
	v_sub_f32_e32 v31, v23, v14
	v_pk_add_f32 v[28:29], v[28:29], v[28:29] op_sel:[0,1] op_sel_hi:[0,1]
	v_pk_add_f32 v[6:7], v[48:49], v[50:51]
	v_pk_add_f32 v[36:37], v[58:59], v[60:61] neg_lo:[0,1] neg_hi:[0,1]
	v_pk_add_f32 v[48:49], v[48:49], v[50:51] neg_lo:[0,1] neg_hi:[0,1]
	v_pk_add_f32 v[14:15], v[62:63], v[62:63] op_sel:[0,1] op_sel_hi:[0,1] neg_lo:[0,1] neg_hi:[0,1]
	v_pk_mul_f32 v[28:29], v[28:29], s[22:23]
	v_pk_add_f32 v[52:53], v[38:39], v[26:27]
	v_pk_add_f32 v[54:55], v[42:43], v[34:35]
	v_pk_add_f32 v[10:11], v[58:59], v[60:61]
	v_add_f32_e32 v44, v62, v63
	v_pk_mul_f32 v[50:51], v[48:49], s[20:21] op_sel_hi:[1,0]
	v_mul_f32_e32 v36, 0x3f3504f3, v36
	v_mul_f32_e32 v58, 0x3f3504f3, v37
	v_mul_f32_e32 v61, 0xbf3504f3, v37
	v_fma_f32 v62, v14, s70, v28
	v_fma_f32 v63, v15, s71, -v29
	v_pk_add_f32 v[4:5], v[12:13], v[46:47]
	v_pk_add_f32 v[56:57], v[52:53], v[54:55] neg_lo:[0,1] neg_hi:[0,1]
	v_cvt_f32_i32_e32 v3, v3
	v_mov_b32_e32 v14, v12
	v_sub_f32_e32 v12, v58, v36
	v_sub_f32_e32 v13, v13, v47
	v_sub_f32_e32 v14, v14, v46
	v_sub_f32_e32 v15, v51, v50
	v_mov_b32_e32 v29, v36
	v_pk_add_f32 v[36:37], v[12:13], v[56:57] op_sel:[1,0] op_sel_hi:[0,1]
	v_mov_b32_e32 v47, v56
	v_sub_f32_e32 v28, v53, v55
	v_sub_f32_e32 v29, v61, v29
	v_sub_f32_e32 v56, v38, v26
	v_sub_f32_e32 v57, v16, v24
	v_sub_f32_e32 v58, v43, v35
	v_sub_f32_e32 v59, v21, v33
	v_mul_f32_e32 v72, 0x3f6c835e, v44
	v_mul_f32_e32 v73, 0x3ec3ef15, v40
	v_add_f32_e32 v3, v3, v3
	v_sub_f32_e32 v16, v39, v27
	v_sub_f32_e32 v17, v17, v25
	v_sub_f32_e32 v21, v20, v32
	v_sub_f32_e32 v20, v42, v34
	v_pk_add_f32 v[26:27], v[56:57], v[58:59] neg_lo:[0,1] neg_hi:[0,1]
	v_pk_fma_f32 v[48:49], v[48:49], s[20:21], v[50:51] op_sel:[0,0,1] op_sel_hi:[1,0,0]
	v_mul_f32_e32 v3, 0x3b800000, v3
	v_pk_add_f32 v[60:61], v[56:57], v[58:59]
	v_pk_add_f32 v[24:25], v[16:17], v[20:21] neg_lo:[0,1] neg_hi:[0,1]
	v_pk_add_f32 v[16:17], v[16:17], v[20:21]
	v_mov_b32_e32 v33, v23
	v_mov_b32_e32 v21, v19
	v_mul_f32_e32 v3, 0.5, v3
	v_mov_b32_e32 v46, v48
	v_pk_add_f32 v[48:49], v[48:49], v[12:13] neg_lo:[0,1] neg_hi:[0,1]
	v_mul_f32_e32 v20, 0x3ec3ef15, v27
	v_pk_mul_f32 v[34:35], v[26:27], s[20:21]
	v_mul_f32_e32 v27, s73, v26
	v_mul_f32_e32 v26, s72, v44
	v_sub_f32_e32 v18, v22, v18
	v_sub_f32_e32 v19, v73, v72
	v_pk_mul_f32 v[22:23], v[60:61], s[70:71] op_sel:[1,0]
	v_pk_add_f32 v[8:9], v[52:53], v[54:55]
	v_sin_f32_e32 v52, v3
	v_cos_f32_e32 v70, v3
	v_add_f32_e32 v50, v12, v46
	v_sub_f32_e32 v47, v13, v47
	v_pk_add_f32 v[12:13], v[36:37], v[48:49]
	v_mul_f32_e32 v32, 0x3f6c835e, v17
	v_mul_f32_e32 v3, 0x3f3504f3, v60
	v_mul_f32_e32 v37, 0x3f3504f3, v24
	v_pk_fma_f32 v[34:35], v[16:17], s[28:29], v[34:35] neg_lo:[0,0,1] neg_hi:[0,0,1]
	v_fma_f32 v17, v16, s31, -v27
	v_fma_f32 v16, v40, s30, -v26
	v_fma_f32 v26, v25, s22, v22
	v_fma_f32 v27, v25, s23, -v23
	v_pk_add_f32 v[20:21], v[32:33], v[20:21]
	v_add_f32_e32 v22, v37, v3
	v_fma_f32 v23, v24, s20, -v3
	v_pk_add_f32 v[24:25], v[30:31], v[22:23]
	v_pk_add_f32 v[32:33], v[26:27], v[62:63]
	v_xor_b32_e32 v71, 0x80000000, v52
	v_pk_add_f32 v[38:39], v[32:33], v[24:25]
	v_pk_add_f32 v[64:65], v[4:5], v[8:9]
	v_pk_mul_f32 v[44:45], v[52:53], v[38:39] op_sel_hi:[0,1]
	v_fma_f32 v56, v70, v38, v45
	v_fma_f32 v57, v70, v39, -v44
	v_mov_b32_e32 v53, v70
	v_pk_add_f32 v[66:67], v[6:7], v[10:11]
	v_mul_f32_e32 v38, v52, v52
	v_mul_f32_e32 v39, v53, v71
	v_pk_add_f32 v[68:69], v[66:67], v[64:65]
	v_pk_fma_f32 v[44:45], v[70:71], v[70:71], v[38:39] op_sel_hi:[0,1,1] neg_lo:[0,0,1] neg_hi:[0,0,1]
	v_pk_fma_f32 v[38:39], v[70:71], v[70:71], v[38:39] op_sel_hi:[0,1,1]
	v_pk_add_f32 v[54:55], v[14:15], v[28:29]
	ds_write2_b64 v1, v[68:69], v[56:57] offset1:17
	v_pk_add_f32 v[14:15], v[14:15], v[28:29] neg_lo:[0,1] neg_hi:[0,1]
	v_add_f32_e32 v28, v54, v50
	v_add_f32_e32 v29, v55, v47
	v_mov_b32_e32 v56, v44
	v_mov_b32_e32 v57, v39
	v_mul_f32_e32 v68, v39, v39
	v_mul_f32_e32 v69, v39, v44
	v_pk_mul_f32 v[38:39], v[28:29], v[38:39] op_sel:[1,1] op_sel_hi:[0,1]
	v_pk_fma_f32 v[72:73], v[44:45], v[56:57], v[68:69] op_sel_hi:[0,1,1] neg_lo:[0,0,1] neg_hi:[0,0,1]
	v_pk_fma_f32 v[68:69], v[44:45], v[56:57], v[68:69] op_sel_hi:[0,1,1]
	v_fma_f32 v82, v28, v44, -v38
	v_fma_f32 v83, v29, v44, v39
	v_pk_mul_f32 v[38:39], v[56:57], v[68:69] op_sel:[0,1]
	v_pk_add_f32 v[26:27], v[26:27], v[62:63] neg_lo:[0,1] neg_hi:[0,1]
	v_fma_f32 v44, v56, v72, -v39
	v_fma_f32 v39, v57, v72, v38
	v_sub_f32_e32 v36, v36, v48
	v_mov_b32_e32 v63, v39
	v_mov_b32_e32 v71, v52
	v_mov_b32_e32 v74, v72
	v_mov_b32_e32 v75, v69
	v_pk_add_f32 v[84:85], v[14:15], v[14:15] op_sel:[0,1] op_sel_hi:[0,1]
	v_mul_f32_e32 v37, v36, v44
	v_mul_f32_e32 v36, v36, v39
	v_pk_mul_f32 v[58:59], v[70:71], v[56:57]
	v_pk_mul_f32 v[60:61], v[52:53], v[56:57]
	v_mov_b32_e32 v62, v44
	v_fma_f32 v38, v84, v44, -v36
	v_pk_mul_f32 v[44:45], v[74:75], v[68:69] op_sel:[0,1]
	v_pk_add_f32 v[24:25], v[24:25], v[32:33] neg_lo:[0,1] neg_hi:[0,1]
	v_pk_add_f32 v[32:33], v[34:35], v[18:19]
	v_pk_add_f32 v[40:41], v[20:21], v[16:17]
	v_fma_f32 v39, v85, v63, v37
	v_pk_fma_f32 v[48:49], v[72:73], v[74:75], v[44:45] op_sel:[0,0,1] op_sel_hi:[0,1,0] neg_lo:[0,0,1] neg_hi:[0,0,1]
	v_pk_fma_f32 v[44:45], v[72:73], v[74:75], v[44:45] op_sel:[0,0,1] op_sel_hi:[0,1,0]
	v_mov_b32_e32 v86, v58
	v_mov_b32_e32 v87, v61
	v_pk_mov_b32 v[58:59], v[58:59], v[60:61] op_sel:[1,0]
	v_pk_add_f32 v[42:43], v[32:33], v[40:41]
	v_pk_add_f32 v[36:37], v[64:65], v[66:67] neg_lo:[0,1] neg_hi:[0,1]
	v_pk_mov_b32 v[66:67], v[44:45], v[48:49] op_sel:[1,0]
	v_pk_add_f32 v[60:61], v[86:87], v[58:59]
	v_pk_add_f32 v[58:59], v[86:87], v[58:59] neg_lo:[0,1] neg_hi:[0,1]
	v_pk_mul_f32 v[76:77], v[70:71], v[74:75]
	v_pk_mul_f32 v[78:79], v[52:53], v[74:75]
	v_pk_add_f32 v[22:23], v[30:31], v[22:23] neg_lo:[0,1] neg_hi:[0,1]
	v_mov_b32_e32 v64, v48
	v_mov_b32_e32 v65, v45
	v_pk_mul_f32 v[52:53], v[52:53], v[66:67] op_sel_hi:[0,1]
	v_pk_mul_f32 v[88:89], v[42:43], v[58:59] op_sel:[0,1]
	v_pk_mov_b32 v[80:81], v[68:69], v[72:73] op_sel:[1,0]
	v_pk_add_f32 v[28:29], v[22:23], v[26:27] op_sel:[0,1] op_sel_hi:[1,0]
	v_pk_add_f32 v[22:23], v[22:23], v[26:27] op_sel:[0,1] op_sel_hi:[1,0] neg_lo:[0,1] neg_hi:[0,1]
	v_fma_f32 v68, v70, v64, v52
	v_fma_f32 v53, v70, v65, -v53
	v_fma_f32 v90, v42, v60, -v89
	v_fma_f32 v91, v43, v60, v88
	v_mov_b32_e32 v92, v76
	v_mov_b32_e32 v93, v79
	v_pk_mov_b32 v[76:77], v[76:77], v[78:79] op_sel:[1,0]
	v_mov_b32_e32 v71, v53
	v_pk_mul_f32 v[42:43], v[74:75], v[58:59] op_sel:[0,1]
	v_pk_add_f32 v[78:79], v[92:93], v[76:77]
	v_sub_f32_e32 v77, v93, v77
	v_mov_b32_e32 v70, v68
	v_mov_b32_e32 v87, v59
	v_pk_fma_f32 v[58:59], v[74:75], v[60:61], v[42:43] op_sel:[0,0,1] op_sel_hi:[1,0,0] neg_lo:[0,0,1] neg_hi:[0,0,1]
	v_pk_fma_f32 v[42:43], v[74:75], v[60:61], v[42:43] op_sel:[0,0,1] op_sel_hi:[1,0,0]
	v_mul_f32_e32 v30, v23, v77
	v_mul_f32_e32 v31, v28, v77
	v_mul_f32_e32 v52, v25, v53
	v_mul_f32_e32 v53, v25, v68
	v_mov_b32_e32 v86, v60
	v_mov_b32_e32 v60, v58
	v_mov_b32_e32 v61, v43
	v_mov_b32_e32 v92, v78
	v_mov_b32_e32 v93, v77
	v_fma_f32 v76, v28, v78, -v30
	v_fma_f32 v77, v23, v78, v31
	v_fma_f32 v68, v24, v68, -v52
	v_fma_f32 v69, v24, v71, v53
	v_pk_mul_f32 v[44:45], v[36:37], v[44:45] op_sel:[1,1] op_sel_hi:[0,1]
	v_pk_mul_f32 v[84:85], v[56:57], v[64:65]
	v_pk_mul_f32 v[56:57], v[56:57], v[66:67]
	ds_write2_b64 v1, v[82:83], v[90:91] offset0:34 offset1:51
	v_pk_mul_f32 v[82:83], v[86:87], v[64:65]
	v_pk_mul_f32 v[86:87], v[86:87], v[66:67]
	v_pk_mul_f32 v[88:89], v[74:75], v[64:65]
	v_pk_mul_f32 v[90:91], v[74:75], v[66:67]
	v_pk_mul_f32 v[26:27], v[64:65], v[92:93]
	v_pk_mul_f32 v[30:31], v[66:67], v[92:93]
	v_pk_mul_f32 v[24:25], v[64:65], v[62:63]
	v_pk_mul_f32 v[52:53], v[66:67], v[62:63]
	v_pk_mul_f32 v[62:63], v[64:65], v[60:61]
	v_pk_mul_f32 v[64:65], v[66:67], v[60:61]
	v_fma_f32 v66, v36, v48, -v44
	v_fma_f32 v67, v37, v48, v45
	v_mov_b32_e32 v51, v55
	v_sub_f32_e32 v36, v54, v50
	v_sub_f32_e32 v37, v47, v51
	v_pk_add_f32 v[44:45], v[56:57], v[56:57] op_sel:[0,1] op_sel_hi:[0,1]
	v_pk_mul_f32 v[44:45], v[36:37], v[44:45] op_sel:[1,0] op_sel_hi:[0,1]
	v_pk_add_f32 v[46:47], v[84:85], v[84:85] op_sel:[0,1] op_sel_hi:[0,1] neg_lo:[0,1] neg_hi:[0,1]
	v_fma_f32 v48, v36, v46, -v44
	v_fma_f32 v49, v37, v47, v45
	v_pk_add_f32 v[4:5], v[4:5], v[8:9] neg_lo:[0,1] neg_hi:[0,1]
	v_sub_f32_e32 v32, v32, v40
	v_sub_f32_e32 v33, v41, v33
	v_pk_add_f32 v[36:37], v[86:87], v[86:87] op_sel:[0,1] op_sel_hi:[0,1]
	v_pk_add_f32 v[6:7], v[6:7], v[10:11] neg_lo:[0,1] neg_hi:[0,1]
	v_pk_mul_f32 v[36:37], v[32:33], v[36:37] op_sel:[1,0] op_sel_hi:[0,1]
	v_pk_add_f32 v[40:41], v[82:83], v[82:83] op_sel:[0,1] op_sel_hi:[0,1] neg_lo:[0,1] neg_hi:[0,1]
	v_pk_add_f32 v[8:9], v[4:5], v[6:7] op_sel:[0,1] op_sel_hi:[1,0]
	v_pk_add_f32 v[4:5], v[4:5], v[6:7] op_sel:[0,1] op_sel_hi:[1,0] neg_lo:[0,1] neg_hi:[0,1]
	v_fma_f32 v44, v32, v40, -v36
	v_fma_f32 v45, v33, v41, v37
	v_pk_mul_f32 v[10:11], v[4:5], v[80:81] op_sel:[1,0]
	v_fma_f32 v32, v8, v72, -v10
	v_fma_f32 v33, v8, v75, v11
	v_mov_b32_e32 v7, v9
	v_pk_add_f32 v[10:11], v[90:91], v[90:91] op_sel:[0,1] op_sel_hi:[0,1]
	v_mul_f32_e32 v8, v9, v10
	v_mul_f32_e32 v9, v4, v11
	v_pk_add_f32 v[10:11], v[88:89], v[88:89] op_sel:[0,1] op_sel_hi:[0,1] neg_lo:[0,1] neg_hi:[0,1]
	v_fma_f32 v4, v4, v10, -v8
	v_fma_f32 v5, v7, v11, v9
	v_pk_add_f32 v[10:11], v[30:31], v[30:31] op_sel:[0,1] op_sel_hi:[0,1]
	v_mul_f32_e32 v8, v29, v10
	v_mul_f32_e32 v9, v22, v11
	v_pk_add_f32 v[10:11], v[26:27], v[26:27] op_sel:[0,1] op_sel_hi:[0,1] neg_lo:[0,1] neg_hi:[0,1]
	v_fma_f32 v22, v22, v10, -v8
	v_fma_f32 v23, v29, v11, v9
	v_pk_add_f32 v[8:9], v[52:53], v[52:53] op_sel:[0,1] op_sel_hi:[0,1]
	ds_write2_b64 v1, v[4:5], v[22:23] offset0:204 offset1:221
	v_sub_f32_e32 v4, v14, v15
	v_sub_f32_e32 v5, v24, v25
	v_mul_f32_e32 v6, v12, v8
	v_mul_f32_e32 v7, v4, v9
	v_pk_mov_b32 v[8:9], v[4:5], v[12:13] op_sel:[1,0]
	v_pk_mov_b32 v[42:43], v[42:43], v[58:59] op_sel:[1,0]
	v_fma_f32 v10, v4, v8, -v6
	v_fma_f32 v11, v5, v9, v7
	v_sub_f32_e32 v4, v18, v34
	v_sub_f32_e32 v5, v20, v16
	v_sub_f32_e32 v6, v35, v19
	v_sub_f32_e32 v7, v21, v17
	ds_write2_b64 v1, v[66:67], v[68:69] offset0:136 offset1:153
	v_pk_add_f32 v[8:9], v[6:7], v[4:5]
	v_sub_f32_e32 v12, v4, v6
	v_sub_f32_e32 v4, v7, v5
	v_pk_mul_f32 v[4:5], v[4:5], v[42:43] op_sel_hi:[0,1]
	v_fma_f32 v6, v8, v58, -v4
	v_fma_f32 v7, v8, v61, v5
	ds_write2_b64 v1, v[38:39], v[6:7] offset0:102 offset1:119
	v_pk_add_f32 v[6:7], v[64:65], v[64:65] op_sel:[0,1] op_sel_hi:[0,1]
	v_mul_f32_e32 v4, v9, v6
	v_mul_f32_e32 v5, v12, v7
	v_pk_add_f32 v[6:7], v[62:63], v[62:63] op_sel:[0,1] op_sel_hi:[0,1] neg_lo:[0,1] neg_hi:[0,1]
	v_fma_f32 v8, v12, v6, -v4
	v_fma_f32 v9, v9, v7, v5
	ds_write2_b64 v1, v[48:49], v[44:45] offset0:170 offset1:187
	ds_write2_b64 v1, v[32:33], v[76:77] offset0:68 offset1:85
	ds_write2_b64 v1, v[10:11], v[8:9] offset0:238 offset1:255
	v_mov_b32_e32 v1, v2
	s_waitcnt lgkmcnt(0)
	s_barrier
	v_readlane_b32 s5, v246, 29
	v_mul_lo_u32 v1, v1, s33
	ds_read2_b64 v[4:7], v1 offset1:1
	ds_read2_b64 v[8:11], v1 offset0:2 offset1:3
	ds_read2_b64 v[12:15], v1 offset0:8 offset1:9
	ds_read2_b64 v[16:19], v1 offset0:14 offset1:15
	ds_read2_b64 v[20:23], v1 offset0:12 offset1:13
	ds_read2_b64 v[24:27], v1 offset0:4 offset1:5
	ds_read2_b64 v[28:31], v1 offset0:6 offset1:7
	ds_read2_b64 v[32:35], v1 offset0:10 offset1:11
	s_waitcnt lgkmcnt(5)
	v_add_f32_e32 v1, v4, v12
	v_sub_f32_e32 v3, v4, v12
	s_waitcnt lgkmcnt(2)
	v_add_f32_e32 v4, v24, v20
	v_sub_f32_e32 v5, v25, v21
	v_add_f32_e32 v12, v1, v4
	v_sub_f32_e32 v1, v1, v4
	v_add_f32_e32 v4, v3, v5
	v_sub_f32_e32 v3, v3, v5
	v_add_f32_e32 v5, v6, v14
	v_add_f32_e32 v13, v7, v15
	v_sub_f32_e32 v6, v6, v14
	v_sub_f32_e32 v7, v7, v15
	v_add_f32_e32 v14, v26, v22
	v_add_f32_e32 v15, v27, v23
	v_sub_f32_e32 v20, v26, v22
	v_sub_f32_e32 v21, v27, v23
	v_add_f32_e32 v22, v5, v14
	v_add_f32_e32 v23, v13, v15
	v_sub_f32_e32 v5, v5, v14
	v_sub_f32_e32 v13, v13, v15
	v_add_f32_e32 v14, v6, v21
	v_sub_f32_e32 v15, v7, v20
	v_sub_f32_e32 v6, v6, v21
	v_add_f32_e32 v7, v7, v20
	s_waitcnt lgkmcnt(0)
	v_add_f32_e32 v20, v8, v32
	v_add_f32_e32 v21, v9, v33
	v_sub_f32_e32 v8, v8, v32
	v_sub_f32_e32 v9, v9, v33
	v_add_f32_e32 v24, v28, v16
	v_add_f32_e32 v25, v29, v17
	v_sub_f32_e32 v16, v28, v16
	v_sub_f32_e32 v17, v29, v17
	v_add_f32_e32 v20, v20, v24
	v_sub_f32_e32 v21, v21, v25
	v_add_f32_e32 v24, v8, v17
	v_sub_f32_e32 v25, v9, v16
	v_sub_f32_e32 v8, v8, v17
	v_add_f32_e32 v9, v9, v16
	v_add_f32_e32 v16, v10, v34
	v_add_f32_e32 v17, v11, v35
	v_sub_f32_e32 v11, v11, v35
	v_add_f32_e32 v26, v30, v18
	v_add_f32_e32 v27, v31, v19
	v_sub_f32_e32 v18, v30, v18
	v_sub_f32_e32 v10, v10, v34
	v_sub_f32_e32 v19, v31, v19
	v_add_f32_e32 v28, v16, v26
	v_add_f32_e32 v29, v17, v27
	v_sub_f32_e32 v16, v16, v26
	v_sub_f32_e32 v17, v17, v27
	v_sub_f32_e32 v27, v11, v18
	v_add_f32_e32 v11, v11, v18
	v_mul_f32_e32 v18, 0x3f6c835e, v14
	v_mul_f32_e32 v14, 0x3ec3ef15, v14
	v_mul_f32_e32 v5, 0x3f3504f3, v5
	v_add_f32_e32 v26, v10, v19
	v_fmac_f32_e32 v18, 0x3ec3ef15, v15
	v_fma_f32 v14, v15, s21, -v14
	v_fmamk_f32 v15, v13, 0x3f3504f3, v5
	v_fma_f32 v5, v13, s20, -v5
	v_mul_f32_e32 v13, 0x3ec3ef15, v6
	v_mul_f32_e32 v6, 0xbf6c835e, v6
	v_mul_f32_e32 v8, 0xbf3504f3, v8
	v_mul_f32_e32 v16, 0xbf3504f3, v16
	v_sub_f32_e32 v10, v10, v19
	v_fmac_f32_e32 v13, 0x3f6c835e, v7
	v_fmac_f32_e32 v6, 0x3ec3ef15, v7
	v_mul_f32_e32 v7, 0x3f3504f3, v24
	v_fmac_f32_e32 v8, 0x3f3504f3, v9
	v_mul_f32_e32 v9, 0x3ec3ef15, v26
	v_mul_f32_e32 v19, 0xbf6c835e, v26
	v_fmamk_f32 v24, v17, 0x3f3504f3, v16
	v_fmac_f32_e32 v16, 0xbf3504f3, v17
	v_mul_f32_e32 v17, 0x3ec3ef15, v11
	v_mul_f32_e32 v11, 0xbf6c835e, v11
	v_fmac_f32_e32 v7, 0x3f3504f3, v25
	v_fmac_f32_e32 v9, 0x3f6c835e, v27
	v_fmac_f32_e32 v19, 0x3ec3ef15, v27
	v_fma_f32 v17, v10, s76, -v17
	v_fmac_f32_e32 v11, 0x3ec3ef15, v10
	v_add_f32_e32 v10, v12, v20
	v_sub_f32_e32 v12, v12, v20
	v_add_f32_e32 v20, v22, v28
	v_sub_f32_e32 v22, v23, v29
	v_add_f32_e32 v23, v20, v10
	v_sub_f32_e32 v10, v10, v20
	v_add_f32_e32 v20, v12, v22
	v_sub_f32_e32 v12, v12, v22
	v_add_f32_e32 v22, v4, v7
	v_sub_f32_e32 v4, v4, v7
	v_add_f32_e32 v7, v18, v9
	v_sub_f32_e32 v9, v14, v19
	v_add_f32_e32 v18, v9, v4
	v_sub_f32_e32 v4, v4, v9
	v_add_f32_e32 v9, v1, v21
	v_sub_f32_e32 v1, v1, v21
	v_add_f32_e32 v15, v15, v24
	v_sub_f32_e32 v5, v5, v16
	v_add_f32_e32 v16, v9, v15
	v_sub_f32_e32 v9, v9, v15
	v_add_f32_e32 v15, v1, v5
	v_sub_f32_e32 v1, v1, v5
	v_add_f32_e32 v5, v3, v8
	v_sub_f32_e32 v3, v3, v8
	v_add_f32_e32 v8, v13, v17
	v_sub_f32_e32 v6, v6, v11
	v_add_f32_e32 v11, v8, v5
	v_sub_f32_e32 v5, v5, v8
	v_add_f32_e32 v8, v6, v3
	v_sub_f32_e32 v3, v3, v6
	v_lshlrev_b32_e32 v6, 4, v2
	v_and_b32_e32 v6, 0xf0, v6
	v_ashrrev_i32_e32 v13, 4, v2
	v_add_u32_e32 v6, v6, v13
	v_ashrrev_i32_e32 v17, 4, v6
	v_lshlrev_b32_e32 v19, 2, v6
	v_mul_f32_e32 v13, 0x3ab504f3, v23
	v_lshl_add_u32 v17, v17, 2, v19
	s_barrier
	ds_write_b32 v17, v13
	v_add_u32_e32 v13, 0x100, v6
	v_add_f32_e32 v14, v7, v22
	v_ashrrev_i32_e32 v13, 4, v13
	v_mul_f32_e32 v14, 0x3ab504f3, v14
	v_lshl_add_u32 v13, v13, 2, v19
	ds_write_b32 v13, v14 offset:1024
	v_add_u32_e32 v13, 0x200, v6
	v_ashrrev_i32_e32 v13, 4, v13
	v_mul_f32_e32 v14, 0x3ab504f3, v16
	v_lshl_add_u32 v13, v13, 2, v19
	ds_write_b32 v13, v14 offset:2048
	v_add_u32_e32 v13, 0x300, v6
	v_ashrrev_i32_e32 v13, 4, v13
	v_mul_f32_e32 v11, 0x3ab504f3, v11
	v_lshl_add_u32 v13, v13, 2, v19
	ds_write_b32 v13, v11 offset:3072
	v_add_u32_e32 v11, 0x400, v6
	v_ashrrev_i32_e32 v11, 4, v11
	v_mul_f32_e32 v13, 0x3ab504f3, v20
	v_lshl_add_u32 v11, v11, 2, v19
	ds_write_b32 v11, v13 offset:4096
	v_add_u32_e32 v11, 0x500, v6
	v_ashrrev_i32_e32 v11, 4, v11
	v_mul_f32_e32 v13, 0x3ab504f3, v18
	v_lshl_add_u32 v11, v11, 2, v19
	ds_write_b32 v11, v13 offset:5120
	v_add_u32_e32 v11, 0x600, v6
	v_ashrrev_i32_e32 v11, 4, v11
	v_mul_f32_e32 v13, 0x3ab504f3, v15
	v_lshl_add_u32 v11, v11, 2, v19
	ds_write_b32 v11, v13 offset:6144
	v_add_u32_e32 v11, 0x700, v6
	v_ashrrev_i32_e32 v11, 4, v11
	v_mul_f32_e32 v8, 0x3ab504f3, v8
	v_lshl_add_u32 v11, v11, 2, v19
	ds_write_b32 v11, v8 offset:7168
	v_add_u32_e32 v8, 0x800, v6
	v_ashrrev_i32_e32 v8, 4, v8
	v_mul_f32_e32 v10, 0x3ab504f3, v10
	v_lshl_add_u32 v8, v8, 2, v19
	ds_write_b32 v8, v10 offset:8192
	v_add_u32_e32 v8, 0x900, v6
	v_sub_f32_e32 v7, v22, v7
	v_ashrrev_i32_e32 v8, 4, v8
	v_mul_f32_e32 v7, 0x3ab504f3, v7
	v_lshl_add_u32 v8, v8, 2, v19
	ds_write_b32 v8, v7 offset:9216
	v_add_u32_e32 v7, 0xa00, v6
	v_ashrrev_i32_e32 v7, 4, v7
	v_mul_f32_e32 v8, 0x3ab504f3, v9
	v_lshl_add_u32 v7, v7, 2, v19
	ds_write_b32 v7, v8 offset:10240
	v_add_u32_e32 v7, 0xb00, v6
	v_ashrrev_i32_e32 v7, 4, v7
	v_mul_f32_e32 v5, 0x3ab504f3, v5
	v_lshl_add_u32 v7, v7, 2, v19
	ds_write_b32 v7, v5 offset:11264
	v_add_u32_e32 v5, 0xc00, v6
	v_ashrrev_i32_e32 v5, 4, v5
	v_mul_f32_e32 v7, 0x3ab504f3, v12
	v_lshl_add_u32 v5, v5, 2, v19
	ds_write_b32 v5, v7 offset:12288
	v_add_u32_e32 v5, 0xd00, v6
	v_ashrrev_i32_e32 v5, 4, v5
	v_mul_f32_e32 v4, 0x3ab504f3, v4
	v_lshl_add_u32 v5, v5, 2, v19
	ds_write_b32 v5, v4 offset:13312
	v_add_u32_e32 v4, 0xe00, v6
	v_ashrrev_i32_e32 v4, 4, v4
	v_mul_f32_e32 v1, 0x3ab504f3, v1
	v_lshl_add_u32 v4, v4, 2, v19
	s_add_u32 s22, s4, s0
	ds_write_b32 v4, v1 offset:14336
	s_addc_u32 s23, s5, s1
	v_lshlrev_b32_e32 v4, 3, v2
	v_add_u32_e32 v1, 0xf00, v6
	s_add_u32 s22, s22, s2
	v_ashrrev_i32_e32 v5, 31, v4
	v_ashrrev_i32_e32 v1, 4, v1
	s_addc_u32 s23, s23, 0
	v_lshlrev_b64 v[6:7], 1, v[4:5]
	v_mul_f32_e32 v3, 0x3ab504f3, v3
	v_lshl_add_u32 v1, v1, 2, v19
	v_lshl_add_u64 v[8:9], s[22:23], 0, v[6:7]
	ds_write_b32 v1, v3 offset:15360
	s_waitcnt lgkmcnt(0)
	s_barrier
	global_load_dwordx4 v[8:11], v[8:9], off
	v_bfe_i32 v1, v2, 1, 28
	v_lshlrev_b32_e32 v5, 5, v2
	v_lshl_add_u32 v1, v1, 2, v5
	ds_read2_b32 v[12:13], v1 offset1:1
	ds_read2_b32 v[14:15], v1 offset0:2 offset1:3
	ds_read2_b32 v[16:17], v1 offset0:4 offset1:5
	ds_read2_b32 v[18:19], v1 offset0:6 offset1:7
	v_readlane_b32 s4, v247, 56
	v_readlane_b32 s5, v247, 57
	s_add_u32 s0, s4, s0
	s_addc_u32 s1, s5, s1
	s_add_u32 s0, s0, s2
	s_addc_u32 s1, s1, 0
	s_and_b64 vcc, exec, s[36:37]
	s_waitcnt vmcnt(0)
	v_lshlrev_b32_e32 v2, 16, v8
	v_and_b32_e32 v3, 0xffff0000, v8
	s_waitcnt lgkmcnt(3)
	v_pk_mul_f32 v[2:3], v[12:13], v[2:3]
	s_nop 0
	v_cvt_pk_bf16_f32 v8, v2, v3
	v_lshlrev_b32_e32 v2, 16, v9
	v_and_b32_e32 v3, 0xffff0000, v9
	s_waitcnt lgkmcnt(2)
	v_pk_mul_f32 v[2:3], v[14:15], v[2:3]
	s_nop 0
	v_cvt_pk_bf16_f32 v9, v2, v3
	v_lshlrev_b32_e32 v2, 16, v10
	v_and_b32_e32 v3, 0xffff0000, v10
	s_waitcnt lgkmcnt(1)
	v_pk_mul_f32 v[2:3], v[16:17], v[2:3]
	s_nop 0
	v_cvt_pk_bf16_f32 v10, v2, v3
	v_lshlrev_b32_e32 v2, 16, v11
	v_and_b32_e32 v3, 0xffff0000, v11
	s_waitcnt lgkmcnt(0)
	v_pk_mul_f32 v[2:3], v[18:19], v[2:3]
	s_nop 0
	v_cvt_pk_bf16_f32 v11, v2, v3
	v_lshl_add_u64 v[2:3], s[0:1], 0, v[6:7]
	global_store_dwordx4 v[2:3], v[8:11], off
	s_nop 1
	v_add_u32_e32 v8, 0x800, v4
	v_ashrrev_i32_e32 v9, 31, v8
	v_lshlrev_b64 v[2:3], 1, v[8:9]
	v_lshl_add_u64 v[10:11], s[22:23], 0, v[2:3]
	global_load_dwordx4 v[10:13], v[10:11], off
	v_ashrrev_i32_e32 v1, 4, v8
	v_lshl_add_u32 v1, v1, 2, v5
	v_add_u32_e32 v5, 0x2000, v1
	ds_read2_b32 v[16:17], v5 offset1:1
	v_add_u32_e32 v9, 0x2008, v1
	v_add_u32_e32 v20, 0x2010, v1
	v_add_u32_e32 v1, 0x2018, v1
	ds_read2_b32 v[18:19], v9 offset1:1
	ds_read2_b32 v[20:21], v20 offset1:1
	ds_read2_b32 v[22:23], v1 offset1:1
	s_waitcnt vmcnt(0)
	v_lshlrev_b32_e32 v14, 16, v10
	v_and_b32_e32 v15, 0xffff0000, v10
	s_waitcnt lgkmcnt(3)
	v_pk_mul_f32 v[14:15], v[16:17], v[14:15]
	s_nop 0
	v_cvt_pk_bf16_f32 v10, v14, v15
	v_lshlrev_b32_e32 v14, 16, v11
	v_and_b32_e32 v15, 0xffff0000, v11
	s_waitcnt lgkmcnt(2)
	v_pk_mul_f32 v[14:15], v[18:19], v[14:15]
	s_nop 0
	v_cvt_pk_bf16_f32 v11, v14, v15
	v_lshlrev_b32_e32 v14, 16, v12
	v_and_b32_e32 v15, 0xffff0000, v12
	s_waitcnt lgkmcnt(1)
	v_pk_mul_f32 v[14:15], v[20:21], v[14:15]
	s_nop 0
	v_cvt_pk_bf16_f32 v12, v14, v15
	v_lshlrev_b32_e32 v14, 16, v13
	v_and_b32_e32 v15, 0xffff0000, v13
	s_waitcnt lgkmcnt(0)
	v_pk_mul_f32 v[14:15], v[22:23], v[14:15]
	s_nop 0
	v_cvt_pk_bf16_f32 v13, v14, v15
	v_lshl_add_u64 v[14:15], s[0:1], 0, v[2:3]
	global_store_dwordx4 v[14:15], v[10:13], off
	s_cbranch_vccnz .LBB0_692
	s_sub_i32 s0, s34, s24
	s_addk_i32 s0, 0x80
	s_mul_hi_i32 s22, s0, 0x14000
	s_mul_i32 s23, s0, 0x14000
	v_readlane_b32 s0, v246, 28
	v_readlane_b32 s1, v246, 29
	s_add_u32 s0, s0, s23
	s_addc_u32 s1, s1, s22
	s_add_u32 s0, s0, s2
	s_addc_u32 s1, s1, 0
	v_lshl_add_u64 v[10:11], s[0:1], 0, v[6:7]
	global_load_dwordx4 v[10:13], v[10:11], off
	v_and_b32_e32 v1, 0xfffff000, v4
	v_sub_u32_e32 v5, 0, v4
	v_xor_b32_e32 v9, 0xff0, v4
	v_sub_u32_e32 v15, 0xffe, v4
	v_sub_u32_e32 v16, 0xffd, v4
	v_sub_u32_e32 v17, 0xffc, v4
	v_sub_u32_e32 v18, 0xffb, v4
	v_sub_u32_e32 v19, 0xffa, v4
	v_sub_u32_e32 v20, 0xff9, v4
	s_movk_i32 s7, 0xff8
	s_movk_i32 s6, 0xffe
	s_movk_i32 s8, 0xffd
	s_movk_i32 s9, 0xffc
	s_movk_i32 s10, 0xffb
	s_movk_i32 s11, 0xffa
	s_movk_i32 s12, 0xff9
	v_and_or_b32 v5, v5, s7, v1
	v_ashrrev_i32_e32 v9, 4, v9
	v_and_or_b32 v15, v15, s6, v1
	v_and_or_b32 v16, v16, s8, v1
	v_and_or_b32 v17, v17, s9, v1
	v_and_or_b32 v18, v18, s10, v1
	v_and_or_b32 v19, v19, s11, v1
	v_and_or_b32 v1, v20, s12, v1
	v_xor_b32_e32 v14, 0xff8, v4
	v_ashrrev_i32_e32 v20, 4, v5
	v_lshlrev_b32_e32 v9, 2, v9
	v_ashrrev_i32_e32 v21, 4, v15
	v_ashrrev_i32_e32 v22, 4, v16
	v_ashrrev_i32_e32 v23, 4, v17
	v_ashrrev_i32_e32 v24, 4, v18
	v_ashrrev_i32_e32 v25, 4, v19
	v_ashrrev_i32_e32 v26, 4, v1
	v_lshlrev_b32_e32 v20, 2, v20
	v_lshl_add_u32 v9, v14, 2, v9
	v_lshlrev_b32_e32 v14, 2, v21
	v_lshlrev_b32_e32 v21, 2, v22
	v_lshlrev_b32_e32 v22, 2, v23
	v_lshlrev_b32_e32 v23, 2, v24
	v_lshlrev_b32_e32 v24, 2, v25
	v_lshlrev_b32_e32 v25, 2, v26
	v_lshl_add_u32 v5, v5, 2, v20
	v_lshl_add_u32 v14, v15, 2, v14
	v_lshl_add_u32 v15, v16, 2, v21
	v_lshl_add_u32 v16, v17, 2, v22
	v_lshl_add_u32 v17, v18, 2, v23
	v_lshl_add_u32 v18, v19, 2, v24
	v_lshl_add_u32 v1, v1, 2, v25
	ds_read_b32 v5, v5
	ds_read_b32 v9, v9 offset:28
	ds_read_b32 v19, v14
	ds_read_b32 v20, v15
	ds_read_b32 v16, v16
	ds_read_b32 v17, v17
	ds_read_b32 v18, v18
	ds_read_b32 v1, v1
	v_readlane_b32 s4, v247, 56
	v_readlane_b32 s5, v247, 57
	s_add_u32 s23, s4, s23
	v_lshl_add_u64 v[14:15], s[0:1], 0, v[2:3]
	s_addc_u32 s1, s5, s22
	s_add_u32 s0, s23, s2
	s_addc_u32 s1, s1, 0
	v_lshl_add_u64 v[6:7], s[0:1], 0, v[6:7]
	v_lshl_add_u64 v[2:3], s[0:1], 0, v[2:3]
	s_waitcnt vmcnt(0)
	v_lshlrev_b32_e32 v21, 16, v10
	v_and_b32_e32 v10, 0xffff0000, v10
	v_lshlrev_b32_e32 v22, 16, v11
	v_and_b32_e32 v11, 0xffff0000, v11
	v_lshlrev_b32_e32 v23, 16, v12
	v_and_b32_e32 v12, 0xffff0000, v12
	v_lshlrev_b32_e32 v24, 16, v13
	v_and_b32_e32 v13, 0xffff0000, v13
	s_waitcnt lgkmcnt(7)
	v_mul_f32_e32 v5, v5, v21
	s_waitcnt lgkmcnt(6)
	v_mul_f32_e32 v9, v9, v10
	s_waitcnt lgkmcnt(5)
	v_mul_f32_e32 v19, v19, v22
	s_waitcnt lgkmcnt(4)
	v_mul_f32_e32 v11, v20, v11
	s_waitcnt lgkmcnt(3)
	v_mul_f32_e32 v16, v16, v23
	s_waitcnt lgkmcnt(2)
	v_mul_f32_e32 v12, v17, v12
	s_waitcnt lgkmcnt(1)
	v_mul_f32_e32 v17, v18, v24
	s_waitcnt lgkmcnt(0)
	v_mul_f32_e32 v1, v1, v13
	v_cvt_pk_bf16_f32 v10, v5, v9
	v_cvt_pk_bf16_f32 v11, v19, v11
	v_cvt_pk_bf16_f32 v12, v16, v12
	v_cvt_pk_bf16_f32 v13, v17, v1
	global_store_dwordx4 v[6:7], v[10:13], off
	global_load_dwordx4 v[10:13], v[14:15], off
	v_and_b32_e32 v1, 0xfffff000, v8
	v_sub_u32_e32 v5, 0x800, v4
	v_xor_b32_e32 v6, 0xff0, v8
	v_xor_b32_e32 v7, 0xff8, v8
	v_sub_u32_e32 v8, 0x7fe, v4
	v_sub_u32_e32 v9, 0x7fd, v4
	v_sub_u32_e32 v14, 0x7fc, v4
	v_sub_u32_e32 v15, 0x7fb, v4
	v_sub_u32_e32 v16, 0x7fa, v4
	v_sub_u32_e32 v4, 0x7f9, v4
	v_and_or_b32 v5, v5, s7, v1
	v_ashrrev_i32_e32 v6, 4, v6
	v_and_or_b32 v8, v8, s6, v1
	v_and_or_b32 v9, v9, s8, v1
	v_and_or_b32 v14, v14, s9, v1
	v_and_or_b32 v15, v15, s10, v1
	v_and_or_b32 v16, v16, s11, v1
	v_and_or_b32 v1, v4, s12, v1
	v_ashrrev_i32_e32 v4, 4, v5
	v_lshlrev_b32_e32 v6, 2, v6
	v_ashrrev_i32_e32 v17, 4, v8
	v_ashrrev_i32_e32 v18, 4, v9
	v_ashrrev_i32_e32 v19, 4, v14
	v_ashrrev_i32_e32 v20, 4, v15
	v_ashrrev_i32_e32 v21, 4, v16
	v_ashrrev_i32_e32 v22, 4, v1
	v_lshlrev_b32_e32 v4, 2, v4
	v_lshl_add_u32 v6, v7, 2, v6
	v_lshlrev_b32_e32 v7, 2, v17
	v_lshlrev_b32_e32 v17, 2, v18
	v_lshlrev_b32_e32 v18, 2, v19
	v_lshlrev_b32_e32 v19, 2, v20
	v_lshlrev_b32_e32 v20, 2, v21
	v_lshlrev_b32_e32 v21, 2, v22
	v_lshl_add_u32 v4, v5, 2, v4
	v_lshl_add_u32 v5, v8, 2, v7
	v_lshl_add_u32 v7, v9, 2, v17
	v_lshl_add_u32 v8, v14, 2, v18
	v_lshl_add_u32 v9, v15, 2, v19
	v_lshl_add_u32 v14, v16, 2, v20
	v_lshl_add_u32 v1, v1, 2, v21
	ds_read_b32 v4, v4
	ds_read_b32 v6, v6 offset:28
	ds_read_b32 v5, v5
	ds_read_b32 v7, v7
	ds_read_b32 v8, v8
	ds_read_b32 v9, v9
	ds_read_b32 v14, v14
	ds_read_b32 v1, v1
	s_waitcnt vmcnt(0)
	v_lshlrev_b32_e32 v15, 16, v10
	v_and_b32_e32 v10, 0xffff0000, v10
	v_lshlrev_b32_e32 v16, 16, v11
	v_and_b32_e32 v11, 0xffff0000, v11
	v_lshlrev_b32_e32 v17, 16, v12
	v_and_b32_e32 v12, 0xffff0000, v12
	v_lshlrev_b32_e32 v18, 16, v13
	v_and_b32_e32 v13, 0xffff0000, v13
	s_waitcnt lgkmcnt(7)
	v_mul_f32_e32 v4, v4, v15
	s_waitcnt lgkmcnt(6)
	v_mul_f32_e32 v6, v6, v10
	s_waitcnt lgkmcnt(5)
	v_mul_f32_e32 v5, v5, v16
	s_waitcnt lgkmcnt(4)
	v_mul_f32_e32 v7, v7, v11
	s_waitcnt lgkmcnt(3)
	v_mul_f32_e32 v8, v8, v17
	s_waitcnt lgkmcnt(2)
	v_mul_f32_e32 v9, v9, v12
	s_waitcnt lgkmcnt(1)
	v_mul_f32_e32 v10, v14, v18
	s_waitcnt lgkmcnt(0)
	v_mul_f32_e32 v1, v1, v13
	v_cvt_pk_bf16_f32 v4, v4, v6
	v_cvt_pk_bf16_f32 v5, v5, v7
	v_cvt_pk_bf16_f32 v6, v8, v9
	v_cvt_pk_bf16_f32 v7, v10, v1
	global_store_dwordx4 v[2:3], v[4:7], off
